# v023 + first K-iteration of every GEMM unit peeled: first MFMA per accumulator takes srcC=0, the 128-register accumulator zero fill per unit is gone
# speedup vs baseline: 1.0199x; 1.0199x over previous
; #define PG8_STAGE(bufoff, gbase, voff) do { _Pragma("unroll") for (int _i = 0; _i < 2; ++_i) \
;         __builtin_amdgcn_global_load_lds((const unsigned*)((const char*)(gbase) + (voff)[_i]), (PG8_LAS unsigned*)(lds + (bufoff) + ldsw + _i * 8192), 16, 0, AUX_A); } while (0)
; #define PG8_LDA(dst, b, h) do { _Pragma("unroll") for (int m = 0; m < 4; ++m) _Pragma("unroll") for (int k = 0; k < 2; ++k) dst[m][k] = *(const PG8_LAS bf16x8*)(lds + PG8_SA(b, h) + aoff + m * 2048 + k * 1024); } while (0)
; #define PG8_LDB(dst, b, h) do { _Pragma("unroll") for (int n = 0; n < 2; ++n) _Pragma("unroll") for (int k = 0; k < 2; ++k) dst[n][k] = *(const PG8_LAS bf16x8*)(lds + PG8_SB(b, h) + boff + n * 2048 + k * 1024); } while (0)
; #define PG8_WAIT_V(n) asm volatile("s_waitcnt vmcnt(" #n ")" ::: "memory")
; #define PG8_WAIT_L(n) asm volatile("s_waitcnt lgkmcnt(" #n ")" ::: "memory")
; #define PG8_BAR __builtin_amdgcn_s_barrier()
; #define PG8_SCHED __builtin_amdgcn_sched_barrier(0)
; template <class Epi, class Sched, bool ALIGN_EPI = false, bool SP2 = false>
; __device__ __forceinline__ void gemm_phase(PG8_LAS unsigned char* lds, const Gemm g, const Sched& S, const Epi& E) {
;     ...
;     for (;;) {
;         const bool has_next = S.next(ui + 1, nxt);
;         const char* nA = has_next ? (const char*)g.A + (size_t)nxt.pm * tstep + (size_t)nxt.kt0 * kstep : cA; const char* nB = has_next ? (const char*)g.Bt + (size_t)nxt.pn * tstep + (size_t)nxt.kt0 * kstep : cB;
;         const int nt = cur.nkt, rot = cur.krot;
;         const char* nAr = has_next ? nA + (size_t)nxt.krot * kstep : PG8_KP(cA, 0, rot, nt); const char* nBr = has_next ? nB + (size_t)nxt.krot * kstep : PG8_KP(cB, 0, rot, nt);
;         for (int t = 0; t < nt; t += 2) {
;             const bool last = (t == nt - 2);
;             const char* a1 = PG8_KP(cA, t + 1, rot, nt);
;             const char* a2 = last ? nAr : PG8_KP(cA, t + 2, rot, nt); const char* b2 = last ? nBr : PG8_KP(cB, t + 2, rot, nt);
;             const char* a3 = a2 + kstep; const char* b3 = b2 + kstep;
;             if (last && has_next) S.a_ready(nxt);
;             if constexpr (SP2) {
;             PG8_LDB(B0, 0, 0); PG8_LDB(B1, 0, 1); PG8_SCHED; PG8_LDA(At, 0, 0); PG8_STAGE(PG8_SA(1, 1), a1 + hstep, voffA);
;             PG8_WAIT_V(8); PG8_WAIT_L(0); PG8_BAR; PG8_MMA(0, 0, At, B0); PG8_MMA(0, 1, At, B1); PG8_BAR; PG8_SCHED;
.LBB0_269:
	s_ashr_i32 s29, s28, 31
	s_lshl_b64 s[0:1], s[28:29], 20
	s_add_u32 s52, s88, s0
	s_addc_u32 s53, s8, s1
	s_ashr_i32 s35, s34, 31
	s_lshl_b64 s[0:1], s[34:35], 20
	s_add_u32 s54, s24, s0
	s_addc_u32 s55, s25, s1
	s_and_b64 s[0:1], s[26:27], exec
	s_cselect_b32 s49, s53, s41
	s_cselect_b32 s51, s52, s40
	s_cselect_b32 vcc_lo, s55, s39
	s_cselect_b32 vcc_hi, s54, s38
	s_add_u32 s0, s40, 0x80080
	s_addc_u32 s1, s41, 0
	s_waitcnt vmcnt(0)
	v_lshl_add_u64 v[132:133], s[0:1], 0, v[188:189]
	v_lshl_add_u64 v[134:135], s[0:1], 0, v[190:191]
	s_mov_b32 s29, 0
	s_waitcnt lgkmcnt(0)
.Lpk_270:
	s_add_i32 s81, s29, 2
	s_cmp_lt_u32 s29, 30
	s_cselect_b32 s0, 0, 0xffffffe0
	s_add_i32 s0, s81, s0
	s_ashr_i32 s1, s0, 31
	s_lshl_b64 s[0:1], s[0:1], 7
	s_add_u32 s42, s40, s0
	s_addc_u32 s43, s41, s1
	s_add_u32 s0, s38, s0
	s_addc_u32 s1, s39, s1
	s_cmp_eq_u32 s29, 30
	s_cselect_b32 s59, s49, s43
	s_cselect_b32 s58, s51, s42
	s_cselect_b32 s61, vcc_lo, s1
	s_cselect_b32 s60, vcc_hi, s0
	s_add_i32 s43, 0, 0x10000
	s_add_i32 s97, s43, s70
	s_add_i32 s46, 0, 0x14000
	s_add_i32 m0, s96, 0xc000
	s_add_i32 s69, s96, 0xe000
	s_add_i32 s84, s97, 0x2000
	s_add_u32 s62, s60, 0x80000
	s_addc_u32 s63, s61, 0
	s_add_i32 s4, s46, s70
	v_add_u32_e32 v148, s43, v221
	v_add_u32_e32 v164, s46, v221
	s_add_i32 s5, s4, 0x2000
	s_add_i32 s1, 0, 0x18000
	s_add_i32 s47, 0, 0x1c000
	ds_read_b128 v[136:139], v148
	ds_read_b128 v[140:143], v148 offset:1024
	ds_read_b128 v[144:147], v148 offset:2048
	ds_read_b128 v[148:151], v148 offset:3072
	ds_read_b128 v[152:155], v164
	ds_read_b128 v[156:159], v164 offset:1024
	ds_read_b128 v[160:163], v164 offset:2048
	ds_read_b128 v[164:167], v164 offset:3072
	s_add_u32 s56, s58, 0x80000
	s_addc_u32 s57, s59, 0
	s_add_i32 s0, s1, s70
	s_add_i32 s89, s0, 0x2000
	s_add_u32 s42, s60, 0x80080
	s_addc_u32 s43, s61, 0
	s_add_i32 s46, s47, s70
	s_add_i32 s92, s46, 0x2000
	s_cmp_gt_u32 s29, 29
	ds_read_b128 v[192:195], v222
	ds_read_b128 v[196:199], v222 offset:1024
	ds_read_b128 v[200:203], v222 offset:2048
	ds_read_b128 v[224:227], v222 offset:3072
	ds_read_b128 v[228:231], v222 offset:4096
	ds_read_b128 v[232:235], v222 offset:5120
	ds_read_b128 v[236:239], v222 offset:6144
	ds_read_b128 v[240:243], v222 offset:7168
	global_load_lds_dwordx4 v[134:135], off
	s_mov_b32 m0, s69
	s_nop 0
	global_load_lds_dwordx4 v[132:133], off
	s_waitcnt vmcnt(8)
	s_waitcnt lgkmcnt(0)
	s_setprio 1
	s_barrier
	v_mfma_f32_16x16x32_bf16 v[128:131], v[136:139], v[192:195], 0
	v_mfma_f32_16x16x32_bf16 v[128:131], v[140:143], v[196:199], v[128:131]
	v_mfma_f32_16x16x32_bf16 v[124:127], v[144:147], v[192:195], 0
	v_mfma_f32_16x16x32_bf16 v[124:127], v[148:151], v[196:199], v[124:127]
	v_mfma_f32_16x16x32_bf16 v[112:115], v[136:139], v[200:203], 0
	v_mfma_f32_16x16x32_bf16 v[112:115], v[140:143], v[224:227], v[112:115]
	v_mfma_f32_16x16x32_bf16 v[108:111], v[144:147], v[200:203], 0
	v_mfma_f32_16x16x32_bf16 v[108:111], v[148:151], v[224:227], v[108:111]
	v_mfma_f32_16x16x32_bf16 v[94:97], v[136:139], v[228:231], 0
	v_mfma_f32_16x16x32_bf16 v[94:97], v[140:143], v[232:235], v[94:97]
	v_mfma_f32_16x16x32_bf16 v[90:93], v[144:147], v[228:231], 0
	v_mfma_f32_16x16x32_bf16 v[90:93], v[148:151], v[232:235], v[90:93]
	v_mfma_f32_16x16x32_bf16 v[78:81], v[136:139], v[236:239], 0
	v_mfma_f32_16x16x32_bf16 v[78:81], v[140:143], v[240:243], v[78:81]
	v_mfma_f32_16x16x32_bf16 v[74:77], v[144:147], v[236:239], 0
	v_mfma_f32_16x16x32_bf16 v[74:77], v[148:151], v[240:243], v[74:77]
	s_setprio 0
	s_setprio 1
	v_mfma_f32_16x16x32_bf16 v[120:123], v[152:155], v[192:195], 0
	v_mfma_f32_16x16x32_bf16 v[120:123], v[156:159], v[196:199], v[120:123]
	v_mfma_f32_16x16x32_bf16 v[116:119], v[160:163], v[192:195], 0
	v_mfma_f32_16x16x32_bf16 v[116:119], v[164:167], v[196:199], v[116:119]
	v_mfma_f32_16x16x32_bf16 v[104:107], v[152:155], v[200:203], 0
	v_mfma_f32_16x16x32_bf16 v[104:107], v[156:159], v[224:227], v[104:107]
	v_mfma_f32_16x16x32_bf16 v[100:103], v[160:163], v[200:203], 0
	v_mfma_f32_16x16x32_bf16 v[100:103], v[164:167], v[224:227], v[100:103]
	v_mfma_f32_16x16x32_bf16 v[86:89], v[152:155], v[228:231], 0
	v_mfma_f32_16x16x32_bf16 v[86:89], v[156:159], v[232:235], v[86:89]
	v_mfma_f32_16x16x32_bf16 v[82:85], v[160:163], v[228:231], 0
	v_mfma_f32_16x16x32_bf16 v[82:85], v[164:167], v[232:235], v[82:85]
	v_mfma_f32_16x16x32_bf16 v[70:73], v[152:155], v[236:239], 0
	v_mfma_f32_16x16x32_bf16 v[70:73], v[156:159], v[240:243], v[70:73]
	s_setprio 2
	s_barrier
	v_mfma_f32_16x16x32_bf16 v[66:69], v[160:163], v[236:239], 0
	v_mfma_f32_16x16x32_bf16 v[66:69], v[164:167], v[240:243], v[66:69]
	s_setprio 0
	s_mov_b32 m0, s97
	v_lshl_add_u64 v[244:245], s[60:61], 0, v[184:185]
	ds_read_b128 v[192:195], v222 offset:16384
	ds_read_b128 v[196:199], v222 offset:17408
	ds_read_b128 v[200:203], v222 offset:18432
	ds_read_b128 v[224:227], v222 offset:19456
	ds_read_b128 v[228:231], v222 offset:20480
	ds_read_b128 v[232:235], v222 offset:21504
	ds_read_b128 v[236:239], v222 offset:22528
	ds_read_b128 v[240:243], v222 offset:23552
	global_load_lds_dwordx4 v[244:245], off
	v_lshl_add_u64 v[246:247], s[60:61], 0, v[180:181]
	s_mov_b32 m0, s84
	v_lshl_add_u64 v[212:213], s[62:63], 0, v[184:185]
	global_load_lds_dwordx4 v[246:247], off
	s_mov_b32 m0, s4
	v_lshl_add_u64 v[172:173], s[58:59], 0, v[182:183]
	global_load_lds_dwordx4 v[212:213], off
	v_lshl_add_u64 v[212:213], s[62:63], 0, v[180:181]
	s_mov_b32 m0, s5
	s_nop 0
	global_load_lds_dwordx4 v[212:213], off
	v_lshl_add_u64 v[212:213], s[58:59], 0, v[186:187]
	s_mov_b32 m0, s96
	s_nop 0
	global_load_lds_dwordx4 v[212:213], off
	s_mov_b32 m0, s71
	s_nop 0
	global_load_lds_dwordx4 v[172:173], off
	s_waitcnt vmcnt(8)
	s_waitcnt lgkmcnt(0)
	s_setprio 1
	s_barrier
; #define PG8_STAGE(bufoff, gbase, voff) do { _Pragma("unroll") for (int _i = 0; _i < 2; ++_i) \
;         __builtin_amdgcn_global_load_lds((const unsigned*)((const char*)(gbase) + (voff)[_i]), (PG8_LAS unsigned*)(lds + (bufoff) + ldsw + _i * 8192), 16, 0, AUX_A); } while (0)
; #define PG8_STAGEB(bufoff, gbase, voff) do { _Pragma("unroll") for (int _i = 0; _i < 2; ++_i) \
;         __builtin_amdgcn_global_load_lds((const unsigned*)((const char*)(gbase) + (voff)[_i]), (PG8_LAS unsigned*)(lds + (bufoff) + ldsw + _i * 8192), 16, 0, AUX_B); } while (0)
; #define PG8_LDA(dst, b, h) do { _Pragma("unroll") for (int m = 0; m < 4; ++m) _Pragma("unroll") for (int k = 0; k < 2; ++k) dst[m][k] = *(const PG8_LAS bf16x8*)(lds + PG8_SA(b, h) + aoff + m * 2048 + k * 1024); } while (0)
; #define PG8_LDB(dst, b, h) do { _Pragma("unroll") for (int n = 0; n < 2; ++n) _Pragma("unroll") for (int k = 0; k < 2; ++k) dst[n][k] = *(const PG8_LAS bf16x8*)(lds + PG8_SB(b, h) + boff + n * 2048 + k * 1024); } while (0)
; #define PG8_MMA(ai, bj, At, Bt) do { __builtin_amdgcn_s_setprio(1); _Pragma("unroll") for (int m = 0; m < 4; ++m) _Pragma("unroll") for (int n = 0; n < 2; ++n) _Pragma("unroll") for (int k = 0; k < 2; ++k) \
;         acc[ai][bj][m][n] = __builtin_amdgcn_mfma_f32_16x16x32_bf16(Bt[n][k], At[m][k], acc[ai][bj][m][n], 0, 0, 0); __builtin_amdgcn_s_setprio(0); } while (0)
; #define PG8_WAIT_V(n) asm volatile("s_waitcnt vmcnt(" #n ")" ::: "memory")
; #define PG8_WAIT_L(n) asm volatile("s_waitcnt lgkmcnt(" #n ")" ::: "memory")
; #define PG8_BAR __builtin_amdgcn_s_barrier()
; #define PG8_SCHED __builtin_amdgcn_sched_barrier(0)
; template <class Epi, class Sched, bool ALIGN_EPI = false, bool SP2 = false>
; __device__ __forceinline__ void gemm_phase(PG8_LAS unsigned char* lds, const Gemm g, const Sched& S, const Epi& E) {
;     ...
;             PG8_LDA(At, 0, 1); PG8_STAGEB(PG8_SB(0, 0), b2, voffB); PG8_STAGEB(PG8_SB(0, 1), b2 + hstep, voffB); PG8_STAGE(PG8_SA(0, 0), a2, voffA);
;             PG8_WAIT_V(8); PG8_WAIT_L(0); PG8_BAR; PG8_MMA(1, 0, At, B0); PG8_MMA(1, 1, At, B1); PG8_BAR; PG8_SCHED;
;             PG8_LDB(B0, 1, 0); PG8_LDB(B1, 1, 1); PG8_SCHED; PG8_LDA(At, 1, 0); PG8_STAGE(PG8_SA(0, 1), a2 + hstep, voffA);
;             PG8_WAIT_V(8); PG8_WAIT_L(0); PG8_BAR; PG8_MMA(0, 0, At, B0); PG8_MMA(0, 1, At, B1); PG8_BAR; PG8_SCHED;
	v_mfma_f32_16x16x32_bf16 v[62:65], v[136:139], v[192:195], 0
	v_mfma_f32_16x16x32_bf16 v[62:65], v[140:143], v[196:199], v[62:65]
	v_mfma_f32_16x16x32_bf16 v[58:61], v[144:147], v[192:195], 0
	v_mfma_f32_16x16x32_bf16 v[58:61], v[148:151], v[196:199], v[58:61]
	v_mfma_f32_16x16x32_bf16 v[46:49], v[136:139], v[200:203], 0
	v_mfma_f32_16x16x32_bf16 v[46:49], v[140:143], v[224:227], v[46:49]
	v_mfma_f32_16x16x32_bf16 v[42:45], v[144:147], v[200:203], 0
	v_mfma_f32_16x16x32_bf16 v[42:45], v[148:151], v[224:227], v[42:45]
	v_mfma_f32_16x16x32_bf16 v[30:33], v[136:139], v[228:231], 0
	v_mfma_f32_16x16x32_bf16 v[30:33], v[140:143], v[232:235], v[30:33]
	v_mfma_f32_16x16x32_bf16 v[26:29], v[144:147], v[228:231], 0
	v_mfma_f32_16x16x32_bf16 v[26:29], v[148:151], v[232:235], v[26:29]
	v_mfma_f32_16x16x32_bf16 v[14:17], v[136:139], v[236:239], 0
	v_mfma_f32_16x16x32_bf16 v[14:17], v[140:143], v[240:243], v[14:17]
	v_mfma_f32_16x16x32_bf16 v[10:13], v[144:147], v[236:239], 0
	v_mfma_f32_16x16x32_bf16 v[10:13], v[148:151], v[240:243], v[10:13]
	s_setprio 0
	s_setprio 1
	v_mfma_f32_16x16x32_bf16 v[54:57], v[152:155], v[192:195], 0
	v_mfma_f32_16x16x32_bf16 v[54:57], v[156:159], v[196:199], v[54:57]
	v_mfma_f32_16x16x32_bf16 v[50:53], v[160:163], v[192:195], 0
	v_mfma_f32_16x16x32_bf16 v[50:53], v[164:167], v[196:199], v[50:53]
	v_mfma_f32_16x16x32_bf16 v[38:41], v[152:155], v[200:203], 0
	v_mfma_f32_16x16x32_bf16 v[38:41], v[156:159], v[224:227], v[38:41]
	v_mfma_f32_16x16x32_bf16 v[34:37], v[160:163], v[200:203], 0
	v_mfma_f32_16x16x32_bf16 v[34:37], v[164:167], v[224:227], v[34:37]
	v_mfma_f32_16x16x32_bf16 v[22:25], v[152:155], v[228:231], 0
	v_mfma_f32_16x16x32_bf16 v[22:25], v[156:159], v[232:235], v[22:25]
	v_mfma_f32_16x16x32_bf16 v[18:21], v[160:163], v[228:231], 0
	v_mfma_f32_16x16x32_bf16 v[18:21], v[164:167], v[232:235], v[18:21]
	v_mfma_f32_16x16x32_bf16 v[6:9], v[152:155], v[236:239], 0
	v_mfma_f32_16x16x32_bf16 v[6:9], v[156:159], v[240:243], v[6:9]
	s_setprio 2
	s_barrier
	v_mfma_f32_16x16x32_bf16 v[2:5], v[160:163], v[236:239], 0
	v_mfma_f32_16x16x32_bf16 v[2:5], v[164:167], v[240:243], v[2:5]
	s_setprio 0
	v_add_u32_e32 v148, s1, v221
	v_add_u32_e32 v164, s47, v221
	ds_read_b128 v[136:139], v148
	ds_read_b128 v[140:143], v148 offset:1024
	ds_read_b128 v[144:147], v148 offset:2048
	ds_read_b128 v[148:151], v148 offset:3072
	ds_read_b128 v[152:155], v164
	ds_read_b128 v[156:159], v164 offset:1024
	ds_read_b128 v[160:163], v164 offset:2048
	ds_read_b128 v[164:167], v164 offset:3072
	s_mov_b32 m0, s33
	v_lshl_add_u64 v[168:169], s[56:57], 0, v[186:187]
	ds_read_b128 v[192:195], v222 offset:32768
	ds_read_b128 v[196:199], v222 offset:33792
	ds_read_b128 v[200:203], v222 offset:34816
	ds_read_b128 v[224:227], v222 offset:35840
	ds_read_b128 v[228:231], v222 offset:36864
	ds_read_b128 v[232:235], v222 offset:37888
	ds_read_b128 v[236:239], v222 offset:38912
	ds_read_b128 v[240:243], v222 offset:39936
	global_load_lds_dwordx4 v[168:169], off
	v_lshl_add_u64 v[168:169], s[56:57], 0, v[182:183]
	s_mov_b32 m0, s30
	s_nop 0
	global_load_lds_dwordx4 v[168:169], off
	s_waitcnt vmcnt(8)
	s_waitcnt lgkmcnt(0)
	s_setprio 1
	s_barrier
	v_mfma_f32_16x16x32_bf16 v[128:131], v[136:139], v[192:195], v[128:131]
	v_mfma_f32_16x16x32_bf16 v[128:131], v[140:143], v[196:199], v[128:131]
	v_mfma_f32_16x16x32_bf16 v[124:127], v[144:147], v[192:195], v[124:127]
	v_mfma_f32_16x16x32_bf16 v[124:127], v[148:151], v[196:199], v[124:127]
	v_mfma_f32_16x16x32_bf16 v[112:115], v[136:139], v[200:203], v[112:115]
	v_mfma_f32_16x16x32_bf16 v[112:115], v[140:143], v[224:227], v[112:115]
	v_mfma_f32_16x16x32_bf16 v[108:111], v[144:147], v[200:203], v[108:111]
	v_mfma_f32_16x16x32_bf16 v[108:111], v[148:151], v[224:227], v[108:111]
	v_mfma_f32_16x16x32_bf16 v[94:97], v[136:139], v[228:231], v[94:97]
	v_mfma_f32_16x16x32_bf16 v[94:97], v[140:143], v[232:235], v[94:97]
	v_mfma_f32_16x16x32_bf16 v[90:93], v[144:147], v[228:231], v[90:93]
	v_mfma_f32_16x16x32_bf16 v[90:93], v[148:151], v[232:235], v[90:93]
	v_mfma_f32_16x16x32_bf16 v[78:81], v[136:139], v[236:239], v[78:81]
	v_mfma_f32_16x16x32_bf16 v[78:81], v[140:143], v[240:243], v[78:81]
	v_mfma_f32_16x16x32_bf16 v[74:77], v[144:147], v[236:239], v[74:77]
	v_mfma_f32_16x16x32_bf16 v[74:77], v[148:151], v[240:243], v[74:77]
	s_setprio 0
	s_setprio 1
	v_mfma_f32_16x16x32_bf16 v[120:123], v[152:155], v[192:195], v[120:123]
	v_mfma_f32_16x16x32_bf16 v[120:123], v[156:159], v[196:199], v[120:123]
	v_mfma_f32_16x16x32_bf16 v[116:119], v[160:163], v[192:195], v[116:119]
	v_mfma_f32_16x16x32_bf16 v[116:119], v[164:167], v[196:199], v[116:119]
	v_mfma_f32_16x16x32_bf16 v[104:107], v[152:155], v[200:203], v[104:107]
	v_mfma_f32_16x16x32_bf16 v[104:107], v[156:159], v[224:227], v[104:107]
	v_mfma_f32_16x16x32_bf16 v[100:103], v[160:163], v[200:203], v[100:103]
	v_mfma_f32_16x16x32_bf16 v[100:103], v[164:167], v[224:227], v[100:103]
	v_mfma_f32_16x16x32_bf16 v[86:89], v[152:155], v[228:231], v[86:89]
	v_mfma_f32_16x16x32_bf16 v[86:89], v[156:159], v[232:235], v[86:89]
	v_mfma_f32_16x16x32_bf16 v[82:85], v[160:163], v[228:231], v[82:85]
	v_mfma_f32_16x16x32_bf16 v[82:85], v[164:167], v[232:235], v[82:85]
	v_mfma_f32_16x16x32_bf16 v[70:73], v[152:155], v[236:239], v[70:73]
	v_mfma_f32_16x16x32_bf16 v[70:73], v[156:159], v[240:243], v[70:73]
	s_setprio 2
	s_barrier
; #define PG8_STAGE(bufoff, gbase, voff) do { _Pragma("unroll") for (int _i = 0; _i < 2; ++_i) \
;         __builtin_amdgcn_global_load_lds((const unsigned*)((const char*)(gbase) + (voff)[_i]), (PG8_LAS unsigned*)(lds + (bufoff) + ldsw + _i * 8192), 16, 0, AUX_A); } while (0)
; #define PG8_STAGEB(bufoff, gbase, voff) do { _Pragma("unroll") for (int _i = 0; _i < 2; ++_i) \
;         __builtin_amdgcn_global_load_lds((const unsigned*)((const char*)(gbase) + (voff)[_i]), (PG8_LAS unsigned*)(lds + (bufoff) + ldsw + _i * 8192), 16, 0, AUX_B); } while (0)
; #define PG8_LDA(dst, b, h) do { _Pragma("unroll") for (int m = 0; m < 4; ++m) _Pragma("unroll") for (int k = 0; k < 2; ++k) dst[m][k] = *(const PG8_LAS bf16x8*)(lds + PG8_SA(b, h) + aoff + m * 2048 + k * 1024); } while (0)
; #define PG8_LDB(dst, b, h) do { _Pragma("unroll") for (int n = 0; n < 2; ++n) _Pragma("unroll") for (int k = 0; k < 2; ++k) dst[n][k] = *(const PG8_LAS bf16x8*)(lds + PG8_SB(b, h) + boff + n * 2048 + k * 1024); } while (0)
; #define PG8_MMA(ai, bj, At, Bt) do { __builtin_amdgcn_s_setprio(1); _Pragma("unroll") for (int m = 0; m < 4; ++m) _Pragma("unroll") for (int n = 0; n < 2; ++n) _Pragma("unroll") for (int k = 0; k < 2; ++k) \
;         acc[ai][bj][m][n] = __builtin_amdgcn_mfma_f32_16x16x32_bf16(Bt[n][k], At[m][k], acc[ai][bj][m][n], 0, 0, 0); __builtin_amdgcn_s_setprio(0); } while (0)
; #define PG8_WAIT_V(n) asm volatile("s_waitcnt vmcnt(" #n ")" ::: "memory")
; #define PG8_WAIT_L(n) asm volatile("s_waitcnt lgkmcnt(" #n ")" ::: "memory")
; #define PG8_BAR __builtin_amdgcn_s_barrier()
; #define PG8_SCHED __builtin_amdgcn_sched_barrier(0)
; template <class Epi, class Sched, bool ALIGN_EPI = false, bool SP2 = false>
; __device__ __forceinline__ void gemm_phase(PG8_LAS unsigned char* lds, const Gemm g, const Sched& S, const Epi& E) {
;     ...
;             PG8_LDB(B0, 1, 0); PG8_LDB(B1, 1, 1); PG8_SCHED; PG8_LDA(At, 1, 0); PG8_STAGE(PG8_SA(0, 1), a2 + hstep, voffA);
;             PG8_WAIT_V(8); PG8_WAIT_L(0); PG8_BAR; PG8_MMA(0, 0, At, B0); PG8_MMA(0, 1, At, B1); PG8_BAR; PG8_SCHED;
;             PG8_LDA(At, 1, 1); PG8_STAGEB(PG8_SB(1, 0), b3, voffB); PG8_STAGEB(PG8_SB(1, 1), b3 + hstep, voffB); PG8_STAGE(PG8_SA(1, 0), a3, voffA);
;             PG8_WAIT_V(8); PG8_WAIT_L(0); PG8_BAR; PG8_MMA(1, 0, At, B0); PG8_MMA(1, 1, At, B1); PG8_BAR; PG8_SCHED;
	v_mfma_f32_16x16x32_bf16 v[66:69], v[160:163], v[236:239], v[66:69]
	v_mfma_f32_16x16x32_bf16 v[66:69], v[164:167], v[240:243], v[66:69]
	s_setprio 0
	s_mov_b32 m0, s0
	v_lshl_add_u64 v[168:169], v[244:245], 0, s[76:77]
	ds_read_b128 v[192:195], v222 offset:49152
	ds_read_b128 v[196:199], v222 offset:50176
	ds_read_b128 v[200:203], v222 offset:51200
	ds_read_b128 v[224:227], v222 offset:52224
	ds_read_b128 v[228:231], v222 offset:53248
	ds_read_b128 v[232:235], v222 offset:54272
	ds_read_b128 v[236:239], v222 offset:55296
	ds_read_b128 v[240:243], v222 offset:56320
	global_load_lds_dwordx4 v[168:169], off
	v_lshl_add_u64 v[168:169], v[246:247], 0, s[76:77]
	s_mov_b32 m0, s89
	s_nop 0
	global_load_lds_dwordx4 v[168:169], off
	v_lshl_add_u64 v[168:169], s[42:43], 0, v[184:185]
	s_mov_b32 m0, s46
	s_nop 0
	global_load_lds_dwordx4 v[168:169], off
	v_lshl_add_u64 v[168:169], s[42:43], 0, v[180:181]
	s_mov_b32 m0, s92
	s_nop 0
	global_load_lds_dwordx4 v[168:169], off
	v_lshl_add_u64 v[168:169], v[212:213], 0, s[76:77]
	s_mov_b32 m0, s90
	s_nop 0
	global_load_lds_dwordx4 v[168:169], off
	v_lshl_add_u64 v[168:169], v[172:173], 0, s[76:77]
	s_mov_b32 m0, s91
	s_nop 0
	global_load_lds_dwordx4 v[168:169], off
	s_waitcnt vmcnt(8)
	s_waitcnt lgkmcnt(0)
	s_setprio 1
	s_barrier
	v_mfma_f32_16x16x32_bf16 v[62:65], v[136:139], v[192:195], v[62:65]
	v_mfma_f32_16x16x32_bf16 v[62:65], v[140:143], v[196:199], v[62:65]
	v_mfma_f32_16x16x32_bf16 v[58:61], v[144:147], v[192:195], v[58:61]
	v_mfma_f32_16x16x32_bf16 v[58:61], v[148:151], v[196:199], v[58:61]
	v_mfma_f32_16x16x32_bf16 v[46:49], v[136:139], v[200:203], v[46:49]
	v_mfma_f32_16x16x32_bf16 v[46:49], v[140:143], v[224:227], v[46:49]
	v_mfma_f32_16x16x32_bf16 v[42:45], v[144:147], v[200:203], v[42:45]
	v_mfma_f32_16x16x32_bf16 v[42:45], v[148:151], v[224:227], v[42:45]
	v_mfma_f32_16x16x32_bf16 v[30:33], v[136:139], v[228:231], v[30:33]
	v_mfma_f32_16x16x32_bf16 v[30:33], v[140:143], v[232:235], v[30:33]
	v_mfma_f32_16x16x32_bf16 v[26:29], v[144:147], v[228:231], v[26:29]
	v_mfma_f32_16x16x32_bf16 v[26:29], v[148:151], v[232:235], v[26:29]
	v_mfma_f32_16x16x32_bf16 v[14:17], v[136:139], v[236:239], v[14:17]
	v_mfma_f32_16x16x32_bf16 v[14:17], v[140:143], v[240:243], v[14:17]
	v_mfma_f32_16x16x32_bf16 v[10:13], v[144:147], v[236:239], v[10:13]
	v_mfma_f32_16x16x32_bf16 v[10:13], v[148:151], v[240:243], v[10:13]
	s_setprio 0
	s_setprio 1
	v_mfma_f32_16x16x32_bf16 v[54:57], v[152:155], v[192:195], v[54:57]
	v_mfma_f32_16x16x32_bf16 v[54:57], v[156:159], v[196:199], v[54:57]
	v_mfma_f32_16x16x32_bf16 v[50:53], v[160:163], v[192:195], v[50:53]
	v_mfma_f32_16x16x32_bf16 v[50:53], v[164:167], v[196:199], v[50:53]
	v_mfma_f32_16x16x32_bf16 v[38:41], v[152:155], v[200:203], v[38:41]
	v_mfma_f32_16x16x32_bf16 v[38:41], v[156:159], v[224:227], v[38:41]
	v_mfma_f32_16x16x32_bf16 v[34:37], v[160:163], v[200:203], v[34:37]
	v_mfma_f32_16x16x32_bf16 v[34:37], v[164:167], v[224:227], v[34:37]
	v_mfma_f32_16x16x32_bf16 v[22:25], v[152:155], v[228:231], v[22:25]
	v_mfma_f32_16x16x32_bf16 v[22:25], v[156:159], v[232:235], v[22:25]
	v_mfma_f32_16x16x32_bf16 v[18:21], v[160:163], v[228:231], v[18:21]
	v_mfma_f32_16x16x32_bf16 v[18:21], v[164:167], v[232:235], v[18:21]
	v_mfma_f32_16x16x32_bf16 v[6:9], v[152:155], v[236:239], v[6:9]
	v_mfma_f32_16x16x32_bf16 v[6:9], v[156:159], v[240:243], v[6:9]
	s_setprio 2
	s_barrier
	v_mfma_f32_16x16x32_bf16 v[2:5], v[160:163], v[236:239], v[2:5]
	v_mfma_f32_16x16x32_bf16 v[2:5], v[164:167], v[240:243], v[2:5]
	s_setprio 0
	v_lshl_add_u64 v[132:133], v[132:133], 0, s[86:87]
	v_lshl_add_u64 v[134:135], v[134:135], 0, s[86:87]
	s_mov_b32 s29, s81
	s_cbranch_scc1 .Lpx_270
.LBB0_270:
	s_add_i32 s81, s29, 2
	s_cmp_lt_u32 s29, 30
	s_cselect_b32 s0, 0, 0xffffffe0
	s_add_i32 s0, s81, s0
	s_ashr_i32 s1, s0, 31
	s_lshl_b64 s[0:1], s[0:1], 7
	s_add_u32 s42, s40, s0
	s_addc_u32 s43, s41, s1
	s_add_u32 s0, s38, s0
	s_addc_u32 s1, s39, s1
	s_cmp_eq_u32 s29, 30
	s_cselect_b32 s59, s49, s43
	s_cselect_b32 s58, s51, s42
	s_cselect_b32 s61, vcc_lo, s1
	s_cselect_b32 s60, vcc_hi, s0
	s_add_i32 s43, 0, 0x10000
	s_add_i32 s97, s43, s70
	s_add_i32 s46, 0, 0x14000
	s_add_i32 m0, s96, 0xc000
	s_add_i32 s69, s96, 0xe000
	s_add_i32 s84, s97, 0x2000
	s_add_u32 s62, s60, 0x80000
	s_addc_u32 s63, s61, 0
	s_add_i32 s4, s46, s70
	v_add_u32_e32 v148, s43, v221
	v_add_u32_e32 v164, s46, v221
	s_add_i32 s5, s4, 0x2000
	s_add_i32 s1, 0, 0x18000
	s_add_i32 s47, 0, 0x1c000
	ds_read_b128 v[136:139], v148
	ds_read_b128 v[140:143], v148 offset:1024
	ds_read_b128 v[144:147], v148 offset:2048
	ds_read_b128 v[148:151], v148 offset:3072
	ds_read_b128 v[152:155], v164
	ds_read_b128 v[156:159], v164 offset:1024
	ds_read_b128 v[160:163], v164 offset:2048
	ds_read_b128 v[164:167], v164 offset:3072
	s_add_u32 s56, s58, 0x80000
	s_addc_u32 s57, s59, 0
	s_add_i32 s0, s1, s70
	s_add_i32 s89, s0, 0x2000
	s_add_u32 s42, s60, 0x80080
	s_addc_u32 s43, s61, 0
	s_add_i32 s46, s47, s70
	s_add_i32 s92, s46, 0x2000
	s_cmp_gt_u32 s29, 29
	ds_read_b128 v[192:195], v222
	ds_read_b128 v[196:199], v222 offset:1024
	ds_read_b128 v[200:203], v222 offset:2048
	ds_read_b128 v[224:227], v222 offset:3072
	ds_read_b128 v[228:231], v222 offset:4096
	ds_read_b128 v[232:235], v222 offset:5120
	ds_read_b128 v[236:239], v222 offset:6144
	ds_read_b128 v[240:243], v222 offset:7168
	global_load_lds_dwordx4 v[134:135], off
	s_mov_b32 m0, s69
	s_nop 0
	global_load_lds_dwordx4 v[132:133], off
	s_waitcnt vmcnt(8)
	s_waitcnt lgkmcnt(0)
	s_setprio 1
	s_barrier
; #define PG8_STAGE(bufoff, gbase, voff) do { _Pragma("unroll") for (int _i = 0; _i < 2; ++_i) \
;         __builtin_amdgcn_global_load_lds((const unsigned*)((const char*)(gbase) + (voff)[_i]), (PG8_LAS unsigned*)(lds + (bufoff) + ldsw + _i * 8192), 16, 0, AUX_A); } while (0)
; #define PG8_STAGEB(bufoff, gbase, voff) do { _Pragma("unroll") for (int _i = 0; _i < 2; ++_i) \
;         __builtin_amdgcn_global_load_lds((const unsigned*)((const char*)(gbase) + (voff)[_i]), (PG8_LAS unsigned*)(lds + (bufoff) + ldsw + _i * 8192), 16, 0, AUX_B); } while (0)
; #define PG8_LDA(dst, b, h) do { _Pragma("unroll") for (int m = 0; m < 4; ++m) _Pragma("unroll") for (int k = 0; k < 2; ++k) dst[m][k] = *(const PG8_LAS bf16x8*)(lds + PG8_SA(b, h) + aoff + m * 2048 + k * 1024); } while (0)
; #define PG8_LDB(dst, b, h) do { _Pragma("unroll") for (int n = 0; n < 2; ++n) _Pragma("unroll") for (int k = 0; k < 2; ++k) dst[n][k] = *(const PG8_LAS bf16x8*)(lds + PG8_SB(b, h) + boff + n * 2048 + k * 1024); } while (0)
; #define PG8_MMA(ai, bj, At, Bt) do { __builtin_amdgcn_s_setprio(1); _Pragma("unroll") for (int m = 0; m < 4; ++m) _Pragma("unroll") for (int n = 0; n < 2; ++n) _Pragma("unroll") for (int k = 0; k < 2; ++k) \
;         acc[ai][bj][m][n] = __builtin_amdgcn_mfma_f32_16x16x32_bf16(Bt[n][k], At[m][k], acc[ai][bj][m][n], 0, 0, 0); __builtin_amdgcn_s_setprio(0); } while (0)
; #define PG8_WAIT_V(n) asm volatile("s_waitcnt vmcnt(" #n ")" ::: "memory")
; #define PG8_WAIT_L(n) asm volatile("s_waitcnt lgkmcnt(" #n ")" ::: "memory")
; #define PG8_BAR __builtin_amdgcn_s_barrier()
; #define PG8_SCHED __builtin_amdgcn_sched_barrier(0)
; template <class Epi, class Sched, bool ALIGN_EPI = false, bool SP2 = false>
; __device__ __forceinline__ void gemm_phase(PG8_LAS unsigned char* lds, const Gemm g, const Sched& S, const Epi& E) {
;     ...
;             PG8_LDB(B0, 0, 0); PG8_LDB(B1, 0, 1); PG8_SCHED; PG8_LDA(At, 0, 0); PG8_STAGE(PG8_SA(1, 1), a1 + hstep, voffA);
;             PG8_WAIT_V(8); PG8_WAIT_L(0); PG8_BAR; PG8_MMA(0, 0, At, B0); PG8_MMA(0, 1, At, B1); PG8_BAR; PG8_SCHED;
;             PG8_LDA(At, 0, 1); PG8_STAGEB(PG8_SB(0, 0), b2, voffB); PG8_STAGEB(PG8_SB(0, 1), b2 + hstep, voffB); PG8_STAGE(PG8_SA(0, 0), a2, voffA);
;             PG8_WAIT_V(8); PG8_WAIT_L(0); PG8_BAR; PG8_MMA(1, 0, At, B0); PG8_MMA(1, 1, At, B1); PG8_BAR; PG8_SCHED;
	v_mfma_f32_16x16x32_bf16 v[128:131], v[136:139], v[192:195], v[128:131]
	v_mfma_f32_16x16x32_bf16 v[128:131], v[140:143], v[196:199], v[128:131]
	v_mfma_f32_16x16x32_bf16 v[124:127], v[144:147], v[192:195], v[124:127]
	v_mfma_f32_16x16x32_bf16 v[124:127], v[148:151], v[196:199], v[124:127]
	v_mfma_f32_16x16x32_bf16 v[112:115], v[136:139], v[200:203], v[112:115]
	v_mfma_f32_16x16x32_bf16 v[112:115], v[140:143], v[224:227], v[112:115]
	v_mfma_f32_16x16x32_bf16 v[108:111], v[144:147], v[200:203], v[108:111]
	v_mfma_f32_16x16x32_bf16 v[108:111], v[148:151], v[224:227], v[108:111]
	v_mfma_f32_16x16x32_bf16 v[94:97], v[136:139], v[228:231], v[94:97]
	v_mfma_f32_16x16x32_bf16 v[94:97], v[140:143], v[232:235], v[94:97]
	v_mfma_f32_16x16x32_bf16 v[90:93], v[144:147], v[228:231], v[90:93]
	v_mfma_f32_16x16x32_bf16 v[90:93], v[148:151], v[232:235], v[90:93]
	v_mfma_f32_16x16x32_bf16 v[78:81], v[136:139], v[236:239], v[78:81]
	v_mfma_f32_16x16x32_bf16 v[78:81], v[140:143], v[240:243], v[78:81]
	v_mfma_f32_16x16x32_bf16 v[74:77], v[144:147], v[236:239], v[74:77]
	v_mfma_f32_16x16x32_bf16 v[74:77], v[148:151], v[240:243], v[74:77]
	s_setprio 0
	s_setprio 1
	v_mfma_f32_16x16x32_bf16 v[120:123], v[152:155], v[192:195], v[120:123]
	v_mfma_f32_16x16x32_bf16 v[120:123], v[156:159], v[196:199], v[120:123]
	v_mfma_f32_16x16x32_bf16 v[116:119], v[160:163], v[192:195], v[116:119]
	v_mfma_f32_16x16x32_bf16 v[116:119], v[164:167], v[196:199], v[116:119]
	v_mfma_f32_16x16x32_bf16 v[104:107], v[152:155], v[200:203], v[104:107]
	v_mfma_f32_16x16x32_bf16 v[104:107], v[156:159], v[224:227], v[104:107]
	v_mfma_f32_16x16x32_bf16 v[100:103], v[160:163], v[200:203], v[100:103]
	v_mfma_f32_16x16x32_bf16 v[100:103], v[164:167], v[224:227], v[100:103]
	v_mfma_f32_16x16x32_bf16 v[86:89], v[152:155], v[228:231], v[86:89]
	v_mfma_f32_16x16x32_bf16 v[86:89], v[156:159], v[232:235], v[86:89]
	v_mfma_f32_16x16x32_bf16 v[82:85], v[160:163], v[228:231], v[82:85]
	v_mfma_f32_16x16x32_bf16 v[82:85], v[164:167], v[232:235], v[82:85]
	v_mfma_f32_16x16x32_bf16 v[70:73], v[152:155], v[236:239], v[70:73]
	v_mfma_f32_16x16x32_bf16 v[70:73], v[156:159], v[240:243], v[70:73]
	s_setprio 2
	s_barrier
	v_mfma_f32_16x16x32_bf16 v[66:69], v[160:163], v[236:239], v[66:69]
	v_mfma_f32_16x16x32_bf16 v[66:69], v[164:167], v[240:243], v[66:69]
	s_setprio 0
	s_mov_b32 m0, s97
	v_lshl_add_u64 v[244:245], s[60:61], 0, v[184:185]
	ds_read_b128 v[192:195], v222 offset:16384
	ds_read_b128 v[196:199], v222 offset:17408
	ds_read_b128 v[200:203], v222 offset:18432
	ds_read_b128 v[224:227], v222 offset:19456
	ds_read_b128 v[228:231], v222 offset:20480
	ds_read_b128 v[232:235], v222 offset:21504
	ds_read_b128 v[236:239], v222 offset:22528
	ds_read_b128 v[240:243], v222 offset:23552
	global_load_lds_dwordx4 v[244:245], off
	v_lshl_add_u64 v[246:247], s[60:61], 0, v[180:181]
	s_mov_b32 m0, s84
	v_lshl_add_u64 v[212:213], s[62:63], 0, v[184:185]
	global_load_lds_dwordx4 v[246:247], off
	s_mov_b32 m0, s4
	v_lshl_add_u64 v[172:173], s[58:59], 0, v[182:183]
	global_load_lds_dwordx4 v[212:213], off
	v_lshl_add_u64 v[212:213], s[62:63], 0, v[180:181]
	s_mov_b32 m0, s5
	s_nop 0
	global_load_lds_dwordx4 v[212:213], off
	v_lshl_add_u64 v[212:213], s[58:59], 0, v[186:187]
	s_mov_b32 m0, s96
	s_nop 0
	global_load_lds_dwordx4 v[212:213], off
	s_mov_b32 m0, s71
	s_nop 0
	global_load_lds_dwordx4 v[172:173], off
	s_waitcnt vmcnt(8)
	s_waitcnt lgkmcnt(0)
	s_setprio 1
	s_barrier
	v_mfma_f32_16x16x32_bf16 v[62:65], v[136:139], v[192:195], v[62:65]
	v_mfma_f32_16x16x32_bf16 v[62:65], v[140:143], v[196:199], v[62:65]
	v_mfma_f32_16x16x32_bf16 v[58:61], v[144:147], v[192:195], v[58:61]
	v_mfma_f32_16x16x32_bf16 v[58:61], v[148:151], v[196:199], v[58:61]
	v_mfma_f32_16x16x32_bf16 v[46:49], v[136:139], v[200:203], v[46:49]
	v_mfma_f32_16x16x32_bf16 v[46:49], v[140:143], v[224:227], v[46:49]
	v_mfma_f32_16x16x32_bf16 v[42:45], v[144:147], v[200:203], v[42:45]
	v_mfma_f32_16x16x32_bf16 v[42:45], v[148:151], v[224:227], v[42:45]
	v_mfma_f32_16x16x32_bf16 v[30:33], v[136:139], v[228:231], v[30:33]
	v_mfma_f32_16x16x32_bf16 v[30:33], v[140:143], v[232:235], v[30:33]
	v_mfma_f32_16x16x32_bf16 v[26:29], v[144:147], v[228:231], v[26:29]
	v_mfma_f32_16x16x32_bf16 v[26:29], v[148:151], v[232:235], v[26:29]
	v_mfma_f32_16x16x32_bf16 v[14:17], v[136:139], v[236:239], v[14:17]
	v_mfma_f32_16x16x32_bf16 v[14:17], v[140:143], v[240:243], v[14:17]
	v_mfma_f32_16x16x32_bf16 v[10:13], v[144:147], v[236:239], v[10:13]
	v_mfma_f32_16x16x32_bf16 v[10:13], v[148:151], v[240:243], v[10:13]
	s_setprio 0
	s_setprio 1
	v_mfma_f32_16x16x32_bf16 v[54:57], v[152:155], v[192:195], v[54:57]
	v_mfma_f32_16x16x32_bf16 v[54:57], v[156:159], v[196:199], v[54:57]
	v_mfma_f32_16x16x32_bf16 v[50:53], v[160:163], v[192:195], v[50:53]
	v_mfma_f32_16x16x32_bf16 v[50:53], v[164:167], v[196:199], v[50:53]
	v_mfma_f32_16x16x32_bf16 v[38:41], v[152:155], v[200:203], v[38:41]
	v_mfma_f32_16x16x32_bf16 v[38:41], v[156:159], v[224:227], v[38:41]
	v_mfma_f32_16x16x32_bf16 v[34:37], v[160:163], v[200:203], v[34:37]
	v_mfma_f32_16x16x32_bf16 v[34:37], v[164:167], v[224:227], v[34:37]
	v_mfma_f32_16x16x32_bf16 v[22:25], v[152:155], v[228:231], v[22:25]
	v_mfma_f32_16x16x32_bf16 v[22:25], v[156:159], v[232:235], v[22:25]
	v_mfma_f32_16x16x32_bf16 v[18:21], v[160:163], v[228:231], v[18:21]
	v_mfma_f32_16x16x32_bf16 v[18:21], v[164:167], v[232:235], v[18:21]
	v_mfma_f32_16x16x32_bf16 v[6:9], v[152:155], v[236:239], v[6:9]
	v_mfma_f32_16x16x32_bf16 v[6:9], v[156:159], v[240:243], v[6:9]
	s_setprio 2
	s_barrier
; #define PG8_STAGE(bufoff, gbase, voff) do { _Pragma("unroll") for (int _i = 0; _i < 2; ++_i) \
;         __builtin_amdgcn_global_load_lds((const unsigned*)((const char*)(gbase) + (voff)[_i]), (PG8_LAS unsigned*)(lds + (bufoff) + ldsw + _i * 8192), 16, 0, AUX_A); } while (0)
; #define PG8_STAGEB(bufoff, gbase, voff) do { _Pragma("unroll") for (int _i = 0; _i < 2; ++_i) \
;         __builtin_amdgcn_global_load_lds((const unsigned*)((const char*)(gbase) + (voff)[_i]), (PG8_LAS unsigned*)(lds + (bufoff) + ldsw + _i * 8192), 16, 0, AUX_B); } while (0)
; #define PG8_LDA(dst, b, h) do { _Pragma("unroll") for (int m = 0; m < 4; ++m) _Pragma("unroll") for (int k = 0; k < 2; ++k) dst[m][k] = *(const PG8_LAS bf16x8*)(lds + PG8_SA(b, h) + aoff + m * 2048 + k * 1024); } while (0)
; #define PG8_LDB(dst, b, h) do { _Pragma("unroll") for (int n = 0; n < 2; ++n) _Pragma("unroll") for (int k = 0; k < 2; ++k) dst[n][k] = *(const PG8_LAS bf16x8*)(lds + PG8_SB(b, h) + boff + n * 2048 + k * 1024); } while (0)
; #define PG8_MMA(ai, bj, At, Bt) do { __builtin_amdgcn_s_setprio(1); _Pragma("unroll") for (int m = 0; m < 4; ++m) _Pragma("unroll") for (int n = 0; n < 2; ++n) _Pragma("unroll") for (int k = 0; k < 2; ++k) \
;         acc[ai][bj][m][n] = __builtin_amdgcn_mfma_f32_16x16x32_bf16(Bt[n][k], At[m][k], acc[ai][bj][m][n], 0, 0, 0); __builtin_amdgcn_s_setprio(0); } while (0)
; #define PG8_WAIT_V(n) asm volatile("s_waitcnt vmcnt(" #n ")" ::: "memory")
; #define PG8_WAIT_L(n) asm volatile("s_waitcnt lgkmcnt(" #n ")" ::: "memory")
; template <class Epi, class Sched, bool ALIGN_EPI = false, bool SP2 = false>
; __device__ __forceinline__ void gemm_phase(PG8_LAS unsigned char* lds, const Gemm g, const Sched& S, const Epi& E) {
;     ...
;             PG8_WAIT_V(8); PG8_WAIT_L(0); PG8_BAR; PG8_MMA(1, 0, At, B0); PG8_MMA(1, 1, At, B1); PG8_BAR; PG8_SCHED;
;             PG8_LDB(B0, 1, 0); PG8_LDB(B1, 1, 1); PG8_SCHED; PG8_LDA(At, 1, 0); PG8_STAGE(PG8_SA(0, 1), a2 + hstep, voffA);
;             PG8_WAIT_V(8); PG8_WAIT_L(0); PG8_BAR; PG8_MMA(0, 0, At, B0); PG8_MMA(0, 1, At, B1); PG8_BAR; PG8_SCHED;
;             PG8_LDA(At, 1, 1); PG8_STAGEB(PG8_SB(1, 0), b3, voffB); PG8_STAGEB(PG8_SB(1, 1), b3 + hstep, voffB); PG8_STAGE(PG8_SA(1, 0), a3, voffA);
;             PG8_WAIT_V(8); PG8_WAIT_L(0); PG8_BAR; PG8_MMA(1, 0, At, B0); PG8_MMA(1, 1, At, B1); PG8_BAR; PG8_SCHED;
	v_mfma_f32_16x16x32_bf16 v[2:5], v[160:163], v[236:239], v[2:5]
	v_mfma_f32_16x16x32_bf16 v[2:5], v[164:167], v[240:243], v[2:5]
	s_setprio 0
	v_add_u32_e32 v148, s1, v221
	v_add_u32_e32 v164, s47, v221
	ds_read_b128 v[136:139], v148
	ds_read_b128 v[140:143], v148 offset:1024
	ds_read_b128 v[144:147], v148 offset:2048
	ds_read_b128 v[148:151], v148 offset:3072
	ds_read_b128 v[152:155], v164
	ds_read_b128 v[156:159], v164 offset:1024
	ds_read_b128 v[160:163], v164 offset:2048
	ds_read_b128 v[164:167], v164 offset:3072
	s_mov_b32 m0, s33
	v_lshl_add_u64 v[168:169], s[56:57], 0, v[186:187]
	ds_read_b128 v[192:195], v222 offset:32768
	ds_read_b128 v[196:199], v222 offset:33792
	ds_read_b128 v[200:203], v222 offset:34816
	ds_read_b128 v[224:227], v222 offset:35840
	ds_read_b128 v[228:231], v222 offset:36864
	ds_read_b128 v[232:235], v222 offset:37888
	ds_read_b128 v[236:239], v222 offset:38912
	ds_read_b128 v[240:243], v222 offset:39936
	global_load_lds_dwordx4 v[168:169], off
	v_lshl_add_u64 v[168:169], s[56:57], 0, v[182:183]
	s_mov_b32 m0, s30
	s_nop 0
	global_load_lds_dwordx4 v[168:169], off
	s_waitcnt vmcnt(8)
	s_waitcnt lgkmcnt(0)
	s_setprio 1
	s_barrier
	v_mfma_f32_16x16x32_bf16 v[128:131], v[136:139], v[192:195], v[128:131]
	v_mfma_f32_16x16x32_bf16 v[128:131], v[140:143], v[196:199], v[128:131]
	v_mfma_f32_16x16x32_bf16 v[124:127], v[144:147], v[192:195], v[124:127]
	v_mfma_f32_16x16x32_bf16 v[124:127], v[148:151], v[196:199], v[124:127]
	v_mfma_f32_16x16x32_bf16 v[112:115], v[136:139], v[200:203], v[112:115]
	v_mfma_f32_16x16x32_bf16 v[112:115], v[140:143], v[224:227], v[112:115]
	v_mfma_f32_16x16x32_bf16 v[108:111], v[144:147], v[200:203], v[108:111]
	v_mfma_f32_16x16x32_bf16 v[108:111], v[148:151], v[224:227], v[108:111]
	v_mfma_f32_16x16x32_bf16 v[94:97], v[136:139], v[228:231], v[94:97]
	v_mfma_f32_16x16x32_bf16 v[94:97], v[140:143], v[232:235], v[94:97]
	v_mfma_f32_16x16x32_bf16 v[90:93], v[144:147], v[228:231], v[90:93]
	v_mfma_f32_16x16x32_bf16 v[90:93], v[148:151], v[232:235], v[90:93]
	v_mfma_f32_16x16x32_bf16 v[78:81], v[136:139], v[236:239], v[78:81]
	v_mfma_f32_16x16x32_bf16 v[78:81], v[140:143], v[240:243], v[78:81]
	v_mfma_f32_16x16x32_bf16 v[74:77], v[144:147], v[236:239], v[74:77]
	v_mfma_f32_16x16x32_bf16 v[74:77], v[148:151], v[240:243], v[74:77]
	s_setprio 0
	s_setprio 1
	v_mfma_f32_16x16x32_bf16 v[120:123], v[152:155], v[192:195], v[120:123]
	v_mfma_f32_16x16x32_bf16 v[120:123], v[156:159], v[196:199], v[120:123]
	v_mfma_f32_16x16x32_bf16 v[116:119], v[160:163], v[192:195], v[116:119]
	v_mfma_f32_16x16x32_bf16 v[116:119], v[164:167], v[196:199], v[116:119]
	v_mfma_f32_16x16x32_bf16 v[104:107], v[152:155], v[200:203], v[104:107]
	v_mfma_f32_16x16x32_bf16 v[104:107], v[156:159], v[224:227], v[104:107]
	v_mfma_f32_16x16x32_bf16 v[100:103], v[160:163], v[200:203], v[100:103]
	v_mfma_f32_16x16x32_bf16 v[100:103], v[164:167], v[224:227], v[100:103]
	v_mfma_f32_16x16x32_bf16 v[86:89], v[152:155], v[228:231], v[86:89]
	v_mfma_f32_16x16x32_bf16 v[86:89], v[156:159], v[232:235], v[86:89]
	v_mfma_f32_16x16x32_bf16 v[82:85], v[160:163], v[228:231], v[82:85]
	v_mfma_f32_16x16x32_bf16 v[82:85], v[164:167], v[232:235], v[82:85]
	v_mfma_f32_16x16x32_bf16 v[70:73], v[152:155], v[236:239], v[70:73]
	v_mfma_f32_16x16x32_bf16 v[70:73], v[156:159], v[240:243], v[70:73]
	s_setprio 2
	s_barrier
	v_mfma_f32_16x16x32_bf16 v[66:69], v[160:163], v[236:239], v[66:69]
	v_mfma_f32_16x16x32_bf16 v[66:69], v[164:167], v[240:243], v[66:69]
	s_setprio 0
	s_mov_b32 m0, s0
	v_lshl_add_u64 v[168:169], v[244:245], 0, s[76:77]
	ds_read_b128 v[192:195], v222 offset:49152
	ds_read_b128 v[196:199], v222 offset:50176
	ds_read_b128 v[200:203], v222 offset:51200
	ds_read_b128 v[224:227], v222 offset:52224
	ds_read_b128 v[228:231], v222 offset:53248
	ds_read_b128 v[232:235], v222 offset:54272
	ds_read_b128 v[236:239], v222 offset:55296
	ds_read_b128 v[240:243], v222 offset:56320
	global_load_lds_dwordx4 v[168:169], off
	v_lshl_add_u64 v[168:169], v[246:247], 0, s[76:77]
	s_mov_b32 m0, s89
	s_nop 0
	global_load_lds_dwordx4 v[168:169], off
	v_lshl_add_u64 v[168:169], s[42:43], 0, v[184:185]
	s_mov_b32 m0, s46
	s_nop 0
	global_load_lds_dwordx4 v[168:169], off
	v_lshl_add_u64 v[168:169], s[42:43], 0, v[180:181]
	s_mov_b32 m0, s92
	s_nop 0
	global_load_lds_dwordx4 v[168:169], off
	v_lshl_add_u64 v[168:169], v[212:213], 0, s[76:77]
	s_mov_b32 m0, s90
	s_nop 0
	global_load_lds_dwordx4 v[168:169], off
	v_lshl_add_u64 v[168:169], v[172:173], 0, s[76:77]
	s_mov_b32 m0, s91
	s_nop 0
	global_load_lds_dwordx4 v[168:169], off
	s_waitcnt vmcnt(8)
	s_waitcnt lgkmcnt(0)
	s_setprio 1
	s_barrier
	v_mfma_f32_16x16x32_bf16 v[62:65], v[136:139], v[192:195], v[62:65]
	v_mfma_f32_16x16x32_bf16 v[62:65], v[140:143], v[196:199], v[62:65]
	v_mfma_f32_16x16x32_bf16 v[58:61], v[144:147], v[192:195], v[58:61]
	v_mfma_f32_16x16x32_bf16 v[58:61], v[148:151], v[196:199], v[58:61]
	v_mfma_f32_16x16x32_bf16 v[46:49], v[136:139], v[200:203], v[46:49]
	v_mfma_f32_16x16x32_bf16 v[46:49], v[140:143], v[224:227], v[46:49]
	v_mfma_f32_16x16x32_bf16 v[42:45], v[144:147], v[200:203], v[42:45]
	v_mfma_f32_16x16x32_bf16 v[42:45], v[148:151], v[224:227], v[42:45]
	v_mfma_f32_16x16x32_bf16 v[30:33], v[136:139], v[228:231], v[30:33]
	v_mfma_f32_16x16x32_bf16 v[30:33], v[140:143], v[232:235], v[30:33]
	v_mfma_f32_16x16x32_bf16 v[26:29], v[144:147], v[228:231], v[26:29]
	v_mfma_f32_16x16x32_bf16 v[26:29], v[148:151], v[232:235], v[26:29]
	v_mfma_f32_16x16x32_bf16 v[14:17], v[136:139], v[236:239], v[14:17]
	v_mfma_f32_16x16x32_bf16 v[14:17], v[140:143], v[240:243], v[14:17]
	v_mfma_f32_16x16x32_bf16 v[10:13], v[144:147], v[236:239], v[10:13]
	v_mfma_f32_16x16x32_bf16 v[10:13], v[148:151], v[240:243], v[10:13]
	s_setprio 0
	s_setprio 1
	v_mfma_f32_16x16x32_bf16 v[54:57], v[152:155], v[192:195], v[54:57]
	v_mfma_f32_16x16x32_bf16 v[54:57], v[156:159], v[196:199], v[54:57]
	v_mfma_f32_16x16x32_bf16 v[50:53], v[160:163], v[192:195], v[50:53]
	v_mfma_f32_16x16x32_bf16 v[50:53], v[164:167], v[196:199], v[50:53]
	v_mfma_f32_16x16x32_bf16 v[38:41], v[152:155], v[200:203], v[38:41]
	v_mfma_f32_16x16x32_bf16 v[38:41], v[156:159], v[224:227], v[38:41]
	v_mfma_f32_16x16x32_bf16 v[34:37], v[160:163], v[200:203], v[34:37]
	v_mfma_f32_16x16x32_bf16 v[34:37], v[164:167], v[224:227], v[34:37]
	v_mfma_f32_16x16x32_bf16 v[22:25], v[152:155], v[228:231], v[22:25]
	v_mfma_f32_16x16x32_bf16 v[22:25], v[156:159], v[232:235], v[22:25]
	v_mfma_f32_16x16x32_bf16 v[18:21], v[160:163], v[228:231], v[18:21]
	v_mfma_f32_16x16x32_bf16 v[18:21], v[164:167], v[232:235], v[18:21]
	v_mfma_f32_16x16x32_bf16 v[6:9], v[152:155], v[236:239], v[6:9]
	v_mfma_f32_16x16x32_bf16 v[6:9], v[156:159], v[240:243], v[6:9]
	s_setprio 2
	s_barrier
	v_mfma_f32_16x16x32_bf16 v[2:5], v[160:163], v[236:239], v[2:5]
	v_mfma_f32_16x16x32_bf16 v[2:5], v[164:167], v[240:243], v[2:5]
	s_setprio 0
	v_lshl_add_u64 v[132:133], v[132:133], 0, s[86:87]
	v_lshl_add_u64 v[134:135], v[134:135], 0, s[86:87]
	s_mov_b32 s29, s81
	s_cbranch_scc0 .LBB0_270
; #define PG8_BAR __builtin_amdgcn_s_barrier()
; template <class Epi, class Sched, bool ALIGN_EPI = false, bool SP2 = false>
; __device__ __forceinline__ void gemm_phase(PG8_LAS unsigned char* lds, const Gemm g, const Sched& S, const Epi& E) {
;     ...
;         }
;         if constexpr (ALIGN_EPI) { if (wr == 0) PG8_BAR; }
.Lpx_270:
	s_and_b64 vcc, exec, s[10:11]
	s_cbranch_vccz .LBB0_273
	s_barrier

; #define PG8_STAGE(bufoff, gbase, voff) do { _Pragma("unroll") for (int _i = 0; _i < 2; ++_i) \
;         __builtin_amdgcn_global_load_lds((const unsigned*)((const char*)(gbase) + (voff)[_i]), (PG8_LAS unsigned*)(lds + (bufoff) + ldsw + _i * 8192), 16, 0, AUX_A); } while (0)
; #define PG8_LDA(dst, b, h) do { _Pragma("unroll") for (int m = 0; m < 4; ++m) _Pragma("unroll") for (int k = 0; k < 2; ++k) dst[m][k] = *(const PG8_LAS bf16x8*)(lds + PG8_SA(b, h) + aoff + m * 2048 + k * 1024); } while (0)
; #define PG8_LDB(dst, b, h) do { _Pragma("unroll") for (int n = 0; n < 2; ++n) _Pragma("unroll") for (int k = 0; k < 2; ++k) dst[n][k] = *(const PG8_LAS bf16x8*)(lds + PG8_SB(b, h) + boff + n * 2048 + k * 1024); } while (0)
; #define PG8_WAIT_V(n) asm volatile("s_waitcnt vmcnt(" #n ")" ::: "memory")
; #define PG8_WAIT_L(n) asm volatile("s_waitcnt lgkmcnt(" #n ")" ::: "memory")
; #define PG8_BAR __builtin_amdgcn_s_barrier()
; #define PG8_SCHED __builtin_amdgcn_sched_barrier(0)
; template <class Epi, class Sched, bool ALIGN_EPI = false, bool SP2 = false>
; __device__ __forceinline__ void gemm_phase(PG8_LAS unsigned char* lds, const Gemm g, const Sched& S, const Epi& E) {
;     ...
;     for (;;) {
;         const bool has_next = S.next(ui + 1, nxt);
;         const char* nA = has_next ? (const char*)g.A + (size_t)nxt.pm * tstep + (size_t)nxt.kt0 * kstep : cA; const char* nB = has_next ? (const char*)g.Bt + (size_t)nxt.pn * tstep + (size_t)nxt.kt0 * kstep : cB;
;         const int nt = cur.nkt, rot = cur.krot;
;         const char* nAr = has_next ? nA + (size_t)nxt.krot * kstep : PG8_KP(cA, 0, rot, nt); const char* nBr = has_next ? nB + (size_t)nxt.krot * kstep : PG8_KP(cB, 0, rot, nt);
;         for (int t = 0; t < nt; t += 2) {
;             const bool last = (t == nt - 2);
;             const char* a1 = PG8_KP(cA, t + 1, rot, nt);
;             const char* a2 = last ? nAr : PG8_KP(cA, t + 2, rot, nt); const char* b2 = last ? nBr : PG8_KP(cB, t + 2, rot, nt);
;             const char* a3 = a2 + kstep; const char* b3 = b2 + kstep;
;             if (last && has_next) S.a_ready(nxt);
;             if constexpr (SP2) {
;             PG8_LDB(B0, 0, 0); PG8_LDB(B1, 0, 1); PG8_SCHED; PG8_LDA(At, 0, 0); PG8_STAGE(PG8_SA(1, 1), a1 + hstep, voffA);
;             PG8_WAIT_V(8); PG8_WAIT_L(0); PG8_BAR; PG8_MMA(0, 0, At, B0); PG8_MMA(0, 1, At, B1); PG8_BAR; PG8_SCHED;
.LBB0_935:
	s_mov_b32 s14, s1
	s_ashr_i32 s15, s1, 31
	s_mov_b32 s16, s0
	s_lshl_b64 s[0:1], s[14:15], 19
	s_add_u32 s38, s4, s0
	s_addc_u32 s39, s5, s1
	s_ashr_i32 s17, s16, 31
	s_lshl_b64 s[0:1], s[16:17], 19
	s_add_u32 s40, s30, s0
	s_addc_u32 s41, s31, s1
	s_and_b64 s[0:1], s[18:19], exec
	s_cselect_b32 s15, s39, s65
	s_cselect_b32 s17, s38, s64
	s_cselect_b32 s43, s41, s27
	s_cselect_b32 s78, s40, s26
	s_add_u32 s0, s64, 0x40080
	s_addc_u32 s1, s65, 0
	v_lshl_add_u64 v[14:15], s[0:1], 0, v[156:157]
	v_lshl_add_u64 v[16:17], s[0:1], 0, v[158:159]
	s_mov_b32 s29, 0
	s_waitcnt vmcnt(0)
	s_waitcnt lgkmcnt(0)
	s_waitcnt vmcnt(0)
.Lpk_936:
	s_add_i32 s81, s29, 2
	s_cmp_lt_u32 s29, 14
	s_cselect_b32 s0, 0, -16
	s_add_i32 s0, s81, s0
	s_ashr_i32 s1, s0, 31
	s_lshl_b64 s[0:1], s[0:1], 7
	s_add_u32 s2, s64, s0
	s_addc_u32 s46, s65, s1
	s_add_u32 s0, s26, s0
	s_addc_u32 s1, s27, s1
	s_cmp_eq_u32 s29, 14
	s_cselect_b32 s57, s15, s46
	s_cselect_b32 s56, s17, s2
	s_cselect_b32 s59, s43, s1
	s_cselect_b32 s58, s78, s0
	s_add_i32 s2, 0, 0x10000
	s_add_i32 s83, s2, s33
	s_add_i32 s46, 0, 0x14000
	s_add_i32 m0, s25, 0xc000
	s_add_i32 s82, s25, 0xe000
	s_add_i32 s84, s83, 0x2000
	s_add_u32 s60, s58, 0x40000
	s_addc_u32 s61, s59, 0
	s_add_i32 s88, s46, s33
	v_add_u32_e32 v160, s2, v99
	v_add_u32_e32 v166, s46, v99
	s_add_i32 s89, s88, 0x2000
	s_add_i32 s90, 0, 0x18000
	s_add_i32 s91, 0, 0x1c000
	ds_read_b128 v[22:25], v160
	ds_read_b128 v[34:37], v160 offset:1024
	ds_read_b128 v[38:41], v160 offset:2048
	ds_read_b128 v[160:163], v160 offset:3072
	ds_read_b128 v[180:183], v166
	ds_read_b128 v[184:187], v166 offset:1024
	ds_read_b128 v[188:191], v166 offset:2048
	ds_read_b128 v[192:195], v166 offset:3072
	s_add_u32 s54, s56, 0x40000
	s_addc_u32 s55, s57, 0
	s_add_i32 s1, s90, s33
	s_add_i32 s0, s1, 0x2000
	s_add_u32 s52, s58, 0x40080
	s_addc_u32 s53, s59, 0
	s_add_i32 s47, s91, s33
	s_add_i32 s46, s47, 0x2000
	s_cmp_gt_u32 s29, 13
	ds_read_b128 v[196:199], v165
	ds_read_b128 v[200:203], v165 offset:1024
	ds_read_b128 v[222:225], v165 offset:2048
	ds_read_b128 v[226:229], v165 offset:3072
	ds_read_b128 v[230:233], v165 offset:4096
	ds_read_b128 v[234:237], v165 offset:5120
	ds_read_b128 v[238:241], v165 offset:6144
	ds_read_b128 v[242:245], v165 offset:7168
	global_load_lds_dwordx4 v[16:17], off
	s_mov_b32 m0, s82
	s_nop 0
	global_load_lds_dwordx4 v[14:15], off
	s_waitcnt vmcnt(8)
	s_waitcnt lgkmcnt(0)
	s_setprio 1
	s_barrier
	v_mfma_f32_16x16x32_bf16 v[144:147], v[22:25], v[196:199], 0
	v_mfma_f32_16x16x32_bf16 v[144:147], v[34:37], v[200:203], v[144:147]
	v_mfma_f32_16x16x32_bf16 v[140:143], v[38:41], v[196:199], 0
	v_mfma_f32_16x16x32_bf16 v[140:143], v[160:163], v[200:203], v[140:143]
	v_mfma_f32_16x16x32_bf16 v[128:131], v[22:25], v[222:225], 0
	v_mfma_f32_16x16x32_bf16 v[128:131], v[34:37], v[226:229], v[128:131]
	v_mfma_f32_16x16x32_bf16 v[124:127], v[38:41], v[222:225], 0
	v_mfma_f32_16x16x32_bf16 v[124:127], v[160:163], v[226:229], v[124:127]
	v_mfma_f32_16x16x32_bf16 v[112:115], v[22:25], v[230:233], 0
	v_mfma_f32_16x16x32_bf16 v[112:115], v[34:37], v[234:237], v[112:115]
	v_mfma_f32_16x16x32_bf16 v[108:111], v[38:41], v[230:233], 0
	v_mfma_f32_16x16x32_bf16 v[108:111], v[160:163], v[234:237], v[108:111]
	v_mfma_f32_16x16x32_bf16 v[94:97], v[22:25], v[238:241], 0
	v_mfma_f32_16x16x32_bf16 v[94:97], v[34:37], v[242:245], v[94:97]
	v_mfma_f32_16x16x32_bf16 v[90:93], v[38:41], v[238:241], 0
	v_mfma_f32_16x16x32_bf16 v[90:93], v[160:163], v[242:245], v[90:93]
	s_setprio 0
	s_setprio 1
	v_mfma_f32_16x16x32_bf16 v[136:139], v[180:183], v[196:199], 0
	v_mfma_f32_16x16x32_bf16 v[136:139], v[184:187], v[200:203], v[136:139]
	v_mfma_f32_16x16x32_bf16 v[132:135], v[188:191], v[196:199], 0
	v_mfma_f32_16x16x32_bf16 v[132:135], v[192:195], v[200:203], v[132:135]
	v_mfma_f32_16x16x32_bf16 v[120:123], v[180:183], v[222:225], 0
	v_mfma_f32_16x16x32_bf16 v[120:123], v[184:187], v[226:229], v[120:123]
	v_mfma_f32_16x16x32_bf16 v[116:119], v[188:191], v[222:225], 0
	v_mfma_f32_16x16x32_bf16 v[116:119], v[192:195], v[226:229], v[116:119]
	v_mfma_f32_16x16x32_bf16 v[104:107], v[180:183], v[230:233], 0
	v_mfma_f32_16x16x32_bf16 v[104:107], v[184:187], v[234:237], v[104:107]
	v_mfma_f32_16x16x32_bf16 v[100:103], v[188:191], v[230:233], 0
	v_mfma_f32_16x16x32_bf16 v[100:103], v[192:195], v[234:237], v[100:103]
	v_mfma_f32_16x16x32_bf16 v[86:89], v[180:183], v[238:241], 0
	v_mfma_f32_16x16x32_bf16 v[86:89], v[184:187], v[242:245], v[86:89]
	s_setprio 2
	s_barrier
	v_mfma_f32_16x16x32_bf16 v[82:85], v[188:191], v[238:241], 0
	v_mfma_f32_16x16x32_bf16 v[82:85], v[192:195], v[242:245], v[82:85]
	s_setprio 0
	s_mov_b32 m0, s83
	v_lshl_add_u64 v[166:167], s[58:59], 0, v[150:151]
	ds_read_b128 v[196:199], v165 offset:16384
	ds_read_b128 v[200:203], v165 offset:17408
	ds_read_b128 v[222:225], v165 offset:18432
	ds_read_b128 v[226:229], v165 offset:19456
	ds_read_b128 v[230:233], v165 offset:20480
	ds_read_b128 v[234:237], v165 offset:21504
	ds_read_b128 v[238:241], v165 offset:22528
	ds_read_b128 v[242:245], v165 offset:23552
	global_load_lds_dwordx4 v[166:167], off
	v_lshl_add_u64 v[168:169], s[58:59], 0, v[154:155]
	s_mov_b32 m0, s84
	v_lshl_add_u64 v[172:173], s[60:61], 0, v[150:151]
	global_load_lds_dwordx4 v[168:169], off
	s_mov_b32 m0, s88
	v_lshl_add_u64 v[212:213], s[56:57], 0, v[152:153]
	global_load_lds_dwordx4 v[172:173], off
	v_lshl_add_u64 v[172:173], s[60:61], 0, v[154:155]
	s_mov_b32 m0, s89
	s_nop 0
	global_load_lds_dwordx4 v[172:173], off
	v_lshl_add_u64 v[172:173], s[56:57], 0, v[148:149]
	s_mov_b32 m0, s25
	s_nop 0
	global_load_lds_dwordx4 v[172:173], off
	s_mov_b32 m0, s62
	s_nop 0
	global_load_lds_dwordx4 v[212:213], off
	s_waitcnt vmcnt(8)
	s_waitcnt lgkmcnt(0)
	s_setprio 1
	s_barrier
; #define PG8_STAGE(bufoff, gbase, voff) do { _Pragma("unroll") for (int _i = 0; _i < 2; ++_i) \
;         __builtin_amdgcn_global_load_lds((const unsigned*)((const char*)(gbase) + (voff)[_i]), (PG8_LAS unsigned*)(lds + (bufoff) + ldsw + _i * 8192), 16, 0, AUX_A); } while (0)
; #define PG8_STAGEB(bufoff, gbase, voff) do { _Pragma("unroll") for (int _i = 0; _i < 2; ++_i) \
;         __builtin_amdgcn_global_load_lds((const unsigned*)((const char*)(gbase) + (voff)[_i]), (PG8_LAS unsigned*)(lds + (bufoff) + ldsw + _i * 8192), 16, 0, AUX_B); } while (0)
; #define PG8_LDA(dst, b, h) do { _Pragma("unroll") for (int m = 0; m < 4; ++m) _Pragma("unroll") for (int k = 0; k < 2; ++k) dst[m][k] = *(const PG8_LAS bf16x8*)(lds + PG8_SA(b, h) + aoff + m * 2048 + k * 1024); } while (0)
; #define PG8_LDB(dst, b, h) do { _Pragma("unroll") for (int n = 0; n < 2; ++n) _Pragma("unroll") for (int k = 0; k < 2; ++k) dst[n][k] = *(const PG8_LAS bf16x8*)(lds + PG8_SB(b, h) + boff + n * 2048 + k * 1024); } while (0)
; #define PG8_MMA(ai, bj, At, Bt) do { __builtin_amdgcn_s_setprio(1); _Pragma("unroll") for (int m = 0; m < 4; ++m) _Pragma("unroll") for (int n = 0; n < 2; ++n) _Pragma("unroll") for (int k = 0; k < 2; ++k) \
;         acc[ai][bj][m][n] = __builtin_amdgcn_mfma_f32_16x16x32_bf16(Bt[n][k], At[m][k], acc[ai][bj][m][n], 0, 0, 0); __builtin_amdgcn_s_setprio(0); } while (0)
; #define PG8_WAIT_V(n) asm volatile("s_waitcnt vmcnt(" #n ")" ::: "memory")
; #define PG8_WAIT_L(n) asm volatile("s_waitcnt lgkmcnt(" #n ")" ::: "memory")
; #define PG8_BAR __builtin_amdgcn_s_barrier()
; #define PG8_SCHED __builtin_amdgcn_sched_barrier(0)
; template <class Epi, class Sched, bool ALIGN_EPI = false, bool SP2 = false>
; __device__ __forceinline__ void gemm_phase(PG8_LAS unsigned char* lds, const Gemm g, const Sched& S, const Epi& E) {
;     ...
;             PG8_LDA(At, 0, 1); PG8_STAGEB(PG8_SB(0, 0), b2, voffB); PG8_STAGEB(PG8_SB(0, 1), b2 + hstep, voffB); PG8_STAGE(PG8_SA(0, 0), a2, voffA);
;             PG8_WAIT_V(8); PG8_WAIT_L(0); PG8_BAR; PG8_MMA(1, 0, At, B0); PG8_MMA(1, 1, At, B1); PG8_BAR; PG8_SCHED;
;             PG8_LDB(B0, 1, 0); PG8_LDB(B1, 1, 1); PG8_SCHED; PG8_LDA(At, 1, 0); PG8_STAGE(PG8_SA(0, 1), a2 + hstep, voffA);
;             PG8_WAIT_V(8); PG8_WAIT_L(0); PG8_BAR; PG8_MMA(0, 0, At, B0); PG8_MMA(0, 1, At, B1); PG8_BAR; PG8_SCHED;
	v_mfma_f32_16x16x32_bf16 v[78:81], v[22:25], v[196:199], 0
	v_mfma_f32_16x16x32_bf16 v[78:81], v[34:37], v[200:203], v[78:81]
	v_mfma_f32_16x16x32_bf16 v[74:77], v[38:41], v[196:199], 0
	v_mfma_f32_16x16x32_bf16 v[74:77], v[160:163], v[200:203], v[74:77]
	v_mfma_f32_16x16x32_bf16 v[62:65], v[22:25], v[222:225], 0
	v_mfma_f32_16x16x32_bf16 v[62:65], v[34:37], v[226:229], v[62:65]
	v_mfma_f32_16x16x32_bf16 v[58:61], v[38:41], v[222:225], 0
	v_mfma_f32_16x16x32_bf16 v[58:61], v[160:163], v[226:229], v[58:61]
	v_mfma_f32_16x16x32_bf16 v[46:49], v[22:25], v[230:233], 0
	v_mfma_f32_16x16x32_bf16 v[46:49], v[34:37], v[234:237], v[46:49]
	v_mfma_f32_16x16x32_bf16 v[42:45], v[38:41], v[230:233], 0
	v_mfma_f32_16x16x32_bf16 v[42:45], v[160:163], v[234:237], v[42:45]
	v_mfma_f32_16x16x32_bf16 v[18:21], v[22:25], v[238:241], 0
	v_mfma_f32_16x16x32_bf16 v[18:21], v[34:37], v[242:245], v[18:21]
	v_mfma_f32_16x16x32_bf16 v[10:13], v[38:41], v[238:241], 0
	v_mfma_f32_16x16x32_bf16 v[10:13], v[160:163], v[242:245], v[10:13]
	s_setprio 0
	s_setprio 1
	v_mfma_f32_16x16x32_bf16 v[50:53], v[188:191], v[222:225], 0
	v_mfma_f32_16x16x32_bf16 v[30:33], v[180:183], v[230:233], 0
	v_mfma_f32_16x16x32_bf16 v[26:29], v[188:191], v[230:233], 0
	v_mfma_f32_16x16x32_bf16 v[6:9], v[180:183], v[238:241], 0
	v_mfma_f32_16x16x32_bf16 v[2:5], v[188:191], v[238:241], 0
	v_mfma_f32_16x16x32_bf16 v[22:25], v[180:183], v[196:199], 0
	v_mfma_f32_16x16x32_bf16 v[34:37], v[188:191], v[196:199], 0
	v_mfma_f32_16x16x32_bf16 v[38:41], v[180:183], v[222:225], 0
	v_mfma_f32_16x16x32_bf16 v[50:53], v[192:195], v[226:229], v[50:53]
	v_mfma_f32_16x16x32_bf16 v[30:33], v[184:187], v[234:237], v[30:33]
	v_mfma_f32_16x16x32_bf16 v[26:29], v[192:195], v[234:237], v[26:29]
	v_mfma_f32_16x16x32_bf16 v[6:9], v[184:187], v[242:245], v[6:9]
	v_mfma_f32_16x16x32_bf16 v[2:5], v[192:195], v[242:245], v[2:5]
	v_mfma_f32_16x16x32_bf16 v[22:25], v[184:187], v[200:203], v[22:25]
	s_setprio 2
	s_barrier
	v_mfma_f32_16x16x32_bf16 v[34:37], v[192:195], v[200:203], v[34:37]
	v_mfma_f32_16x16x32_bf16 v[38:41], v[184:187], v[226:229], v[38:41]
	s_setprio 0
	v_add_u32_e32 v160, s90, v99
	v_add_u32_e32 v192, s91, v99
	ds_read_b128 v[54:57], v160
	ds_read_b128 v[66:69], v160 offset:1024
	ds_read_b128 v[70:73], v160 offset:2048
	ds_read_b128 v[160:163], v160 offset:3072
	ds_read_b128 v[180:183], v192
	ds_read_b128 v[184:187], v192 offset:1024
	ds_read_b128 v[188:191], v192 offset:2048
	ds_read_b128 v[192:195], v192 offset:3072
	s_mov_b32 m0, s63
	v_lshl_add_u64 v[246:247], s[54:55], 0, v[148:149]
	ds_read_b128 v[196:199], v165 offset:32768
	ds_read_b128 v[200:203], v165 offset:33792
	ds_read_b128 v[222:225], v165 offset:34816
	ds_read_b128 v[226:229], v165 offset:35840
	ds_read_b128 v[230:233], v165 offset:36864
	ds_read_b128 v[234:237], v165 offset:37888
	ds_read_b128 v[238:241], v165 offset:38912
	ds_read_b128 v[242:245], v165 offset:39936
	global_load_lds_dwordx4 v[246:247], off
	v_lshl_add_u64 v[246:247], s[54:55], 0, v[152:153]
	s_mov_b32 m0, s69
	s_nop 0
	global_load_lds_dwordx4 v[246:247], off
	s_waitcnt vmcnt(8)
	s_waitcnt lgkmcnt(0)
	s_setprio 1
	s_barrier
	v_mfma_f32_16x16x32_bf16 v[144:147], v[54:57], v[196:199], v[144:147]
	v_mfma_f32_16x16x32_bf16 v[144:147], v[66:69], v[200:203], v[144:147]
	v_mfma_f32_16x16x32_bf16 v[140:143], v[70:73], v[196:199], v[140:143]
	v_mfma_f32_16x16x32_bf16 v[140:143], v[160:163], v[200:203], v[140:143]
	v_mfma_f32_16x16x32_bf16 v[128:131], v[54:57], v[222:225], v[128:131]
	v_mfma_f32_16x16x32_bf16 v[128:131], v[66:69], v[226:229], v[128:131]
	v_mfma_f32_16x16x32_bf16 v[124:127], v[70:73], v[222:225], v[124:127]
	v_mfma_f32_16x16x32_bf16 v[124:127], v[160:163], v[226:229], v[124:127]
	v_mfma_f32_16x16x32_bf16 v[112:115], v[54:57], v[230:233], v[112:115]
	v_mfma_f32_16x16x32_bf16 v[112:115], v[66:69], v[234:237], v[112:115]
	v_mfma_f32_16x16x32_bf16 v[108:111], v[70:73], v[230:233], v[108:111]
	v_mfma_f32_16x16x32_bf16 v[108:111], v[160:163], v[234:237], v[108:111]
	v_mfma_f32_16x16x32_bf16 v[94:97], v[54:57], v[238:241], v[94:97]
	v_mfma_f32_16x16x32_bf16 v[94:97], v[66:69], v[242:245], v[94:97]
	v_mfma_f32_16x16x32_bf16 v[90:93], v[70:73], v[238:241], v[90:93]
	v_mfma_f32_16x16x32_bf16 v[90:93], v[160:163], v[242:245], v[90:93]
	s_setprio 0
	s_setprio 1
	v_mfma_f32_16x16x32_bf16 v[136:139], v[180:183], v[196:199], v[136:139]
	v_mfma_f32_16x16x32_bf16 v[136:139], v[184:187], v[200:203], v[136:139]
	v_mfma_f32_16x16x32_bf16 v[132:135], v[188:191], v[196:199], v[132:135]
	v_mfma_f32_16x16x32_bf16 v[132:135], v[192:195], v[200:203], v[132:135]
	v_mfma_f32_16x16x32_bf16 v[120:123], v[180:183], v[222:225], v[120:123]
	v_mfma_f32_16x16x32_bf16 v[120:123], v[184:187], v[226:229], v[120:123]
	v_mfma_f32_16x16x32_bf16 v[116:119], v[188:191], v[222:225], v[116:119]
	v_mfma_f32_16x16x32_bf16 v[116:119], v[192:195], v[226:229], v[116:119]
	v_mfma_f32_16x16x32_bf16 v[104:107], v[180:183], v[230:233], v[104:107]
	v_mfma_f32_16x16x32_bf16 v[104:107], v[184:187], v[234:237], v[104:107]
	v_mfma_f32_16x16x32_bf16 v[100:103], v[188:191], v[230:233], v[100:103]
	v_mfma_f32_16x16x32_bf16 v[100:103], v[192:195], v[234:237], v[100:103]
	v_mfma_f32_16x16x32_bf16 v[86:89], v[180:183], v[238:241], v[86:89]
	v_mfma_f32_16x16x32_bf16 v[86:89], v[184:187], v[242:245], v[86:89]
	s_setprio 2
	s_barrier
; #define PG8_STAGE(bufoff, gbase, voff) do { _Pragma("unroll") for (int _i = 0; _i < 2; ++_i) \
;         __builtin_amdgcn_global_load_lds((const unsigned*)((const char*)(gbase) + (voff)[_i]), (PG8_LAS unsigned*)(lds + (bufoff) + ldsw + _i * 8192), 16, 0, AUX_A); } while (0)
; #define PG8_STAGEB(bufoff, gbase, voff) do { _Pragma("unroll") for (int _i = 0; _i < 2; ++_i) \
;         __builtin_amdgcn_global_load_lds((const unsigned*)((const char*)(gbase) + (voff)[_i]), (PG8_LAS unsigned*)(lds + (bufoff) + ldsw + _i * 8192), 16, 0, AUX_B); } while (0)
; #define PG8_LDA(dst, b, h) do { _Pragma("unroll") for (int m = 0; m < 4; ++m) _Pragma("unroll") for (int k = 0; k < 2; ++k) dst[m][k] = *(const PG8_LAS bf16x8*)(lds + PG8_SA(b, h) + aoff + m * 2048 + k * 1024); } while (0)
; #define PG8_LDB(dst, b, h) do { _Pragma("unroll") for (int n = 0; n < 2; ++n) _Pragma("unroll") for (int k = 0; k < 2; ++k) dst[n][k] = *(const PG8_LAS bf16x8*)(lds + PG8_SB(b, h) + boff + n * 2048 + k * 1024); } while (0)
; #define PG8_WAIT_V(n) asm volatile("s_waitcnt vmcnt(" #n ")" ::: "memory")
; #define PG8_WAIT_L(n) asm volatile("s_waitcnt lgkmcnt(" #n ")" ::: "memory")
; #define PG8_BAR __builtin_amdgcn_s_barrier()
; #define PG8_SCHED __builtin_amdgcn_sched_barrier(0)
; template <class Epi, class Sched, bool ALIGN_EPI = false, bool SP2 = false>
; __device__ __forceinline__ void gemm_phase(PG8_LAS unsigned char* lds, const Gemm g, const Sched& S, const Epi& E) {
;     ...
;         for (int t = 0; t < nt; t += 2) {
;             const bool last = (t == nt - 2);
;             const char* a1 = PG8_KP(cA, t + 1, rot, nt);
;             const char* a2 = last ? nAr : PG8_KP(cA, t + 2, rot, nt); const char* b2 = last ? nBr : PG8_KP(cB, t + 2, rot, nt);
;             const char* a3 = a2 + kstep; const char* b3 = b2 + kstep;
;     ...
;             PG8_LDB(B0, 1, 0); PG8_LDB(B1, 1, 1); PG8_SCHED; PG8_LDA(At, 1, 0); PG8_STAGE(PG8_SA(0, 1), a2 + hstep, voffA);
;             PG8_WAIT_V(8); PG8_WAIT_L(0); PG8_BAR; PG8_MMA(0, 0, At, B0); PG8_MMA(0, 1, At, B1); PG8_BAR; PG8_SCHED;
;             PG8_LDA(At, 1, 1); PG8_STAGEB(PG8_SB(1, 0), b3, voffB); PG8_STAGEB(PG8_SB(1, 1), b3 + hstep, voffB); PG8_STAGE(PG8_SA(1, 0), a3, voffA);
;             PG8_WAIT_V(8); PG8_WAIT_L(0); PG8_BAR; PG8_MMA(1, 0, At, B0); PG8_MMA(1, 1, At, B1); PG8_BAR; PG8_SCHED;
	v_mfma_f32_16x16x32_bf16 v[82:85], v[188:191], v[238:241], v[82:85]
	v_mfma_f32_16x16x32_bf16 v[82:85], v[192:195], v[242:245], v[82:85]
	s_setprio 0
	s_mov_b32 m0, s1
	v_lshl_add_u64 v[166:167], v[166:167], 0, s[76:77]
	ds_read_b128 v[196:199], v165 offset:49152
	ds_read_b128 v[200:203], v165 offset:50176
	ds_read_b128 v[222:225], v165 offset:51200
	ds_read_b128 v[226:229], v165 offset:52224
	ds_read_b128 v[230:233], v165 offset:53248
	ds_read_b128 v[234:237], v165 offset:54272
	ds_read_b128 v[238:241], v165 offset:55296
	ds_read_b128 v[242:245], v165 offset:56320
	global_load_lds_dwordx4 v[166:167], off
	v_lshl_add_u64 v[166:167], v[168:169], 0, s[76:77]
	s_mov_b32 m0, s0
	s_nop 0
	global_load_lds_dwordx4 v[166:167], off
	v_lshl_add_u64 v[166:167], s[52:53], 0, v[150:151]
	s_mov_b32 m0, s47
	s_nop 0
	global_load_lds_dwordx4 v[166:167], off
	v_lshl_add_u64 v[166:167], s[52:53], 0, v[154:155]
	s_mov_b32 m0, s46
	s_nop 0
	global_load_lds_dwordx4 v[166:167], off
	v_lshl_add_u64 v[166:167], v[172:173], 0, s[76:77]
	s_mov_b32 m0, s70
	s_nop 0
	global_load_lds_dwordx4 v[166:167], off
	v_lshl_add_u64 v[166:167], v[212:213], 0, s[76:77]
	s_mov_b32 m0, s71
	s_nop 0
	global_load_lds_dwordx4 v[166:167], off
	s_waitcnt vmcnt(8)
	s_waitcnt lgkmcnt(0)
	s_setprio 1
	s_barrier
	v_mfma_f32_16x16x32_bf16 v[78:81], v[54:57], v[196:199], v[78:81]
	v_mfma_f32_16x16x32_bf16 v[78:81], v[66:69], v[200:203], v[78:81]
	v_mfma_f32_16x16x32_bf16 v[74:77], v[70:73], v[196:199], v[74:77]
	v_mfma_f32_16x16x32_bf16 v[74:77], v[160:163], v[200:203], v[74:77]
	v_mfma_f32_16x16x32_bf16 v[62:65], v[54:57], v[222:225], v[62:65]
	v_mfma_f32_16x16x32_bf16 v[62:65], v[66:69], v[226:229], v[62:65]
	v_mfma_f32_16x16x32_bf16 v[58:61], v[70:73], v[222:225], v[58:61]
	v_mfma_f32_16x16x32_bf16 v[58:61], v[160:163], v[226:229], v[58:61]
	v_mfma_f32_16x16x32_bf16 v[46:49], v[54:57], v[230:233], v[46:49]
	v_mfma_f32_16x16x32_bf16 v[46:49], v[66:69], v[234:237], v[46:49]
	v_mfma_f32_16x16x32_bf16 v[42:45], v[70:73], v[230:233], v[42:45]
	v_mfma_f32_16x16x32_bf16 v[42:45], v[160:163], v[234:237], v[42:45]
	v_mfma_f32_16x16x32_bf16 v[18:21], v[54:57], v[238:241], v[18:21]
	v_mfma_f32_16x16x32_bf16 v[18:21], v[66:69], v[242:245], v[18:21]
	v_mfma_f32_16x16x32_bf16 v[10:13], v[70:73], v[238:241], v[10:13]
	v_mfma_f32_16x16x32_bf16 v[10:13], v[160:163], v[242:245], v[10:13]
	s_setprio 0
	s_setprio 1
	v_mfma_f32_16x16x32_bf16 v[22:25], v[180:183], v[196:199], v[22:25]
	v_mfma_f32_16x16x32_bf16 v[70:73], v[184:187], v[200:203], v[22:25]
	v_mfma_f32_16x16x32_bf16 v[22:25], v[188:191], v[196:199], v[34:37]
	v_mfma_f32_16x16x32_bf16 v[66:69], v[192:195], v[200:203], v[22:25]
	v_mfma_f32_16x16x32_bf16 v[22:25], v[180:183], v[222:225], v[38:41]
	v_mfma_f32_16x16x32_bf16 v[54:57], v[184:187], v[226:229], v[22:25]
	v_mfma_f32_16x16x32_bf16 v[22:25], v[188:191], v[222:225], v[50:53]
	v_mfma_f32_16x16x32_bf16 v[50:53], v[192:195], v[226:229], v[22:25]
	v_mfma_f32_16x16x32_bf16 v[22:25], v[180:183], v[230:233], v[30:33]
	v_mfma_f32_16x16x32_bf16 v[30:33], v[184:187], v[234:237], v[22:25]
	v_mfma_f32_16x16x32_bf16 v[22:25], v[188:191], v[230:233], v[26:29]
	v_mfma_f32_16x16x32_bf16 v[6:9], v[180:183], v[238:241], v[6:9]
	v_mfma_f32_16x16x32_bf16 v[2:5], v[188:191], v[238:241], v[2:5]
	v_mfma_f32_16x16x32_bf16 v[26:29], v[192:195], v[234:237], v[22:25]
	s_setprio 2
	s_barrier
	v_mfma_f32_16x16x32_bf16 v[6:9], v[184:187], v[242:245], v[6:9]
	v_mfma_f32_16x16x32_bf16 v[2:5], v[192:195], v[242:245], v[2:5]
	s_setprio 0
	v_lshl_add_u64 v[14:15], v[14:15], 0, s[86:87]
	v_lshl_add_u64 v[16:17], v[16:17], 0, s[86:87]
	s_mov_b32 s29, s81
	s_cbranch_scc1 .Lpx_936
.LBB0_936:
	s_add_i32 s81, s29, 2
	s_cmp_lt_u32 s29, 14
	s_cselect_b32 s0, 0, -16
	s_add_i32 s0, s81, s0
	s_ashr_i32 s1, s0, 31
	s_lshl_b64 s[0:1], s[0:1], 7
	s_add_u32 s2, s64, s0
	s_addc_u32 s46, s65, s1
	s_add_u32 s0, s26, s0
	s_addc_u32 s1, s27, s1
	s_cmp_eq_u32 s29, 14
	s_cselect_b32 s57, s15, s46
	s_cselect_b32 s56, s17, s2
	s_cselect_b32 s59, s43, s1
	s_cselect_b32 s58, s78, s0
	s_add_i32 s2, 0, 0x10000
	s_add_i32 s83, s2, s33
	s_add_i32 s46, 0, 0x14000
	s_add_i32 m0, s25, 0xc000
	s_add_i32 s82, s25, 0xe000
	s_add_i32 s84, s83, 0x2000
	s_add_u32 s60, s58, 0x40000
	s_addc_u32 s61, s59, 0
	s_add_i32 s88, s46, s33
	v_add_u32_e32 v160, s2, v99
	v_add_u32_e32 v166, s46, v99
	s_add_i32 s89, s88, 0x2000
	s_add_i32 s90, 0, 0x18000
	s_add_i32 s91, 0, 0x1c000
	ds_read_b128 v[22:25], v160
	ds_read_b128 v[34:37], v160 offset:1024
	ds_read_b128 v[38:41], v160 offset:2048
	ds_read_b128 v[160:163], v160 offset:3072
	ds_read_b128 v[180:183], v166
	ds_read_b128 v[184:187], v166 offset:1024
	ds_read_b128 v[188:191], v166 offset:2048
	ds_read_b128 v[192:195], v166 offset:3072
	s_add_u32 s54, s56, 0x40000
	s_addc_u32 s55, s57, 0
	s_add_i32 s1, s90, s33
	s_add_i32 s0, s1, 0x2000
	s_add_u32 s52, s58, 0x40080
	s_addc_u32 s53, s59, 0
	s_add_i32 s47, s91, s33
	s_add_i32 s46, s47, 0x2000
	s_cmp_gt_u32 s29, 13
	ds_read_b128 v[196:199], v165
	ds_read_b128 v[200:203], v165 offset:1024
	ds_read_b128 v[222:225], v165 offset:2048
	ds_read_b128 v[226:229], v165 offset:3072
	ds_read_b128 v[230:233], v165 offset:4096
	ds_read_b128 v[234:237], v165 offset:5120
	ds_read_b128 v[238:241], v165 offset:6144
	ds_read_b128 v[242:245], v165 offset:7168
	global_load_lds_dwordx4 v[16:17], off
	s_mov_b32 m0, s82
	s_nop 0
	global_load_lds_dwordx4 v[14:15], off
	s_waitcnt vmcnt(8)
	s_waitcnt lgkmcnt(0)
	s_setprio 1
	s_barrier
; #define PG8_STAGE(bufoff, gbase, voff) do { _Pragma("unroll") for (int _i = 0; _i < 2; ++_i) \
;         __builtin_amdgcn_global_load_lds((const unsigned*)((const char*)(gbase) + (voff)[_i]), (PG8_LAS unsigned*)(lds + (bufoff) + ldsw + _i * 8192), 16, 0, AUX_A); } while (0)
; #define PG8_STAGEB(bufoff, gbase, voff) do { _Pragma("unroll") for (int _i = 0; _i < 2; ++_i) \
;         __builtin_amdgcn_global_load_lds((const unsigned*)((const char*)(gbase) + (voff)[_i]), (PG8_LAS unsigned*)(lds + (bufoff) + ldsw + _i * 8192), 16, 0, AUX_B); } while (0)
; #define PG8_LDA(dst, b, h) do { _Pragma("unroll") for (int m = 0; m < 4; ++m) _Pragma("unroll") for (int k = 0; k < 2; ++k) dst[m][k] = *(const PG8_LAS bf16x8*)(lds + PG8_SA(b, h) + aoff + m * 2048 + k * 1024); } while (0)
; #define PG8_LDB(dst, b, h) do { _Pragma("unroll") for (int n = 0; n < 2; ++n) _Pragma("unroll") for (int k = 0; k < 2; ++k) dst[n][k] = *(const PG8_LAS bf16x8*)(lds + PG8_SB(b, h) + boff + n * 2048 + k * 1024); } while (0)
; #define PG8_MMA(ai, bj, At, Bt) do { __builtin_amdgcn_s_setprio(1); _Pragma("unroll") for (int m = 0; m < 4; ++m) _Pragma("unroll") for (int n = 0; n < 2; ++n) _Pragma("unroll") for (int k = 0; k < 2; ++k) \
;         acc[ai][bj][m][n] = __builtin_amdgcn_mfma_f32_16x16x32_bf16(Bt[n][k], At[m][k], acc[ai][bj][m][n], 0, 0, 0); __builtin_amdgcn_s_setprio(0); } while (0)
; #define PG8_WAIT_V(n) asm volatile("s_waitcnt vmcnt(" #n ")" ::: "memory")
; #define PG8_WAIT_L(n) asm volatile("s_waitcnt lgkmcnt(" #n ")" ::: "memory")
; #define PG8_BAR __builtin_amdgcn_s_barrier()
; #define PG8_SCHED __builtin_amdgcn_sched_barrier(0)
; template <class Epi, class Sched, bool ALIGN_EPI = false, bool SP2 = false>
; __device__ __forceinline__ void gemm_phase(PG8_LAS unsigned char* lds, const Gemm g, const Sched& S, const Epi& E) {
;     ...
;             PG8_LDB(B0, 0, 0); PG8_LDB(B1, 0, 1); PG8_SCHED; PG8_LDA(At, 0, 0); PG8_STAGE(PG8_SA(1, 1), a1 + hstep, voffA);
;             PG8_WAIT_V(8); PG8_WAIT_L(0); PG8_BAR; PG8_MMA(0, 0, At, B0); PG8_MMA(0, 1, At, B1); PG8_BAR; PG8_SCHED;
;             PG8_LDA(At, 0, 1); PG8_STAGEB(PG8_SB(0, 0), b2, voffB); PG8_STAGEB(PG8_SB(0, 1), b2 + hstep, voffB); PG8_STAGE(PG8_SA(0, 0), a2, voffA);
;             PG8_WAIT_V(8); PG8_WAIT_L(0); PG8_BAR; PG8_MMA(1, 0, At, B0); PG8_MMA(1, 1, At, B1); PG8_BAR; PG8_SCHED;
	v_mfma_f32_16x16x32_bf16 v[144:147], v[22:25], v[196:199], v[144:147]
	v_mfma_f32_16x16x32_bf16 v[144:147], v[34:37], v[200:203], v[144:147]
	v_mfma_f32_16x16x32_bf16 v[140:143], v[38:41], v[196:199], v[140:143]
	v_mfma_f32_16x16x32_bf16 v[140:143], v[160:163], v[200:203], v[140:143]
	v_mfma_f32_16x16x32_bf16 v[128:131], v[22:25], v[222:225], v[128:131]
	v_mfma_f32_16x16x32_bf16 v[128:131], v[34:37], v[226:229], v[128:131]
	v_mfma_f32_16x16x32_bf16 v[124:127], v[38:41], v[222:225], v[124:127]
	v_mfma_f32_16x16x32_bf16 v[124:127], v[160:163], v[226:229], v[124:127]
	v_mfma_f32_16x16x32_bf16 v[112:115], v[22:25], v[230:233], v[112:115]
	v_mfma_f32_16x16x32_bf16 v[112:115], v[34:37], v[234:237], v[112:115]
	v_mfma_f32_16x16x32_bf16 v[108:111], v[38:41], v[230:233], v[108:111]
	v_mfma_f32_16x16x32_bf16 v[108:111], v[160:163], v[234:237], v[108:111]
	v_mfma_f32_16x16x32_bf16 v[94:97], v[22:25], v[238:241], v[94:97]
	v_mfma_f32_16x16x32_bf16 v[94:97], v[34:37], v[242:245], v[94:97]
	v_mfma_f32_16x16x32_bf16 v[90:93], v[38:41], v[238:241], v[90:93]
	v_mfma_f32_16x16x32_bf16 v[90:93], v[160:163], v[242:245], v[90:93]
	s_setprio 0
	s_setprio 1
	v_mfma_f32_16x16x32_bf16 v[136:139], v[180:183], v[196:199], v[136:139]
	v_mfma_f32_16x16x32_bf16 v[136:139], v[184:187], v[200:203], v[136:139]
	v_mfma_f32_16x16x32_bf16 v[132:135], v[188:191], v[196:199], v[132:135]
	v_mfma_f32_16x16x32_bf16 v[132:135], v[192:195], v[200:203], v[132:135]
	v_mfma_f32_16x16x32_bf16 v[120:123], v[180:183], v[222:225], v[120:123]
	v_mfma_f32_16x16x32_bf16 v[120:123], v[184:187], v[226:229], v[120:123]
	v_mfma_f32_16x16x32_bf16 v[116:119], v[188:191], v[222:225], v[116:119]
	v_mfma_f32_16x16x32_bf16 v[116:119], v[192:195], v[226:229], v[116:119]
	v_mfma_f32_16x16x32_bf16 v[104:107], v[180:183], v[230:233], v[104:107]
	v_mfma_f32_16x16x32_bf16 v[104:107], v[184:187], v[234:237], v[104:107]
	v_mfma_f32_16x16x32_bf16 v[100:103], v[188:191], v[230:233], v[100:103]
	v_mfma_f32_16x16x32_bf16 v[100:103], v[192:195], v[234:237], v[100:103]
	v_mfma_f32_16x16x32_bf16 v[86:89], v[180:183], v[238:241], v[86:89]
	v_mfma_f32_16x16x32_bf16 v[86:89], v[184:187], v[242:245], v[86:89]
	s_setprio 2
	s_barrier
	v_mfma_f32_16x16x32_bf16 v[82:85], v[188:191], v[238:241], v[82:85]
	v_mfma_f32_16x16x32_bf16 v[82:85], v[192:195], v[242:245], v[82:85]
	s_setprio 0
	s_mov_b32 m0, s83
	v_lshl_add_u64 v[166:167], s[58:59], 0, v[150:151]
	ds_read_b128 v[196:199], v165 offset:16384
	ds_read_b128 v[200:203], v165 offset:17408
	ds_read_b128 v[222:225], v165 offset:18432
	ds_read_b128 v[226:229], v165 offset:19456
	ds_read_b128 v[230:233], v165 offset:20480
	ds_read_b128 v[234:237], v165 offset:21504
	ds_read_b128 v[238:241], v165 offset:22528
	ds_read_b128 v[242:245], v165 offset:23552
	global_load_lds_dwordx4 v[166:167], off
	v_lshl_add_u64 v[168:169], s[58:59], 0, v[154:155]
	s_mov_b32 m0, s84
	v_lshl_add_u64 v[172:173], s[60:61], 0, v[150:151]
	global_load_lds_dwordx4 v[168:169], off
	s_mov_b32 m0, s88
	v_lshl_add_u64 v[212:213], s[56:57], 0, v[152:153]
	global_load_lds_dwordx4 v[172:173], off
	v_lshl_add_u64 v[172:173], s[60:61], 0, v[154:155]
	s_mov_b32 m0, s89
	s_nop 0
	global_load_lds_dwordx4 v[172:173], off
	v_lshl_add_u64 v[172:173], s[56:57], 0, v[148:149]
	s_mov_b32 m0, s25
	s_nop 0
	global_load_lds_dwordx4 v[172:173], off
	s_mov_b32 m0, s62
	s_nop 0
	global_load_lds_dwordx4 v[212:213], off
	s_waitcnt vmcnt(8)
	s_waitcnt lgkmcnt(0)
	s_setprio 1
	s_barrier
	v_mfma_f32_16x16x32_bf16 v[78:81], v[22:25], v[196:199], v[78:81]
	v_mfma_f32_16x16x32_bf16 v[78:81], v[34:37], v[200:203], v[78:81]
	v_mfma_f32_16x16x32_bf16 v[74:77], v[38:41], v[196:199], v[74:77]
	v_mfma_f32_16x16x32_bf16 v[74:77], v[160:163], v[200:203], v[74:77]
	v_mfma_f32_16x16x32_bf16 v[62:65], v[22:25], v[222:225], v[62:65]
	v_mfma_f32_16x16x32_bf16 v[62:65], v[34:37], v[226:229], v[62:65]
	v_mfma_f32_16x16x32_bf16 v[58:61], v[38:41], v[222:225], v[58:61]
	v_mfma_f32_16x16x32_bf16 v[58:61], v[160:163], v[226:229], v[58:61]
	v_mfma_f32_16x16x32_bf16 v[46:49], v[22:25], v[230:233], v[46:49]
	v_mfma_f32_16x16x32_bf16 v[46:49], v[34:37], v[234:237], v[46:49]
	v_mfma_f32_16x16x32_bf16 v[42:45], v[38:41], v[230:233], v[42:45]
	v_mfma_f32_16x16x32_bf16 v[42:45], v[160:163], v[234:237], v[42:45]
	v_mfma_f32_16x16x32_bf16 v[18:21], v[22:25], v[238:241], v[18:21]
	v_mfma_f32_16x16x32_bf16 v[18:21], v[34:37], v[242:245], v[18:21]
	v_mfma_f32_16x16x32_bf16 v[10:13], v[38:41], v[238:241], v[10:13]
	v_mfma_f32_16x16x32_bf16 v[10:13], v[160:163], v[242:245], v[10:13]
	s_setprio 0
	s_setprio 1
	v_mfma_f32_16x16x32_bf16 v[50:53], v[188:191], v[222:225], v[50:53]
	v_mfma_f32_16x16x32_bf16 v[30:33], v[180:183], v[230:233], v[30:33]
	v_mfma_f32_16x16x32_bf16 v[26:29], v[188:191], v[230:233], v[26:29]
	v_mfma_f32_16x16x32_bf16 v[6:9], v[180:183], v[238:241], v[6:9]
	v_mfma_f32_16x16x32_bf16 v[2:5], v[188:191], v[238:241], v[2:5]
	v_mfma_f32_16x16x32_bf16 v[22:25], v[180:183], v[196:199], v[70:73]
	v_mfma_f32_16x16x32_bf16 v[34:37], v[188:191], v[196:199], v[66:69]
	v_mfma_f32_16x16x32_bf16 v[38:41], v[180:183], v[222:225], v[54:57]
	v_mfma_f32_16x16x32_bf16 v[50:53], v[192:195], v[226:229], v[50:53]
	v_mfma_f32_16x16x32_bf16 v[30:33], v[184:187], v[234:237], v[30:33]
	v_mfma_f32_16x16x32_bf16 v[26:29], v[192:195], v[234:237], v[26:29]
	v_mfma_f32_16x16x32_bf16 v[6:9], v[184:187], v[242:245], v[6:9]
	v_mfma_f32_16x16x32_bf16 v[2:5], v[192:195], v[242:245], v[2:5]
	v_mfma_f32_16x16x32_bf16 v[22:25], v[184:187], v[200:203], v[22:25]
	s_setprio 2
	s_barrier
; #define PG8_STAGE(bufoff, gbase, voff) do { _Pragma("unroll") for (int _i = 0; _i < 2; ++_i) \
;         __builtin_amdgcn_global_load_lds((const unsigned*)((const char*)(gbase) + (voff)[_i]), (PG8_LAS unsigned*)(lds + (bufoff) + ldsw + _i * 8192), 16, 0, AUX_A); } while (0)
; #define PG8_STAGEB(bufoff, gbase, voff) do { _Pragma("unroll") for (int _i = 0; _i < 2; ++_i) \
;         __builtin_amdgcn_global_load_lds((const unsigned*)((const char*)(gbase) + (voff)[_i]), (PG8_LAS unsigned*)(lds + (bufoff) + ldsw + _i * 8192), 16, 0, AUX_B); } while (0)
; #define PG8_LDA(dst, b, h) do { _Pragma("unroll") for (int m = 0; m < 4; ++m) _Pragma("unroll") for (int k = 0; k < 2; ++k) dst[m][k] = *(const PG8_LAS bf16x8*)(lds + PG8_SA(b, h) + aoff + m * 2048 + k * 1024); } while (0)
; #define PG8_LDB(dst, b, h) do { _Pragma("unroll") for (int n = 0; n < 2; ++n) _Pragma("unroll") for (int k = 0; k < 2; ++k) dst[n][k] = *(const PG8_LAS bf16x8*)(lds + PG8_SB(b, h) + boff + n * 2048 + k * 1024); } while (0)
; #define PG8_MMA(ai, bj, At, Bt) do { __builtin_amdgcn_s_setprio(1); _Pragma("unroll") for (int m = 0; m < 4; ++m) _Pragma("unroll") for (int n = 0; n < 2; ++n) _Pragma("unroll") for (int k = 0; k < 2; ++k) \
;         acc[ai][bj][m][n] = __builtin_amdgcn_mfma_f32_16x16x32_bf16(Bt[n][k], At[m][k], acc[ai][bj][m][n], 0, 0, 0); __builtin_amdgcn_s_setprio(0); } while (0)
; #define PG8_WAIT_V(n) asm volatile("s_waitcnt vmcnt(" #n ")" ::: "memory")
; #define PG8_WAIT_L(n) asm volatile("s_waitcnt lgkmcnt(" #n ")" ::: "memory")
; template <class Epi, class Sched, bool ALIGN_EPI = false, bool SP2 = false>
; __device__ __forceinline__ void gemm_phase(PG8_LAS unsigned char* lds, const Gemm g, const Sched& S, const Epi& E) {
;     ...
;             PG8_WAIT_V(8); PG8_WAIT_L(0); PG8_BAR; PG8_MMA(1, 0, At, B0); PG8_MMA(1, 1, At, B1); PG8_BAR; PG8_SCHED;
;             PG8_LDB(B0, 1, 0); PG8_LDB(B1, 1, 1); PG8_SCHED; PG8_LDA(At, 1, 0); PG8_STAGE(PG8_SA(0, 1), a2 + hstep, voffA);
;             PG8_WAIT_V(8); PG8_WAIT_L(0); PG8_BAR; PG8_MMA(0, 0, At, B0); PG8_MMA(0, 1, At, B1); PG8_BAR; PG8_SCHED;
;             PG8_LDA(At, 1, 1); PG8_STAGEB(PG8_SB(1, 0), b3, voffB); PG8_STAGEB(PG8_SB(1, 1), b3 + hstep, voffB); PG8_STAGE(PG8_SA(1, 0), a3, voffA);
;             PG8_WAIT_V(8); PG8_WAIT_L(0); PG8_BAR; PG8_MMA(1, 0, At, B0); PG8_MMA(1, 1, At, B1); PG8_BAR; PG8_SCHED;
	v_mfma_f32_16x16x32_bf16 v[34:37], v[192:195], v[200:203], v[34:37]
	v_mfma_f32_16x16x32_bf16 v[38:41], v[184:187], v[226:229], v[38:41]
	s_setprio 0
	v_add_u32_e32 v160, s90, v99
	v_add_u32_e32 v192, s91, v99
	ds_read_b128 v[54:57], v160
	ds_read_b128 v[66:69], v160 offset:1024
	ds_read_b128 v[70:73], v160 offset:2048
	ds_read_b128 v[160:163], v160 offset:3072
	ds_read_b128 v[180:183], v192
	ds_read_b128 v[184:187], v192 offset:1024
	ds_read_b128 v[188:191], v192 offset:2048
	ds_read_b128 v[192:195], v192 offset:3072
	s_mov_b32 m0, s63
	v_lshl_add_u64 v[246:247], s[54:55], 0, v[148:149]
	ds_read_b128 v[196:199], v165 offset:32768
	ds_read_b128 v[200:203], v165 offset:33792
	ds_read_b128 v[222:225], v165 offset:34816
	ds_read_b128 v[226:229], v165 offset:35840
	ds_read_b128 v[230:233], v165 offset:36864
	ds_read_b128 v[234:237], v165 offset:37888
	ds_read_b128 v[238:241], v165 offset:38912
	ds_read_b128 v[242:245], v165 offset:39936
	global_load_lds_dwordx4 v[246:247], off
	v_lshl_add_u64 v[246:247], s[54:55], 0, v[152:153]
	s_mov_b32 m0, s69
	s_nop 0
	global_load_lds_dwordx4 v[246:247], off
	s_waitcnt vmcnt(8)
	s_waitcnt lgkmcnt(0)
	s_setprio 1
	s_barrier
	v_mfma_f32_16x16x32_bf16 v[144:147], v[54:57], v[196:199], v[144:147]
	v_mfma_f32_16x16x32_bf16 v[144:147], v[66:69], v[200:203], v[144:147]
	v_mfma_f32_16x16x32_bf16 v[140:143], v[70:73], v[196:199], v[140:143]
	v_mfma_f32_16x16x32_bf16 v[140:143], v[160:163], v[200:203], v[140:143]
	v_mfma_f32_16x16x32_bf16 v[128:131], v[54:57], v[222:225], v[128:131]
	v_mfma_f32_16x16x32_bf16 v[128:131], v[66:69], v[226:229], v[128:131]
	v_mfma_f32_16x16x32_bf16 v[124:127], v[70:73], v[222:225], v[124:127]
	v_mfma_f32_16x16x32_bf16 v[124:127], v[160:163], v[226:229], v[124:127]
	v_mfma_f32_16x16x32_bf16 v[112:115], v[54:57], v[230:233], v[112:115]
	v_mfma_f32_16x16x32_bf16 v[112:115], v[66:69], v[234:237], v[112:115]
	v_mfma_f32_16x16x32_bf16 v[108:111], v[70:73], v[230:233], v[108:111]
	v_mfma_f32_16x16x32_bf16 v[108:111], v[160:163], v[234:237], v[108:111]
	v_mfma_f32_16x16x32_bf16 v[94:97], v[54:57], v[238:241], v[94:97]
	v_mfma_f32_16x16x32_bf16 v[94:97], v[66:69], v[242:245], v[94:97]
	v_mfma_f32_16x16x32_bf16 v[90:93], v[70:73], v[238:241], v[90:93]
	v_mfma_f32_16x16x32_bf16 v[90:93], v[160:163], v[242:245], v[90:93]
	s_setprio 0
	s_setprio 1
	v_mfma_f32_16x16x32_bf16 v[136:139], v[180:183], v[196:199], v[136:139]
	v_mfma_f32_16x16x32_bf16 v[136:139], v[184:187], v[200:203], v[136:139]
	v_mfma_f32_16x16x32_bf16 v[132:135], v[188:191], v[196:199], v[132:135]
	v_mfma_f32_16x16x32_bf16 v[132:135], v[192:195], v[200:203], v[132:135]
	v_mfma_f32_16x16x32_bf16 v[120:123], v[180:183], v[222:225], v[120:123]
	v_mfma_f32_16x16x32_bf16 v[120:123], v[184:187], v[226:229], v[120:123]
	v_mfma_f32_16x16x32_bf16 v[116:119], v[188:191], v[222:225], v[116:119]
	v_mfma_f32_16x16x32_bf16 v[116:119], v[192:195], v[226:229], v[116:119]
	v_mfma_f32_16x16x32_bf16 v[104:107], v[180:183], v[230:233], v[104:107]
	v_mfma_f32_16x16x32_bf16 v[104:107], v[184:187], v[234:237], v[104:107]
	v_mfma_f32_16x16x32_bf16 v[100:103], v[188:191], v[230:233], v[100:103]
	v_mfma_f32_16x16x32_bf16 v[100:103], v[192:195], v[234:237], v[100:103]
	v_mfma_f32_16x16x32_bf16 v[86:89], v[180:183], v[238:241], v[86:89]
	v_mfma_f32_16x16x32_bf16 v[86:89], v[184:187], v[242:245], v[86:89]
	s_setprio 2
	s_barrier
	v_mfma_f32_16x16x32_bf16 v[82:85], v[188:191], v[238:241], v[82:85]
	v_mfma_f32_16x16x32_bf16 v[82:85], v[192:195], v[242:245], v[82:85]
	s_setprio 0
	s_mov_b32 m0, s1
	v_lshl_add_u64 v[166:167], v[166:167], 0, s[76:77]
	ds_read_b128 v[196:199], v165 offset:49152
	ds_read_b128 v[200:203], v165 offset:50176
	ds_read_b128 v[222:225], v165 offset:51200
	ds_read_b128 v[226:229], v165 offset:52224
	ds_read_b128 v[230:233], v165 offset:53248
	ds_read_b128 v[234:237], v165 offset:54272
	ds_read_b128 v[238:241], v165 offset:55296
	ds_read_b128 v[242:245], v165 offset:56320
	global_load_lds_dwordx4 v[166:167], off
	v_lshl_add_u64 v[166:167], v[168:169], 0, s[76:77]
	s_mov_b32 m0, s0
	s_nop 0
	global_load_lds_dwordx4 v[166:167], off
	v_lshl_add_u64 v[166:167], s[52:53], 0, v[150:151]
	s_mov_b32 m0, s47
	s_nop 0
	global_load_lds_dwordx4 v[166:167], off
	v_lshl_add_u64 v[166:167], s[52:53], 0, v[154:155]
	s_mov_b32 m0, s46
	s_nop 0
	global_load_lds_dwordx4 v[166:167], off
	v_lshl_add_u64 v[166:167], v[172:173], 0, s[76:77]
	s_mov_b32 m0, s70
	s_nop 0
	global_load_lds_dwordx4 v[166:167], off
	v_lshl_add_u64 v[166:167], v[212:213], 0, s[76:77]
	s_mov_b32 m0, s71
	s_nop 0
	global_load_lds_dwordx4 v[166:167], off
	s_waitcnt vmcnt(8)
	s_waitcnt lgkmcnt(0)
	s_setprio 1
	s_barrier
	v_mfma_f32_16x16x32_bf16 v[78:81], v[54:57], v[196:199], v[78:81]
	v_mfma_f32_16x16x32_bf16 v[78:81], v[66:69], v[200:203], v[78:81]
	v_mfma_f32_16x16x32_bf16 v[74:77], v[70:73], v[196:199], v[74:77]
	v_mfma_f32_16x16x32_bf16 v[74:77], v[160:163], v[200:203], v[74:77]
	v_mfma_f32_16x16x32_bf16 v[62:65], v[54:57], v[222:225], v[62:65]
	v_mfma_f32_16x16x32_bf16 v[62:65], v[66:69], v[226:229], v[62:65]
	v_mfma_f32_16x16x32_bf16 v[58:61], v[70:73], v[222:225], v[58:61]
	v_mfma_f32_16x16x32_bf16 v[58:61], v[160:163], v[226:229], v[58:61]
	v_mfma_f32_16x16x32_bf16 v[46:49], v[54:57], v[230:233], v[46:49]
	v_mfma_f32_16x16x32_bf16 v[46:49], v[66:69], v[234:237], v[46:49]
	v_mfma_f32_16x16x32_bf16 v[42:45], v[70:73], v[230:233], v[42:45]
	v_mfma_f32_16x16x32_bf16 v[42:45], v[160:163], v[234:237], v[42:45]
	v_mfma_f32_16x16x32_bf16 v[18:21], v[54:57], v[238:241], v[18:21]
	v_mfma_f32_16x16x32_bf16 v[18:21], v[66:69], v[242:245], v[18:21]
	v_mfma_f32_16x16x32_bf16 v[10:13], v[70:73], v[238:241], v[10:13]
	v_mfma_f32_16x16x32_bf16 v[10:13], v[160:163], v[242:245], v[10:13]
	s_setprio 0
	s_setprio 1
	v_mfma_f32_16x16x32_bf16 v[22:25], v[180:183], v[196:199], v[22:25]
	v_mfma_f32_16x16x32_bf16 v[70:73], v[184:187], v[200:203], v[22:25]
	v_mfma_f32_16x16x32_bf16 v[22:25], v[188:191], v[196:199], v[34:37]
	v_mfma_f32_16x16x32_bf16 v[66:69], v[192:195], v[200:203], v[22:25]
	v_mfma_f32_16x16x32_bf16 v[22:25], v[180:183], v[222:225], v[38:41]
	v_mfma_f32_16x16x32_bf16 v[54:57], v[184:187], v[226:229], v[22:25]
	v_mfma_f32_16x16x32_bf16 v[22:25], v[188:191], v[222:225], v[50:53]
	v_mfma_f32_16x16x32_bf16 v[50:53], v[192:195], v[226:229], v[22:25]
	v_mfma_f32_16x16x32_bf16 v[22:25], v[180:183], v[230:233], v[30:33]
	v_mfma_f32_16x16x32_bf16 v[30:33], v[184:187], v[234:237], v[22:25]
	v_mfma_f32_16x16x32_bf16 v[22:25], v[188:191], v[230:233], v[26:29]
	v_mfma_f32_16x16x32_bf16 v[6:9], v[180:183], v[238:241], v[6:9]
	v_mfma_f32_16x16x32_bf16 v[2:5], v[188:191], v[238:241], v[2:5]
	v_mfma_f32_16x16x32_bf16 v[26:29], v[192:195], v[234:237], v[22:25]
	s_setprio 2
	s_barrier
	v_mfma_f32_16x16x32_bf16 v[6:9], v[184:187], v[242:245], v[6:9]
	v_mfma_f32_16x16x32_bf16 v[2:5], v[192:195], v[242:245], v[2:5]
	s_setprio 0
	v_lshl_add_u64 v[14:15], v[14:15], 0, s[86:87]
	v_lshl_add_u64 v[16:17], v[16:17], 0, s[86:87]
	s_mov_b32 s29, s81
	s_cbranch_scc0 .LBB0_936
; #define PG8_BAR __builtin_amdgcn_s_barrier()
; template <class Epi, class Sched, bool ALIGN_EPI = false, bool SP2 = false>
; __device__ __forceinline__ void gemm_phase(PG8_LAS unsigned char* lds, const Gemm g, const Sched& S, const Epi& E) {
;     ...
;         }
;         if constexpr (ALIGN_EPI) { if (wr == 0) PG8_BAR; }
.Lpx_936:
	s_and_b64 vcc, exec, s[12:13]
	s_cbranch_vccz .LBB0_939
	s_barrier

; #define PG8_STAGE(bufoff, gbase, voff) do { _Pragma("unroll") for (int _i = 0; _i < 2; ++_i) \
;         __builtin_amdgcn_global_load_lds((const unsigned*)((const char*)(gbase) + (voff)[_i]), (PG8_LAS unsigned*)(lds + (bufoff) + ldsw + _i * 8192), 16, 0, AUX_A); } while (0)
; #define PG8_STAGEB(bufoff, gbase, voff) do { _Pragma("unroll") for (int _i = 0; _i < 2; ++_i) \
;         __builtin_amdgcn_global_load_lds((const unsigned*)((const char*)(gbase) + (voff)[_i]), (PG8_LAS unsigned*)(lds + (bufoff) + ldsw + _i * 8192), 16, 0, AUX_B); } while (0)
; #define PG8_LDA(dst, b, h) do { _Pragma("unroll") for (int m = 0; m < 4; ++m) _Pragma("unroll") for (int k = 0; k < 2; ++k) dst[m][k] = *(const PG8_LAS bf16x8*)(lds + PG8_SA(b, h) + aoff + m * 2048 + k * 1024); } while (0)
; template <class Epi, class Sched, bool ALIGN_EPI = false, bool SP2 = false>
; __device__ __forceinline__ void gemm_phase(PG8_LAS unsigned char* lds, const Gemm g, const Sched& S, const Epi& E) {
;     ...
;         const char* nA = has_next ? (const char*)g.A + (size_t)nxt.pm * tstep + (size_t)nxt.kt0 * kstep : cA; const char* nB = has_next ? (const char*)g.Bt + (size_t)nxt.pn * tstep + (size_t)nxt.kt0 * kstep : cB;
;         const int nt = cur.nkt, rot = cur.krot;
;         const char* nAr = has_next ? nA + (size_t)nxt.krot * kstep : PG8_KP(cA, 0, rot, nt); const char* nBr = has_next ? nB + (size_t)nxt.krot * kstep : PG8_KP(cB, 0, rot, nt);
;         for (int t = 0; t < nt; t += 2) {
;             const bool last = (t == nt - 2);
;             const char* a1 = PG8_KP(cA, t + 1, rot, nt);
;             const char* a2 = last ? nAr : PG8_KP(cA, t + 2, rot, nt); const char* b2 = last ? nBr : PG8_KP(cB, t + 2, rot, nt);
;             const char* a3 = a2 + kstep; const char* b3 = b2 + kstep;
;             if (last && has_next) S.a_ready(nxt);
;             if constexpr (SP2) {
;             PG8_LDB(B0, 0, 0); PG8_LDB(B1, 0, 1); PG8_SCHED; PG8_LDA(At, 0, 0); PG8_STAGE(PG8_SA(1, 1), a1 + hstep, voffA);
;             PG8_WAIT_V(8); PG8_WAIT_L(0); PG8_BAR; PG8_MMA(0, 0, At, B0); PG8_MMA(0, 1, At, B1); PG8_BAR; PG8_SCHED;
;             PG8_LDA(At, 0, 1); PG8_STAGEB(PG8_SB(0, 0), b2, voffB); PG8_STAGEB(PG8_SB(0, 1), b2 + hstep, voffB); PG8_STAGE(PG8_SA(0, 0), a2, voffA);
;             PG8_WAIT_V(8); PG8_WAIT_L(0); PG8_BAR; PG8_MMA(1, 0, At, B0); PG8_MMA(1, 1, At, B1); PG8_BAR; PG8_SCHED;
.LBB0_1066:
	s_mov_b32 s14, s15
	s_ashr_i32 s15, s15, 31
	s_mov_b32 s16, s1
	s_lshl_b64 s[0:1], s[14:15], 19
	s_add_u32 s48, s33, s0
	s_addc_u32 s49, s69, s1
	s_ashr_i32 s17, s16, 31
	s_lshl_b64 s[0:1], s[16:17], 19
	s_add_u32 s50, s34, s0
	s_addc_u32 s51, s35, s1
	s_and_b64 s[0:1], s[18:19], exec
	s_cselect_b32 s15, s49, s53
	s_cselect_b32 s17, s48, s52
	s_cselect_b32 s92, s51, s43
	s_cselect_b32 s93, s50, s42
	s_add_u32 s0, s52, 0x40080
	s_addc_u32 s1, s53, 0
	v_lshl_add_u64 v[144:145], s[0:1], 0, v[140:141]
	v_lshl_add_u64 v[146:147], s[0:1], 0, v[142:143]
	s_mov_b32 s29, 0
	s_waitcnt vmcnt(0)
	s_waitcnt lgkmcnt(0)
.Lpk_1067:
	s_add_i32 s81, s29, 2
	s_cmp_lt_u32 s29, 14
	s_cselect_b32 s0, 0, -16
	s_add_i32 s0, s81, s0
	s_ashr_i32 s1, s0, 31
	s_lshl_b64 s[0:1], s[0:1], 7
	s_add_u32 s2, s52, s0
	s_addc_u32 s46, s53, s1
	s_add_u32 s0, s42, s0
	s_addc_u32 s1, s43, s1
	s_cmp_eq_u32 s29, 14
	s_cselect_b32 s59, s15, s46
	s_cselect_b32 s58, s17, s2
	s_cselect_b32 s61, s92, s1
	s_cselect_b32 s60, s93, s0
	s_add_i32 s2, 0, 0x10000
	s_add_i32 s94, s2, s70
	s_add_i32 s46, 0, 0x14000
	s_add_i32 m0, s71, 0xc000
	s_add_i32 s84, s71, 0xe000
	s_add_i32 s95, s94, 0x2000
	s_add_u32 s62, s60, 0x40000
	v_add_u32_e32 v148, s2, v99
	s_addc_u32 s63, s61, 0
	s_add_i32 s96, s46, s70
	ds_read_b128 v[152:155], v148
	ds_read_b128 v[156:159], v148 offset:1024
	ds_read_b128 v[160:163], v148 offset:2048
	ds_read_b128 v[164:167], v148 offset:3072
	v_add_u32_e32 v148, s46, v99
	s_add_i32 s97, s96, 0x2000
	s_add_i32 vcc_lo, 0, 0x18000
	s_add_i32 vcc_hi, 0, 0x1c000
	ds_read_b128 v[180:183], v148
	ds_read_b128 v[184:187], v148 offset:1024
	ds_read_b128 v[188:191], v148 offset:2048
	ds_read_b128 v[192:195], v148 offset:3072
	s_add_u32 s56, s58, 0x40000
	s_addc_u32 s57, s59, 0
	s_add_i32 s1, vcc_lo, s70
	s_add_i32 s0, s1, 0x2000
	s_add_u32 s54, s60, 0x40080
	s_addc_u32 s55, s61, 0
	s_add_i32 s47, vcc_hi, s70
	s_add_i32 s46, s47, 0x2000
	s_cmp_gt_u32 s29, 13
	ds_read_b128 v[196:199], v151
	ds_read_b128 v[200:203], v151 offset:1024
	ds_read_b128 v[222:225], v151 offset:2048
	ds_read_b128 v[226:229], v151 offset:3072
	ds_read_b128 v[230:233], v151 offset:4096
	ds_read_b128 v[234:237], v151 offset:5120
	ds_read_b128 v[238:241], v151 offset:6144
	ds_read_b128 v[242:245], v151 offset:7168
	global_load_lds_dwordx4 v[146:147], off
	s_mov_b32 m0, s84
	s_nop 0
	global_load_lds_dwordx4 v[144:145], off
	s_waitcnt vmcnt(8)
	s_waitcnt lgkmcnt(0)
	s_setprio 1
	s_barrier
	v_mfma_f32_16x16x32_bf16 v[128:131], v[152:155], v[196:199], 0
	v_mfma_f32_16x16x32_bf16 v[128:131], v[156:159], v[200:203], v[128:131]
	v_mfma_f32_16x16x32_bf16 v[124:127], v[160:163], v[196:199], 0
	v_mfma_f32_16x16x32_bf16 v[124:127], v[164:167], v[200:203], v[124:127]
	v_mfma_f32_16x16x32_bf16 v[112:115], v[152:155], v[222:225], 0
	v_mfma_f32_16x16x32_bf16 v[112:115], v[156:159], v[226:229], v[112:115]
	v_mfma_f32_16x16x32_bf16 v[108:111], v[160:163], v[222:225], 0
	v_mfma_f32_16x16x32_bf16 v[108:111], v[164:167], v[226:229], v[108:111]
	v_mfma_f32_16x16x32_bf16 v[94:97], v[152:155], v[230:233], 0
	v_mfma_f32_16x16x32_bf16 v[94:97], v[156:159], v[234:237], v[94:97]
	v_mfma_f32_16x16x32_bf16 v[90:93], v[160:163], v[230:233], 0
	v_mfma_f32_16x16x32_bf16 v[90:93], v[164:167], v[234:237], v[90:93]
	v_mfma_f32_16x16x32_bf16 v[78:81], v[152:155], v[238:241], 0
	v_mfma_f32_16x16x32_bf16 v[78:81], v[156:159], v[242:245], v[78:81]
	v_mfma_f32_16x16x32_bf16 v[74:77], v[160:163], v[238:241], 0
	v_mfma_f32_16x16x32_bf16 v[74:77], v[164:167], v[242:245], v[74:77]
	s_setprio 0
	s_setprio 1
	v_mfma_f32_16x16x32_bf16 v[120:123], v[180:183], v[196:199], 0
	v_mfma_f32_16x16x32_bf16 v[120:123], v[184:187], v[200:203], v[120:123]
	v_mfma_f32_16x16x32_bf16 v[116:119], v[188:191], v[196:199], 0
	v_mfma_f32_16x16x32_bf16 v[116:119], v[192:195], v[200:203], v[116:119]
	v_mfma_f32_16x16x32_bf16 v[104:107], v[180:183], v[222:225], 0
	v_mfma_f32_16x16x32_bf16 v[104:107], v[184:187], v[226:229], v[104:107]
	v_mfma_f32_16x16x32_bf16 v[100:103], v[188:191], v[222:225], 0
	v_mfma_f32_16x16x32_bf16 v[100:103], v[192:195], v[226:229], v[100:103]
	v_mfma_f32_16x16x32_bf16 v[86:89], v[180:183], v[230:233], 0
	v_mfma_f32_16x16x32_bf16 v[86:89], v[184:187], v[234:237], v[86:89]
	v_mfma_f32_16x16x32_bf16 v[82:85], v[188:191], v[230:233], 0
	v_mfma_f32_16x16x32_bf16 v[82:85], v[192:195], v[234:237], v[82:85]
	v_mfma_f32_16x16x32_bf16 v[70:73], v[180:183], v[238:241], 0
	v_mfma_f32_16x16x32_bf16 v[70:73], v[184:187], v[242:245], v[70:73]
	s_setprio 2
	s_barrier
	v_mfma_f32_16x16x32_bf16 v[66:69], v[188:191], v[238:241], 0
	v_mfma_f32_16x16x32_bf16 v[66:69], v[192:195], v[242:245], v[66:69]
	s_setprio 0
	s_mov_b32 m0, s94
	v_lshl_add_u64 v[148:149], s[60:61], 0, v[136:137]
	ds_read_b128 v[196:199], v151 offset:16384
	ds_read_b128 v[200:203], v151 offset:17408
	ds_read_b128 v[222:225], v151 offset:18432
	ds_read_b128 v[226:229], v151 offset:19456
	ds_read_b128 v[230:233], v151 offset:20480
	ds_read_b128 v[234:237], v151 offset:21504
	ds_read_b128 v[238:241], v151 offset:22528
	ds_read_b128 v[242:245], v151 offset:23552
	global_load_lds_dwordx4 v[148:149], off
	v_lshl_add_u64 v[168:169], s[60:61], 0, v[132:133]
	s_mov_b32 m0, s95
	v_lshl_add_u64 v[172:173], s[62:63], 0, v[136:137]
	global_load_lds_dwordx4 v[168:169], off
	s_mov_b32 m0, s96
	v_lshl_add_u64 v[212:213], s[58:59], 0, v[134:135]
	global_load_lds_dwordx4 v[172:173], off
	v_lshl_add_u64 v[172:173], s[62:63], 0, v[132:133]
	s_mov_b32 m0, s97
	s_nop 0
	global_load_lds_dwordx4 v[172:173], off
	v_lshl_add_u64 v[172:173], s[58:59], 0, v[138:139]
	s_mov_b32 m0, s71
	s_nop 0
	global_load_lds_dwordx4 v[172:173], off
	s_mov_b32 m0, s75
	s_nop 0
	global_load_lds_dwordx4 v[212:213], off
	s_waitcnt vmcnt(8)
	s_waitcnt lgkmcnt(0)
	s_setprio 1
	s_barrier
; #define PG8_STAGE(bufoff, gbase, voff) do { _Pragma("unroll") for (int _i = 0; _i < 2; ++_i) \
;         __builtin_amdgcn_global_load_lds((const unsigned*)((const char*)(gbase) + (voff)[_i]), (PG8_LAS unsigned*)(lds + (bufoff) + ldsw + _i * 8192), 16, 0, AUX_A); } while (0)
; #define PG8_STAGEB(bufoff, gbase, voff) do { _Pragma("unroll") for (int _i = 0; _i < 2; ++_i) \
;         __builtin_amdgcn_global_load_lds((const unsigned*)((const char*)(gbase) + (voff)[_i]), (PG8_LAS unsigned*)(lds + (bufoff) + ldsw + _i * 8192), 16, 0, AUX_B); } while (0)
; #define PG8_LDA(dst, b, h) do { _Pragma("unroll") for (int m = 0; m < 4; ++m) _Pragma("unroll") for (int k = 0; k < 2; ++k) dst[m][k] = *(const PG8_LAS bf16x8*)(lds + PG8_SA(b, h) + aoff + m * 2048 + k * 1024); } while (0)
; #define PG8_LDB(dst, b, h) do { _Pragma("unroll") for (int n = 0; n < 2; ++n) _Pragma("unroll") for (int k = 0; k < 2; ++k) dst[n][k] = *(const PG8_LAS bf16x8*)(lds + PG8_SB(b, h) + boff + n * 2048 + k * 1024); } while (0)
; #define PG8_MMA(ai, bj, At, Bt) do { __builtin_amdgcn_s_setprio(1); _Pragma("unroll") for (int m = 0; m < 4; ++m) _Pragma("unroll") for (int n = 0; n < 2; ++n) _Pragma("unroll") for (int k = 0; k < 2; ++k) \
;         acc[ai][bj][m][n] = __builtin_amdgcn_mfma_f32_16x16x32_bf16(Bt[n][k], At[m][k], acc[ai][bj][m][n], 0, 0, 0); __builtin_amdgcn_s_setprio(0); } while (0)
; #define PG8_WAIT_V(n) asm volatile("s_waitcnt vmcnt(" #n ")" ::: "memory")
; #define PG8_WAIT_L(n) asm volatile("s_waitcnt lgkmcnt(" #n ")" ::: "memory")
; #define PG8_BAR __builtin_amdgcn_s_barrier()
; #define PG8_SCHED __builtin_amdgcn_sched_barrier(0)
; template <class Epi, class Sched, bool ALIGN_EPI = false, bool SP2 = false>
; __device__ __forceinline__ void gemm_phase(PG8_LAS unsigned char* lds, const Gemm g, const Sched& S, const Epi& E) {
;     ...
;             PG8_LDA(At, 0, 1); PG8_STAGEB(PG8_SB(0, 0), b2, voffB); PG8_STAGEB(PG8_SB(0, 1), b2 + hstep, voffB); PG8_STAGE(PG8_SA(0, 0), a2, voffA);
;             PG8_WAIT_V(8); PG8_WAIT_L(0); PG8_BAR; PG8_MMA(1, 0, At, B0); PG8_MMA(1, 1, At, B1); PG8_BAR; PG8_SCHED;
;             PG8_LDB(B0, 1, 0); PG8_LDB(B1, 1, 1); PG8_SCHED; PG8_LDA(At, 1, 0); PG8_STAGE(PG8_SA(0, 1), a2 + hstep, voffA);
;             PG8_WAIT_V(8); PG8_WAIT_L(0); PG8_BAR; PG8_MMA(0, 0, At, B0); PG8_MMA(0, 1, At, B1); PG8_BAR; PG8_SCHED;
	v_mfma_f32_16x16x32_bf16 v[62:65], v[152:155], v[196:199], 0
	v_mfma_f32_16x16x32_bf16 v[62:65], v[156:159], v[200:203], v[62:65]
	v_mfma_f32_16x16x32_bf16 v[58:61], v[160:163], v[196:199], 0
	v_mfma_f32_16x16x32_bf16 v[58:61], v[164:167], v[200:203], v[58:61]
	v_mfma_f32_16x16x32_bf16 v[46:49], v[152:155], v[222:225], 0
	v_mfma_f32_16x16x32_bf16 v[46:49], v[156:159], v[226:229], v[46:49]
	v_mfma_f32_16x16x32_bf16 v[42:45], v[160:163], v[222:225], 0
	v_mfma_f32_16x16x32_bf16 v[42:45], v[164:167], v[226:229], v[42:45]
	v_mfma_f32_16x16x32_bf16 v[30:33], v[152:155], v[230:233], 0
	v_mfma_f32_16x16x32_bf16 v[30:33], v[156:159], v[234:237], v[30:33]
	v_mfma_f32_16x16x32_bf16 v[26:29], v[160:163], v[230:233], 0
	v_mfma_f32_16x16x32_bf16 v[26:29], v[164:167], v[234:237], v[26:29]
	v_mfma_f32_16x16x32_bf16 v[14:17], v[152:155], v[238:241], 0
	v_mfma_f32_16x16x32_bf16 v[14:17], v[156:159], v[242:245], v[14:17]
	v_mfma_f32_16x16x32_bf16 v[10:13], v[160:163], v[238:241], 0
	v_mfma_f32_16x16x32_bf16 v[10:13], v[164:167], v[242:245], v[10:13]
	s_setprio 0
	s_setprio 1
	v_mfma_f32_16x16x32_bf16 v[54:57], v[180:183], v[196:199], 0
	v_mfma_f32_16x16x32_bf16 v[54:57], v[184:187], v[200:203], v[54:57]
	v_mfma_f32_16x16x32_bf16 v[50:53], v[188:191], v[196:199], 0
	v_mfma_f32_16x16x32_bf16 v[50:53], v[192:195], v[200:203], v[50:53]
	v_mfma_f32_16x16x32_bf16 v[38:41], v[180:183], v[222:225], 0
	v_mfma_f32_16x16x32_bf16 v[38:41], v[184:187], v[226:229], v[38:41]
	v_mfma_f32_16x16x32_bf16 v[34:37], v[188:191], v[222:225], 0
	v_mfma_f32_16x16x32_bf16 v[34:37], v[192:195], v[226:229], v[34:37]
	v_mfma_f32_16x16x32_bf16 v[22:25], v[180:183], v[230:233], 0
	v_mfma_f32_16x16x32_bf16 v[22:25], v[184:187], v[234:237], v[22:25]
	v_mfma_f32_16x16x32_bf16 v[18:21], v[188:191], v[230:233], 0
	v_mfma_f32_16x16x32_bf16 v[18:21], v[192:195], v[234:237], v[18:21]
	v_mfma_f32_16x16x32_bf16 v[6:9], v[180:183], v[238:241], 0
	v_mfma_f32_16x16x32_bf16 v[6:9], v[184:187], v[242:245], v[6:9]
	s_setprio 2
	s_barrier
	v_mfma_f32_16x16x32_bf16 v[2:5], v[188:191], v[238:241], 0
	v_mfma_f32_16x16x32_bf16 v[2:5], v[192:195], v[242:245], v[2:5]
	s_setprio 0
	v_add_u32_e32 v164, vcc_lo, v99
	v_add_u32_e32 v192, vcc_hi, v99
	ds_read_b128 v[152:155], v164
	ds_read_b128 v[156:159], v164 offset:1024
	ds_read_b128 v[160:163], v164 offset:2048
	ds_read_b128 v[164:167], v164 offset:3072
	ds_read_b128 v[180:183], v192
	ds_read_b128 v[184:187], v192 offset:1024
	ds_read_b128 v[188:191], v192 offset:2048
	ds_read_b128 v[192:195], v192 offset:3072
	s_mov_b32 m0, s78
	v_lshl_add_u64 v[246:247], s[56:57], 0, v[138:139]
	ds_read_b128 v[196:199], v151 offset:32768
	ds_read_b128 v[200:203], v151 offset:33792
	ds_read_b128 v[222:225], v151 offset:34816
	ds_read_b128 v[226:229], v151 offset:35840
	ds_read_b128 v[230:233], v151 offset:36864
	ds_read_b128 v[234:237], v151 offset:37888
	ds_read_b128 v[238:241], v151 offset:38912
	ds_read_b128 v[242:245], v151 offset:39936
	global_load_lds_dwordx4 v[246:247], off
	v_lshl_add_u64 v[246:247], s[56:57], 0, v[134:135]
	s_mov_b32 m0, s82
	s_nop 0
	global_load_lds_dwordx4 v[246:247], off
	s_waitcnt vmcnt(8)
	s_waitcnt lgkmcnt(0)
	s_setprio 1
	s_barrier
	v_mfma_f32_16x16x32_bf16 v[128:131], v[152:155], v[196:199], v[128:131]
	v_mfma_f32_16x16x32_bf16 v[128:131], v[156:159], v[200:203], v[128:131]
	v_mfma_f32_16x16x32_bf16 v[124:127], v[160:163], v[196:199], v[124:127]
	v_mfma_f32_16x16x32_bf16 v[124:127], v[164:167], v[200:203], v[124:127]
	v_mfma_f32_16x16x32_bf16 v[112:115], v[152:155], v[222:225], v[112:115]
	v_mfma_f32_16x16x32_bf16 v[112:115], v[156:159], v[226:229], v[112:115]
	v_mfma_f32_16x16x32_bf16 v[108:111], v[160:163], v[222:225], v[108:111]
	v_mfma_f32_16x16x32_bf16 v[108:111], v[164:167], v[226:229], v[108:111]
	v_mfma_f32_16x16x32_bf16 v[94:97], v[152:155], v[230:233], v[94:97]
	v_mfma_f32_16x16x32_bf16 v[94:97], v[156:159], v[234:237], v[94:97]
	v_mfma_f32_16x16x32_bf16 v[90:93], v[160:163], v[230:233], v[90:93]
	v_mfma_f32_16x16x32_bf16 v[90:93], v[164:167], v[234:237], v[90:93]
	v_mfma_f32_16x16x32_bf16 v[78:81], v[152:155], v[238:241], v[78:81]
	v_mfma_f32_16x16x32_bf16 v[78:81], v[156:159], v[242:245], v[78:81]
	v_mfma_f32_16x16x32_bf16 v[74:77], v[160:163], v[238:241], v[74:77]
	v_mfma_f32_16x16x32_bf16 v[74:77], v[164:167], v[242:245], v[74:77]
	s_setprio 0
	s_setprio 1
	v_mfma_f32_16x16x32_bf16 v[120:123], v[180:183], v[196:199], v[120:123]
	v_mfma_f32_16x16x32_bf16 v[120:123], v[184:187], v[200:203], v[120:123]
	v_mfma_f32_16x16x32_bf16 v[116:119], v[188:191], v[196:199], v[116:119]
	v_mfma_f32_16x16x32_bf16 v[116:119], v[192:195], v[200:203], v[116:119]
	v_mfma_f32_16x16x32_bf16 v[104:107], v[180:183], v[222:225], v[104:107]
	v_mfma_f32_16x16x32_bf16 v[104:107], v[184:187], v[226:229], v[104:107]
	v_mfma_f32_16x16x32_bf16 v[100:103], v[188:191], v[222:225], v[100:103]
	v_mfma_f32_16x16x32_bf16 v[100:103], v[192:195], v[226:229], v[100:103]
	v_mfma_f32_16x16x32_bf16 v[86:89], v[180:183], v[230:233], v[86:89]
	v_mfma_f32_16x16x32_bf16 v[86:89], v[184:187], v[234:237], v[86:89]
	v_mfma_f32_16x16x32_bf16 v[82:85], v[188:191], v[230:233], v[82:85]
	v_mfma_f32_16x16x32_bf16 v[82:85], v[192:195], v[234:237], v[82:85]
	v_mfma_f32_16x16x32_bf16 v[70:73], v[180:183], v[238:241], v[70:73]
	v_mfma_f32_16x16x32_bf16 v[70:73], v[184:187], v[242:245], v[70:73]
	s_setprio 2
	s_barrier
; #define PG8_STAGE(bufoff, gbase, voff) do { _Pragma("unroll") for (int _i = 0; _i < 2; ++_i) \
;         __builtin_amdgcn_global_load_lds((const unsigned*)((const char*)(gbase) + (voff)[_i]), (PG8_LAS unsigned*)(lds + (bufoff) + ldsw + _i * 8192), 16, 0, AUX_A); } while (0)
; #define PG8_STAGEB(bufoff, gbase, voff) do { _Pragma("unroll") for (int _i = 0; _i < 2; ++_i) \
;         __builtin_amdgcn_global_load_lds((const unsigned*)((const char*)(gbase) + (voff)[_i]), (PG8_LAS unsigned*)(lds + (bufoff) + ldsw + _i * 8192), 16, 0, AUX_B); } while (0)
; #define PG8_WAIT_V(n) asm volatile("s_waitcnt vmcnt(" #n ")" ::: "memory")
; #define PG8_WAIT_L(n) asm volatile("s_waitcnt lgkmcnt(" #n ")" ::: "memory")
; template <class Epi, class Sched, bool ALIGN_EPI = false, bool SP2 = false>
; __device__ __forceinline__ void gemm_phase(PG8_LAS unsigned char* lds, const Gemm g, const Sched& S, const Epi& E) {
;     ...
;         for (int t = 0; t < nt; t += 2) {
;             const bool last = (t == nt - 2);
;             const char* a1 = PG8_KP(cA, t + 1, rot, nt);
;             const char* a2 = last ? nAr : PG8_KP(cA, t + 2, rot, nt); const char* b2 = last ? nBr : PG8_KP(cB, t + 2, rot, nt);
;             const char* a3 = a2 + kstep; const char* b3 = b2 + kstep;
;             if (last && has_next) S.a_ready(nxt);
;             if constexpr (SP2) {
;             PG8_LDB(B0, 0, 0); PG8_LDB(B1, 0, 1); PG8_SCHED; PG8_LDA(At, 0, 0); PG8_STAGE(PG8_SA(1, 1), a1 + hstep, voffA);
;             PG8_WAIT_V(8); PG8_WAIT_L(0); PG8_BAR; PG8_MMA(0, 0, At, B0); PG8_MMA(0, 1, At, B1); PG8_BAR; PG8_SCHED;
;             PG8_LDA(At, 0, 1); PG8_STAGEB(PG8_SB(0, 0), b2, voffB); PG8_STAGEB(PG8_SB(0, 1), b2 + hstep, voffB); PG8_STAGE(PG8_SA(0, 0), a2, voffA);
;             PG8_WAIT_V(8); PG8_WAIT_L(0); PG8_BAR; PG8_MMA(1, 0, At, B0); PG8_MMA(1, 1, At, B1); PG8_BAR; PG8_SCHED;
;             PG8_LDB(B0, 1, 0); PG8_LDB(B1, 1, 1); PG8_SCHED; PG8_LDA(At, 1, 0); PG8_STAGE(PG8_SA(0, 1), a2 + hstep, voffA);
;             PG8_WAIT_V(8); PG8_WAIT_L(0); PG8_BAR; PG8_MMA(0, 0, At, B0); PG8_MMA(0, 1, At, B1); PG8_BAR; PG8_SCHED;
;             PG8_LDA(At, 1, 1); PG8_STAGEB(PG8_SB(1, 0), b3, voffB); PG8_STAGEB(PG8_SB(1, 1), b3 + hstep, voffB); PG8_STAGE(PG8_SA(1, 0), a3, voffA);
;             PG8_WAIT_V(8); PG8_WAIT_L(0); PG8_BAR; PG8_MMA(1, 0, At, B0); PG8_MMA(1, 1, At, B1); PG8_BAR; PG8_SCHED;
	v_mfma_f32_16x16x32_bf16 v[66:69], v[188:191], v[238:241], v[66:69]
	v_mfma_f32_16x16x32_bf16 v[66:69], v[192:195], v[242:245], v[66:69]
	s_setprio 0
	s_mov_b32 m0, s1
	v_lshl_add_u64 v[148:149], v[148:149], 0, s[76:77]
	ds_read_b128 v[196:199], v151 offset:49152
	ds_read_b128 v[200:203], v151 offset:50176
	ds_read_b128 v[222:225], v151 offset:51200
	ds_read_b128 v[226:229], v151 offset:52224
	ds_read_b128 v[230:233], v151 offset:53248
	ds_read_b128 v[234:237], v151 offset:54272
	ds_read_b128 v[238:241], v151 offset:55296
	ds_read_b128 v[242:245], v151 offset:56320
	global_load_lds_dwordx4 v[148:149], off
	v_lshl_add_u64 v[148:149], v[168:169], 0, s[76:77]
	s_mov_b32 m0, s0
	s_nop 0
	global_load_lds_dwordx4 v[148:149], off
	v_lshl_add_u64 v[148:149], s[54:55], 0, v[136:137]
	s_mov_b32 m0, s47
	s_nop 0
	global_load_lds_dwordx4 v[148:149], off
	v_lshl_add_u64 v[148:149], s[54:55], 0, v[132:133]
	s_mov_b32 m0, s46
	s_nop 0
	global_load_lds_dwordx4 v[148:149], off
	v_lshl_add_u64 v[148:149], v[172:173], 0, s[76:77]
	s_mov_b32 m0, s83
	s_nop 0
	global_load_lds_dwordx4 v[148:149], off
	v_lshl_add_u64 v[148:149], v[212:213], 0, s[76:77]
	s_mov_b32 m0, s88
	s_nop 0
	global_load_lds_dwordx4 v[148:149], off
	s_waitcnt vmcnt(8)
	s_waitcnt lgkmcnt(0)
	s_setprio 1
	s_barrier
	v_mfma_f32_16x16x32_bf16 v[62:65], v[152:155], v[196:199], v[62:65]
	v_mfma_f32_16x16x32_bf16 v[62:65], v[156:159], v[200:203], v[62:65]
	v_mfma_f32_16x16x32_bf16 v[58:61], v[160:163], v[196:199], v[58:61]
	v_mfma_f32_16x16x32_bf16 v[58:61], v[164:167], v[200:203], v[58:61]
	v_mfma_f32_16x16x32_bf16 v[46:49], v[152:155], v[222:225], v[46:49]
	v_mfma_f32_16x16x32_bf16 v[46:49], v[156:159], v[226:229], v[46:49]
	v_mfma_f32_16x16x32_bf16 v[42:45], v[160:163], v[222:225], v[42:45]
	v_mfma_f32_16x16x32_bf16 v[42:45], v[164:167], v[226:229], v[42:45]
	v_mfma_f32_16x16x32_bf16 v[30:33], v[152:155], v[230:233], v[30:33]
	v_mfma_f32_16x16x32_bf16 v[30:33], v[156:159], v[234:237], v[30:33]
	v_mfma_f32_16x16x32_bf16 v[26:29], v[160:163], v[230:233], v[26:29]
	v_mfma_f32_16x16x32_bf16 v[26:29], v[164:167], v[234:237], v[26:29]
	v_mfma_f32_16x16x32_bf16 v[14:17], v[152:155], v[238:241], v[14:17]
	v_mfma_f32_16x16x32_bf16 v[14:17], v[156:159], v[242:245], v[14:17]
	v_mfma_f32_16x16x32_bf16 v[10:13], v[160:163], v[238:241], v[10:13]
	v_mfma_f32_16x16x32_bf16 v[10:13], v[164:167], v[242:245], v[10:13]
	s_setprio 0
	s_setprio 1
	v_mfma_f32_16x16x32_bf16 v[54:57], v[180:183], v[196:199], v[54:57]
	v_mfma_f32_16x16x32_bf16 v[54:57], v[184:187], v[200:203], v[54:57]
	v_mfma_f32_16x16x32_bf16 v[50:53], v[188:191], v[196:199], v[50:53]
	v_mfma_f32_16x16x32_bf16 v[50:53], v[192:195], v[200:203], v[50:53]
	v_mfma_f32_16x16x32_bf16 v[38:41], v[180:183], v[222:225], v[38:41]
	v_mfma_f32_16x16x32_bf16 v[38:41], v[184:187], v[226:229], v[38:41]
	v_mfma_f32_16x16x32_bf16 v[34:37], v[188:191], v[222:225], v[34:37]
	v_mfma_f32_16x16x32_bf16 v[34:37], v[192:195], v[226:229], v[34:37]
	v_mfma_f32_16x16x32_bf16 v[22:25], v[180:183], v[230:233], v[22:25]
	v_mfma_f32_16x16x32_bf16 v[22:25], v[184:187], v[234:237], v[22:25]
	v_mfma_f32_16x16x32_bf16 v[18:21], v[188:191], v[230:233], v[18:21]
	v_mfma_f32_16x16x32_bf16 v[18:21], v[192:195], v[234:237], v[18:21]
	v_mfma_f32_16x16x32_bf16 v[6:9], v[180:183], v[238:241], v[6:9]
	v_mfma_f32_16x16x32_bf16 v[6:9], v[184:187], v[242:245], v[6:9]
	s_setprio 2
	s_barrier
	v_mfma_f32_16x16x32_bf16 v[2:5], v[188:191], v[238:241], v[2:5]
	v_mfma_f32_16x16x32_bf16 v[2:5], v[192:195], v[242:245], v[2:5]
	s_setprio 0
	v_lshl_add_u64 v[144:145], v[144:145], 0, s[86:87]
	v_lshl_add_u64 v[146:147], v[146:147], 0, s[86:87]
	s_mov_b32 s29, s81
	s_cbranch_scc1 .Lpx_1067
.LBB0_1067:
	s_add_i32 s81, s29, 2
	s_cmp_lt_u32 s29, 14
	s_cselect_b32 s0, 0, -16
	s_add_i32 s0, s81, s0
	s_ashr_i32 s1, s0, 31
	s_lshl_b64 s[0:1], s[0:1], 7
	s_add_u32 s2, s52, s0
	s_addc_u32 s46, s53, s1
	s_add_u32 s0, s42, s0
	s_addc_u32 s1, s43, s1
	s_cmp_eq_u32 s29, 14
	s_cselect_b32 s59, s15, s46
	s_cselect_b32 s58, s17, s2
	s_cselect_b32 s61, s92, s1
	s_cselect_b32 s60, s93, s0
	s_add_i32 s2, 0, 0x10000
	s_add_i32 s94, s2, s70
	s_add_i32 s46, 0, 0x14000
	s_add_i32 m0, s71, 0xc000
	s_add_i32 s84, s71, 0xe000
	s_add_i32 s95, s94, 0x2000
	s_add_u32 s62, s60, 0x40000
	v_add_u32_e32 v148, s2, v99
	s_addc_u32 s63, s61, 0
	s_add_i32 s96, s46, s70
	ds_read_b128 v[152:155], v148
	ds_read_b128 v[156:159], v148 offset:1024
	ds_read_b128 v[160:163], v148 offset:2048
	ds_read_b128 v[164:167], v148 offset:3072
	v_add_u32_e32 v148, s46, v99
	s_add_i32 s97, s96, 0x2000
	s_add_i32 vcc_lo, 0, 0x18000
	s_add_i32 vcc_hi, 0, 0x1c000
	ds_read_b128 v[180:183], v148
	ds_read_b128 v[184:187], v148 offset:1024
	ds_read_b128 v[188:191], v148 offset:2048
	ds_read_b128 v[192:195], v148 offset:3072
	s_add_u32 s56, s58, 0x40000
	s_addc_u32 s57, s59, 0
	s_add_i32 s1, vcc_lo, s70
	s_add_i32 s0, s1, 0x2000
	s_add_u32 s54, s60, 0x40080
	s_addc_u32 s55, s61, 0
	s_add_i32 s47, vcc_hi, s70
	s_add_i32 s46, s47, 0x2000
	s_cmp_gt_u32 s29, 13
	ds_read_b128 v[196:199], v151
	ds_read_b128 v[200:203], v151 offset:1024
	ds_read_b128 v[222:225], v151 offset:2048
	ds_read_b128 v[226:229], v151 offset:3072
	ds_read_b128 v[230:233], v151 offset:4096
	ds_read_b128 v[234:237], v151 offset:5120
	ds_read_b128 v[238:241], v151 offset:6144
	ds_read_b128 v[242:245], v151 offset:7168
	global_load_lds_dwordx4 v[146:147], off
	s_mov_b32 m0, s84
	s_nop 0
	global_load_lds_dwordx4 v[144:145], off
	s_waitcnt vmcnt(8)
	s_waitcnt lgkmcnt(0)
	s_setprio 1
	s_barrier
; #define PG8_STAGE(bufoff, gbase, voff) do { _Pragma("unroll") for (int _i = 0; _i < 2; ++_i) \
;         __builtin_amdgcn_global_load_lds((const unsigned*)((const char*)(gbase) + (voff)[_i]), (PG8_LAS unsigned*)(lds + (bufoff) + ldsw + _i * 8192), 16, 0, AUX_A); } while (0)
; #define PG8_STAGEB(bufoff, gbase, voff) do { _Pragma("unroll") for (int _i = 0; _i < 2; ++_i) \
;         __builtin_amdgcn_global_load_lds((const unsigned*)((const char*)(gbase) + (voff)[_i]), (PG8_LAS unsigned*)(lds + (bufoff) + ldsw + _i * 8192), 16, 0, AUX_B); } while (0)
; #define PG8_LDA(dst, b, h) do { _Pragma("unroll") for (int m = 0; m < 4; ++m) _Pragma("unroll") for (int k = 0; k < 2; ++k) dst[m][k] = *(const PG8_LAS bf16x8*)(lds + PG8_SA(b, h) + aoff + m * 2048 + k * 1024); } while (0)
; #define PG8_LDB(dst, b, h) do { _Pragma("unroll") for (int n = 0; n < 2; ++n) _Pragma("unroll") for (int k = 0; k < 2; ++k) dst[n][k] = *(const PG8_LAS bf16x8*)(lds + PG8_SB(b, h) + boff + n * 2048 + k * 1024); } while (0)
; #define PG8_MMA(ai, bj, At, Bt) do { __builtin_amdgcn_s_setprio(1); _Pragma("unroll") for (int m = 0; m < 4; ++m) _Pragma("unroll") for (int n = 0; n < 2; ++n) _Pragma("unroll") for (int k = 0; k < 2; ++k) \
;         acc[ai][bj][m][n] = __builtin_amdgcn_mfma_f32_16x16x32_bf16(Bt[n][k], At[m][k], acc[ai][bj][m][n], 0, 0, 0); __builtin_amdgcn_s_setprio(0); } while (0)
; #define PG8_BAR __builtin_amdgcn_s_barrier()
; template <class Epi, class Sched, bool ALIGN_EPI = false, bool SP2 = false>
; __device__ __forceinline__ void gemm_phase(PG8_LAS unsigned char* lds, const Gemm g, const Sched& S, const Epi& E) {
;     ...
;             PG8_LDB(B0, 0, 0); PG8_LDB(B1, 0, 1); PG8_SCHED; PG8_LDA(At, 0, 0); PG8_STAGE(PG8_SA(1, 1), a1 + hstep, voffA);
;             PG8_WAIT_V(8); PG8_WAIT_L(0); PG8_BAR; PG8_MMA(0, 0, At, B0); PG8_MMA(0, 1, At, B1); PG8_BAR; PG8_SCHED;
;             PG8_LDA(At, 0, 1); PG8_STAGEB(PG8_SB(0, 0), b2, voffB); PG8_STAGEB(PG8_SB(0, 1), b2 + hstep, voffB); PG8_STAGE(PG8_SA(0, 0), a2, voffA);
;             PG8_WAIT_V(8); PG8_WAIT_L(0); PG8_BAR; PG8_MMA(1, 0, At, B0); PG8_MMA(1, 1, At, B1); PG8_BAR; PG8_SCHED;
;             PG8_LDB(B0, 1, 0); PG8_LDB(B1, 1, 1); PG8_SCHED; PG8_LDA(At, 1, 0); PG8_STAGE(PG8_SA(0, 1), a2 + hstep, voffA);
;             PG8_WAIT_V(8); PG8_WAIT_L(0); PG8_BAR; PG8_MMA(0, 0, At, B0); PG8_MMA(0, 1, At, B1); PG8_BAR; PG8_SCHED;
	v_mfma_f32_16x16x32_bf16 v[128:131], v[152:155], v[196:199], v[128:131]
	v_mfma_f32_16x16x32_bf16 v[128:131], v[156:159], v[200:203], v[128:131]
	v_mfma_f32_16x16x32_bf16 v[124:127], v[160:163], v[196:199], v[124:127]
	v_mfma_f32_16x16x32_bf16 v[124:127], v[164:167], v[200:203], v[124:127]
	v_mfma_f32_16x16x32_bf16 v[112:115], v[152:155], v[222:225], v[112:115]
	v_mfma_f32_16x16x32_bf16 v[112:115], v[156:159], v[226:229], v[112:115]
	v_mfma_f32_16x16x32_bf16 v[108:111], v[160:163], v[222:225], v[108:111]
	v_mfma_f32_16x16x32_bf16 v[108:111], v[164:167], v[226:229], v[108:111]
	v_mfma_f32_16x16x32_bf16 v[94:97], v[152:155], v[230:233], v[94:97]
	v_mfma_f32_16x16x32_bf16 v[94:97], v[156:159], v[234:237], v[94:97]
	v_mfma_f32_16x16x32_bf16 v[90:93], v[160:163], v[230:233], v[90:93]
	v_mfma_f32_16x16x32_bf16 v[90:93], v[164:167], v[234:237], v[90:93]
	v_mfma_f32_16x16x32_bf16 v[78:81], v[152:155], v[238:241], v[78:81]
	v_mfma_f32_16x16x32_bf16 v[78:81], v[156:159], v[242:245], v[78:81]
	v_mfma_f32_16x16x32_bf16 v[74:77], v[160:163], v[238:241], v[74:77]
	v_mfma_f32_16x16x32_bf16 v[74:77], v[164:167], v[242:245], v[74:77]
	s_setprio 0
	s_setprio 1
	v_mfma_f32_16x16x32_bf16 v[120:123], v[180:183], v[196:199], v[120:123]
	v_mfma_f32_16x16x32_bf16 v[120:123], v[184:187], v[200:203], v[120:123]
	v_mfma_f32_16x16x32_bf16 v[116:119], v[188:191], v[196:199], v[116:119]
	v_mfma_f32_16x16x32_bf16 v[116:119], v[192:195], v[200:203], v[116:119]
	v_mfma_f32_16x16x32_bf16 v[104:107], v[180:183], v[222:225], v[104:107]
	v_mfma_f32_16x16x32_bf16 v[104:107], v[184:187], v[226:229], v[104:107]
	v_mfma_f32_16x16x32_bf16 v[100:103], v[188:191], v[222:225], v[100:103]
	v_mfma_f32_16x16x32_bf16 v[100:103], v[192:195], v[226:229], v[100:103]
	v_mfma_f32_16x16x32_bf16 v[86:89], v[180:183], v[230:233], v[86:89]
	v_mfma_f32_16x16x32_bf16 v[86:89], v[184:187], v[234:237], v[86:89]
	v_mfma_f32_16x16x32_bf16 v[82:85], v[188:191], v[230:233], v[82:85]
	v_mfma_f32_16x16x32_bf16 v[82:85], v[192:195], v[234:237], v[82:85]
	v_mfma_f32_16x16x32_bf16 v[70:73], v[180:183], v[238:241], v[70:73]
	v_mfma_f32_16x16x32_bf16 v[70:73], v[184:187], v[242:245], v[70:73]
	s_setprio 2
	s_barrier
	v_mfma_f32_16x16x32_bf16 v[66:69], v[188:191], v[238:241], v[66:69]
	v_mfma_f32_16x16x32_bf16 v[66:69], v[192:195], v[242:245], v[66:69]
	s_setprio 0
	s_mov_b32 m0, s94
	v_lshl_add_u64 v[148:149], s[60:61], 0, v[136:137]
	ds_read_b128 v[196:199], v151 offset:16384
	ds_read_b128 v[200:203], v151 offset:17408
	ds_read_b128 v[222:225], v151 offset:18432
	ds_read_b128 v[226:229], v151 offset:19456
	ds_read_b128 v[230:233], v151 offset:20480
	ds_read_b128 v[234:237], v151 offset:21504
	ds_read_b128 v[238:241], v151 offset:22528
	ds_read_b128 v[242:245], v151 offset:23552
	global_load_lds_dwordx4 v[148:149], off
	v_lshl_add_u64 v[168:169], s[60:61], 0, v[132:133]
	s_mov_b32 m0, s95
	v_lshl_add_u64 v[172:173], s[62:63], 0, v[136:137]
	global_load_lds_dwordx4 v[168:169], off
	s_mov_b32 m0, s96
	v_lshl_add_u64 v[212:213], s[58:59], 0, v[134:135]
	global_load_lds_dwordx4 v[172:173], off
	v_lshl_add_u64 v[172:173], s[62:63], 0, v[132:133]
	s_mov_b32 m0, s97
	s_nop 0
	global_load_lds_dwordx4 v[172:173], off
	v_lshl_add_u64 v[172:173], s[58:59], 0, v[138:139]
	s_mov_b32 m0, s71
	s_nop 0
	global_load_lds_dwordx4 v[172:173], off
	s_mov_b32 m0, s75
	s_nop 0
	global_load_lds_dwordx4 v[212:213], off
	s_waitcnt vmcnt(8)
	s_waitcnt lgkmcnt(0)
	s_setprio 1
	s_barrier
	v_mfma_f32_16x16x32_bf16 v[62:65], v[152:155], v[196:199], v[62:65]
	v_mfma_f32_16x16x32_bf16 v[62:65], v[156:159], v[200:203], v[62:65]
	v_mfma_f32_16x16x32_bf16 v[58:61], v[160:163], v[196:199], v[58:61]
	v_mfma_f32_16x16x32_bf16 v[58:61], v[164:167], v[200:203], v[58:61]
	v_mfma_f32_16x16x32_bf16 v[46:49], v[152:155], v[222:225], v[46:49]
	v_mfma_f32_16x16x32_bf16 v[46:49], v[156:159], v[226:229], v[46:49]
	v_mfma_f32_16x16x32_bf16 v[42:45], v[160:163], v[222:225], v[42:45]
	v_mfma_f32_16x16x32_bf16 v[42:45], v[164:167], v[226:229], v[42:45]
	v_mfma_f32_16x16x32_bf16 v[30:33], v[152:155], v[230:233], v[30:33]
	v_mfma_f32_16x16x32_bf16 v[30:33], v[156:159], v[234:237], v[30:33]
	v_mfma_f32_16x16x32_bf16 v[26:29], v[160:163], v[230:233], v[26:29]
	v_mfma_f32_16x16x32_bf16 v[26:29], v[164:167], v[234:237], v[26:29]
	v_mfma_f32_16x16x32_bf16 v[14:17], v[152:155], v[238:241], v[14:17]
	v_mfma_f32_16x16x32_bf16 v[14:17], v[156:159], v[242:245], v[14:17]
	v_mfma_f32_16x16x32_bf16 v[10:13], v[160:163], v[238:241], v[10:13]
	v_mfma_f32_16x16x32_bf16 v[10:13], v[164:167], v[242:245], v[10:13]
	s_setprio 0
	s_setprio 1
	v_mfma_f32_16x16x32_bf16 v[54:57], v[180:183], v[196:199], v[54:57]
	v_mfma_f32_16x16x32_bf16 v[54:57], v[184:187], v[200:203], v[54:57]
	v_mfma_f32_16x16x32_bf16 v[50:53], v[188:191], v[196:199], v[50:53]
	v_mfma_f32_16x16x32_bf16 v[50:53], v[192:195], v[200:203], v[50:53]
	v_mfma_f32_16x16x32_bf16 v[38:41], v[180:183], v[222:225], v[38:41]
	v_mfma_f32_16x16x32_bf16 v[38:41], v[184:187], v[226:229], v[38:41]
	v_mfma_f32_16x16x32_bf16 v[34:37], v[188:191], v[222:225], v[34:37]
	v_mfma_f32_16x16x32_bf16 v[34:37], v[192:195], v[226:229], v[34:37]
	v_mfma_f32_16x16x32_bf16 v[22:25], v[180:183], v[230:233], v[22:25]
	v_mfma_f32_16x16x32_bf16 v[22:25], v[184:187], v[234:237], v[22:25]
	v_mfma_f32_16x16x32_bf16 v[18:21], v[188:191], v[230:233], v[18:21]
	v_mfma_f32_16x16x32_bf16 v[18:21], v[192:195], v[234:237], v[18:21]
	v_mfma_f32_16x16x32_bf16 v[6:9], v[180:183], v[238:241], v[6:9]
	v_mfma_f32_16x16x32_bf16 v[6:9], v[184:187], v[242:245], v[6:9]
	s_setprio 2
	s_barrier
; #define PG8_STAGE(bufoff, gbase, voff) do { _Pragma("unroll") for (int _i = 0; _i < 2; ++_i) \
;         __builtin_amdgcn_global_load_lds((const unsigned*)((const char*)(gbase) + (voff)[_i]), (PG8_LAS unsigned*)(lds + (bufoff) + ldsw + _i * 8192), 16, 0, AUX_A); } while (0)
; #define PG8_STAGEB(bufoff, gbase, voff) do { _Pragma("unroll") for (int _i = 0; _i < 2; ++_i) \
;         __builtin_amdgcn_global_load_lds((const unsigned*)((const char*)(gbase) + (voff)[_i]), (PG8_LAS unsigned*)(lds + (bufoff) + ldsw + _i * 8192), 16, 0, AUX_B); } while (0)
; #define PG8_LDA(dst, b, h) do { _Pragma("unroll") for (int m = 0; m < 4; ++m) _Pragma("unroll") for (int k = 0; k < 2; ++k) dst[m][k] = *(const PG8_LAS bf16x8*)(lds + PG8_SA(b, h) + aoff + m * 2048 + k * 1024); } while (0)
; #define PG8_LDB(dst, b, h) do { _Pragma("unroll") for (int n = 0; n < 2; ++n) _Pragma("unroll") for (int k = 0; k < 2; ++k) dst[n][k] = *(const PG8_LAS bf16x8*)(lds + PG8_SB(b, h) + boff + n * 2048 + k * 1024); } while (0)
; #define PG8_MMA(ai, bj, At, Bt) do { __builtin_amdgcn_s_setprio(1); _Pragma("unroll") for (int m = 0; m < 4; ++m) _Pragma("unroll") for (int n = 0; n < 2; ++n) _Pragma("unroll") for (int k = 0; k < 2; ++k) \
;         acc[ai][bj][m][n] = __builtin_amdgcn_mfma_f32_16x16x32_bf16(Bt[n][k], At[m][k], acc[ai][bj][m][n], 0, 0, 0); __builtin_amdgcn_s_setprio(0); } while (0)
; #define PG8_WAIT_V(n) asm volatile("s_waitcnt vmcnt(" #n ")" ::: "memory")
; #define PG8_WAIT_L(n) asm volatile("s_waitcnt lgkmcnt(" #n ")" ::: "memory")
; #define PG8_BAR __builtin_amdgcn_s_barrier()
; #define PG8_SCHED __builtin_amdgcn_sched_barrier(0)
; template <class Epi, class Sched, bool ALIGN_EPI = false, bool SP2 = false>
; __device__ __forceinline__ void gemm_phase(PG8_LAS unsigned char* lds, const Gemm g, const Sched& S, const Epi& E) {
;     ...
;             PG8_WAIT_V(8); PG8_WAIT_L(0); PG8_BAR; PG8_MMA(1, 0, At, B0); PG8_MMA(1, 1, At, B1); PG8_BAR; PG8_SCHED;
;             PG8_LDB(B0, 1, 0); PG8_LDB(B1, 1, 1); PG8_SCHED; PG8_LDA(At, 1, 0); PG8_STAGE(PG8_SA(0, 1), a2 + hstep, voffA);
;             PG8_WAIT_V(8); PG8_WAIT_L(0); PG8_BAR; PG8_MMA(0, 0, At, B0); PG8_MMA(0, 1, At, B1); PG8_BAR; PG8_SCHED;
;             PG8_LDA(At, 1, 1); PG8_STAGEB(PG8_SB(1, 0), b3, voffB); PG8_STAGEB(PG8_SB(1, 1), b3 + hstep, voffB); PG8_STAGE(PG8_SA(1, 0), a3, voffA);
	v_mfma_f32_16x16x32_bf16 v[2:5], v[188:191], v[238:241], v[2:5]
	v_mfma_f32_16x16x32_bf16 v[2:5], v[192:195], v[242:245], v[2:5]
	s_setprio 0
	v_add_u32_e32 v164, vcc_lo, v99
	v_add_u32_e32 v192, vcc_hi, v99
	ds_read_b128 v[152:155], v164
	ds_read_b128 v[156:159], v164 offset:1024
	ds_read_b128 v[160:163], v164 offset:2048
	ds_read_b128 v[164:167], v164 offset:3072
	ds_read_b128 v[180:183], v192
	ds_read_b128 v[184:187], v192 offset:1024
	ds_read_b128 v[188:191], v192 offset:2048
	ds_read_b128 v[192:195], v192 offset:3072
	s_mov_b32 m0, s78
	v_lshl_add_u64 v[246:247], s[56:57], 0, v[138:139]
	ds_read_b128 v[196:199], v151 offset:32768
	ds_read_b128 v[200:203], v151 offset:33792
	ds_read_b128 v[222:225], v151 offset:34816
	ds_read_b128 v[226:229], v151 offset:35840
	ds_read_b128 v[230:233], v151 offset:36864
	ds_read_b128 v[234:237], v151 offset:37888
	ds_read_b128 v[238:241], v151 offset:38912
	ds_read_b128 v[242:245], v151 offset:39936
	global_load_lds_dwordx4 v[246:247], off
	v_lshl_add_u64 v[246:247], s[56:57], 0, v[134:135]
	s_mov_b32 m0, s82
	s_nop 0
	global_load_lds_dwordx4 v[246:247], off
	s_waitcnt vmcnt(8)
	s_waitcnt lgkmcnt(0)
	s_setprio 1
	s_barrier
	v_mfma_f32_16x16x32_bf16 v[128:131], v[152:155], v[196:199], v[128:131]
	v_mfma_f32_16x16x32_bf16 v[128:131], v[156:159], v[200:203], v[128:131]
	v_mfma_f32_16x16x32_bf16 v[124:127], v[160:163], v[196:199], v[124:127]
	v_mfma_f32_16x16x32_bf16 v[124:127], v[164:167], v[200:203], v[124:127]
	v_mfma_f32_16x16x32_bf16 v[112:115], v[152:155], v[222:225], v[112:115]
	v_mfma_f32_16x16x32_bf16 v[112:115], v[156:159], v[226:229], v[112:115]
	v_mfma_f32_16x16x32_bf16 v[108:111], v[160:163], v[222:225], v[108:111]
	v_mfma_f32_16x16x32_bf16 v[108:111], v[164:167], v[226:229], v[108:111]
	v_mfma_f32_16x16x32_bf16 v[94:97], v[152:155], v[230:233], v[94:97]
	v_mfma_f32_16x16x32_bf16 v[94:97], v[156:159], v[234:237], v[94:97]
	v_mfma_f32_16x16x32_bf16 v[90:93], v[160:163], v[230:233], v[90:93]
	v_mfma_f32_16x16x32_bf16 v[90:93], v[164:167], v[234:237], v[90:93]
	v_mfma_f32_16x16x32_bf16 v[78:81], v[152:155], v[238:241], v[78:81]
	v_mfma_f32_16x16x32_bf16 v[78:81], v[156:159], v[242:245], v[78:81]
	v_mfma_f32_16x16x32_bf16 v[74:77], v[160:163], v[238:241], v[74:77]
	v_mfma_f32_16x16x32_bf16 v[74:77], v[164:167], v[242:245], v[74:77]
	s_setprio 0
	s_setprio 1
	v_mfma_f32_16x16x32_bf16 v[120:123], v[180:183], v[196:199], v[120:123]
	v_mfma_f32_16x16x32_bf16 v[120:123], v[184:187], v[200:203], v[120:123]
	v_mfma_f32_16x16x32_bf16 v[116:119], v[188:191], v[196:199], v[116:119]
	v_mfma_f32_16x16x32_bf16 v[116:119], v[192:195], v[200:203], v[116:119]
	v_mfma_f32_16x16x32_bf16 v[104:107], v[180:183], v[222:225], v[104:107]
	v_mfma_f32_16x16x32_bf16 v[104:107], v[184:187], v[226:229], v[104:107]
	v_mfma_f32_16x16x32_bf16 v[100:103], v[188:191], v[222:225], v[100:103]
	v_mfma_f32_16x16x32_bf16 v[100:103], v[192:195], v[226:229], v[100:103]
	v_mfma_f32_16x16x32_bf16 v[86:89], v[180:183], v[230:233], v[86:89]
	v_mfma_f32_16x16x32_bf16 v[86:89], v[184:187], v[234:237], v[86:89]
	v_mfma_f32_16x16x32_bf16 v[82:85], v[188:191], v[230:233], v[82:85]
	v_mfma_f32_16x16x32_bf16 v[82:85], v[192:195], v[234:237], v[82:85]
	v_mfma_f32_16x16x32_bf16 v[70:73], v[180:183], v[238:241], v[70:73]
	v_mfma_f32_16x16x32_bf16 v[70:73], v[184:187], v[242:245], v[70:73]
	s_setprio 2
	s_barrier
; #define PG8_STAGE(bufoff, gbase, voff) do { _Pragma("unroll") for (int _i = 0; _i < 2; ++_i) \
;         __builtin_amdgcn_global_load_lds((const unsigned*)((const char*)(gbase) + (voff)[_i]), (PG8_LAS unsigned*)(lds + (bufoff) + ldsw + _i * 8192), 16, 0, AUX_A); } while (0)
; #define PG8_STAGEB(bufoff, gbase, voff) do { _Pragma("unroll") for (int _i = 0; _i < 2; ++_i) \
;         __builtin_amdgcn_global_load_lds((const unsigned*)((const char*)(gbase) + (voff)[_i]), (PG8_LAS unsigned*)(lds + (bufoff) + ldsw + _i * 8192), 16, 0, AUX_B); } while (0)
; #define PG8_LDA(dst, b, h) do { _Pragma("unroll") for (int m = 0; m < 4; ++m) _Pragma("unroll") for (int k = 0; k < 2; ++k) dst[m][k] = *(const PG8_LAS bf16x8*)(lds + PG8_SA(b, h) + aoff + m * 2048 + k * 1024); } while (0)
; #define PG8_LDB(dst, b, h) do { _Pragma("unroll") for (int n = 0; n < 2; ++n) _Pragma("unroll") for (int k = 0; k < 2; ++k) dst[n][k] = *(const PG8_LAS bf16x8*)(lds + PG8_SB(b, h) + boff + n * 2048 + k * 1024); } while (0)
; #define PG8_MMA(ai, bj, At, Bt) do { __builtin_amdgcn_s_setprio(1); _Pragma("unroll") for (int m = 0; m < 4; ++m) _Pragma("unroll") for (int n = 0; n < 2; ++n) _Pragma("unroll") for (int k = 0; k < 2; ++k) \
;         acc[ai][bj][m][n] = __builtin_amdgcn_mfma_f32_16x16x32_bf16(Bt[n][k], At[m][k], acc[ai][bj][m][n], 0, 0, 0); __builtin_amdgcn_s_setprio(0); } while (0)
; #define PG8_WAIT_V(n) asm volatile("s_waitcnt vmcnt(" #n ")" ::: "memory")
; #define PG8_WAIT_L(n) asm volatile("s_waitcnt lgkmcnt(" #n ")" ::: "memory")
; #define PG8_BAR __builtin_amdgcn_s_barrier()
; #define PG8_SCHED __builtin_amdgcn_sched_barrier(0)
; template <class Epi, class Sched, bool ALIGN_EPI = false, bool SP2 = false>
; __device__ __forceinline__ void gemm_phase(PG8_LAS unsigned char* lds, const Gemm g, const Sched& S, const Epi& E) {
;     ...
;             PG8_LDB(B0, 1, 0); PG8_LDB(B1, 1, 1); PG8_SCHED; PG8_LDA(At, 1, 0); PG8_STAGE(PG8_SA(0, 1), a2 + hstep, voffA);
;             PG8_WAIT_V(8); PG8_WAIT_L(0); PG8_BAR; PG8_MMA(0, 0, At, B0); PG8_MMA(0, 1, At, B1); PG8_BAR; PG8_SCHED;
;             PG8_LDA(At, 1, 1); PG8_STAGEB(PG8_SB(1, 0), b3, voffB); PG8_STAGEB(PG8_SB(1, 1), b3 + hstep, voffB); PG8_STAGE(PG8_SA(1, 0), a3, voffA);
;             PG8_WAIT_V(8); PG8_WAIT_L(0); PG8_BAR; PG8_MMA(1, 0, At, B0); PG8_MMA(1, 1, At, B1); PG8_BAR; PG8_SCHED;
	v_mfma_f32_16x16x32_bf16 v[66:69], v[188:191], v[238:241], v[66:69]
	v_mfma_f32_16x16x32_bf16 v[66:69], v[192:195], v[242:245], v[66:69]
	s_setprio 0
	s_mov_b32 m0, s1
	v_lshl_add_u64 v[148:149], v[148:149], 0, s[76:77]
	ds_read_b128 v[196:199], v151 offset:49152
	ds_read_b128 v[200:203], v151 offset:50176
	ds_read_b128 v[222:225], v151 offset:51200
	ds_read_b128 v[226:229], v151 offset:52224
	ds_read_b128 v[230:233], v151 offset:53248
	ds_read_b128 v[234:237], v151 offset:54272
	ds_read_b128 v[238:241], v151 offset:55296
	ds_read_b128 v[242:245], v151 offset:56320
	global_load_lds_dwordx4 v[148:149], off
	v_lshl_add_u64 v[148:149], v[168:169], 0, s[76:77]
	s_mov_b32 m0, s0
	s_nop 0
	global_load_lds_dwordx4 v[148:149], off
	v_lshl_add_u64 v[148:149], s[54:55], 0, v[136:137]
	s_mov_b32 m0, s47
	s_nop 0
	global_load_lds_dwordx4 v[148:149], off
	v_lshl_add_u64 v[148:149], s[54:55], 0, v[132:133]
	s_mov_b32 m0, s46
	s_nop 0
	global_load_lds_dwordx4 v[148:149], off
	v_lshl_add_u64 v[148:149], v[172:173], 0, s[76:77]
	s_mov_b32 m0, s83
	s_nop 0
	global_load_lds_dwordx4 v[148:149], off
	v_lshl_add_u64 v[148:149], v[212:213], 0, s[76:77]
	s_mov_b32 m0, s88
	s_nop 0
	global_load_lds_dwordx4 v[148:149], off
	s_waitcnt vmcnt(8)
	s_waitcnt lgkmcnt(0)
	s_setprio 1
	s_barrier
	v_mfma_f32_16x16x32_bf16 v[62:65], v[152:155], v[196:199], v[62:65]
	v_mfma_f32_16x16x32_bf16 v[62:65], v[156:159], v[200:203], v[62:65]
	v_mfma_f32_16x16x32_bf16 v[58:61], v[160:163], v[196:199], v[58:61]
	v_mfma_f32_16x16x32_bf16 v[58:61], v[164:167], v[200:203], v[58:61]
	v_mfma_f32_16x16x32_bf16 v[46:49], v[152:155], v[222:225], v[46:49]
	v_mfma_f32_16x16x32_bf16 v[46:49], v[156:159], v[226:229], v[46:49]
	v_mfma_f32_16x16x32_bf16 v[42:45], v[160:163], v[222:225], v[42:45]
	v_mfma_f32_16x16x32_bf16 v[42:45], v[164:167], v[226:229], v[42:45]
	v_mfma_f32_16x16x32_bf16 v[30:33], v[152:155], v[230:233], v[30:33]
	v_mfma_f32_16x16x32_bf16 v[30:33], v[156:159], v[234:237], v[30:33]
	v_mfma_f32_16x16x32_bf16 v[26:29], v[160:163], v[230:233], v[26:29]
	v_mfma_f32_16x16x32_bf16 v[26:29], v[164:167], v[234:237], v[26:29]
	v_mfma_f32_16x16x32_bf16 v[14:17], v[152:155], v[238:241], v[14:17]
	v_mfma_f32_16x16x32_bf16 v[14:17], v[156:159], v[242:245], v[14:17]
	v_mfma_f32_16x16x32_bf16 v[10:13], v[160:163], v[238:241], v[10:13]
	v_mfma_f32_16x16x32_bf16 v[10:13], v[164:167], v[242:245], v[10:13]
	s_setprio 0
	s_setprio 1
	v_mfma_f32_16x16x32_bf16 v[54:57], v[180:183], v[196:199], v[54:57]
	v_mfma_f32_16x16x32_bf16 v[54:57], v[184:187], v[200:203], v[54:57]
	v_mfma_f32_16x16x32_bf16 v[50:53], v[188:191], v[196:199], v[50:53]
	v_mfma_f32_16x16x32_bf16 v[50:53], v[192:195], v[200:203], v[50:53]
	v_mfma_f32_16x16x32_bf16 v[38:41], v[180:183], v[222:225], v[38:41]
	v_mfma_f32_16x16x32_bf16 v[38:41], v[184:187], v[226:229], v[38:41]
	v_mfma_f32_16x16x32_bf16 v[34:37], v[188:191], v[222:225], v[34:37]
	v_mfma_f32_16x16x32_bf16 v[34:37], v[192:195], v[226:229], v[34:37]
	v_mfma_f32_16x16x32_bf16 v[22:25], v[180:183], v[230:233], v[22:25]
	v_mfma_f32_16x16x32_bf16 v[22:25], v[184:187], v[234:237], v[22:25]
	v_mfma_f32_16x16x32_bf16 v[18:21], v[188:191], v[230:233], v[18:21]
	v_mfma_f32_16x16x32_bf16 v[18:21], v[192:195], v[234:237], v[18:21]
	v_mfma_f32_16x16x32_bf16 v[6:9], v[180:183], v[238:241], v[6:9]
	v_mfma_f32_16x16x32_bf16 v[6:9], v[184:187], v[242:245], v[6:9]
	s_setprio 2
	s_barrier
	v_mfma_f32_16x16x32_bf16 v[2:5], v[188:191], v[238:241], v[2:5]
	v_mfma_f32_16x16x32_bf16 v[2:5], v[192:195], v[242:245], v[2:5]
	s_setprio 0
	v_lshl_add_u64 v[144:145], v[144:145], 0, s[86:87]
	v_lshl_add_u64 v[146:147], v[146:147], 0, s[86:87]
	s_mov_b32 s29, s81
	s_cbranch_scc0 .LBB0_1067

; #define PG8_STAGE(bufoff, gbase, voff) do { _Pragma("unroll") for (int _i = 0; _i < 2; ++_i) \
;         __builtin_amdgcn_global_load_lds((const unsigned*)((const char*)(gbase) + (voff)[_i]), (PG8_LAS unsigned*)(lds + (bufoff) + ldsw + _i * 8192), 16, 0, AUX_A); } while (0)
; #define PG8_STAGEB(bufoff, gbase, voff) do { _Pragma("unroll") for (int _i = 0; _i < 2; ++_i) \
;         __builtin_amdgcn_global_load_lds((const unsigned*)((const char*)(gbase) + (voff)[_i]), (PG8_LAS unsigned*)(lds + (bufoff) + ldsw + _i * 8192), 16, 0, AUX_B); } while (0)
; #define PG8_LDA(dst, b, h) do { _Pragma("unroll") for (int m = 0; m < 4; ++m) _Pragma("unroll") for (int k = 0; k < 2; ++k) dst[m][k] = *(const PG8_LAS bf16x8*)(lds + PG8_SA(b, h) + aoff + m * 2048 + k * 1024); } while (0)
; template <class Epi, class Sched, bool ALIGN_EPI = false, bool SP2 = false>
; __device__ __forceinline__ void gemm_phase(PG8_LAS unsigned char* lds, const Gemm g, const Sched& S, const Epi& E) {
;     ...
;         const char* nA = has_next ? (const char*)g.A + (size_t)nxt.pm * tstep + (size_t)nxt.kt0 * kstep : cA; const char* nB = has_next ? (const char*)g.Bt + (size_t)nxt.pn * tstep + (size_t)nxt.kt0 * kstep : cB;
;         const int nt = cur.nkt, rot = cur.krot;
;         const char* nAr = has_next ? nA + (size_t)nxt.krot * kstep : PG8_KP(cA, 0, rot, nt); const char* nBr = has_next ? nB + (size_t)nxt.krot * kstep : PG8_KP(cB, 0, rot, nt);
;         for (int t = 0; t < nt; t += 2) {
;             const bool last = (t == nt - 2);
;             const char* a1 = PG8_KP(cA, t + 1, rot, nt);
;             const char* a2 = last ? nAr : PG8_KP(cA, t + 2, rot, nt); const char* b2 = last ? nBr : PG8_KP(cB, t + 2, rot, nt);
;             const char* a3 = a2 + kstep; const char* b3 = b2 + kstep;
;             if (last && has_next) S.a_ready(nxt);
;             if constexpr (SP2) {
;             PG8_LDB(B0, 0, 0); PG8_LDB(B1, 0, 1); PG8_SCHED; PG8_LDA(At, 0, 0); PG8_STAGE(PG8_SA(1, 1), a1 + hstep, voffA);
;             PG8_WAIT_V(8); PG8_WAIT_L(0); PG8_BAR; PG8_MMA(0, 0, At, B0); PG8_MMA(0, 1, At, B1); PG8_BAR; PG8_SCHED;
;             PG8_LDA(At, 0, 1); PG8_STAGEB(PG8_SB(0, 0), b2, voffB); PG8_STAGEB(PG8_SB(0, 1), b2 + hstep, voffB); PG8_STAGE(PG8_SA(0, 0), a2, voffA);
;             PG8_WAIT_V(8); PG8_WAIT_L(0); PG8_BAR; PG8_MMA(1, 0, At, B0); PG8_MMA(1, 1, At, B1); PG8_BAR; PG8_SCHED;
.LBB0_1156:
	s_mov_b32 s18, s19
	s_ashr_i32 s19, s19, 31
	s_mov_b32 s38, s1
	s_lshl_b64 s[0:1], s[18:19], 19
	s_add_u32 s40, s33, s0
	s_addc_u32 s41, s69, s1
	s_ashr_i32 s39, s38, 31
	s_lshl_b64 s[0:1], s[38:39], 19
	s_add_u32 s48, s6, s0
	s_addc_u32 s49, s7, s1
	s_and_b64 s[0:1], s[42:43], exec
	s_cselect_b32 s19, s41, s53
	s_cselect_b32 s39, s40, s52
	s_cselect_b32 s92, s49, s51
	s_cselect_b32 s93, s48, s50
	s_add_u32 s0, s52, 0x40080
	s_addc_u32 s1, s53, 0
	v_lshl_add_u64 v[144:145], s[0:1], 0, v[140:141]
	v_lshl_add_u64 v[146:147], s[0:1], 0, v[142:143]
	s_mov_b32 s29, 0
.Lpk_1157:
	s_add_i32 s81, s29, 2
	s_cmp_lt_u32 s29, 14
	s_cselect_b32 s0, 0, -16
	s_add_i32 s0, s81, s0
	s_ashr_i32 s1, s0, 31
	s_lshl_b64 s[0:1], s[0:1], 7
	s_add_u32 s2, s52, s0
	s_addc_u32 s46, s53, s1
	s_add_u32 s0, s50, s0
	s_addc_u32 s1, s51, s1
	s_cmp_eq_u32 s29, 14
	s_cselect_b32 s59, s19, s46
	s_cselect_b32 s58, s39, s2
	s_cselect_b32 s61, s92, s1
	s_cselect_b32 s60, s93, s0
	s_add_i32 s2, 0, 0x10000
	s_add_i32 s94, s2, s70
	s_add_i32 s46, 0, 0x14000
	s_add_i32 m0, s71, 0xc000
	s_add_i32 s84, s71, 0xe000
	s_add_i32 s95, s94, 0x2000
	s_add_u32 s62, s60, 0x40000
	s_addc_u32 s63, s61, 0
	s_add_i32 s96, s46, s70
	v_add_u32_e32 v162, s2, v99
	v_add_u32_e32 v166, s46, v99
	s_add_i32 s97, s96, 0x2000
	s_add_i32 vcc_lo, 0, 0x18000
	s_add_i32 vcc_hi, 0, 0x1c000
	ds_read_b128 v[148:151], v162
	ds_read_b128 v[154:157], v162 offset:1024
	ds_read_b128 v[158:161], v162 offset:2048
	ds_read_b128 v[162:165], v162 offset:3072
	ds_read_b128 v[180:183], v166
	ds_read_b128 v[184:187], v166 offset:1024
	ds_read_b128 v[188:191], v166 offset:2048
	ds_read_b128 v[192:195], v166 offset:3072
	s_add_u32 s56, s58, 0x40000
	s_addc_u32 s57, s59, 0
	s_add_i32 s1, vcc_lo, s70
	s_add_i32 s0, s1, 0x2000
	s_add_u32 s54, s60, 0x40080
	s_addc_u32 s55, s61, 0
	s_add_i32 s47, vcc_hi, s70
	s_add_i32 s46, s47, 0x2000
	s_cmp_gt_u32 s29, 13
	ds_read_b128 v[196:199], v153
	ds_read_b128 v[200:203], v153 offset:1024
	ds_read_b128 v[222:225], v153 offset:2048
	ds_read_b128 v[226:229], v153 offset:3072
	ds_read_b128 v[230:233], v153 offset:4096
	ds_read_b128 v[234:237], v153 offset:5120
	ds_read_b128 v[238:241], v153 offset:6144
	ds_read_b128 v[242:245], v153 offset:7168
	global_load_lds_dwordx4 v[146:147], off
	s_mov_b32 m0, s84
	s_nop 0
	global_load_lds_dwordx4 v[144:145], off
	s_waitcnt vmcnt(8)
	s_waitcnt lgkmcnt(0)
	s_setprio 1
	s_barrier
	v_mfma_f32_16x16x32_bf16 v[128:131], v[148:151], v[196:199], 0
	v_mfma_f32_16x16x32_bf16 v[128:131], v[154:157], v[200:203], v[128:131]
	v_mfma_f32_16x16x32_bf16 v[124:127], v[158:161], v[196:199], 0
	v_mfma_f32_16x16x32_bf16 v[124:127], v[162:165], v[200:203], v[124:127]
	v_mfma_f32_16x16x32_bf16 v[112:115], v[148:151], v[222:225], 0
	v_mfma_f32_16x16x32_bf16 v[112:115], v[154:157], v[226:229], v[112:115]
	v_mfma_f32_16x16x32_bf16 v[108:111], v[158:161], v[222:225], 0
	v_mfma_f32_16x16x32_bf16 v[108:111], v[162:165], v[226:229], v[108:111]
	v_mfma_f32_16x16x32_bf16 v[94:97], v[148:151], v[230:233], 0
	v_mfma_f32_16x16x32_bf16 v[94:97], v[154:157], v[234:237], v[94:97]
	v_mfma_f32_16x16x32_bf16 v[90:93], v[158:161], v[230:233], 0
	v_mfma_f32_16x16x32_bf16 v[90:93], v[162:165], v[234:237], v[90:93]
	v_mfma_f32_16x16x32_bf16 v[78:81], v[148:151], v[238:241], 0
	v_mfma_f32_16x16x32_bf16 v[78:81], v[154:157], v[242:245], v[78:81]
	v_mfma_f32_16x16x32_bf16 v[74:77], v[158:161], v[238:241], 0
	v_mfma_f32_16x16x32_bf16 v[74:77], v[162:165], v[242:245], v[74:77]
	s_setprio 0
	s_setprio 1
	v_mfma_f32_16x16x32_bf16 v[120:123], v[180:183], v[196:199], 0
	v_mfma_f32_16x16x32_bf16 v[120:123], v[184:187], v[200:203], v[120:123]
	v_mfma_f32_16x16x32_bf16 v[116:119], v[188:191], v[196:199], 0
	v_mfma_f32_16x16x32_bf16 v[116:119], v[192:195], v[200:203], v[116:119]
	v_mfma_f32_16x16x32_bf16 v[104:107], v[180:183], v[222:225], 0
	v_mfma_f32_16x16x32_bf16 v[104:107], v[184:187], v[226:229], v[104:107]
	v_mfma_f32_16x16x32_bf16 v[100:103], v[188:191], v[222:225], 0
	v_mfma_f32_16x16x32_bf16 v[100:103], v[192:195], v[226:229], v[100:103]
	v_mfma_f32_16x16x32_bf16 v[86:89], v[180:183], v[230:233], 0
	v_mfma_f32_16x16x32_bf16 v[86:89], v[184:187], v[234:237], v[86:89]
	v_mfma_f32_16x16x32_bf16 v[82:85], v[188:191], v[230:233], 0
	v_mfma_f32_16x16x32_bf16 v[82:85], v[192:195], v[234:237], v[82:85]
	v_mfma_f32_16x16x32_bf16 v[70:73], v[180:183], v[238:241], 0
	v_mfma_f32_16x16x32_bf16 v[70:73], v[184:187], v[242:245], v[70:73]
	s_setprio 2
	s_barrier
	v_mfma_f32_16x16x32_bf16 v[66:69], v[188:191], v[238:241], 0
	v_mfma_f32_16x16x32_bf16 v[66:69], v[192:195], v[242:245], v[66:69]
	s_setprio 0
	s_mov_b32 m0, s94
	v_lshl_add_u64 v[166:167], s[60:61], 0, v[136:137]
	ds_read_b128 v[196:199], v153 offset:16384
	ds_read_b128 v[200:203], v153 offset:17408
	ds_read_b128 v[222:225], v153 offset:18432
	ds_read_b128 v[226:229], v153 offset:19456
	ds_read_b128 v[230:233], v153 offset:20480
	ds_read_b128 v[234:237], v153 offset:21504
	ds_read_b128 v[238:241], v153 offset:22528
	ds_read_b128 v[242:245], v153 offset:23552
	global_load_lds_dwordx4 v[166:167], off
	v_lshl_add_u64 v[168:169], s[60:61], 0, v[132:133]
	s_mov_b32 m0, s95
	v_lshl_add_u64 v[172:173], s[62:63], 0, v[136:137]
	global_load_lds_dwordx4 v[168:169], off
	s_mov_b32 m0, s96
	v_lshl_add_u64 v[212:213], s[58:59], 0, v[134:135]
	global_load_lds_dwordx4 v[172:173], off
	v_lshl_add_u64 v[172:173], s[62:63], 0, v[132:133]
	s_mov_b32 m0, s97
	s_nop 0
	global_load_lds_dwordx4 v[172:173], off
	v_lshl_add_u64 v[172:173], s[58:59], 0, v[138:139]
	s_mov_b32 m0, s71
	s_nop 0
	global_load_lds_dwordx4 v[172:173], off
	s_mov_b32 m0, s75
	s_nop 0
	global_load_lds_dwordx4 v[212:213], off
	s_waitcnt vmcnt(8)
	s_waitcnt lgkmcnt(0)
	s_setprio 1
	s_barrier
; #define PG8_STAGE(bufoff, gbase, voff) do { _Pragma("unroll") for (int _i = 0; _i < 2; ++_i) \
;         __builtin_amdgcn_global_load_lds((const unsigned*)((const char*)(gbase) + (voff)[_i]), (PG8_LAS unsigned*)(lds + (bufoff) + ldsw + _i * 8192), 16, 0, AUX_A); } while (0)
; #define PG8_STAGEB(bufoff, gbase, voff) do { _Pragma("unroll") for (int _i = 0; _i < 2; ++_i) \
;         __builtin_amdgcn_global_load_lds((const unsigned*)((const char*)(gbase) + (voff)[_i]), (PG8_LAS unsigned*)(lds + (bufoff) + ldsw + _i * 8192), 16, 0, AUX_B); } while (0)
; #define PG8_LDA(dst, b, h) do { _Pragma("unroll") for (int m = 0; m < 4; ++m) _Pragma("unroll") for (int k = 0; k < 2; ++k) dst[m][k] = *(const PG8_LAS bf16x8*)(lds + PG8_SA(b, h) + aoff + m * 2048 + k * 1024); } while (0)
; #define PG8_LDB(dst, b, h) do { _Pragma("unroll") for (int n = 0; n < 2; ++n) _Pragma("unroll") for (int k = 0; k < 2; ++k) dst[n][k] = *(const PG8_LAS bf16x8*)(lds + PG8_SB(b, h) + boff + n * 2048 + k * 1024); } while (0)
; #define PG8_MMA(ai, bj, At, Bt) do { __builtin_amdgcn_s_setprio(1); _Pragma("unroll") for (int m = 0; m < 4; ++m) _Pragma("unroll") for (int n = 0; n < 2; ++n) _Pragma("unroll") for (int k = 0; k < 2; ++k) \
;         acc[ai][bj][m][n] = __builtin_amdgcn_mfma_f32_16x16x32_bf16(Bt[n][k], At[m][k], acc[ai][bj][m][n], 0, 0, 0); __builtin_amdgcn_s_setprio(0); } while (0)
; #define PG8_WAIT_V(n) asm volatile("s_waitcnt vmcnt(" #n ")" ::: "memory")
; #define PG8_WAIT_L(n) asm volatile("s_waitcnt lgkmcnt(" #n ")" ::: "memory")
; #define PG8_BAR __builtin_amdgcn_s_barrier()
; #define PG8_SCHED __builtin_amdgcn_sched_barrier(0)
; template <class Epi, class Sched, bool ALIGN_EPI = false, bool SP2 = false>
; __device__ __forceinline__ void gemm_phase(PG8_LAS unsigned char* lds, const Gemm g, const Sched& S, const Epi& E) {
;     ...
;             PG8_LDA(At, 0, 1); PG8_STAGEB(PG8_SB(0, 0), b2, voffB); PG8_STAGEB(PG8_SB(0, 1), b2 + hstep, voffB); PG8_STAGE(PG8_SA(0, 0), a2, voffA);
;             PG8_WAIT_V(8); PG8_WAIT_L(0); PG8_BAR; PG8_MMA(1, 0, At, B0); PG8_MMA(1, 1, At, B1); PG8_BAR; PG8_SCHED;
;             PG8_LDB(B0, 1, 0); PG8_LDB(B1, 1, 1); PG8_SCHED; PG8_LDA(At, 1, 0); PG8_STAGE(PG8_SA(0, 1), a2 + hstep, voffA);
;             PG8_WAIT_V(8); PG8_WAIT_L(0); PG8_BAR; PG8_MMA(0, 0, At, B0); PG8_MMA(0, 1, At, B1); PG8_BAR; PG8_SCHED;
	v_mfma_f32_16x16x32_bf16 v[62:65], v[148:151], v[196:199], 0
	v_mfma_f32_16x16x32_bf16 v[62:65], v[154:157], v[200:203], v[62:65]
	v_mfma_f32_16x16x32_bf16 v[58:61], v[158:161], v[196:199], 0
	v_mfma_f32_16x16x32_bf16 v[58:61], v[162:165], v[200:203], v[58:61]
	v_mfma_f32_16x16x32_bf16 v[46:49], v[148:151], v[222:225], 0
	v_mfma_f32_16x16x32_bf16 v[46:49], v[154:157], v[226:229], v[46:49]
	v_mfma_f32_16x16x32_bf16 v[42:45], v[158:161], v[222:225], 0
	v_mfma_f32_16x16x32_bf16 v[42:45], v[162:165], v[226:229], v[42:45]
	v_mfma_f32_16x16x32_bf16 v[30:33], v[148:151], v[230:233], 0
	v_mfma_f32_16x16x32_bf16 v[30:33], v[154:157], v[234:237], v[30:33]
	v_mfma_f32_16x16x32_bf16 v[26:29], v[158:161], v[230:233], 0
	v_mfma_f32_16x16x32_bf16 v[26:29], v[162:165], v[234:237], v[26:29]
	v_mfma_f32_16x16x32_bf16 v[14:17], v[148:151], v[238:241], 0
	v_mfma_f32_16x16x32_bf16 v[14:17], v[154:157], v[242:245], v[14:17]
	v_mfma_f32_16x16x32_bf16 v[10:13], v[158:161], v[238:241], 0
	v_mfma_f32_16x16x32_bf16 v[10:13], v[162:165], v[242:245], v[10:13]
	s_setprio 0
	s_setprio 1
	v_mfma_f32_16x16x32_bf16 v[54:57], v[180:183], v[196:199], 0
	v_mfma_f32_16x16x32_bf16 v[54:57], v[184:187], v[200:203], v[54:57]
	v_mfma_f32_16x16x32_bf16 v[50:53], v[188:191], v[196:199], 0
	v_mfma_f32_16x16x32_bf16 v[50:53], v[192:195], v[200:203], v[50:53]
	v_mfma_f32_16x16x32_bf16 v[38:41], v[180:183], v[222:225], 0
	v_mfma_f32_16x16x32_bf16 v[38:41], v[184:187], v[226:229], v[38:41]
	v_mfma_f32_16x16x32_bf16 v[34:37], v[188:191], v[222:225], 0
	v_mfma_f32_16x16x32_bf16 v[34:37], v[192:195], v[226:229], v[34:37]
	v_mfma_f32_16x16x32_bf16 v[22:25], v[180:183], v[230:233], 0
	v_mfma_f32_16x16x32_bf16 v[22:25], v[184:187], v[234:237], v[22:25]
	v_mfma_f32_16x16x32_bf16 v[18:21], v[188:191], v[230:233], 0
	v_mfma_f32_16x16x32_bf16 v[18:21], v[192:195], v[234:237], v[18:21]
	v_mfma_f32_16x16x32_bf16 v[6:9], v[180:183], v[238:241], 0
	v_mfma_f32_16x16x32_bf16 v[6:9], v[184:187], v[242:245], v[6:9]
	s_setprio 2
	s_barrier
	v_mfma_f32_16x16x32_bf16 v[2:5], v[188:191], v[238:241], 0
	v_mfma_f32_16x16x32_bf16 v[2:5], v[192:195], v[242:245], v[2:5]
	s_setprio 0
	v_add_u32_e32 v162, vcc_lo, v99
	v_add_u32_e32 v192, vcc_hi, v99
	ds_read_b128 v[148:151], v162
	ds_read_b128 v[154:157], v162 offset:1024
	ds_read_b128 v[158:161], v162 offset:2048
	ds_read_b128 v[162:165], v162 offset:3072
	ds_read_b128 v[180:183], v192
	ds_read_b128 v[184:187], v192 offset:1024
	ds_read_b128 v[188:191], v192 offset:2048
	ds_read_b128 v[192:195], v192 offset:3072
	s_mov_b32 m0, s78
	v_lshl_add_u64 v[246:247], s[56:57], 0, v[138:139]
	ds_read_b128 v[196:199], v153 offset:32768
	ds_read_b128 v[200:203], v153 offset:33792
	ds_read_b128 v[222:225], v153 offset:34816
	ds_read_b128 v[226:229], v153 offset:35840
	ds_read_b128 v[230:233], v153 offset:36864
	ds_read_b128 v[234:237], v153 offset:37888
	ds_read_b128 v[238:241], v153 offset:38912
	ds_read_b128 v[242:245], v153 offset:39936
	global_load_lds_dwordx4 v[246:247], off
	v_lshl_add_u64 v[246:247], s[56:57], 0, v[134:135]
	s_mov_b32 m0, s82
	s_nop 0
	global_load_lds_dwordx4 v[246:247], off
	s_waitcnt vmcnt(8)
	s_waitcnt lgkmcnt(0)
	s_setprio 1
	s_barrier
	v_mfma_f32_16x16x32_bf16 v[128:131], v[148:151], v[196:199], v[128:131]
	v_mfma_f32_16x16x32_bf16 v[128:131], v[154:157], v[200:203], v[128:131]
	v_mfma_f32_16x16x32_bf16 v[124:127], v[158:161], v[196:199], v[124:127]
	v_mfma_f32_16x16x32_bf16 v[124:127], v[162:165], v[200:203], v[124:127]
	v_mfma_f32_16x16x32_bf16 v[112:115], v[148:151], v[222:225], v[112:115]
	v_mfma_f32_16x16x32_bf16 v[112:115], v[154:157], v[226:229], v[112:115]
	v_mfma_f32_16x16x32_bf16 v[108:111], v[158:161], v[222:225], v[108:111]
	v_mfma_f32_16x16x32_bf16 v[108:111], v[162:165], v[226:229], v[108:111]
	v_mfma_f32_16x16x32_bf16 v[94:97], v[148:151], v[230:233], v[94:97]
	v_mfma_f32_16x16x32_bf16 v[94:97], v[154:157], v[234:237], v[94:97]
	v_mfma_f32_16x16x32_bf16 v[90:93], v[158:161], v[230:233], v[90:93]
	v_mfma_f32_16x16x32_bf16 v[90:93], v[162:165], v[234:237], v[90:93]
	v_mfma_f32_16x16x32_bf16 v[78:81], v[148:151], v[238:241], v[78:81]
	v_mfma_f32_16x16x32_bf16 v[78:81], v[154:157], v[242:245], v[78:81]
	v_mfma_f32_16x16x32_bf16 v[74:77], v[158:161], v[238:241], v[74:77]
	v_mfma_f32_16x16x32_bf16 v[74:77], v[162:165], v[242:245], v[74:77]
	s_setprio 0
	s_setprio 1
	v_mfma_f32_16x16x32_bf16 v[120:123], v[180:183], v[196:199], v[120:123]
	v_mfma_f32_16x16x32_bf16 v[120:123], v[184:187], v[200:203], v[120:123]
	v_mfma_f32_16x16x32_bf16 v[116:119], v[188:191], v[196:199], v[116:119]
	v_mfma_f32_16x16x32_bf16 v[116:119], v[192:195], v[200:203], v[116:119]
	v_mfma_f32_16x16x32_bf16 v[104:107], v[180:183], v[222:225], v[104:107]
	v_mfma_f32_16x16x32_bf16 v[104:107], v[184:187], v[226:229], v[104:107]
	v_mfma_f32_16x16x32_bf16 v[100:103], v[188:191], v[222:225], v[100:103]
	v_mfma_f32_16x16x32_bf16 v[100:103], v[192:195], v[226:229], v[100:103]
	v_mfma_f32_16x16x32_bf16 v[86:89], v[180:183], v[230:233], v[86:89]
	v_mfma_f32_16x16x32_bf16 v[86:89], v[184:187], v[234:237], v[86:89]
	v_mfma_f32_16x16x32_bf16 v[82:85], v[188:191], v[230:233], v[82:85]
	v_mfma_f32_16x16x32_bf16 v[82:85], v[192:195], v[234:237], v[82:85]
	v_mfma_f32_16x16x32_bf16 v[70:73], v[180:183], v[238:241], v[70:73]
	v_mfma_f32_16x16x32_bf16 v[70:73], v[184:187], v[242:245], v[70:73]
	s_setprio 2
	s_barrier
; #define PG8_STAGE(bufoff, gbase, voff) do { _Pragma("unroll") for (int _i = 0; _i < 2; ++_i) \
;         __builtin_amdgcn_global_load_lds((const unsigned*)((const char*)(gbase) + (voff)[_i]), (PG8_LAS unsigned*)(lds + (bufoff) + ldsw + _i * 8192), 16, 0, AUX_A); } while (0)
; #define PG8_STAGEB(bufoff, gbase, voff) do { _Pragma("unroll") for (int _i = 0; _i < 2; ++_i) \
;         __builtin_amdgcn_global_load_lds((const unsigned*)((const char*)(gbase) + (voff)[_i]), (PG8_LAS unsigned*)(lds + (bufoff) + ldsw + _i * 8192), 16, 0, AUX_B); } while (0)
; #define PG8_WAIT_V(n) asm volatile("s_waitcnt vmcnt(" #n ")" ::: "memory")
; #define PG8_WAIT_L(n) asm volatile("s_waitcnt lgkmcnt(" #n ")" ::: "memory")
; template <class Epi, class Sched, bool ALIGN_EPI = false, bool SP2 = false>
; __device__ __forceinline__ void gemm_phase(PG8_LAS unsigned char* lds, const Gemm g, const Sched& S, const Epi& E) {
;     ...
;         for (int t = 0; t < nt; t += 2) {
;             const bool last = (t == nt - 2);
;             const char* a1 = PG8_KP(cA, t + 1, rot, nt);
;             const char* a2 = last ? nAr : PG8_KP(cA, t + 2, rot, nt); const char* b2 = last ? nBr : PG8_KP(cB, t + 2, rot, nt);
;             const char* a3 = a2 + kstep; const char* b3 = b2 + kstep;
;             if (last && has_next) S.a_ready(nxt);
;             if constexpr (SP2) {
;             PG8_LDB(B0, 0, 0); PG8_LDB(B1, 0, 1); PG8_SCHED; PG8_LDA(At, 0, 0); PG8_STAGE(PG8_SA(1, 1), a1 + hstep, voffA);
;             PG8_WAIT_V(8); PG8_WAIT_L(0); PG8_BAR; PG8_MMA(0, 0, At, B0); PG8_MMA(0, 1, At, B1); PG8_BAR; PG8_SCHED;
;             PG8_LDA(At, 0, 1); PG8_STAGEB(PG8_SB(0, 0), b2, voffB); PG8_STAGEB(PG8_SB(0, 1), b2 + hstep, voffB); PG8_STAGE(PG8_SA(0, 0), a2, voffA);
;             PG8_WAIT_V(8); PG8_WAIT_L(0); PG8_BAR; PG8_MMA(1, 0, At, B0); PG8_MMA(1, 1, At, B1); PG8_BAR; PG8_SCHED;
;             PG8_LDB(B0, 1, 0); PG8_LDB(B1, 1, 1); PG8_SCHED; PG8_LDA(At, 1, 0); PG8_STAGE(PG8_SA(0, 1), a2 + hstep, voffA);
;             PG8_WAIT_V(8); PG8_WAIT_L(0); PG8_BAR; PG8_MMA(0, 0, At, B0); PG8_MMA(0, 1, At, B1); PG8_BAR; PG8_SCHED;
;             PG8_LDA(At, 1, 1); PG8_STAGEB(PG8_SB(1, 0), b3, voffB); PG8_STAGEB(PG8_SB(1, 1), b3 + hstep, voffB); PG8_STAGE(PG8_SA(1, 0), a3, voffA);
;             PG8_WAIT_V(8); PG8_WAIT_L(0); PG8_BAR; PG8_MMA(1, 0, At, B0); PG8_MMA(1, 1, At, B1); PG8_BAR; PG8_SCHED;
	v_mfma_f32_16x16x32_bf16 v[66:69], v[188:191], v[238:241], v[66:69]
	v_mfma_f32_16x16x32_bf16 v[66:69], v[192:195], v[242:245], v[66:69]
	s_setprio 0
	s_mov_b32 m0, s1
	v_lshl_add_u64 v[166:167], v[166:167], 0, s[76:77]
	ds_read_b128 v[196:199], v153 offset:49152
	ds_read_b128 v[200:203], v153 offset:50176
	ds_read_b128 v[222:225], v153 offset:51200
	ds_read_b128 v[226:229], v153 offset:52224
	ds_read_b128 v[230:233], v153 offset:53248
	ds_read_b128 v[234:237], v153 offset:54272
	ds_read_b128 v[238:241], v153 offset:55296
	ds_read_b128 v[242:245], v153 offset:56320
	global_load_lds_dwordx4 v[166:167], off
	v_lshl_add_u64 v[166:167], v[168:169], 0, s[76:77]
	s_mov_b32 m0, s0
	s_nop 0
	global_load_lds_dwordx4 v[166:167], off
	v_lshl_add_u64 v[166:167], s[54:55], 0, v[136:137]
	s_mov_b32 m0, s47
	s_nop 0
	global_load_lds_dwordx4 v[166:167], off
	v_lshl_add_u64 v[166:167], s[54:55], 0, v[132:133]
	s_mov_b32 m0, s46
	s_nop 0
	global_load_lds_dwordx4 v[166:167], off
	v_lshl_add_u64 v[166:167], v[172:173], 0, s[76:77]
	s_mov_b32 m0, s83
	s_nop 0
	global_load_lds_dwordx4 v[166:167], off
	v_lshl_add_u64 v[166:167], v[212:213], 0, s[76:77]
	s_mov_b32 m0, s88
	s_nop 0
	global_load_lds_dwordx4 v[166:167], off
	s_waitcnt vmcnt(8)
	s_waitcnt lgkmcnt(0)
	s_setprio 1
	s_barrier
	v_mfma_f32_16x16x32_bf16 v[62:65], v[148:151], v[196:199], v[62:65]
	v_mfma_f32_16x16x32_bf16 v[62:65], v[154:157], v[200:203], v[62:65]
	v_mfma_f32_16x16x32_bf16 v[58:61], v[158:161], v[196:199], v[58:61]
	v_mfma_f32_16x16x32_bf16 v[58:61], v[162:165], v[200:203], v[58:61]
	v_mfma_f32_16x16x32_bf16 v[46:49], v[148:151], v[222:225], v[46:49]
	v_mfma_f32_16x16x32_bf16 v[46:49], v[154:157], v[226:229], v[46:49]
	v_mfma_f32_16x16x32_bf16 v[42:45], v[158:161], v[222:225], v[42:45]
	v_mfma_f32_16x16x32_bf16 v[42:45], v[162:165], v[226:229], v[42:45]
	v_mfma_f32_16x16x32_bf16 v[30:33], v[148:151], v[230:233], v[30:33]
	v_mfma_f32_16x16x32_bf16 v[30:33], v[154:157], v[234:237], v[30:33]
	v_mfma_f32_16x16x32_bf16 v[26:29], v[158:161], v[230:233], v[26:29]
	v_mfma_f32_16x16x32_bf16 v[26:29], v[162:165], v[234:237], v[26:29]
	v_mfma_f32_16x16x32_bf16 v[14:17], v[148:151], v[238:241], v[14:17]
	v_mfma_f32_16x16x32_bf16 v[14:17], v[154:157], v[242:245], v[14:17]
	v_mfma_f32_16x16x32_bf16 v[10:13], v[158:161], v[238:241], v[10:13]
	v_mfma_f32_16x16x32_bf16 v[10:13], v[162:165], v[242:245], v[10:13]
	s_setprio 0
	s_setprio 1
	v_mfma_f32_16x16x32_bf16 v[54:57], v[180:183], v[196:199], v[54:57]
	v_mfma_f32_16x16x32_bf16 v[54:57], v[184:187], v[200:203], v[54:57]
	v_mfma_f32_16x16x32_bf16 v[50:53], v[188:191], v[196:199], v[50:53]
	v_mfma_f32_16x16x32_bf16 v[50:53], v[192:195], v[200:203], v[50:53]
	v_mfma_f32_16x16x32_bf16 v[38:41], v[180:183], v[222:225], v[38:41]
	v_mfma_f32_16x16x32_bf16 v[38:41], v[184:187], v[226:229], v[38:41]
	v_mfma_f32_16x16x32_bf16 v[34:37], v[188:191], v[222:225], v[34:37]
	v_mfma_f32_16x16x32_bf16 v[34:37], v[192:195], v[226:229], v[34:37]
	v_mfma_f32_16x16x32_bf16 v[22:25], v[180:183], v[230:233], v[22:25]
	v_mfma_f32_16x16x32_bf16 v[22:25], v[184:187], v[234:237], v[22:25]
	v_mfma_f32_16x16x32_bf16 v[18:21], v[188:191], v[230:233], v[18:21]
	v_mfma_f32_16x16x32_bf16 v[18:21], v[192:195], v[234:237], v[18:21]
	v_mfma_f32_16x16x32_bf16 v[6:9], v[180:183], v[238:241], v[6:9]
	v_mfma_f32_16x16x32_bf16 v[6:9], v[184:187], v[242:245], v[6:9]
	s_setprio 2
	s_barrier
	v_mfma_f32_16x16x32_bf16 v[2:5], v[188:191], v[238:241], v[2:5]
	v_mfma_f32_16x16x32_bf16 v[2:5], v[192:195], v[242:245], v[2:5]
	s_setprio 0
	v_lshl_add_u64 v[144:145], v[144:145], 0, s[86:87]
	v_lshl_add_u64 v[146:147], v[146:147], 0, s[86:87]
	s_mov_b32 s29, s81
	s_cbranch_scc1 .Lpx_1157
.LBB0_1157:
	s_add_i32 s81, s29, 2
	s_cmp_lt_u32 s29, 14
	s_cselect_b32 s0, 0, -16
	s_add_i32 s0, s81, s0
	s_ashr_i32 s1, s0, 31
	s_lshl_b64 s[0:1], s[0:1], 7
	s_add_u32 s2, s52, s0
	s_addc_u32 s46, s53, s1
	s_add_u32 s0, s50, s0
	s_addc_u32 s1, s51, s1
	s_cmp_eq_u32 s29, 14
	s_cselect_b32 s59, s19, s46
	s_cselect_b32 s58, s39, s2
	s_cselect_b32 s61, s92, s1
	s_cselect_b32 s60, s93, s0
	s_add_i32 s2, 0, 0x10000
	s_add_i32 s94, s2, s70
	s_add_i32 s46, 0, 0x14000
	s_add_i32 m0, s71, 0xc000
	s_add_i32 s84, s71, 0xe000
	s_add_i32 s95, s94, 0x2000
	s_add_u32 s62, s60, 0x40000
	s_addc_u32 s63, s61, 0
	s_add_i32 s96, s46, s70
	v_add_u32_e32 v162, s2, v99
	v_add_u32_e32 v166, s46, v99
	s_add_i32 s97, s96, 0x2000
	s_add_i32 vcc_lo, 0, 0x18000
	s_add_i32 vcc_hi, 0, 0x1c000
	ds_read_b128 v[148:151], v162
	ds_read_b128 v[154:157], v162 offset:1024
	ds_read_b128 v[158:161], v162 offset:2048
	ds_read_b128 v[162:165], v162 offset:3072
	ds_read_b128 v[180:183], v166
	ds_read_b128 v[184:187], v166 offset:1024
	ds_read_b128 v[188:191], v166 offset:2048
	ds_read_b128 v[192:195], v166 offset:3072
	s_add_u32 s56, s58, 0x40000
	s_addc_u32 s57, s59, 0
	s_add_i32 s1, vcc_lo, s70
	s_add_i32 s0, s1, 0x2000
	s_add_u32 s54, s60, 0x40080
	s_addc_u32 s55, s61, 0
	s_add_i32 s47, vcc_hi, s70
	s_add_i32 s46, s47, 0x2000
	s_cmp_gt_u32 s29, 13
	ds_read_b128 v[196:199], v153
	ds_read_b128 v[200:203], v153 offset:1024
	ds_read_b128 v[222:225], v153 offset:2048
	ds_read_b128 v[226:229], v153 offset:3072
	ds_read_b128 v[230:233], v153 offset:4096
	ds_read_b128 v[234:237], v153 offset:5120
	ds_read_b128 v[238:241], v153 offset:6144
	ds_read_b128 v[242:245], v153 offset:7168
	global_load_lds_dwordx4 v[146:147], off
	s_mov_b32 m0, s84
	s_nop 0
	global_load_lds_dwordx4 v[144:145], off
	s_waitcnt vmcnt(8)
	s_waitcnt lgkmcnt(0)
	s_setprio 1
	s_barrier
; #define PG8_STAGE(bufoff, gbase, voff) do { _Pragma("unroll") for (int _i = 0; _i < 2; ++_i) \
;         __builtin_amdgcn_global_load_lds((const unsigned*)((const char*)(gbase) + (voff)[_i]), (PG8_LAS unsigned*)(lds + (bufoff) + ldsw + _i * 8192), 16, 0, AUX_A); } while (0)
; #define PG8_STAGEB(bufoff, gbase, voff) do { _Pragma("unroll") for (int _i = 0; _i < 2; ++_i) \
;         __builtin_amdgcn_global_load_lds((const unsigned*)((const char*)(gbase) + (voff)[_i]), (PG8_LAS unsigned*)(lds + (bufoff) + ldsw + _i * 8192), 16, 0, AUX_B); } while (0)
; #define PG8_LDA(dst, b, h) do { _Pragma("unroll") for (int m = 0; m < 4; ++m) _Pragma("unroll") for (int k = 0; k < 2; ++k) dst[m][k] = *(const PG8_LAS bf16x8*)(lds + PG8_SA(b, h) + aoff + m * 2048 + k * 1024); } while (0)
; #define PG8_LDB(dst, b, h) do { _Pragma("unroll") for (int n = 0; n < 2; ++n) _Pragma("unroll") for (int k = 0; k < 2; ++k) dst[n][k] = *(const PG8_LAS bf16x8*)(lds + PG8_SB(b, h) + boff + n * 2048 + k * 1024); } while (0)
; #define PG8_MMA(ai, bj, At, Bt) do { __builtin_amdgcn_s_setprio(1); _Pragma("unroll") for (int m = 0; m < 4; ++m) _Pragma("unroll") for (int n = 0; n < 2; ++n) _Pragma("unroll") for (int k = 0; k < 2; ++k) \
;         acc[ai][bj][m][n] = __builtin_amdgcn_mfma_f32_16x16x32_bf16(Bt[n][k], At[m][k], acc[ai][bj][m][n], 0, 0, 0); __builtin_amdgcn_s_setprio(0); } while (0)
; #define PG8_BAR __builtin_amdgcn_s_barrier()
; template <class Epi, class Sched, bool ALIGN_EPI = false, bool SP2 = false>
; __device__ __forceinline__ void gemm_phase(PG8_LAS unsigned char* lds, const Gemm g, const Sched& S, const Epi& E) {
;     ...
;             PG8_LDB(B0, 0, 0); PG8_LDB(B1, 0, 1); PG8_SCHED; PG8_LDA(At, 0, 0); PG8_STAGE(PG8_SA(1, 1), a1 + hstep, voffA);
;             PG8_WAIT_V(8); PG8_WAIT_L(0); PG8_BAR; PG8_MMA(0, 0, At, B0); PG8_MMA(0, 1, At, B1); PG8_BAR; PG8_SCHED;
;             PG8_LDA(At, 0, 1); PG8_STAGEB(PG8_SB(0, 0), b2, voffB); PG8_STAGEB(PG8_SB(0, 1), b2 + hstep, voffB); PG8_STAGE(PG8_SA(0, 0), a2, voffA);
;             PG8_WAIT_V(8); PG8_WAIT_L(0); PG8_BAR; PG8_MMA(1, 0, At, B0); PG8_MMA(1, 1, At, B1); PG8_BAR; PG8_SCHED;
;             PG8_LDB(B0, 1, 0); PG8_LDB(B1, 1, 1); PG8_SCHED; PG8_LDA(At, 1, 0); PG8_STAGE(PG8_SA(0, 1), a2 + hstep, voffA);
;             PG8_WAIT_V(8); PG8_WAIT_L(0); PG8_BAR; PG8_MMA(0, 0, At, B0); PG8_MMA(0, 1, At, B1); PG8_BAR; PG8_SCHED;
	v_mfma_f32_16x16x32_bf16 v[128:131], v[148:151], v[196:199], v[128:131]
	v_mfma_f32_16x16x32_bf16 v[128:131], v[154:157], v[200:203], v[128:131]
	v_mfma_f32_16x16x32_bf16 v[124:127], v[158:161], v[196:199], v[124:127]
	v_mfma_f32_16x16x32_bf16 v[124:127], v[162:165], v[200:203], v[124:127]
	v_mfma_f32_16x16x32_bf16 v[112:115], v[148:151], v[222:225], v[112:115]
	v_mfma_f32_16x16x32_bf16 v[112:115], v[154:157], v[226:229], v[112:115]
	v_mfma_f32_16x16x32_bf16 v[108:111], v[158:161], v[222:225], v[108:111]
	v_mfma_f32_16x16x32_bf16 v[108:111], v[162:165], v[226:229], v[108:111]
	v_mfma_f32_16x16x32_bf16 v[94:97], v[148:151], v[230:233], v[94:97]
	v_mfma_f32_16x16x32_bf16 v[94:97], v[154:157], v[234:237], v[94:97]
	v_mfma_f32_16x16x32_bf16 v[90:93], v[158:161], v[230:233], v[90:93]
	v_mfma_f32_16x16x32_bf16 v[90:93], v[162:165], v[234:237], v[90:93]
	v_mfma_f32_16x16x32_bf16 v[78:81], v[148:151], v[238:241], v[78:81]
	v_mfma_f32_16x16x32_bf16 v[78:81], v[154:157], v[242:245], v[78:81]
	v_mfma_f32_16x16x32_bf16 v[74:77], v[158:161], v[238:241], v[74:77]
	v_mfma_f32_16x16x32_bf16 v[74:77], v[162:165], v[242:245], v[74:77]
	s_setprio 0
	s_setprio 1
	v_mfma_f32_16x16x32_bf16 v[120:123], v[180:183], v[196:199], v[120:123]
	v_mfma_f32_16x16x32_bf16 v[120:123], v[184:187], v[200:203], v[120:123]
	v_mfma_f32_16x16x32_bf16 v[116:119], v[188:191], v[196:199], v[116:119]
	v_mfma_f32_16x16x32_bf16 v[116:119], v[192:195], v[200:203], v[116:119]
	v_mfma_f32_16x16x32_bf16 v[104:107], v[180:183], v[222:225], v[104:107]
	v_mfma_f32_16x16x32_bf16 v[104:107], v[184:187], v[226:229], v[104:107]
	v_mfma_f32_16x16x32_bf16 v[100:103], v[188:191], v[222:225], v[100:103]
	v_mfma_f32_16x16x32_bf16 v[100:103], v[192:195], v[226:229], v[100:103]
	v_mfma_f32_16x16x32_bf16 v[86:89], v[180:183], v[230:233], v[86:89]
	v_mfma_f32_16x16x32_bf16 v[86:89], v[184:187], v[234:237], v[86:89]
	v_mfma_f32_16x16x32_bf16 v[82:85], v[188:191], v[230:233], v[82:85]
	v_mfma_f32_16x16x32_bf16 v[82:85], v[192:195], v[234:237], v[82:85]
	v_mfma_f32_16x16x32_bf16 v[70:73], v[180:183], v[238:241], v[70:73]
	v_mfma_f32_16x16x32_bf16 v[70:73], v[184:187], v[242:245], v[70:73]
	s_setprio 2
	s_barrier
	v_mfma_f32_16x16x32_bf16 v[66:69], v[188:191], v[238:241], v[66:69]
	v_mfma_f32_16x16x32_bf16 v[66:69], v[192:195], v[242:245], v[66:69]
	s_setprio 0
	s_mov_b32 m0, s94
	v_lshl_add_u64 v[166:167], s[60:61], 0, v[136:137]
	ds_read_b128 v[196:199], v153 offset:16384
	ds_read_b128 v[200:203], v153 offset:17408
	ds_read_b128 v[222:225], v153 offset:18432
	ds_read_b128 v[226:229], v153 offset:19456
	ds_read_b128 v[230:233], v153 offset:20480
	ds_read_b128 v[234:237], v153 offset:21504
	ds_read_b128 v[238:241], v153 offset:22528
	ds_read_b128 v[242:245], v153 offset:23552
	global_load_lds_dwordx4 v[166:167], off
	v_lshl_add_u64 v[168:169], s[60:61], 0, v[132:133]
	s_mov_b32 m0, s95
	v_lshl_add_u64 v[172:173], s[62:63], 0, v[136:137]
	global_load_lds_dwordx4 v[168:169], off
	s_mov_b32 m0, s96
	v_lshl_add_u64 v[212:213], s[58:59], 0, v[134:135]
	global_load_lds_dwordx4 v[172:173], off
	v_lshl_add_u64 v[172:173], s[62:63], 0, v[132:133]
	s_mov_b32 m0, s97
	s_nop 0
	global_load_lds_dwordx4 v[172:173], off
	v_lshl_add_u64 v[172:173], s[58:59], 0, v[138:139]
	s_mov_b32 m0, s71
	s_nop 0
	global_load_lds_dwordx4 v[172:173], off
	s_mov_b32 m0, s75
	s_nop 0
	global_load_lds_dwordx4 v[212:213], off
	s_waitcnt vmcnt(8)
	s_waitcnt lgkmcnt(0)
	s_setprio 1
	s_barrier
	v_mfma_f32_16x16x32_bf16 v[62:65], v[148:151], v[196:199], v[62:65]
	v_mfma_f32_16x16x32_bf16 v[62:65], v[154:157], v[200:203], v[62:65]
	v_mfma_f32_16x16x32_bf16 v[58:61], v[158:161], v[196:199], v[58:61]
	v_mfma_f32_16x16x32_bf16 v[58:61], v[162:165], v[200:203], v[58:61]
	v_mfma_f32_16x16x32_bf16 v[46:49], v[148:151], v[222:225], v[46:49]
	v_mfma_f32_16x16x32_bf16 v[46:49], v[154:157], v[226:229], v[46:49]
	v_mfma_f32_16x16x32_bf16 v[42:45], v[158:161], v[222:225], v[42:45]
	v_mfma_f32_16x16x32_bf16 v[42:45], v[162:165], v[226:229], v[42:45]
	v_mfma_f32_16x16x32_bf16 v[30:33], v[148:151], v[230:233], v[30:33]
	v_mfma_f32_16x16x32_bf16 v[30:33], v[154:157], v[234:237], v[30:33]
	v_mfma_f32_16x16x32_bf16 v[26:29], v[158:161], v[230:233], v[26:29]
	v_mfma_f32_16x16x32_bf16 v[26:29], v[162:165], v[234:237], v[26:29]
	v_mfma_f32_16x16x32_bf16 v[14:17], v[148:151], v[238:241], v[14:17]
	v_mfma_f32_16x16x32_bf16 v[14:17], v[154:157], v[242:245], v[14:17]
	v_mfma_f32_16x16x32_bf16 v[10:13], v[158:161], v[238:241], v[10:13]
	v_mfma_f32_16x16x32_bf16 v[10:13], v[162:165], v[242:245], v[10:13]
	s_setprio 0
	s_setprio 1
	v_mfma_f32_16x16x32_bf16 v[54:57], v[180:183], v[196:199], v[54:57]
	v_mfma_f32_16x16x32_bf16 v[54:57], v[184:187], v[200:203], v[54:57]
	v_mfma_f32_16x16x32_bf16 v[50:53], v[188:191], v[196:199], v[50:53]
	v_mfma_f32_16x16x32_bf16 v[50:53], v[192:195], v[200:203], v[50:53]
	v_mfma_f32_16x16x32_bf16 v[38:41], v[180:183], v[222:225], v[38:41]
	v_mfma_f32_16x16x32_bf16 v[38:41], v[184:187], v[226:229], v[38:41]
	v_mfma_f32_16x16x32_bf16 v[34:37], v[188:191], v[222:225], v[34:37]
	v_mfma_f32_16x16x32_bf16 v[34:37], v[192:195], v[226:229], v[34:37]
	v_mfma_f32_16x16x32_bf16 v[22:25], v[180:183], v[230:233], v[22:25]
	v_mfma_f32_16x16x32_bf16 v[22:25], v[184:187], v[234:237], v[22:25]
	v_mfma_f32_16x16x32_bf16 v[18:21], v[188:191], v[230:233], v[18:21]
	v_mfma_f32_16x16x32_bf16 v[18:21], v[192:195], v[234:237], v[18:21]
	v_mfma_f32_16x16x32_bf16 v[6:9], v[180:183], v[238:241], v[6:9]
	v_mfma_f32_16x16x32_bf16 v[6:9], v[184:187], v[242:245], v[6:9]
	s_setprio 2
	s_barrier
; #define PG8_STAGE(bufoff, gbase, voff) do { _Pragma("unroll") for (int _i = 0; _i < 2; ++_i) \
;         __builtin_amdgcn_global_load_lds((const unsigned*)((const char*)(gbase) + (voff)[_i]), (PG8_LAS unsigned*)(lds + (bufoff) + ldsw + _i * 8192), 16, 0, AUX_A); } while (0)
; #define PG8_STAGEB(bufoff, gbase, voff) do { _Pragma("unroll") for (int _i = 0; _i < 2; ++_i) \
;         __builtin_amdgcn_global_load_lds((const unsigned*)((const char*)(gbase) + (voff)[_i]), (PG8_LAS unsigned*)(lds + (bufoff) + ldsw + _i * 8192), 16, 0, AUX_B); } while (0)
; #define PG8_LDA(dst, b, h) do { _Pragma("unroll") for (int m = 0; m < 4; ++m) _Pragma("unroll") for (int k = 0; k < 2; ++k) dst[m][k] = *(const PG8_LAS bf16x8*)(lds + PG8_SA(b, h) + aoff + m * 2048 + k * 1024); } while (0)
; #define PG8_LDB(dst, b, h) do { _Pragma("unroll") for (int n = 0; n < 2; ++n) _Pragma("unroll") for (int k = 0; k < 2; ++k) dst[n][k] = *(const PG8_LAS bf16x8*)(lds + PG8_SB(b, h) + boff + n * 2048 + k * 1024); } while (0)
; #define PG8_MMA(ai, bj, At, Bt) do { __builtin_amdgcn_s_setprio(1); _Pragma("unroll") for (int m = 0; m < 4; ++m) _Pragma("unroll") for (int n = 0; n < 2; ++n) _Pragma("unroll") for (int k = 0; k < 2; ++k) \
;         acc[ai][bj][m][n] = __builtin_amdgcn_mfma_f32_16x16x32_bf16(Bt[n][k], At[m][k], acc[ai][bj][m][n], 0, 0, 0); __builtin_amdgcn_s_setprio(0); } while (0)
; #define PG8_WAIT_V(n) asm volatile("s_waitcnt vmcnt(" #n ")" ::: "memory")
; #define PG8_WAIT_L(n) asm volatile("s_waitcnt lgkmcnt(" #n ")" ::: "memory")
; #define PG8_BAR __builtin_amdgcn_s_barrier()
; #define PG8_SCHED __builtin_amdgcn_sched_barrier(0)
; template <class Epi, class Sched, bool ALIGN_EPI = false, bool SP2 = false>
; __device__ __forceinline__ void gemm_phase(PG8_LAS unsigned char* lds, const Gemm g, const Sched& S, const Epi& E) {
;     ...
;             PG8_WAIT_V(8); PG8_WAIT_L(0); PG8_BAR; PG8_MMA(1, 0, At, B0); PG8_MMA(1, 1, At, B1); PG8_BAR; PG8_SCHED;
;             PG8_LDB(B0, 1, 0); PG8_LDB(B1, 1, 1); PG8_SCHED; PG8_LDA(At, 1, 0); PG8_STAGE(PG8_SA(0, 1), a2 + hstep, voffA);
;             PG8_WAIT_V(8); PG8_WAIT_L(0); PG8_BAR; PG8_MMA(0, 0, At, B0); PG8_MMA(0, 1, At, B1); PG8_BAR; PG8_SCHED;
;             PG8_LDA(At, 1, 1); PG8_STAGEB(PG8_SB(1, 0), b3, voffB); PG8_STAGEB(PG8_SB(1, 1), b3 + hstep, voffB); PG8_STAGE(PG8_SA(1, 0), a3, voffA);
	v_mfma_f32_16x16x32_bf16 v[2:5], v[188:191], v[238:241], v[2:5]
	v_mfma_f32_16x16x32_bf16 v[2:5], v[192:195], v[242:245], v[2:5]
	s_setprio 0
	v_add_u32_e32 v162, vcc_lo, v99
	v_add_u32_e32 v192, vcc_hi, v99
	ds_read_b128 v[148:151], v162
	ds_read_b128 v[154:157], v162 offset:1024
	ds_read_b128 v[158:161], v162 offset:2048
	ds_read_b128 v[162:165], v162 offset:3072
	ds_read_b128 v[180:183], v192
	ds_read_b128 v[184:187], v192 offset:1024
	ds_read_b128 v[188:191], v192 offset:2048
	ds_read_b128 v[192:195], v192 offset:3072
	s_mov_b32 m0, s78
	v_lshl_add_u64 v[246:247], s[56:57], 0, v[138:139]
	ds_read_b128 v[196:199], v153 offset:32768
	ds_read_b128 v[200:203], v153 offset:33792
	ds_read_b128 v[222:225], v153 offset:34816
	ds_read_b128 v[226:229], v153 offset:35840
	ds_read_b128 v[230:233], v153 offset:36864
	ds_read_b128 v[234:237], v153 offset:37888
	ds_read_b128 v[238:241], v153 offset:38912
	ds_read_b128 v[242:245], v153 offset:39936
	global_load_lds_dwordx4 v[246:247], off
	v_lshl_add_u64 v[246:247], s[56:57], 0, v[134:135]
	s_mov_b32 m0, s82
	s_nop 0
	global_load_lds_dwordx4 v[246:247], off
	s_waitcnt vmcnt(8)
	s_waitcnt lgkmcnt(0)
	s_setprio 1
	s_barrier
	v_mfma_f32_16x16x32_bf16 v[128:131], v[148:151], v[196:199], v[128:131]
	v_mfma_f32_16x16x32_bf16 v[128:131], v[154:157], v[200:203], v[128:131]
	v_mfma_f32_16x16x32_bf16 v[124:127], v[158:161], v[196:199], v[124:127]
	v_mfma_f32_16x16x32_bf16 v[124:127], v[162:165], v[200:203], v[124:127]
	v_mfma_f32_16x16x32_bf16 v[112:115], v[148:151], v[222:225], v[112:115]
	v_mfma_f32_16x16x32_bf16 v[112:115], v[154:157], v[226:229], v[112:115]
	v_mfma_f32_16x16x32_bf16 v[108:111], v[158:161], v[222:225], v[108:111]
	v_mfma_f32_16x16x32_bf16 v[108:111], v[162:165], v[226:229], v[108:111]
	v_mfma_f32_16x16x32_bf16 v[94:97], v[148:151], v[230:233], v[94:97]
	v_mfma_f32_16x16x32_bf16 v[94:97], v[154:157], v[234:237], v[94:97]
	v_mfma_f32_16x16x32_bf16 v[90:93], v[158:161], v[230:233], v[90:93]
	v_mfma_f32_16x16x32_bf16 v[90:93], v[162:165], v[234:237], v[90:93]
	v_mfma_f32_16x16x32_bf16 v[78:81], v[148:151], v[238:241], v[78:81]
	v_mfma_f32_16x16x32_bf16 v[78:81], v[154:157], v[242:245], v[78:81]
	v_mfma_f32_16x16x32_bf16 v[74:77], v[158:161], v[238:241], v[74:77]
	v_mfma_f32_16x16x32_bf16 v[74:77], v[162:165], v[242:245], v[74:77]
	s_setprio 0
	s_setprio 1
	v_mfma_f32_16x16x32_bf16 v[120:123], v[180:183], v[196:199], v[120:123]
	v_mfma_f32_16x16x32_bf16 v[120:123], v[184:187], v[200:203], v[120:123]
	v_mfma_f32_16x16x32_bf16 v[116:119], v[188:191], v[196:199], v[116:119]
	v_mfma_f32_16x16x32_bf16 v[116:119], v[192:195], v[200:203], v[116:119]
	v_mfma_f32_16x16x32_bf16 v[104:107], v[180:183], v[222:225], v[104:107]
	v_mfma_f32_16x16x32_bf16 v[104:107], v[184:187], v[226:229], v[104:107]
	v_mfma_f32_16x16x32_bf16 v[100:103], v[188:191], v[222:225], v[100:103]
	v_mfma_f32_16x16x32_bf16 v[100:103], v[192:195], v[226:229], v[100:103]
	v_mfma_f32_16x16x32_bf16 v[86:89], v[180:183], v[230:233], v[86:89]
	v_mfma_f32_16x16x32_bf16 v[86:89], v[184:187], v[234:237], v[86:89]
	v_mfma_f32_16x16x32_bf16 v[82:85], v[188:191], v[230:233], v[82:85]
	v_mfma_f32_16x16x32_bf16 v[82:85], v[192:195], v[234:237], v[82:85]
	v_mfma_f32_16x16x32_bf16 v[70:73], v[180:183], v[238:241], v[70:73]
	v_mfma_f32_16x16x32_bf16 v[70:73], v[184:187], v[242:245], v[70:73]
	s_setprio 2
	s_barrier
; #define PG8_STAGE(bufoff, gbase, voff) do { _Pragma("unroll") for (int _i = 0; _i < 2; ++_i) \
;         __builtin_amdgcn_global_load_lds((const unsigned*)((const char*)(gbase) + (voff)[_i]), (PG8_LAS unsigned*)(lds + (bufoff) + ldsw + _i * 8192), 16, 0, AUX_A); } while (0)
; #define PG8_STAGEB(bufoff, gbase, voff) do { _Pragma("unroll") for (int _i = 0; _i < 2; ++_i) \
;         __builtin_amdgcn_global_load_lds((const unsigned*)((const char*)(gbase) + (voff)[_i]), (PG8_LAS unsigned*)(lds + (bufoff) + ldsw + _i * 8192), 16, 0, AUX_B); } while (0)
; #define PG8_LDA(dst, b, h) do { _Pragma("unroll") for (int m = 0; m < 4; ++m) _Pragma("unroll") for (int k = 0; k < 2; ++k) dst[m][k] = *(const PG8_LAS bf16x8*)(lds + PG8_SA(b, h) + aoff + m * 2048 + k * 1024); } while (0)
; #define PG8_LDB(dst, b, h) do { _Pragma("unroll") for (int n = 0; n < 2; ++n) _Pragma("unroll") for (int k = 0; k < 2; ++k) dst[n][k] = *(const PG8_LAS bf16x8*)(lds + PG8_SB(b, h) + boff + n * 2048 + k * 1024); } while (0)
; #define PG8_MMA(ai, bj, At, Bt) do { __builtin_amdgcn_s_setprio(1); _Pragma("unroll") for (int m = 0; m < 4; ++m) _Pragma("unroll") for (int n = 0; n < 2; ++n) _Pragma("unroll") for (int k = 0; k < 2; ++k) \
;         acc[ai][bj][m][n] = __builtin_amdgcn_mfma_f32_16x16x32_bf16(Bt[n][k], At[m][k], acc[ai][bj][m][n], 0, 0, 0); __builtin_amdgcn_s_setprio(0); } while (0)
; #define PG8_WAIT_V(n) asm volatile("s_waitcnt vmcnt(" #n ")" ::: "memory")
; #define PG8_WAIT_L(n) asm volatile("s_waitcnt lgkmcnt(" #n ")" ::: "memory")
; #define PG8_BAR __builtin_amdgcn_s_barrier()
; template <class Epi, class Sched, bool ALIGN_EPI = false, bool SP2 = false>
; __device__ __forceinline__ void gemm_phase(PG8_LAS unsigned char* lds, const Gemm g, const Sched& S, const Epi& E) {
;     ...
;             PG8_LDB(B0, 1, 0); PG8_LDB(B1, 1, 1); PG8_SCHED; PG8_LDA(At, 1, 0); PG8_STAGE(PG8_SA(0, 1), a2 + hstep, voffA);
;             PG8_WAIT_V(8); PG8_WAIT_L(0); PG8_BAR; PG8_MMA(0, 0, At, B0); PG8_MMA(0, 1, At, B1); PG8_BAR; PG8_SCHED;
;             PG8_LDA(At, 1, 1); PG8_STAGEB(PG8_SB(1, 0), b3, voffB); PG8_STAGEB(PG8_SB(1, 1), b3 + hstep, voffB); PG8_STAGE(PG8_SA(1, 0), a3, voffA);
;             PG8_WAIT_V(8); PG8_WAIT_L(0); PG8_BAR; PG8_MMA(1, 0, At, B0); PG8_MMA(1, 1, At, B1); PG8_BAR; PG8_SCHED;
;     ...
;         if constexpr (ALIGN_EPI) { if (wr == 0) PG8_BAR; }
	v_mfma_f32_16x16x32_bf16 v[66:69], v[188:191], v[238:241], v[66:69]
	v_mfma_f32_16x16x32_bf16 v[66:69], v[192:195], v[242:245], v[66:69]
	s_setprio 0
	s_mov_b32 m0, s1
	v_lshl_add_u64 v[166:167], v[166:167], 0, s[76:77]
	ds_read_b128 v[196:199], v153 offset:49152
	ds_read_b128 v[200:203], v153 offset:50176
	ds_read_b128 v[222:225], v153 offset:51200
	ds_read_b128 v[226:229], v153 offset:52224
	ds_read_b128 v[230:233], v153 offset:53248
	ds_read_b128 v[234:237], v153 offset:54272
	ds_read_b128 v[238:241], v153 offset:55296
	ds_read_b128 v[242:245], v153 offset:56320
	global_load_lds_dwordx4 v[166:167], off
	v_lshl_add_u64 v[166:167], v[168:169], 0, s[76:77]
	s_mov_b32 m0, s0
	s_nop 0
	global_load_lds_dwordx4 v[166:167], off
	v_lshl_add_u64 v[166:167], s[54:55], 0, v[136:137]
	s_mov_b32 m0, s47
	s_nop 0
	global_load_lds_dwordx4 v[166:167], off
	v_lshl_add_u64 v[166:167], s[54:55], 0, v[132:133]
	s_mov_b32 m0, s46
	s_nop 0
	global_load_lds_dwordx4 v[166:167], off
	v_lshl_add_u64 v[166:167], v[172:173], 0, s[76:77]
	s_mov_b32 m0, s83
	s_nop 0
	global_load_lds_dwordx4 v[166:167], off
	v_lshl_add_u64 v[166:167], v[212:213], 0, s[76:77]
	s_mov_b32 m0, s88
	s_nop 0
	global_load_lds_dwordx4 v[166:167], off
	s_waitcnt vmcnt(8)
	s_waitcnt lgkmcnt(0)
	s_setprio 1
	s_barrier
	v_mfma_f32_16x16x32_bf16 v[62:65], v[148:151], v[196:199], v[62:65]
	v_mfma_f32_16x16x32_bf16 v[62:65], v[154:157], v[200:203], v[62:65]
	v_mfma_f32_16x16x32_bf16 v[58:61], v[158:161], v[196:199], v[58:61]
	v_mfma_f32_16x16x32_bf16 v[58:61], v[162:165], v[200:203], v[58:61]
	v_mfma_f32_16x16x32_bf16 v[46:49], v[148:151], v[222:225], v[46:49]
	v_mfma_f32_16x16x32_bf16 v[46:49], v[154:157], v[226:229], v[46:49]
	v_mfma_f32_16x16x32_bf16 v[42:45], v[158:161], v[222:225], v[42:45]
	v_mfma_f32_16x16x32_bf16 v[42:45], v[162:165], v[226:229], v[42:45]
	v_mfma_f32_16x16x32_bf16 v[30:33], v[148:151], v[230:233], v[30:33]
	v_mfma_f32_16x16x32_bf16 v[30:33], v[154:157], v[234:237], v[30:33]
	v_mfma_f32_16x16x32_bf16 v[26:29], v[158:161], v[230:233], v[26:29]
	v_mfma_f32_16x16x32_bf16 v[26:29], v[162:165], v[234:237], v[26:29]
	v_mfma_f32_16x16x32_bf16 v[14:17], v[148:151], v[238:241], v[14:17]
	v_mfma_f32_16x16x32_bf16 v[14:17], v[154:157], v[242:245], v[14:17]
	v_mfma_f32_16x16x32_bf16 v[10:13], v[158:161], v[238:241], v[10:13]
	v_mfma_f32_16x16x32_bf16 v[10:13], v[162:165], v[242:245], v[10:13]
	s_setprio 0
	s_setprio 1
	v_mfma_f32_16x16x32_bf16 v[54:57], v[180:183], v[196:199], v[54:57]
	v_mfma_f32_16x16x32_bf16 v[54:57], v[184:187], v[200:203], v[54:57]
	v_mfma_f32_16x16x32_bf16 v[50:53], v[188:191], v[196:199], v[50:53]
	v_mfma_f32_16x16x32_bf16 v[50:53], v[192:195], v[200:203], v[50:53]
	v_mfma_f32_16x16x32_bf16 v[38:41], v[180:183], v[222:225], v[38:41]
	v_mfma_f32_16x16x32_bf16 v[38:41], v[184:187], v[226:229], v[38:41]
	v_mfma_f32_16x16x32_bf16 v[34:37], v[188:191], v[222:225], v[34:37]
	v_mfma_f32_16x16x32_bf16 v[34:37], v[192:195], v[226:229], v[34:37]
	v_mfma_f32_16x16x32_bf16 v[22:25], v[180:183], v[230:233], v[22:25]
	v_mfma_f32_16x16x32_bf16 v[22:25], v[184:187], v[234:237], v[22:25]
	v_mfma_f32_16x16x32_bf16 v[18:21], v[188:191], v[230:233], v[18:21]
	v_mfma_f32_16x16x32_bf16 v[18:21], v[192:195], v[234:237], v[18:21]
	v_mfma_f32_16x16x32_bf16 v[6:9], v[180:183], v[238:241], v[6:9]
	v_mfma_f32_16x16x32_bf16 v[6:9], v[184:187], v[242:245], v[6:9]
	s_setprio 2
	s_barrier
	v_mfma_f32_16x16x32_bf16 v[2:5], v[188:191], v[238:241], v[2:5]
	v_mfma_f32_16x16x32_bf16 v[2:5], v[192:195], v[242:245], v[2:5]
	s_setprio 0
	v_lshl_add_u64 v[144:145], v[144:145], 0, s[86:87]
	v_lshl_add_u64 v[146:147], v[146:147], 0, s[86:87]
	s_mov_b32 s29, s81
	s_cbranch_scc0 .LBB0_1157
.Lpx_1157:
	s_and_b64 vcc, exec, s[16:17]
	s_cbranch_vccz .LBB0_1160
	s_barrier

; #define PG8_STAGE(bufoff, gbase, voff) do { _Pragma("unroll") for (int _i = 0; _i < 2; ++_i) \
;         __builtin_amdgcn_global_load_lds((const unsigned*)((const char*)(gbase) + (voff)[_i]), (PG8_LAS unsigned*)(lds + (bufoff) + ldsw + _i * 8192), 16, 0, AUX_A); } while (0)
; #define PG8_STAGEB(bufoff, gbase, voff) do { _Pragma("unroll") for (int _i = 0; _i < 2; ++_i) \
;         __builtin_amdgcn_global_load_lds((const unsigned*)((const char*)(gbase) + (voff)[_i]), (PG8_LAS unsigned*)(lds + (bufoff) + ldsw + _i * 8192), 16, 0, AUX_B); } while (0)
; #define PG8_LDA(dst, b, h) do { _Pragma("unroll") for (int m = 0; m < 4; ++m) _Pragma("unroll") for (int k = 0; k < 2; ++k) dst[m][k] = *(const PG8_LAS bf16x8*)(lds + PG8_SA(b, h) + aoff + m * 2048 + k * 1024); } while (0)
; template <class Epi, class Sched, bool ALIGN_EPI = false, bool SP2 = false>
; __device__ __forceinline__ void gemm_phase(PG8_LAS unsigned char* lds, const Gemm g, const Sched& S, const Epi& E) {
;     ...
;         const char* nA = has_next ? (const char*)g.A + (size_t)nxt.pm * tstep + (size_t)nxt.kt0 * kstep : cA; const char* nB = has_next ? (const char*)g.Bt + (size_t)nxt.pn * tstep + (size_t)nxt.kt0 * kstep : cB;
;         const int nt = cur.nkt, rot = cur.krot;
;         const char* nAr = has_next ? nA + (size_t)nxt.krot * kstep : PG8_KP(cA, 0, rot, nt); const char* nBr = has_next ? nB + (size_t)nxt.krot * kstep : PG8_KP(cB, 0, rot, nt);
;         for (int t = 0; t < nt; t += 2) {
;             const bool last = (t == nt - 2);
;             const char* a1 = PG8_KP(cA, t + 1, rot, nt);
;             const char* a2 = last ? nAr : PG8_KP(cA, t + 2, rot, nt); const char* b2 = last ? nBr : PG8_KP(cB, t + 2, rot, nt);
;             const char* a3 = a2 + kstep; const char* b3 = b2 + kstep;
;             if (last && has_next) S.a_ready(nxt);
;             if constexpr (SP2) {
;             PG8_LDB(B0, 0, 0); PG8_LDB(B1, 0, 1); PG8_SCHED; PG8_LDA(At, 0, 0); PG8_STAGE(PG8_SA(1, 1), a1 + hstep, voffA);
;             PG8_WAIT_V(8); PG8_WAIT_L(0); PG8_BAR; PG8_MMA(0, 0, At, B0); PG8_MMA(0, 1, At, B1); PG8_BAR; PG8_SCHED;
;             PG8_LDA(At, 0, 1); PG8_STAGEB(PG8_SB(0, 0), b2, voffB); PG8_STAGEB(PG8_SB(0, 1), b2 + hstep, voffB); PG8_STAGE(PG8_SA(0, 0), a2, voffA);
;             PG8_WAIT_V(8); PG8_WAIT_L(0); PG8_BAR; PG8_MMA(1, 0, At, B0); PG8_MMA(1, 1, At, B1); PG8_BAR; PG8_SCHED;
.LBB0_1307:
	s_add_u32 s0, s40, 0x80080
	s_addc_u32 s1, s41, 0
	s_waitcnt vmcnt(0)
	v_lshl_add_u64 v[132:133], s[0:1], 0, v[160:161]
	v_lshl_add_u64 v[134:135], s[0:1], 0, v[162:163]
	s_mov_b32 s11, 0
	s_mov_b32 s13, 2
	s_waitcnt vmcnt(0)
	s_waitcnt lgkmcnt(0)
.Lpk_1308:
	s_or_b32 s0, s11, 1
	s_cmp_ge_i32 s0, s71
	s_cselect_b32 s2, s71, 0
	s_add_i32 s11, s11, 2
	s_cmp_ge_i32 s11, s71
	s_cselect_b32 s0, s71, 0
	s_sub_i32 s0, s13, s0
	s_ashr_i32 s1, s0, 31
	s_lshl_b64 s[0:1], s[0:1], 7
	s_add_u32 s15, s40, s0
	s_addc_u32 s29, s41, s1
	s_add_u32 s0, s34, s0
	s_addc_u32 s1, s35, s1
	s_cmp_eq_u32 s71, s13
	s_cselect_b32 s45, s43, s29
	s_cselect_b32 s44, s42, s15
	s_cselect_b32 s37, s19, s1
	s_cselect_b32 s36, s18, s0
	s_add_i32 s15, 0, 0x10000
	s_add_i32 s29, 0, 0x14000
	v_add_u32_e32 v148, s15, v99
	v_add_u32_e32 v168, s29, v99
	ds_read_b128 v[136:139], v148
	ds_read_b128 v[140:143], v148 offset:1024
	ds_read_b128 v[144:147], v148 offset:2048
	ds_read_b128 v[148:151], v148 offset:3072
	ds_read_b128 v[164:167], v168
	ds_read_b128 v[182:185], v168 offset:1024
	ds_read_b128 v[186:189], v168 offset:2048
	ds_read_b128 v[190:193], v168 offset:3072
	v_mad_i64_i32 v[168:169], s[0:1], s2, v220, v[134:135]
	s_add_i32 m0, s50, 0xc000
	ds_read_b128 v[194:197], v181
	ds_read_b128 v[198:201], v181 offset:1024
	ds_read_b128 v[222:225], v181 offset:2048
	ds_read_b128 v[226:229], v181 offset:3072
	ds_read_b128 v[230:233], v181 offset:4096
	ds_read_b128 v[234:237], v181 offset:5120
	ds_read_b128 v[238:241], v181 offset:6144
	ds_read_b128 v[242:245], v181 offset:7168
	global_load_lds_dwordx4 v[168:169], off
	v_mad_i64_i32 v[168:169], s[0:1], s2, v220, v[132:133]
	s_add_i32 m0, s50, 0xe000
	s_nop 0
	global_load_lds_dwordx4 v[168:169], off
	s_waitcnt vmcnt(8)
	s_waitcnt lgkmcnt(0)
	s_setprio 1
	s_barrier
	v_mfma_f32_16x16x32_bf16 v[128:131], v[136:139], v[194:197], 0
	v_mfma_f32_16x16x32_bf16 v[128:131], v[140:143], v[198:201], v[128:131]
	v_mfma_f32_16x16x32_bf16 v[124:127], v[144:147], v[194:197], 0
	v_mfma_f32_16x16x32_bf16 v[124:127], v[148:151], v[198:201], v[124:127]
	v_mfma_f32_16x16x32_bf16 v[120:123], v[136:139], v[222:225], 0
	v_mfma_f32_16x16x32_bf16 v[120:123], v[140:143], v[226:229], v[120:123]
	v_mfma_f32_16x16x32_bf16 v[112:115], v[144:147], v[222:225], 0
	v_mfma_f32_16x16x32_bf16 v[112:115], v[148:151], v[226:229], v[112:115]
	v_mfma_f32_16x16x32_bf16 v[104:107], v[136:139], v[230:233], 0
	v_mfma_f32_16x16x32_bf16 v[104:107], v[140:143], v[234:237], v[104:107]
	v_mfma_f32_16x16x32_bf16 v[94:97], v[144:147], v[230:233], 0
	v_mfma_f32_16x16x32_bf16 v[94:97], v[148:151], v[234:237], v[94:97]
	v_mfma_f32_16x16x32_bf16 v[86:89], v[136:139], v[238:241], 0
	v_mfma_f32_16x16x32_bf16 v[86:89], v[140:143], v[242:245], v[86:89]
	v_mfma_f32_16x16x32_bf16 v[78:81], v[144:147], v[238:241], 0
	v_mfma_f32_16x16x32_bf16 v[78:81], v[148:151], v[242:245], v[78:81]
	s_setprio 0
	s_setprio 1
	v_mfma_f32_16x16x32_bf16 v[116:119], v[164:167], v[194:197], 0
	v_mfma_f32_16x16x32_bf16 v[116:119], v[182:185], v[198:201], v[116:119]
	v_mfma_f32_16x16x32_bf16 v[108:111], v[186:189], v[194:197], 0
	v_mfma_f32_16x16x32_bf16 v[108:111], v[190:193], v[198:201], v[108:111]
	v_mfma_f32_16x16x32_bf16 v[100:103], v[164:167], v[222:225], 0
	v_mfma_f32_16x16x32_bf16 v[100:103], v[182:185], v[226:229], v[100:103]
	v_mfma_f32_16x16x32_bf16 v[90:93], v[186:189], v[222:225], 0
	v_mfma_f32_16x16x32_bf16 v[90:93], v[190:193], v[226:229], v[90:93]
	v_mfma_f32_16x16x32_bf16 v[82:85], v[164:167], v[230:233], 0
	v_mfma_f32_16x16x32_bf16 v[82:85], v[182:185], v[234:237], v[82:85]
	v_mfma_f32_16x16x32_bf16 v[74:77], v[186:189], v[230:233], 0
	v_mfma_f32_16x16x32_bf16 v[74:77], v[190:193], v[234:237], v[74:77]
	v_mfma_f32_16x16x32_bf16 v[70:73], v[164:167], v[238:241], 0
	v_mfma_f32_16x16x32_bf16 v[70:73], v[182:185], v[242:245], v[70:73]
	s_setprio 2
	s_barrier
	v_mfma_f32_16x16x32_bf16 v[66:69], v[186:189], v[238:241], 0
	v_mfma_f32_16x16x32_bf16 v[66:69], v[190:193], v[242:245], v[66:69]
	s_setprio 0
	s_add_i32 s0, s15, s49
	v_lshl_add_u64 v[168:169], s[36:37], 0, v[156:157]
	s_mov_b32 m0, s0
	ds_read_b128 v[194:197], v181 offset:16384
	ds_read_b128 v[198:201], v181 offset:17408
	ds_read_b128 v[222:225], v181 offset:18432
	ds_read_b128 v[226:229], v181 offset:19456
	ds_read_b128 v[230:233], v181 offset:20480
	ds_read_b128 v[234:237], v181 offset:21504
	ds_read_b128 v[238:241], v181 offset:22528
	ds_read_b128 v[242:245], v181 offset:23552
	global_load_lds_dwordx4 v[168:169], off
	s_add_i32 m0, s0, 0x2000
	s_add_u32 s0, s36, 0x80000
	v_lshl_add_u64 v[172:173], s[36:37], 0, v[152:153]
	s_addc_u32 s1, s37, 0
	s_add_i32 s2, s29, s49
	global_load_lds_dwordx4 v[172:173], off
	v_lshl_add_u64 v[202:203], s[0:1], 0, v[156:157]
	s_mov_b32 m0, s2
	v_lshl_add_u64 v[212:213], s[44:45], 0, v[154:155]
	global_load_lds_dwordx4 v[202:203], off
	v_lshl_add_u64 v[202:203], s[0:1], 0, v[152:153]
	s_add_i32 m0, s2, 0x2000
	s_nop 0
	global_load_lds_dwordx4 v[202:203], off
	v_lshl_add_u64 v[202:203], s[44:45], 0, v[158:159]
	s_mov_b32 m0, s50
	s_nop 0
	global_load_lds_dwordx4 v[202:203], off
	s_mov_b32 m0, s51
	s_nop 0
	global_load_lds_dwordx4 v[212:213], off
	s_waitcnt vmcnt(8)
	s_waitcnt lgkmcnt(0)
	s_setprio 1
	s_barrier
; #define PG8_STAGE(bufoff, gbase, voff) do { _Pragma("unroll") for (int _i = 0; _i < 2; ++_i) \
;         __builtin_amdgcn_global_load_lds((const unsigned*)((const char*)(gbase) + (voff)[_i]), (PG8_LAS unsigned*)(lds + (bufoff) + ldsw + _i * 8192), 16, 0, AUX_A); } while (0)
; #define PG8_STAGEB(bufoff, gbase, voff) do { _Pragma("unroll") for (int _i = 0; _i < 2; ++_i) \
;         __builtin_amdgcn_global_load_lds((const unsigned*)((const char*)(gbase) + (voff)[_i]), (PG8_LAS unsigned*)(lds + (bufoff) + ldsw + _i * 8192), 16, 0, AUX_B); } while (0)
; #define PG8_LDA(dst, b, h) do { _Pragma("unroll") for (int m = 0; m < 4; ++m) _Pragma("unroll") for (int k = 0; k < 2; ++k) dst[m][k] = *(const PG8_LAS bf16x8*)(lds + PG8_SA(b, h) + aoff + m * 2048 + k * 1024); } while (0)
; #define PG8_LDB(dst, b, h) do { _Pragma("unroll") for (int n = 0; n < 2; ++n) _Pragma("unroll") for (int k = 0; k < 2; ++k) dst[n][k] = *(const PG8_LAS bf16x8*)(lds + PG8_SB(b, h) + boff + n * 2048 + k * 1024); } while (0)
; #define PG8_MMA(ai, bj, At, Bt) do { __builtin_amdgcn_s_setprio(1); _Pragma("unroll") for (int m = 0; m < 4; ++m) _Pragma("unroll") for (int n = 0; n < 2; ++n) _Pragma("unroll") for (int k = 0; k < 2; ++k) \
;         acc[ai][bj][m][n] = __builtin_amdgcn_mfma_f32_16x16x32_bf16(Bt[n][k], At[m][k], acc[ai][bj][m][n], 0, 0, 0); __builtin_amdgcn_s_setprio(0); } while (0)
; #define PG8_WAIT_V(n) asm volatile("s_waitcnt vmcnt(" #n ")" ::: "memory")
; #define PG8_WAIT_L(n) asm volatile("s_waitcnt lgkmcnt(" #n ")" ::: "memory")
; #define PG8_BAR __builtin_amdgcn_s_barrier()
; #define PG8_SCHED __builtin_amdgcn_sched_barrier(0)
; template <class Epi, class Sched, bool ALIGN_EPI = false, bool SP2 = false>
; __device__ __forceinline__ void gemm_phase(PG8_LAS unsigned char* lds, const Gemm g, const Sched& S, const Epi& E) {
;     ...
;             PG8_LDA(At, 0, 1); PG8_STAGEB(PG8_SB(0, 0), b2, voffB); PG8_STAGEB(PG8_SB(0, 1), b2 + hstep, voffB); PG8_STAGE(PG8_SA(0, 0), a2, voffA);
;             PG8_WAIT_V(8); PG8_WAIT_L(0); PG8_BAR; PG8_MMA(1, 0, At, B0); PG8_MMA(1, 1, At, B1); PG8_BAR; PG8_SCHED;
;             PG8_LDB(B0, 1, 0); PG8_LDB(B1, 1, 1); PG8_SCHED; PG8_LDA(At, 1, 0); PG8_STAGE(PG8_SA(0, 1), a2 + hstep, voffA);
;             PG8_WAIT_V(8); PG8_WAIT_L(0); PG8_BAR; PG8_MMA(0, 0, At, B0); PG8_MMA(0, 1, At, B1); PG8_BAR; PG8_SCHED;
	v_mfma_f32_16x16x32_bf16 v[62:65], v[136:139], v[194:197], 0
	v_mfma_f32_16x16x32_bf16 v[62:65], v[140:143], v[198:201], v[62:65]
	v_mfma_f32_16x16x32_bf16 v[58:61], v[144:147], v[194:197], 0
	v_mfma_f32_16x16x32_bf16 v[58:61], v[148:151], v[198:201], v[58:61]
	v_mfma_f32_16x16x32_bf16 v[54:57], v[136:139], v[222:225], 0
	v_mfma_f32_16x16x32_bf16 v[54:57], v[140:143], v[226:229], v[54:57]
	v_mfma_f32_16x16x32_bf16 v[46:49], v[144:147], v[222:225], 0
	v_mfma_f32_16x16x32_bf16 v[46:49], v[148:151], v[226:229], v[46:49]
	v_mfma_f32_16x16x32_bf16 v[38:41], v[136:139], v[230:233], 0
	v_mfma_f32_16x16x32_bf16 v[38:41], v[140:143], v[234:237], v[38:41]
	v_mfma_f32_16x16x32_bf16 v[30:33], v[144:147], v[230:233], 0
	v_mfma_f32_16x16x32_bf16 v[30:33], v[148:151], v[234:237], v[30:33]
	v_mfma_f32_16x16x32_bf16 v[22:25], v[136:139], v[238:241], 0
	v_mfma_f32_16x16x32_bf16 v[22:25], v[140:143], v[242:245], v[22:25]
	v_mfma_f32_16x16x32_bf16 v[14:17], v[144:147], v[238:241], 0
	v_mfma_f32_16x16x32_bf16 v[14:17], v[148:151], v[242:245], v[14:17]
	s_setprio 0
	s_setprio 1
	v_mfma_f32_16x16x32_bf16 v[50:53], v[164:167], v[194:197], 0
	v_mfma_f32_16x16x32_bf16 v[50:53], v[182:185], v[198:201], v[50:53]
	v_mfma_f32_16x16x32_bf16 v[42:45], v[186:189], v[194:197], 0
	v_mfma_f32_16x16x32_bf16 v[42:45], v[190:193], v[198:201], v[42:45]
	v_mfma_f32_16x16x32_bf16 v[34:37], v[164:167], v[222:225], 0
	v_mfma_f32_16x16x32_bf16 v[34:37], v[182:185], v[226:229], v[34:37]
	v_mfma_f32_16x16x32_bf16 v[26:29], v[186:189], v[222:225], 0
	v_mfma_f32_16x16x32_bf16 v[26:29], v[190:193], v[226:229], v[26:29]
	v_mfma_f32_16x16x32_bf16 v[18:21], v[164:167], v[230:233], 0
	v_mfma_f32_16x16x32_bf16 v[18:21], v[182:185], v[234:237], v[18:21]
	v_mfma_f32_16x16x32_bf16 v[10:13], v[186:189], v[230:233], 0
	v_mfma_f32_16x16x32_bf16 v[10:13], v[190:193], v[234:237], v[10:13]
	v_mfma_f32_16x16x32_bf16 v[6:9], v[164:167], v[238:241], 0
	v_mfma_f32_16x16x32_bf16 v[6:9], v[182:185], v[242:245], v[6:9]
	s_setprio 2
	s_barrier
	v_mfma_f32_16x16x32_bf16 v[2:5], v[186:189], v[238:241], 0
	v_mfma_f32_16x16x32_bf16 v[2:5], v[190:193], v[242:245], v[2:5]
	s_setprio 0
	s_add_i32 s2, 0, 0x18000
	s_add_i32 s15, 0, 0x1c000
	v_add_u32_e32 v148, s2, v99
	v_add_u32_e32 v190, s15, v99
	ds_read_b128 v[136:139], v148
	ds_read_b128 v[140:143], v148 offset:1024
	ds_read_b128 v[144:147], v148 offset:2048
	ds_read_b128 v[148:151], v148 offset:3072
	ds_read_b128 v[164:167], v190
	ds_read_b128 v[182:185], v190 offset:1024
	ds_read_b128 v[186:189], v190 offset:2048
	ds_read_b128 v[190:193], v190 offset:3072
	s_add_u32 s0, s44, 0x80000
	s_addc_u32 s1, s45, 0
	s_mov_b32 m0, s52
	v_lshl_add_u64 v[246:247], s[0:1], 0, v[158:159]
	ds_read_b128 v[194:197], v181 offset:32768
	ds_read_b128 v[198:201], v181 offset:33792
	ds_read_b128 v[222:225], v181 offset:34816
	ds_read_b128 v[226:229], v181 offset:35840
	ds_read_b128 v[230:233], v181 offset:36864
	ds_read_b128 v[234:237], v181 offset:37888
	ds_read_b128 v[238:241], v181 offset:38912
	ds_read_b128 v[242:245], v181 offset:39936
	global_load_lds_dwordx4 v[246:247], off
	v_lshl_add_u64 v[246:247], s[0:1], 0, v[154:155]
	s_mov_b32 m0, s53
	s_nop 0
	global_load_lds_dwordx4 v[246:247], off
	s_waitcnt vmcnt(8)
	s_waitcnt lgkmcnt(0)
	s_setprio 1
	s_barrier
	v_mfma_f32_16x16x32_bf16 v[128:131], v[136:139], v[194:197], v[128:131]
	v_mfma_f32_16x16x32_bf16 v[128:131], v[140:143], v[198:201], v[128:131]
	v_mfma_f32_16x16x32_bf16 v[124:127], v[144:147], v[194:197], v[124:127]
	v_mfma_f32_16x16x32_bf16 v[124:127], v[148:151], v[198:201], v[124:127]
	v_mfma_f32_16x16x32_bf16 v[120:123], v[136:139], v[222:225], v[120:123]
	v_mfma_f32_16x16x32_bf16 v[120:123], v[140:143], v[226:229], v[120:123]
	v_mfma_f32_16x16x32_bf16 v[112:115], v[144:147], v[222:225], v[112:115]
	v_mfma_f32_16x16x32_bf16 v[112:115], v[148:151], v[226:229], v[112:115]
	v_mfma_f32_16x16x32_bf16 v[104:107], v[136:139], v[230:233], v[104:107]
	v_mfma_f32_16x16x32_bf16 v[104:107], v[140:143], v[234:237], v[104:107]
	v_mfma_f32_16x16x32_bf16 v[94:97], v[144:147], v[230:233], v[94:97]
	v_mfma_f32_16x16x32_bf16 v[94:97], v[148:151], v[234:237], v[94:97]
	v_mfma_f32_16x16x32_bf16 v[86:89], v[136:139], v[238:241], v[86:89]
	v_mfma_f32_16x16x32_bf16 v[86:89], v[140:143], v[242:245], v[86:89]
	v_mfma_f32_16x16x32_bf16 v[78:81], v[144:147], v[238:241], v[78:81]
	v_mfma_f32_16x16x32_bf16 v[78:81], v[148:151], v[242:245], v[78:81]
	s_setprio 0
	s_setprio 1
	v_mfma_f32_16x16x32_bf16 v[116:119], v[164:167], v[194:197], v[116:119]
	v_mfma_f32_16x16x32_bf16 v[116:119], v[182:185], v[198:201], v[116:119]
	v_mfma_f32_16x16x32_bf16 v[108:111], v[186:189], v[194:197], v[108:111]
	v_mfma_f32_16x16x32_bf16 v[108:111], v[190:193], v[198:201], v[108:111]
	v_mfma_f32_16x16x32_bf16 v[100:103], v[164:167], v[222:225], v[100:103]
	v_mfma_f32_16x16x32_bf16 v[100:103], v[182:185], v[226:229], v[100:103]
	v_mfma_f32_16x16x32_bf16 v[90:93], v[186:189], v[222:225], v[90:93]
	v_mfma_f32_16x16x32_bf16 v[90:93], v[190:193], v[226:229], v[90:93]
	v_mfma_f32_16x16x32_bf16 v[82:85], v[164:167], v[230:233], v[82:85]
	v_mfma_f32_16x16x32_bf16 v[82:85], v[182:185], v[234:237], v[82:85]
	v_mfma_f32_16x16x32_bf16 v[74:77], v[186:189], v[230:233], v[74:77]
	v_mfma_f32_16x16x32_bf16 v[74:77], v[190:193], v[234:237], v[74:77]
	v_mfma_f32_16x16x32_bf16 v[70:73], v[164:167], v[238:241], v[70:73]
	v_mfma_f32_16x16x32_bf16 v[70:73], v[182:185], v[242:245], v[70:73]
	s_setprio 2
	s_barrier
; #define PG8_STAGE(bufoff, gbase, voff) do { _Pragma("unroll") for (int _i = 0; _i < 2; ++_i) \
;         __builtin_amdgcn_global_load_lds((const unsigned*)((const char*)(gbase) + (voff)[_i]), (PG8_LAS unsigned*)(lds + (bufoff) + ldsw + _i * 8192), 16, 0, AUX_A); } while (0)
; #define PG8_STAGEB(bufoff, gbase, voff) do { _Pragma("unroll") for (int _i = 0; _i < 2; ++_i) \
;         __builtin_amdgcn_global_load_lds((const unsigned*)((const char*)(gbase) + (voff)[_i]), (PG8_LAS unsigned*)(lds + (bufoff) + ldsw + _i * 8192), 16, 0, AUX_B); } while (0)
; #define PG8_WAIT_V(n) asm volatile("s_waitcnt vmcnt(" #n ")" ::: "memory")
; #define PG8_WAIT_L(n) asm volatile("s_waitcnt lgkmcnt(" #n ")" ::: "memory")
; template <class Epi, class Sched, bool ALIGN_EPI = false, bool SP2 = false>
; __device__ __forceinline__ void gemm_phase(PG8_LAS unsigned char* lds, const Gemm g, const Sched& S, const Epi& E) {
;     ...
;         for (int t = 0; t < nt; t += 2) {
;             const bool last = (t == nt - 2);
;             const char* a1 = PG8_KP(cA, t + 1, rot, nt);
;             const char* a2 = last ? nAr : PG8_KP(cA, t + 2, rot, nt); const char* b2 = last ? nBr : PG8_KP(cB, t + 2, rot, nt);
;             const char* a3 = a2 + kstep; const char* b3 = b2 + kstep;
;             if (last && has_next) S.a_ready(nxt);
;             if constexpr (SP2) {
;             PG8_LDB(B0, 0, 0); PG8_LDB(B1, 0, 1); PG8_SCHED; PG8_LDA(At, 0, 0); PG8_STAGE(PG8_SA(1, 1), a1 + hstep, voffA);
;             PG8_WAIT_V(8); PG8_WAIT_L(0); PG8_BAR; PG8_MMA(0, 0, At, B0); PG8_MMA(0, 1, At, B1); PG8_BAR; PG8_SCHED;
;             PG8_LDA(At, 0, 1); PG8_STAGEB(PG8_SB(0, 0), b2, voffB); PG8_STAGEB(PG8_SB(0, 1), b2 + hstep, voffB); PG8_STAGE(PG8_SA(0, 0), a2, voffA);
;             PG8_WAIT_V(8); PG8_WAIT_L(0); PG8_BAR; PG8_MMA(1, 0, At, B0); PG8_MMA(1, 1, At, B1); PG8_BAR; PG8_SCHED;
;             PG8_LDB(B0, 1, 0); PG8_LDB(B1, 1, 1); PG8_SCHED; PG8_LDA(At, 1, 0); PG8_STAGE(PG8_SA(0, 1), a2 + hstep, voffA);
;             PG8_WAIT_V(8); PG8_WAIT_L(0); PG8_BAR; PG8_MMA(0, 0, At, B0); PG8_MMA(0, 1, At, B1); PG8_BAR; PG8_SCHED;
;             PG8_LDA(At, 1, 1); PG8_STAGEB(PG8_SB(1, 0), b3, voffB); PG8_STAGEB(PG8_SB(1, 1), b3 + hstep, voffB); PG8_STAGE(PG8_SA(1, 0), a3, voffA);
;             PG8_WAIT_V(8); PG8_WAIT_L(0); PG8_BAR; PG8_MMA(1, 0, At, B0); PG8_MMA(1, 1, At, B1); PG8_BAR; PG8_SCHED;
	v_mfma_f32_16x16x32_bf16 v[66:69], v[186:189], v[238:241], v[66:69]
	v_mfma_f32_16x16x32_bf16 v[66:69], v[190:193], v[242:245], v[66:69]
	s_setprio 0
	s_add_i32 s0, s2, s49
	v_lshl_add_u64 v[168:169], v[168:169], 0, s[76:77]
	s_mov_b32 m0, s0
	ds_read_b128 v[194:197], v181 offset:49152
	ds_read_b128 v[198:201], v181 offset:50176
	ds_read_b128 v[222:225], v181 offset:51200
	ds_read_b128 v[226:229], v181 offset:52224
	ds_read_b128 v[230:233], v181 offset:53248
	ds_read_b128 v[234:237], v181 offset:54272
	ds_read_b128 v[238:241], v181 offset:55296
	ds_read_b128 v[242:245], v181 offset:56320
	global_load_lds_dwordx4 v[168:169], off
	s_add_i32 m0, s0, 0x2000
	s_add_u32 s0, s36, 0x80080
	v_lshl_add_u64 v[168:169], v[172:173], 0, s[76:77]
	s_addc_u32 s1, s37, 0
	s_add_i32 s2, s15, s49
	global_load_lds_dwordx4 v[168:169], off
	v_lshl_add_u64 v[168:169], s[0:1], 0, v[156:157]
	s_mov_b32 m0, s2
	s_nop 0
	global_load_lds_dwordx4 v[168:169], off
	v_lshl_add_u64 v[168:169], s[0:1], 0, v[152:153]
	s_add_i32 m0, s2, 0x2000
	s_nop 0
	global_load_lds_dwordx4 v[168:169], off
	v_lshl_add_u64 v[168:169], v[202:203], 0, s[76:77]
	s_mov_b32 m0, s59
	s_nop 0
	global_load_lds_dwordx4 v[168:169], off
	v_lshl_add_u64 v[168:169], v[212:213], 0, s[76:77]
	s_mov_b32 m0, s60
	s_nop 0
	global_load_lds_dwordx4 v[168:169], off
	s_waitcnt vmcnt(8)
	s_waitcnt lgkmcnt(0)
	s_setprio 1
	s_barrier
	v_mfma_f32_16x16x32_bf16 v[62:65], v[136:139], v[194:197], v[62:65]
	v_mfma_f32_16x16x32_bf16 v[62:65], v[140:143], v[198:201], v[62:65]
	v_mfma_f32_16x16x32_bf16 v[58:61], v[144:147], v[194:197], v[58:61]
	v_mfma_f32_16x16x32_bf16 v[58:61], v[148:151], v[198:201], v[58:61]
	v_mfma_f32_16x16x32_bf16 v[54:57], v[136:139], v[222:225], v[54:57]
	v_mfma_f32_16x16x32_bf16 v[54:57], v[140:143], v[226:229], v[54:57]
	v_mfma_f32_16x16x32_bf16 v[46:49], v[144:147], v[222:225], v[46:49]
	v_mfma_f32_16x16x32_bf16 v[46:49], v[148:151], v[226:229], v[46:49]
	v_mfma_f32_16x16x32_bf16 v[38:41], v[136:139], v[230:233], v[38:41]
	v_mfma_f32_16x16x32_bf16 v[38:41], v[140:143], v[234:237], v[38:41]
	v_mfma_f32_16x16x32_bf16 v[30:33], v[144:147], v[230:233], v[30:33]
	v_mfma_f32_16x16x32_bf16 v[30:33], v[148:151], v[234:237], v[30:33]
	v_mfma_f32_16x16x32_bf16 v[22:25], v[136:139], v[238:241], v[22:25]
	v_mfma_f32_16x16x32_bf16 v[22:25], v[140:143], v[242:245], v[22:25]
	v_mfma_f32_16x16x32_bf16 v[14:17], v[144:147], v[238:241], v[14:17]
	v_mfma_f32_16x16x32_bf16 v[14:17], v[148:151], v[242:245], v[14:17]
	s_setprio 0
	s_setprio 1
	v_mfma_f32_16x16x32_bf16 v[50:53], v[164:167], v[194:197], v[50:53]
	v_mfma_f32_16x16x32_bf16 v[50:53], v[182:185], v[198:201], v[50:53]
	v_mfma_f32_16x16x32_bf16 v[42:45], v[186:189], v[194:197], v[42:45]
	v_mfma_f32_16x16x32_bf16 v[42:45], v[190:193], v[198:201], v[42:45]
	v_mfma_f32_16x16x32_bf16 v[34:37], v[164:167], v[222:225], v[34:37]
	v_mfma_f32_16x16x32_bf16 v[34:37], v[182:185], v[226:229], v[34:37]
	v_mfma_f32_16x16x32_bf16 v[26:29], v[186:189], v[222:225], v[26:29]
	v_mfma_f32_16x16x32_bf16 v[26:29], v[190:193], v[226:229], v[26:29]
	v_mfma_f32_16x16x32_bf16 v[18:21], v[164:167], v[230:233], v[18:21]
	v_mfma_f32_16x16x32_bf16 v[18:21], v[182:185], v[234:237], v[18:21]
	v_mfma_f32_16x16x32_bf16 v[10:13], v[186:189], v[230:233], v[10:13]
	v_mfma_f32_16x16x32_bf16 v[10:13], v[190:193], v[234:237], v[10:13]
	v_mfma_f32_16x16x32_bf16 v[6:9], v[164:167], v[238:241], v[6:9]
	v_mfma_f32_16x16x32_bf16 v[6:9], v[182:185], v[242:245], v[6:9]
	s_setprio 2
	s_barrier
	v_mfma_f32_16x16x32_bf16 v[2:5], v[186:189], v[238:241], v[2:5]
	v_mfma_f32_16x16x32_bf16 v[2:5], v[190:193], v[242:245], v[2:5]
	s_setprio 0
	s_add_i32 s0, s13, 2
	v_lshl_add_u64 v[132:133], v[132:133], 0, s[86:87]
	v_lshl_add_u64 v[134:135], v[134:135], 0, s[86:87]
	s_cmp_ge_i32 s13, s71
	s_mov_b32 s13, s0
	s_cbranch_scc1 .Lpx_1308
.LBB0_1308:
	s_or_b32 s0, s11, 1
	s_cmp_ge_i32 s0, s71
	s_cselect_b32 s2, s71, 0
	s_add_i32 s11, s11, 2
	s_cmp_ge_i32 s11, s71
	s_cselect_b32 s0, s71, 0
	s_sub_i32 s0, s13, s0
	s_ashr_i32 s1, s0, 31
	s_lshl_b64 s[0:1], s[0:1], 7
	s_add_u32 s15, s40, s0
	s_addc_u32 s29, s41, s1
	s_add_u32 s0, s34, s0
	s_addc_u32 s1, s35, s1
	s_cmp_eq_u32 s71, s13
	s_cselect_b32 s45, s43, s29
	s_cselect_b32 s44, s42, s15
	s_cselect_b32 s37, s19, s1
	s_cselect_b32 s36, s18, s0
	s_add_i32 s15, 0, 0x10000
	s_add_i32 s29, 0, 0x14000
	v_add_u32_e32 v148, s15, v99
	v_add_u32_e32 v168, s29, v99
	ds_read_b128 v[136:139], v148
	ds_read_b128 v[140:143], v148 offset:1024
	ds_read_b128 v[144:147], v148 offset:2048
	ds_read_b128 v[148:151], v148 offset:3072
	ds_read_b128 v[164:167], v168
	ds_read_b128 v[182:185], v168 offset:1024
	ds_read_b128 v[186:189], v168 offset:2048
	ds_read_b128 v[190:193], v168 offset:3072
	v_mad_i64_i32 v[168:169], s[0:1], s2, v220, v[134:135]
	s_add_i32 m0, s50, 0xc000
	ds_read_b128 v[194:197], v181
	ds_read_b128 v[198:201], v181 offset:1024
	ds_read_b128 v[222:225], v181 offset:2048
	ds_read_b128 v[226:229], v181 offset:3072
	ds_read_b128 v[230:233], v181 offset:4096
	ds_read_b128 v[234:237], v181 offset:5120
	ds_read_b128 v[238:241], v181 offset:6144
	ds_read_b128 v[242:245], v181 offset:7168
	global_load_lds_dwordx4 v[168:169], off
	v_mad_i64_i32 v[168:169], s[0:1], s2, v220, v[132:133]
	s_add_i32 m0, s50, 0xe000
	s_nop 0
	global_load_lds_dwordx4 v[168:169], off
	s_waitcnt vmcnt(8)
	s_waitcnt lgkmcnt(0)
	s_setprio 1
	s_barrier
; #define PG8_STAGE(bufoff, gbase, voff) do { _Pragma("unroll") for (int _i = 0; _i < 2; ++_i) \
;         __builtin_amdgcn_global_load_lds((const unsigned*)((const char*)(gbase) + (voff)[_i]), (PG8_LAS unsigned*)(lds + (bufoff) + ldsw + _i * 8192), 16, 0, AUX_A); } while (0)
; #define PG8_STAGEB(bufoff, gbase, voff) do { _Pragma("unroll") for (int _i = 0; _i < 2; ++_i) \
;         __builtin_amdgcn_global_load_lds((const unsigned*)((const char*)(gbase) + (voff)[_i]), (PG8_LAS unsigned*)(lds + (bufoff) + ldsw + _i * 8192), 16, 0, AUX_B); } while (0)
; #define PG8_LDA(dst, b, h) do { _Pragma("unroll") for (int m = 0; m < 4; ++m) _Pragma("unroll") for (int k = 0; k < 2; ++k) dst[m][k] = *(const PG8_LAS bf16x8*)(lds + PG8_SA(b, h) + aoff + m * 2048 + k * 1024); } while (0)
; #define PG8_LDB(dst, b, h) do { _Pragma("unroll") for (int n = 0; n < 2; ++n) _Pragma("unroll") for (int k = 0; k < 2; ++k) dst[n][k] = *(const PG8_LAS bf16x8*)(lds + PG8_SB(b, h) + boff + n * 2048 + k * 1024); } while (0)
; #define PG8_MMA(ai, bj, At, Bt) do { __builtin_amdgcn_s_setprio(1); _Pragma("unroll") for (int m = 0; m < 4; ++m) _Pragma("unroll") for (int n = 0; n < 2; ++n) _Pragma("unroll") for (int k = 0; k < 2; ++k) \
;         acc[ai][bj][m][n] = __builtin_amdgcn_mfma_f32_16x16x32_bf16(Bt[n][k], At[m][k], acc[ai][bj][m][n], 0, 0, 0); __builtin_amdgcn_s_setprio(0); } while (0)
; #define PG8_BAR __builtin_amdgcn_s_barrier()
; template <class Epi, class Sched, bool ALIGN_EPI = false, bool SP2 = false>
; __device__ __forceinline__ void gemm_phase(PG8_LAS unsigned char* lds, const Gemm g, const Sched& S, const Epi& E) {
;     ...
;             PG8_LDB(B0, 0, 0); PG8_LDB(B1, 0, 1); PG8_SCHED; PG8_LDA(At, 0, 0); PG8_STAGE(PG8_SA(1, 1), a1 + hstep, voffA);
;             PG8_WAIT_V(8); PG8_WAIT_L(0); PG8_BAR; PG8_MMA(0, 0, At, B0); PG8_MMA(0, 1, At, B1); PG8_BAR; PG8_SCHED;
;             PG8_LDA(At, 0, 1); PG8_STAGEB(PG8_SB(0, 0), b2, voffB); PG8_STAGEB(PG8_SB(0, 1), b2 + hstep, voffB); PG8_STAGE(PG8_SA(0, 0), a2, voffA);
;             PG8_WAIT_V(8); PG8_WAIT_L(0); PG8_BAR; PG8_MMA(1, 0, At, B0); PG8_MMA(1, 1, At, B1); PG8_BAR; PG8_SCHED;
;             PG8_LDB(B0, 1, 0); PG8_LDB(B1, 1, 1); PG8_SCHED; PG8_LDA(At, 1, 0); PG8_STAGE(PG8_SA(0, 1), a2 + hstep, voffA);
;             PG8_WAIT_V(8); PG8_WAIT_L(0); PG8_BAR; PG8_MMA(0, 0, At, B0); PG8_MMA(0, 1, At, B1); PG8_BAR; PG8_SCHED;
	v_mfma_f32_16x16x32_bf16 v[128:131], v[136:139], v[194:197], v[128:131]
	v_mfma_f32_16x16x32_bf16 v[128:131], v[140:143], v[198:201], v[128:131]
	v_mfma_f32_16x16x32_bf16 v[124:127], v[144:147], v[194:197], v[124:127]
	v_mfma_f32_16x16x32_bf16 v[124:127], v[148:151], v[198:201], v[124:127]
	v_mfma_f32_16x16x32_bf16 v[120:123], v[136:139], v[222:225], v[120:123]
	v_mfma_f32_16x16x32_bf16 v[120:123], v[140:143], v[226:229], v[120:123]
	v_mfma_f32_16x16x32_bf16 v[112:115], v[144:147], v[222:225], v[112:115]
	v_mfma_f32_16x16x32_bf16 v[112:115], v[148:151], v[226:229], v[112:115]
	v_mfma_f32_16x16x32_bf16 v[104:107], v[136:139], v[230:233], v[104:107]
	v_mfma_f32_16x16x32_bf16 v[104:107], v[140:143], v[234:237], v[104:107]
	v_mfma_f32_16x16x32_bf16 v[94:97], v[144:147], v[230:233], v[94:97]
	v_mfma_f32_16x16x32_bf16 v[94:97], v[148:151], v[234:237], v[94:97]
	v_mfma_f32_16x16x32_bf16 v[86:89], v[136:139], v[238:241], v[86:89]
	v_mfma_f32_16x16x32_bf16 v[86:89], v[140:143], v[242:245], v[86:89]
	v_mfma_f32_16x16x32_bf16 v[78:81], v[144:147], v[238:241], v[78:81]
	v_mfma_f32_16x16x32_bf16 v[78:81], v[148:151], v[242:245], v[78:81]
	s_setprio 0
	s_setprio 1
	v_mfma_f32_16x16x32_bf16 v[116:119], v[164:167], v[194:197], v[116:119]
	v_mfma_f32_16x16x32_bf16 v[116:119], v[182:185], v[198:201], v[116:119]
	v_mfma_f32_16x16x32_bf16 v[108:111], v[186:189], v[194:197], v[108:111]
	v_mfma_f32_16x16x32_bf16 v[108:111], v[190:193], v[198:201], v[108:111]
	v_mfma_f32_16x16x32_bf16 v[100:103], v[164:167], v[222:225], v[100:103]
	v_mfma_f32_16x16x32_bf16 v[100:103], v[182:185], v[226:229], v[100:103]
	v_mfma_f32_16x16x32_bf16 v[90:93], v[186:189], v[222:225], v[90:93]
	v_mfma_f32_16x16x32_bf16 v[90:93], v[190:193], v[226:229], v[90:93]
	v_mfma_f32_16x16x32_bf16 v[82:85], v[164:167], v[230:233], v[82:85]
	v_mfma_f32_16x16x32_bf16 v[82:85], v[182:185], v[234:237], v[82:85]
	v_mfma_f32_16x16x32_bf16 v[74:77], v[186:189], v[230:233], v[74:77]
	v_mfma_f32_16x16x32_bf16 v[74:77], v[190:193], v[234:237], v[74:77]
	v_mfma_f32_16x16x32_bf16 v[70:73], v[164:167], v[238:241], v[70:73]
	v_mfma_f32_16x16x32_bf16 v[70:73], v[182:185], v[242:245], v[70:73]
	s_setprio 2
	s_barrier
	v_mfma_f32_16x16x32_bf16 v[66:69], v[186:189], v[238:241], v[66:69]
	v_mfma_f32_16x16x32_bf16 v[66:69], v[190:193], v[242:245], v[66:69]
	s_setprio 0
	s_add_i32 s0, s15, s49
	v_lshl_add_u64 v[168:169], s[36:37], 0, v[156:157]
	s_mov_b32 m0, s0
	ds_read_b128 v[194:197], v181 offset:16384
	ds_read_b128 v[198:201], v181 offset:17408
	ds_read_b128 v[222:225], v181 offset:18432
	ds_read_b128 v[226:229], v181 offset:19456
	ds_read_b128 v[230:233], v181 offset:20480
	ds_read_b128 v[234:237], v181 offset:21504
	ds_read_b128 v[238:241], v181 offset:22528
	ds_read_b128 v[242:245], v181 offset:23552
	global_load_lds_dwordx4 v[168:169], off
	s_add_i32 m0, s0, 0x2000
	s_add_u32 s0, s36, 0x80000
	v_lshl_add_u64 v[172:173], s[36:37], 0, v[152:153]
	s_addc_u32 s1, s37, 0
	s_add_i32 s2, s29, s49
	global_load_lds_dwordx4 v[172:173], off
	v_lshl_add_u64 v[202:203], s[0:1], 0, v[156:157]
	s_mov_b32 m0, s2
	v_lshl_add_u64 v[212:213], s[44:45], 0, v[154:155]
	global_load_lds_dwordx4 v[202:203], off
	v_lshl_add_u64 v[202:203], s[0:1], 0, v[152:153]
	s_add_i32 m0, s2, 0x2000
	s_nop 0
	global_load_lds_dwordx4 v[202:203], off
	v_lshl_add_u64 v[202:203], s[44:45], 0, v[158:159]
	s_mov_b32 m0, s50
	s_nop 0
	global_load_lds_dwordx4 v[202:203], off
	s_mov_b32 m0, s51
	s_nop 0
	global_load_lds_dwordx4 v[212:213], off
	s_waitcnt vmcnt(8)
	s_waitcnt lgkmcnt(0)
	s_setprio 1
	s_barrier
	v_mfma_f32_16x16x32_bf16 v[62:65], v[136:139], v[194:197], v[62:65]
	v_mfma_f32_16x16x32_bf16 v[62:65], v[140:143], v[198:201], v[62:65]
	v_mfma_f32_16x16x32_bf16 v[58:61], v[144:147], v[194:197], v[58:61]
	v_mfma_f32_16x16x32_bf16 v[58:61], v[148:151], v[198:201], v[58:61]
	v_mfma_f32_16x16x32_bf16 v[54:57], v[136:139], v[222:225], v[54:57]
	v_mfma_f32_16x16x32_bf16 v[54:57], v[140:143], v[226:229], v[54:57]
	v_mfma_f32_16x16x32_bf16 v[46:49], v[144:147], v[222:225], v[46:49]
	v_mfma_f32_16x16x32_bf16 v[46:49], v[148:151], v[226:229], v[46:49]
	v_mfma_f32_16x16x32_bf16 v[38:41], v[136:139], v[230:233], v[38:41]
	v_mfma_f32_16x16x32_bf16 v[38:41], v[140:143], v[234:237], v[38:41]
	v_mfma_f32_16x16x32_bf16 v[30:33], v[144:147], v[230:233], v[30:33]
	v_mfma_f32_16x16x32_bf16 v[30:33], v[148:151], v[234:237], v[30:33]
	v_mfma_f32_16x16x32_bf16 v[22:25], v[136:139], v[238:241], v[22:25]
	v_mfma_f32_16x16x32_bf16 v[22:25], v[140:143], v[242:245], v[22:25]
	v_mfma_f32_16x16x32_bf16 v[14:17], v[144:147], v[238:241], v[14:17]
	v_mfma_f32_16x16x32_bf16 v[14:17], v[148:151], v[242:245], v[14:17]
	s_setprio 0
	s_setprio 1
	v_mfma_f32_16x16x32_bf16 v[50:53], v[164:167], v[194:197], v[50:53]
	v_mfma_f32_16x16x32_bf16 v[50:53], v[182:185], v[198:201], v[50:53]
	v_mfma_f32_16x16x32_bf16 v[42:45], v[186:189], v[194:197], v[42:45]
	v_mfma_f32_16x16x32_bf16 v[42:45], v[190:193], v[198:201], v[42:45]
	v_mfma_f32_16x16x32_bf16 v[34:37], v[164:167], v[222:225], v[34:37]
	v_mfma_f32_16x16x32_bf16 v[34:37], v[182:185], v[226:229], v[34:37]
	v_mfma_f32_16x16x32_bf16 v[26:29], v[186:189], v[222:225], v[26:29]
	v_mfma_f32_16x16x32_bf16 v[26:29], v[190:193], v[226:229], v[26:29]
	v_mfma_f32_16x16x32_bf16 v[18:21], v[164:167], v[230:233], v[18:21]
	v_mfma_f32_16x16x32_bf16 v[18:21], v[182:185], v[234:237], v[18:21]
	v_mfma_f32_16x16x32_bf16 v[10:13], v[186:189], v[230:233], v[10:13]
	v_mfma_f32_16x16x32_bf16 v[10:13], v[190:193], v[234:237], v[10:13]
	v_mfma_f32_16x16x32_bf16 v[6:9], v[164:167], v[238:241], v[6:9]
	v_mfma_f32_16x16x32_bf16 v[6:9], v[182:185], v[242:245], v[6:9]
	s_setprio 2
	s_barrier
; #define PG8_STAGE(bufoff, gbase, voff) do { _Pragma("unroll") for (int _i = 0; _i < 2; ++_i) \
;         __builtin_amdgcn_global_load_lds((const unsigned*)((const char*)(gbase) + (voff)[_i]), (PG8_LAS unsigned*)(lds + (bufoff) + ldsw + _i * 8192), 16, 0, AUX_A); } while (0)
; #define PG8_STAGEB(bufoff, gbase, voff) do { _Pragma("unroll") for (int _i = 0; _i < 2; ++_i) \
;         __builtin_amdgcn_global_load_lds((const unsigned*)((const char*)(gbase) + (voff)[_i]), (PG8_LAS unsigned*)(lds + (bufoff) + ldsw + _i * 8192), 16, 0, AUX_B); } while (0)
; #define PG8_LDA(dst, b, h) do { _Pragma("unroll") for (int m = 0; m < 4; ++m) _Pragma("unroll") for (int k = 0; k < 2; ++k) dst[m][k] = *(const PG8_LAS bf16x8*)(lds + PG8_SA(b, h) + aoff + m * 2048 + k * 1024); } while (0)
; #define PG8_LDB(dst, b, h) do { _Pragma("unroll") for (int n = 0; n < 2; ++n) _Pragma("unroll") for (int k = 0; k < 2; ++k) dst[n][k] = *(const PG8_LAS bf16x8*)(lds + PG8_SB(b, h) + boff + n * 2048 + k * 1024); } while (0)
; #define PG8_MMA(ai, bj, At, Bt) do { __builtin_amdgcn_s_setprio(1); _Pragma("unroll") for (int m = 0; m < 4; ++m) _Pragma("unroll") for (int n = 0; n < 2; ++n) _Pragma("unroll") for (int k = 0; k < 2; ++k) \
;         acc[ai][bj][m][n] = __builtin_amdgcn_mfma_f32_16x16x32_bf16(Bt[n][k], At[m][k], acc[ai][bj][m][n], 0, 0, 0); __builtin_amdgcn_s_setprio(0); } while (0)
; #define PG8_WAIT_V(n) asm volatile("s_waitcnt vmcnt(" #n ")" ::: "memory")
; #define PG8_WAIT_L(n) asm volatile("s_waitcnt lgkmcnt(" #n ")" ::: "memory")
; #define PG8_BAR __builtin_amdgcn_s_barrier()
; #define PG8_SCHED __builtin_amdgcn_sched_barrier(0)
; template <class Epi, class Sched, bool ALIGN_EPI = false, bool SP2 = false>
; __device__ __forceinline__ void gemm_phase(PG8_LAS unsigned char* lds, const Gemm g, const Sched& S, const Epi& E) {
;     ...
;             PG8_WAIT_V(8); PG8_WAIT_L(0); PG8_BAR; PG8_MMA(1, 0, At, B0); PG8_MMA(1, 1, At, B1); PG8_BAR; PG8_SCHED;
;             PG8_LDB(B0, 1, 0); PG8_LDB(B1, 1, 1); PG8_SCHED; PG8_LDA(At, 1, 0); PG8_STAGE(PG8_SA(0, 1), a2 + hstep, voffA);
;             PG8_WAIT_V(8); PG8_WAIT_L(0); PG8_BAR; PG8_MMA(0, 0, At, B0); PG8_MMA(0, 1, At, B1); PG8_BAR; PG8_SCHED;
;             PG8_LDA(At, 1, 1); PG8_STAGEB(PG8_SB(1, 0), b3, voffB); PG8_STAGEB(PG8_SB(1, 1), b3 + hstep, voffB); PG8_STAGE(PG8_SA(1, 0), a3, voffA);
	v_mfma_f32_16x16x32_bf16 v[2:5], v[186:189], v[238:241], v[2:5]
	v_mfma_f32_16x16x32_bf16 v[2:5], v[190:193], v[242:245], v[2:5]
	s_setprio 0
	s_add_i32 s2, 0, 0x18000
	s_add_i32 s15, 0, 0x1c000
	v_add_u32_e32 v148, s2, v99
	v_add_u32_e32 v190, s15, v99
	ds_read_b128 v[136:139], v148
	ds_read_b128 v[140:143], v148 offset:1024
	ds_read_b128 v[144:147], v148 offset:2048
	ds_read_b128 v[148:151], v148 offset:3072
	ds_read_b128 v[164:167], v190
	ds_read_b128 v[182:185], v190 offset:1024
	ds_read_b128 v[186:189], v190 offset:2048
	ds_read_b128 v[190:193], v190 offset:3072
	s_add_u32 s0, s44, 0x80000
	s_addc_u32 s1, s45, 0
	s_mov_b32 m0, s52
	v_lshl_add_u64 v[246:247], s[0:1], 0, v[158:159]
	ds_read_b128 v[194:197], v181 offset:32768
	ds_read_b128 v[198:201], v181 offset:33792
	ds_read_b128 v[222:225], v181 offset:34816
	ds_read_b128 v[226:229], v181 offset:35840
	ds_read_b128 v[230:233], v181 offset:36864
	ds_read_b128 v[234:237], v181 offset:37888
	ds_read_b128 v[238:241], v181 offset:38912
	ds_read_b128 v[242:245], v181 offset:39936
	global_load_lds_dwordx4 v[246:247], off
	v_lshl_add_u64 v[246:247], s[0:1], 0, v[154:155]
	s_mov_b32 m0, s53
	s_nop 0
	global_load_lds_dwordx4 v[246:247], off
	s_waitcnt vmcnt(8)
	s_waitcnt lgkmcnt(0)
	s_setprio 1
	s_barrier
	v_mfma_f32_16x16x32_bf16 v[128:131], v[136:139], v[194:197], v[128:131]
	v_mfma_f32_16x16x32_bf16 v[128:131], v[140:143], v[198:201], v[128:131]
	v_mfma_f32_16x16x32_bf16 v[124:127], v[144:147], v[194:197], v[124:127]
	v_mfma_f32_16x16x32_bf16 v[124:127], v[148:151], v[198:201], v[124:127]
	v_mfma_f32_16x16x32_bf16 v[120:123], v[136:139], v[222:225], v[120:123]
	v_mfma_f32_16x16x32_bf16 v[120:123], v[140:143], v[226:229], v[120:123]
	v_mfma_f32_16x16x32_bf16 v[112:115], v[144:147], v[222:225], v[112:115]
	v_mfma_f32_16x16x32_bf16 v[112:115], v[148:151], v[226:229], v[112:115]
	v_mfma_f32_16x16x32_bf16 v[104:107], v[136:139], v[230:233], v[104:107]
	v_mfma_f32_16x16x32_bf16 v[104:107], v[140:143], v[234:237], v[104:107]
	v_mfma_f32_16x16x32_bf16 v[94:97], v[144:147], v[230:233], v[94:97]
	v_mfma_f32_16x16x32_bf16 v[94:97], v[148:151], v[234:237], v[94:97]
	v_mfma_f32_16x16x32_bf16 v[86:89], v[136:139], v[238:241], v[86:89]
	v_mfma_f32_16x16x32_bf16 v[86:89], v[140:143], v[242:245], v[86:89]
	v_mfma_f32_16x16x32_bf16 v[78:81], v[144:147], v[238:241], v[78:81]
	v_mfma_f32_16x16x32_bf16 v[78:81], v[148:151], v[242:245], v[78:81]
	s_setprio 0
	s_setprio 1
	v_mfma_f32_16x16x32_bf16 v[116:119], v[164:167], v[194:197], v[116:119]
	v_mfma_f32_16x16x32_bf16 v[116:119], v[182:185], v[198:201], v[116:119]
	v_mfma_f32_16x16x32_bf16 v[108:111], v[186:189], v[194:197], v[108:111]
	v_mfma_f32_16x16x32_bf16 v[108:111], v[190:193], v[198:201], v[108:111]
	v_mfma_f32_16x16x32_bf16 v[100:103], v[164:167], v[222:225], v[100:103]
	v_mfma_f32_16x16x32_bf16 v[100:103], v[182:185], v[226:229], v[100:103]
	v_mfma_f32_16x16x32_bf16 v[90:93], v[186:189], v[222:225], v[90:93]
	v_mfma_f32_16x16x32_bf16 v[90:93], v[190:193], v[226:229], v[90:93]
	v_mfma_f32_16x16x32_bf16 v[82:85], v[164:167], v[230:233], v[82:85]
	v_mfma_f32_16x16x32_bf16 v[82:85], v[182:185], v[234:237], v[82:85]
	v_mfma_f32_16x16x32_bf16 v[74:77], v[186:189], v[230:233], v[74:77]
	v_mfma_f32_16x16x32_bf16 v[74:77], v[190:193], v[234:237], v[74:77]
	v_mfma_f32_16x16x32_bf16 v[70:73], v[164:167], v[238:241], v[70:73]
	v_mfma_f32_16x16x32_bf16 v[70:73], v[182:185], v[242:245], v[70:73]
	s_setprio 2
	s_barrier
; #define PG8_STAGE(bufoff, gbase, voff) do { _Pragma("unroll") for (int _i = 0; _i < 2; ++_i) \
;         __builtin_amdgcn_global_load_lds((const unsigned*)((const char*)(gbase) + (voff)[_i]), (PG8_LAS unsigned*)(lds + (bufoff) + ldsw + _i * 8192), 16, 0, AUX_A); } while (0)
; #define PG8_STAGEB(bufoff, gbase, voff) do { _Pragma("unroll") for (int _i = 0; _i < 2; ++_i) \
;         __builtin_amdgcn_global_load_lds((const unsigned*)((const char*)(gbase) + (voff)[_i]), (PG8_LAS unsigned*)(lds + (bufoff) + ldsw + _i * 8192), 16, 0, AUX_B); } while (0)
; #define PG8_LDA(dst, b, h) do { _Pragma("unroll") for (int m = 0; m < 4; ++m) _Pragma("unroll") for (int k = 0; k < 2; ++k) dst[m][k] = *(const PG8_LAS bf16x8*)(lds + PG8_SA(b, h) + aoff + m * 2048 + k * 1024); } while (0)
; #define PG8_LDB(dst, b, h) do { _Pragma("unroll") for (int n = 0; n < 2; ++n) _Pragma("unroll") for (int k = 0; k < 2; ++k) dst[n][k] = *(const PG8_LAS bf16x8*)(lds + PG8_SB(b, h) + boff + n * 2048 + k * 1024); } while (0)
; #define PG8_MMA(ai, bj, At, Bt) do { __builtin_amdgcn_s_setprio(1); _Pragma("unroll") for (int m = 0; m < 4; ++m) _Pragma("unroll") for (int n = 0; n < 2; ++n) _Pragma("unroll") for (int k = 0; k < 2; ++k) \
;         acc[ai][bj][m][n] = __builtin_amdgcn_mfma_f32_16x16x32_bf16(Bt[n][k], At[m][k], acc[ai][bj][m][n], 0, 0, 0); __builtin_amdgcn_s_setprio(0); } while (0)
; #define PG8_WAIT_V(n) asm volatile("s_waitcnt vmcnt(" #n ")" ::: "memory")
; #define PG8_WAIT_L(n) asm volatile("s_waitcnt lgkmcnt(" #n ")" ::: "memory")
; #define PG8_BAR __builtin_amdgcn_s_barrier()
; template <class Epi, class Sched, bool ALIGN_EPI = false, bool SP2 = false>
; __device__ __forceinline__ void gemm_phase(PG8_LAS unsigned char* lds, const Gemm g, const Sched& S, const Epi& E) {
;     ...
;             PG8_LDB(B0, 1, 0); PG8_LDB(B1, 1, 1); PG8_SCHED; PG8_LDA(At, 1, 0); PG8_STAGE(PG8_SA(0, 1), a2 + hstep, voffA);
;             PG8_WAIT_V(8); PG8_WAIT_L(0); PG8_BAR; PG8_MMA(0, 0, At, B0); PG8_MMA(0, 1, At, B1); PG8_BAR; PG8_SCHED;
;             PG8_LDA(At, 1, 1); PG8_STAGEB(PG8_SB(1, 0), b3, voffB); PG8_STAGEB(PG8_SB(1, 1), b3 + hstep, voffB); PG8_STAGE(PG8_SA(1, 0), a3, voffA);
;             PG8_WAIT_V(8); PG8_WAIT_L(0); PG8_BAR; PG8_MMA(1, 0, At, B0); PG8_MMA(1, 1, At, B1); PG8_BAR; PG8_SCHED;
;     ...
;         if constexpr (ALIGN_EPI) { if (wr == 0) PG8_BAR; }
	v_mfma_f32_16x16x32_bf16 v[66:69], v[186:189], v[238:241], v[66:69]
	v_mfma_f32_16x16x32_bf16 v[66:69], v[190:193], v[242:245], v[66:69]
	s_setprio 0
	s_add_i32 s0, s2, s49
	v_lshl_add_u64 v[168:169], v[168:169], 0, s[76:77]
	s_mov_b32 m0, s0
	ds_read_b128 v[194:197], v181 offset:49152
	ds_read_b128 v[198:201], v181 offset:50176
	ds_read_b128 v[222:225], v181 offset:51200
	ds_read_b128 v[226:229], v181 offset:52224
	ds_read_b128 v[230:233], v181 offset:53248
	ds_read_b128 v[234:237], v181 offset:54272
	ds_read_b128 v[238:241], v181 offset:55296
	ds_read_b128 v[242:245], v181 offset:56320
	global_load_lds_dwordx4 v[168:169], off
	s_add_i32 m0, s0, 0x2000
	s_add_u32 s0, s36, 0x80080
	v_lshl_add_u64 v[168:169], v[172:173], 0, s[76:77]
	s_addc_u32 s1, s37, 0
	s_add_i32 s2, s15, s49
	global_load_lds_dwordx4 v[168:169], off
	v_lshl_add_u64 v[168:169], s[0:1], 0, v[156:157]
	s_mov_b32 m0, s2
	s_nop 0
	global_load_lds_dwordx4 v[168:169], off
	v_lshl_add_u64 v[168:169], s[0:1], 0, v[152:153]
	s_add_i32 m0, s2, 0x2000
	s_nop 0
	global_load_lds_dwordx4 v[168:169], off
	v_lshl_add_u64 v[168:169], v[202:203], 0, s[76:77]
	s_mov_b32 m0, s59
	s_nop 0
	global_load_lds_dwordx4 v[168:169], off
	v_lshl_add_u64 v[168:169], v[212:213], 0, s[76:77]
	s_mov_b32 m0, s60
	s_nop 0
	global_load_lds_dwordx4 v[168:169], off
	s_waitcnt vmcnt(8)
	s_waitcnt lgkmcnt(0)
	s_setprio 1
	s_barrier
	v_mfma_f32_16x16x32_bf16 v[62:65], v[136:139], v[194:197], v[62:65]
	v_mfma_f32_16x16x32_bf16 v[62:65], v[140:143], v[198:201], v[62:65]
	v_mfma_f32_16x16x32_bf16 v[58:61], v[144:147], v[194:197], v[58:61]
	v_mfma_f32_16x16x32_bf16 v[58:61], v[148:151], v[198:201], v[58:61]
	v_mfma_f32_16x16x32_bf16 v[54:57], v[136:139], v[222:225], v[54:57]
	v_mfma_f32_16x16x32_bf16 v[54:57], v[140:143], v[226:229], v[54:57]
	v_mfma_f32_16x16x32_bf16 v[46:49], v[144:147], v[222:225], v[46:49]
	v_mfma_f32_16x16x32_bf16 v[46:49], v[148:151], v[226:229], v[46:49]
	v_mfma_f32_16x16x32_bf16 v[38:41], v[136:139], v[230:233], v[38:41]
	v_mfma_f32_16x16x32_bf16 v[38:41], v[140:143], v[234:237], v[38:41]
	v_mfma_f32_16x16x32_bf16 v[30:33], v[144:147], v[230:233], v[30:33]
	v_mfma_f32_16x16x32_bf16 v[30:33], v[148:151], v[234:237], v[30:33]
	v_mfma_f32_16x16x32_bf16 v[22:25], v[136:139], v[238:241], v[22:25]
	v_mfma_f32_16x16x32_bf16 v[22:25], v[140:143], v[242:245], v[22:25]
	v_mfma_f32_16x16x32_bf16 v[14:17], v[144:147], v[238:241], v[14:17]
	v_mfma_f32_16x16x32_bf16 v[14:17], v[148:151], v[242:245], v[14:17]
	s_setprio 0
	s_setprio 1
	v_mfma_f32_16x16x32_bf16 v[50:53], v[164:167], v[194:197], v[50:53]
	v_mfma_f32_16x16x32_bf16 v[50:53], v[182:185], v[198:201], v[50:53]
	v_mfma_f32_16x16x32_bf16 v[42:45], v[186:189], v[194:197], v[42:45]
	v_mfma_f32_16x16x32_bf16 v[42:45], v[190:193], v[198:201], v[42:45]
	v_mfma_f32_16x16x32_bf16 v[34:37], v[164:167], v[222:225], v[34:37]
	v_mfma_f32_16x16x32_bf16 v[34:37], v[182:185], v[226:229], v[34:37]
	v_mfma_f32_16x16x32_bf16 v[26:29], v[186:189], v[222:225], v[26:29]
	v_mfma_f32_16x16x32_bf16 v[26:29], v[190:193], v[226:229], v[26:29]
	v_mfma_f32_16x16x32_bf16 v[18:21], v[164:167], v[230:233], v[18:21]
	v_mfma_f32_16x16x32_bf16 v[18:21], v[182:185], v[234:237], v[18:21]
	v_mfma_f32_16x16x32_bf16 v[10:13], v[186:189], v[230:233], v[10:13]
	v_mfma_f32_16x16x32_bf16 v[10:13], v[190:193], v[234:237], v[10:13]
	v_mfma_f32_16x16x32_bf16 v[6:9], v[164:167], v[238:241], v[6:9]
	v_mfma_f32_16x16x32_bf16 v[6:9], v[182:185], v[242:245], v[6:9]
	s_setprio 2
	s_barrier
	v_mfma_f32_16x16x32_bf16 v[2:5], v[186:189], v[238:241], v[2:5]
	v_mfma_f32_16x16x32_bf16 v[2:5], v[190:193], v[242:245], v[2:5]
	s_setprio 0
	s_add_i32 s0, s13, 2
	v_lshl_add_u64 v[132:133], v[132:133], 0, s[86:87]
	v_lshl_add_u64 v[134:135], v[134:135], 0, s[86:87]
	s_cmp_ge_i32 s13, s71
	s_mov_b32 s13, s0
	s_cbranch_scc0 .LBB0_1308
.Lpx_1308:
	s_and_b64 vcc, exec, s[8:9]
	s_cbranch_vccz .LBB0_1311
	s_barrier

; template <class Epi, class Sched, bool ALIGN_EPI = false, bool SP2 = false>
; __device__ __forceinline__ void gemm_phase(PG8_LAS unsigned char* lds, const Gemm g, const Sched& S, const Epi& E) {
;     ...
;     for (;;) {
;         const bool has_next = S.next(ui + 1, nxt);
;         const char* nA = has_next ? (const char*)g.A + (size_t)nxt.pm * tstep + (size_t)nxt.kt0 * kstep : cA; const char* nB = has_next ? (const char*)g.Bt + (size_t)nxt.pn * tstep + (size_t)nxt.kt0 * kstep : cB;
;         const int nt = cur.nkt, rot = cur.krot;
;         const char* nAr = has_next ? nA + (size_t)nxt.krot * kstep : PG8_KP(cA, 0, rot, nt); const char* nBr = has_next ? nB + (size_t)nxt.krot * kstep : PG8_KP(cB, 0, rot, nt);
;         for (int t = 0; t < nt; t += 2) {
;             const bool last = (t == nt - 2);
;             const char* a1 = PG8_KP(cA, t + 1, rot, nt);
;             const char* a2 = last ? nAr : PG8_KP(cA, t + 2, rot, nt); const char* b2 = last ? nBr : PG8_KP(cB, t + 2, rot, nt);
;             const char* a3 = a2 + kstep; const char* b3 = b2 + kstep;
;             if (last && has_next) S.a_ready(nxt);
;             if constexpr (SP2) {
;             PG8_LDB(B0, 0, 0); PG8_LDB(B1, 0, 1); PG8_SCHED; PG8_LDA(At, 0, 0); PG8_STAGE(PG8_SA(1, 1), a1 + hstep, voffA);
;             PG8_WAIT_V(8); PG8_WAIT_L(0); PG8_BAR; PG8_MMA(0, 0, At, B0); PG8_MMA(0, 1, At, B1); PG8_BAR; PG8_SCHED;
;             PG8_LDA(At, 0, 1); PG8_STAGEB(PG8_SB(0, 0), b2, voffB); PG8_STAGEB(PG8_SB(0, 1), b2 + hstep, voffB); PG8_STAGE(PG8_SA(0, 0), a2, voffA);
;             PG8_WAIT_V(8); PG8_WAIT_L(0); PG8_BAR; PG8_MMA(1, 0, At, B0); PG8_MMA(1, 1, At, B1); PG8_BAR; PG8_SCHED;
;             PG8_LDB(B0, 1, 0); PG8_LDB(B1, 1, 1); PG8_SCHED; PG8_LDA(At, 1, 0); PG8_STAGE(PG8_SA(0, 1), a2 + hstep, voffA);
;             PG8_WAIT_V(8); PG8_WAIT_L(0); PG8_BAR; PG8_MMA(0, 0, At, B0); PG8_MMA(0, 1, At, B1); PG8_BAR; PG8_SCHED;
;             PG8_LDA(At, 1, 1); PG8_STAGEB(PG8_SB(1, 0), b3, voffB); PG8_STAGEB(PG8_SB(1, 1), b3 + hstep, voffB); PG8_STAGE(PG8_SA(1, 0), a3, voffA);
;             PG8_WAIT_V(8); PG8_WAIT_L(0); PG8_BAR; PG8_MMA(1, 0, At, B0); PG8_MMA(1, 1, At, B1); PG8_BAR; PG8_SCHED;
;     ...
;         for (int a = 0; a < 2; ++a)
; #pragma unroll
;             for (int b = 0; b < 2; ++b)
; #pragma unroll
;                 for (int m = 0; m < 4; ++m)
; #pragma unroll
.LBB0_1457:
	s_ashr_i32 s15, s14, 31
	s_lshl_b64 s[0:1], s[14:15], 20
	s_add_u32 s16, s52, s0
	s_addc_u32 s17, s53, s1
	s_ashr_i32 s13, s12, 31
	s_lshl_b64 s[0:1], s[12:13], 20
	s_add_u32 s18, s54, s0
	s_addc_u32 s19, s55, s1
	s_and_b64 s[0:1], s[38:39], exec
	s_cselect_b32 s13, s17, s41
	s_cselect_b32 s15, s16, s40
	s_cselect_b32 s71, s19, s35
	s_cselect_b32 s75, s18, s34
	s_add_u32 s0, s40, 0x80080
	s_addc_u32 s1, s41, 0
	v_lshl_add_u64 v[144:145], s[0:1], 0, v[140:141]
	v_lshl_add_u64 v[146:147], s[0:1], 0, v[142:143]
	s_mov_b32 s29, 0
	s_waitcnt lgkmcnt(0)
.Lpk_1458:
	s_lshl_b32 s100, s29, 7
	s_add_u32 s100, s40, s100
	s_addc_u32 s101, s41, 0
	s_add_u32 s100, s100, 0x80
	s_addc_u32 s101, s101, 0
	s_add_i32 s30, s29, 2
	s_cmp_lt_u32 s29, 30
	s_cselect_b32 s0, 0, 0xffffffe0
	s_add_i32 s0, s30, s0
	s_ashr_i32 s1, s0, 31
	s_lshl_b64 s[0:1], s[0:1], 7
	s_add_u32 s2, s40, s0
	s_addc_u32 s31, s41, s1
	s_add_u32 s0, s34, s0
	s_addc_u32 s1, s35, s1
	s_cmp_eq_u32 s29, 30
	s_cselect_b32 s45, s13, s31
	s_cselect_b32 s44, s15, s2
	s_cselect_b32 s49, s71, s1
	s_cselect_b32 s48, s75, s0
	s_add_i32 s2, 0, 0x10000
	s_add_i32 s78, s2, s56
	s_add_i32 s31, 0, 0x14000
	s_add_i32 s47, s57, 0xe000
	s_add_i32 s81, s78, 0x2000
	s_add_u32 s50, s48, 0x80000
	s_addc_u32 s51, s49, 0
	s_add_i32 s82, s31, s56
	v_add_u32_e32 v162, s2, v99
	v_add_u32_e32 v166, s31, v99
	s_add_i32 s83, s82, 0x2000
	s_add_i32 s84, 0, 0x18000
	s_add_i32 s88, 0, 0x1c000
	ds_read_b128 v[150:153], v162
	ds_read_b128 v[154:157], v162 offset:1024
	ds_read_b128 v[158:161], v162 offset:2048
	ds_read_b128 v[162:165], v162 offset:3072
	ds_read_b128 v[180:183], v166
	ds_read_b128 v[184:187], v166 offset:1024
	ds_read_b128 v[188:191], v166 offset:2048
	ds_read_b128 v[192:195], v166 offset:3072
	s_add_u32 s42, s44, 0x80000
	s_addc_u32 s43, s45, 0
	s_add_i32 s1, s84, s56
	s_add_i32 s0, s1, 0x2000
	s_add_u32 s36, s48, 0x80080
	s_addc_u32 s37, s49, 0
	s_add_i32 s46, s88, s56
	s_add_i32 s31, s46, 0x2000
	ds_read_b128 v[196:199], v149
	ds_read_b128 v[200:203], v149 offset:1024
	ds_read_b128 v[222:225], v149 offset:2048
	ds_read_b128 v[226:229], v149 offset:3072
	ds_read_b128 v[230:233], v149 offset:4096
	ds_read_b128 v[234:237], v149 offset:5120
	ds_read_b128 v[238:241], v149 offset:6144
	ds_read_b128 v[242:245], v149 offset:7168
	v_lshl_add_u64 v[166:167], s[100:101], 0, v[138:139]
	s_mov_b32 m0, s61
	v_lshl_add_u64 v[168:169], s[100:101], 0, v[134:135]
	global_load_lds_dwordx4 v[166:167], off
	s_mov_b32 m0, s62
	s_nop 0
	global_load_lds_dwordx4 v[168:169], off
	s_add_i32 m0, s57, 0xc000
	s_nop 0
	global_load_lds_dwordx4 v[146:147], off
	s_mov_b32 m0, s47
	s_nop 0
	global_load_lds_dwordx4 v[144:145], off
	s_waitcnt vmcnt(8)
	s_waitcnt lgkmcnt(0)
	s_setprio 1
	s_barrier
	v_mfma_f32_16x16x32_bf16 v[128:131], v[150:153], v[196:199], 0
	v_mfma_f32_16x16x32_bf16 v[128:131], v[154:157], v[200:203], v[128:131]
	v_mfma_f32_16x16x32_bf16 v[120:123], v[158:161], v[196:199], 0
	v_mfma_f32_16x16x32_bf16 v[120:123], v[162:165], v[200:203], v[120:123]
	v_mfma_f32_16x16x32_bf16 v[112:115], v[150:153], v[222:225], 0
	v_mfma_f32_16x16x32_bf16 v[112:115], v[154:157], v[226:229], v[112:115]
	v_mfma_f32_16x16x32_bf16 v[104:107], v[158:161], v[222:225], 0
	v_mfma_f32_16x16x32_bf16 v[104:107], v[162:165], v[226:229], v[104:107]
	v_mfma_f32_16x16x32_bf16 v[94:97], v[150:153], v[230:233], 0
	v_mfma_f32_16x16x32_bf16 v[94:97], v[154:157], v[234:237], v[94:97]
	v_mfma_f32_16x16x32_bf16 v[86:89], v[158:161], v[230:233], 0
	v_mfma_f32_16x16x32_bf16 v[86:89], v[162:165], v[234:237], v[86:89]
	v_mfma_f32_16x16x32_bf16 v[78:81], v[150:153], v[238:241], 0
	v_mfma_f32_16x16x32_bf16 v[78:81], v[154:157], v[242:245], v[78:81]
	v_mfma_f32_16x16x32_bf16 v[70:73], v[158:161], v[238:241], 0
	v_mfma_f32_16x16x32_bf16 v[70:73], v[162:165], v[242:245], v[70:73]
	s_setprio 0
	s_setprio 1
	v_mfma_f32_16x16x32_bf16 v[124:127], v[180:183], v[196:199], 0
	v_mfma_f32_16x16x32_bf16 v[124:127], v[184:187], v[200:203], v[124:127]
	v_mfma_f32_16x16x32_bf16 v[116:119], v[188:191], v[196:199], 0
	v_mfma_f32_16x16x32_bf16 v[116:119], v[192:195], v[200:203], v[116:119]
	v_mfma_f32_16x16x32_bf16 v[108:111], v[180:183], v[222:225], 0
	v_mfma_f32_16x16x32_bf16 v[108:111], v[184:187], v[226:229], v[108:111]
	v_mfma_f32_16x16x32_bf16 v[100:103], v[188:191], v[222:225], 0
	v_mfma_f32_16x16x32_bf16 v[100:103], v[192:195], v[226:229], v[100:103]
	v_mfma_f32_16x16x32_bf16 v[90:93], v[180:183], v[230:233], 0
	v_mfma_f32_16x16x32_bf16 v[90:93], v[184:187], v[234:237], v[90:93]
	v_mfma_f32_16x16x32_bf16 v[82:85], v[188:191], v[230:233], 0
	v_mfma_f32_16x16x32_bf16 v[82:85], v[192:195], v[234:237], v[82:85]
	v_mfma_f32_16x16x32_bf16 v[74:77], v[180:183], v[238:241], 0
	v_mfma_f32_16x16x32_bf16 v[74:77], v[184:187], v[242:245], v[74:77]
	s_setprio 2
	s_barrier
	v_mfma_f32_16x16x32_bf16 v[66:69], v[188:191], v[238:241], 0
	v_mfma_f32_16x16x32_bf16 v[66:69], v[192:195], v[242:245], v[66:69]
	s_setprio 0
	s_mov_b32 m0, s78
	v_lshl_add_u64 v[166:167], s[48:49], 0, v[136:137]
	ds_read_b128 v[196:199], v149 offset:16384
	ds_read_b128 v[200:203], v149 offset:17408
	ds_read_b128 v[222:225], v149 offset:18432
	ds_read_b128 v[226:229], v149 offset:19456
	ds_read_b128 v[230:233], v149 offset:20480
	ds_read_b128 v[234:237], v149 offset:21504
	ds_read_b128 v[238:241], v149 offset:22528
	ds_read_b128 v[242:245], v149 offset:23552
	global_load_lds_dwordx4 v[166:167], off
	v_lshl_add_u64 v[168:169], s[48:49], 0, v[132:133]
	s_mov_b32 m0, s81
	v_lshl_add_u64 v[172:173], s[50:51], 0, v[136:137]
	global_load_lds_dwordx4 v[168:169], off
	s_mov_b32 m0, s82
	global_load_lds_dwordx4 v[172:173], off
	v_lshl_add_u64 v[172:173], s[50:51], 0, v[132:133]
	s_mov_b32 m0, s83
	s_nop 0
	global_load_lds_dwordx4 v[172:173], off
	s_waitcnt vmcnt(6)
	s_waitcnt lgkmcnt(0)
	s_setprio 1
	s_barrier
; #define PG8_STAGE(bufoff, gbase, voff) do { _Pragma("unroll") for (int _i = 0; _i < 2; ++_i) \
;         __builtin_amdgcn_global_load_lds((const unsigned*)((const char*)(gbase) + (voff)[_i]), (PG8_LAS unsigned*)(lds + (bufoff) + ldsw + _i * 8192), 16, 0, AUX_A); } while (0)
; #define PG8_STAGEB(bufoff, gbase, voff) do { _Pragma("unroll") for (int _i = 0; _i < 2; ++_i) \
;         __builtin_amdgcn_global_load_lds((const unsigned*)((const char*)(gbase) + (voff)[_i]), (PG8_LAS unsigned*)(lds + (bufoff) + ldsw + _i * 8192), 16, 0, AUX_B); } while (0)
; #define PG8_LDA(dst, b, h) do { _Pragma("unroll") for (int m = 0; m < 4; ++m) _Pragma("unroll") for (int k = 0; k < 2; ++k) dst[m][k] = *(const PG8_LAS bf16x8*)(lds + PG8_SA(b, h) + aoff + m * 2048 + k * 1024); } while (0)
; #define PG8_LDB(dst, b, h) do { _Pragma("unroll") for (int n = 0; n < 2; ++n) _Pragma("unroll") for (int k = 0; k < 2; ++k) dst[n][k] = *(const PG8_LAS bf16x8*)(lds + PG8_SB(b, h) + boff + n * 2048 + k * 1024); } while (0)
; #define PG8_WAIT_V(n) asm volatile("s_waitcnt vmcnt(" #n ")" ::: "memory")
; #define PG8_WAIT_L(n) asm volatile("s_waitcnt lgkmcnt(" #n ")" ::: "memory")
; template <class Epi, class Sched, bool ALIGN_EPI = false, bool SP2 = false>
; __device__ __forceinline__ void gemm_phase(PG8_LAS unsigned char* lds, const Gemm g, const Sched& S, const Epi& E) {
;     ...
;             PG8_LDB(B0, 0, 0); PG8_LDB(B1, 0, 1); PG8_SCHED; PG8_LDA(At, 0, 0); PG8_STAGE(PG8_SA(1, 1), a1 + hstep, voffA);
;             PG8_WAIT_V(8); PG8_WAIT_L(0); PG8_BAR; PG8_MMA(0, 0, At, B0); PG8_MMA(0, 1, At, B1); PG8_BAR; PG8_SCHED;
;             PG8_LDA(At, 0, 1); PG8_STAGEB(PG8_SB(0, 0), b2, voffB); PG8_STAGEB(PG8_SB(0, 1), b2 + hstep, voffB); PG8_STAGE(PG8_SA(0, 0), a2, voffA);
;             PG8_WAIT_V(8); PG8_WAIT_L(0); PG8_BAR; PG8_MMA(1, 0, At, B0); PG8_MMA(1, 1, At, B1); PG8_BAR; PG8_SCHED;
;             PG8_LDB(B0, 1, 0); PG8_LDB(B1, 1, 1); PG8_SCHED; PG8_LDA(At, 1, 0); PG8_STAGE(PG8_SA(0, 1), a2 + hstep, voffA);
;             PG8_WAIT_V(8); PG8_WAIT_L(0); PG8_BAR; PG8_MMA(0, 0, At, B0); PG8_MMA(0, 1, At, B1); PG8_BAR; PG8_SCHED;
;             PG8_LDA(At, 1, 1); PG8_STAGEB(PG8_SB(1, 0), b3, voffB); PG8_STAGEB(PG8_SB(1, 1), b3 + hstep, voffB); PG8_STAGE(PG8_SA(1, 0), a3, voffA);
;             PG8_WAIT_V(8); PG8_WAIT_L(0); PG8_BAR; PG8_MMA(1, 0, At, B0); PG8_MMA(1, 1, At, B1); PG8_BAR; PG8_SCHED;
	v_mfma_f32_16x16x32_bf16 v[62:65], v[150:153], v[196:199], 0
	v_mfma_f32_16x16x32_bf16 v[62:65], v[154:157], v[200:203], v[62:65]
	v_mfma_f32_16x16x32_bf16 v[54:57], v[158:161], v[196:199], 0
	v_mfma_f32_16x16x32_bf16 v[54:57], v[162:165], v[200:203], v[54:57]
	v_mfma_f32_16x16x32_bf16 v[46:49], v[150:153], v[222:225], 0
	v_mfma_f32_16x16x32_bf16 v[46:49], v[154:157], v[226:229], v[46:49]
	v_mfma_f32_16x16x32_bf16 v[38:41], v[158:161], v[222:225], 0
	v_mfma_f32_16x16x32_bf16 v[38:41], v[162:165], v[226:229], v[38:41]
	v_mfma_f32_16x16x32_bf16 v[30:33], v[150:153], v[230:233], 0
	v_mfma_f32_16x16x32_bf16 v[30:33], v[154:157], v[234:237], v[30:33]
	v_mfma_f32_16x16x32_bf16 v[22:25], v[158:161], v[230:233], 0
	v_mfma_f32_16x16x32_bf16 v[22:25], v[162:165], v[234:237], v[22:25]
	v_mfma_f32_16x16x32_bf16 v[14:17], v[150:153], v[238:241], 0
	v_mfma_f32_16x16x32_bf16 v[14:17], v[154:157], v[242:245], v[14:17]
	v_mfma_f32_16x16x32_bf16 v[6:9], v[158:161], v[238:241], 0
	v_mfma_f32_16x16x32_bf16 v[6:9], v[162:165], v[242:245], v[6:9]
	s_setprio 0
	s_setprio 1
	v_mfma_f32_16x16x32_bf16 v[58:61], v[180:183], v[196:199], 0
	v_mfma_f32_16x16x32_bf16 v[58:61], v[184:187], v[200:203], v[58:61]
	v_mfma_f32_16x16x32_bf16 v[50:53], v[188:191], v[196:199], 0
	v_mfma_f32_16x16x32_bf16 v[50:53], v[192:195], v[200:203], v[50:53]
	v_mfma_f32_16x16x32_bf16 v[42:45], v[180:183], v[222:225], 0
	v_mfma_f32_16x16x32_bf16 v[42:45], v[184:187], v[226:229], v[42:45]
	v_mfma_f32_16x16x32_bf16 v[34:37], v[188:191], v[222:225], 0
	v_mfma_f32_16x16x32_bf16 v[34:37], v[192:195], v[226:229], v[34:37]
	v_mfma_f32_16x16x32_bf16 v[26:29], v[180:183], v[230:233], 0
	v_mfma_f32_16x16x32_bf16 v[26:29], v[184:187], v[234:237], v[26:29]
	v_mfma_f32_16x16x32_bf16 v[18:21], v[188:191], v[230:233], 0
	v_mfma_f32_16x16x32_bf16 v[18:21], v[192:195], v[234:237], v[18:21]
	v_mfma_f32_16x16x32_bf16 v[10:13], v[180:183], v[238:241], 0
	v_mfma_f32_16x16x32_bf16 v[10:13], v[184:187], v[242:245], v[10:13]
	s_setprio 2
	s_barrier
	v_mfma_f32_16x16x32_bf16 v[2:5], v[188:191], v[238:241], 0
	v_mfma_f32_16x16x32_bf16 v[2:5], v[192:195], v[242:245], v[2:5]
	s_setprio 0
	v_add_u32_e32 v162, s84, v99
	v_add_u32_e32 v192, s88, v99
	ds_read_b128 v[150:153], v162
	ds_read_b128 v[154:157], v162 offset:1024
	ds_read_b128 v[158:161], v162 offset:2048
	ds_read_b128 v[162:165], v162 offset:3072
	ds_read_b128 v[180:183], v192
	ds_read_b128 v[184:187], v192 offset:1024
	ds_read_b128 v[188:191], v192 offset:2048
	ds_read_b128 v[192:195], v192 offset:3072
	s_mov_b32 m0, s59
	v_lshl_add_u64 v[246:247], s[42:43], 0, v[138:139]
	ds_read_b128 v[196:199], v149 offset:32768
	ds_read_b128 v[200:203], v149 offset:33792
	ds_read_b128 v[222:225], v149 offset:34816
	ds_read_b128 v[226:229], v149 offset:35840
	ds_read_b128 v[230:233], v149 offset:36864
	ds_read_b128 v[234:237], v149 offset:37888
	ds_read_b128 v[238:241], v149 offset:38912
	ds_read_b128 v[242:245], v149 offset:39936
	v_lshl_add_u64 v[172:173], s[44:45], 0, v[138:139]
	s_mov_b32 m0, s57
	v_lshl_add_u64 v[212:213], s[44:45], 0, v[134:135]
	global_load_lds_dwordx4 v[172:173], off
	s_mov_b32 m0, s58
	s_nop 0
	global_load_lds_dwordx4 v[212:213], off
	s_mov_b32 m0, s59
	s_nop 0
	global_load_lds_dwordx4 v[246:247], off
	v_lshl_add_u64 v[246:247], s[42:43], 0, v[134:135]
	s_mov_b32 m0, s60
	s_nop 0
	global_load_lds_dwordx4 v[246:247], off
	s_waitcnt vmcnt(8)
	s_waitcnt lgkmcnt(0)
	s_setprio 1
	s_barrier
	v_mfma_f32_16x16x32_bf16 v[128:131], v[150:153], v[196:199], v[128:131]
	v_mfma_f32_16x16x32_bf16 v[128:131], v[154:157], v[200:203], v[128:131]
	v_mfma_f32_16x16x32_bf16 v[120:123], v[158:161], v[196:199], v[120:123]
	v_mfma_f32_16x16x32_bf16 v[120:123], v[162:165], v[200:203], v[120:123]
	v_mfma_f32_16x16x32_bf16 v[112:115], v[150:153], v[222:225], v[112:115]
	v_mfma_f32_16x16x32_bf16 v[112:115], v[154:157], v[226:229], v[112:115]
	v_mfma_f32_16x16x32_bf16 v[104:107], v[158:161], v[222:225], v[104:107]
	v_mfma_f32_16x16x32_bf16 v[104:107], v[162:165], v[226:229], v[104:107]
	v_mfma_f32_16x16x32_bf16 v[94:97], v[150:153], v[230:233], v[94:97]
	v_mfma_f32_16x16x32_bf16 v[94:97], v[154:157], v[234:237], v[94:97]
	v_mfma_f32_16x16x32_bf16 v[86:89], v[158:161], v[230:233], v[86:89]
	v_mfma_f32_16x16x32_bf16 v[86:89], v[162:165], v[234:237], v[86:89]
	v_mfma_f32_16x16x32_bf16 v[78:81], v[150:153], v[238:241], v[78:81]
	v_mfma_f32_16x16x32_bf16 v[78:81], v[154:157], v[242:245], v[78:81]
	v_mfma_f32_16x16x32_bf16 v[70:73], v[158:161], v[238:241], v[70:73]
	v_mfma_f32_16x16x32_bf16 v[70:73], v[162:165], v[242:245], v[70:73]
	s_setprio 0
	s_setprio 1
	v_mfma_f32_16x16x32_bf16 v[124:127], v[180:183], v[196:199], v[124:127]
	v_mfma_f32_16x16x32_bf16 v[124:127], v[184:187], v[200:203], v[124:127]
	v_mfma_f32_16x16x32_bf16 v[116:119], v[188:191], v[196:199], v[116:119]
	v_mfma_f32_16x16x32_bf16 v[116:119], v[192:195], v[200:203], v[116:119]
	v_mfma_f32_16x16x32_bf16 v[108:111], v[180:183], v[222:225], v[108:111]
	v_mfma_f32_16x16x32_bf16 v[108:111], v[184:187], v[226:229], v[108:111]
	v_mfma_f32_16x16x32_bf16 v[100:103], v[188:191], v[222:225], v[100:103]
	v_mfma_f32_16x16x32_bf16 v[100:103], v[192:195], v[226:229], v[100:103]
	v_mfma_f32_16x16x32_bf16 v[90:93], v[180:183], v[230:233], v[90:93]
	v_mfma_f32_16x16x32_bf16 v[90:93], v[184:187], v[234:237], v[90:93]
	v_mfma_f32_16x16x32_bf16 v[82:85], v[188:191], v[230:233], v[82:85]
	v_mfma_f32_16x16x32_bf16 v[82:85], v[192:195], v[234:237], v[82:85]
	v_mfma_f32_16x16x32_bf16 v[74:77], v[180:183], v[238:241], v[74:77]
	v_mfma_f32_16x16x32_bf16 v[74:77], v[184:187], v[242:245], v[74:77]
	s_setprio 2
	s_barrier
; #define PG8_STAGE(bufoff, gbase, voff) do { _Pragma("unroll") for (int _i = 0; _i < 2; ++_i) \
;         __builtin_amdgcn_global_load_lds((const unsigned*)((const char*)(gbase) + (voff)[_i]), (PG8_LAS unsigned*)(lds + (bufoff) + ldsw + _i * 8192), 16, 0, AUX_A); } while (0)
; #define PG8_STAGEB(bufoff, gbase, voff) do { _Pragma("unroll") for (int _i = 0; _i < 2; ++_i) \
;         __builtin_amdgcn_global_load_lds((const unsigned*)((const char*)(gbase) + (voff)[_i]), (PG8_LAS unsigned*)(lds + (bufoff) + ldsw + _i * 8192), 16, 0, AUX_B); } while (0)
; #define PG8_WAIT_V(n) asm volatile("s_waitcnt vmcnt(" #n ")" ::: "memory")
; #define PG8_WAIT_L(n) asm volatile("s_waitcnt lgkmcnt(" #n ")" ::: "memory")
; template <class Epi, class Sched, bool ALIGN_EPI = false, bool SP2 = false>
; __device__ __forceinline__ void gemm_phase(PG8_LAS unsigned char* lds, const Gemm g, const Sched& S, const Epi& E) {
;     ...
;         for (int t = 0; t < nt; t += 2) {
;             const bool last = (t == nt - 2);
;             const char* a1 = PG8_KP(cA, t + 1, rot, nt);
;             const char* a2 = last ? nAr : PG8_KP(cA, t + 2, rot, nt); const char* b2 = last ? nBr : PG8_KP(cB, t + 2, rot, nt);
;             const char* a3 = a2 + kstep; const char* b3 = b2 + kstep;
;             if (last && has_next) S.a_ready(nxt);
;             if constexpr (SP2) {
;             PG8_LDB(B0, 0, 0); PG8_LDB(B1, 0, 1); PG8_SCHED; PG8_LDA(At, 0, 0); PG8_STAGE(PG8_SA(1, 1), a1 + hstep, voffA);
;             PG8_WAIT_V(8); PG8_WAIT_L(0); PG8_BAR; PG8_MMA(0, 0, At, B0); PG8_MMA(0, 1, At, B1); PG8_BAR; PG8_SCHED;
;             PG8_LDA(At, 0, 1); PG8_STAGEB(PG8_SB(0, 0), b2, voffB); PG8_STAGEB(PG8_SB(0, 1), b2 + hstep, voffB); PG8_STAGE(PG8_SA(0, 0), a2, voffA);
;             PG8_WAIT_V(8); PG8_WAIT_L(0); PG8_BAR; PG8_MMA(1, 0, At, B0); PG8_MMA(1, 1, At, B1); PG8_BAR; PG8_SCHED;
;             PG8_LDB(B0, 1, 0); PG8_LDB(B1, 1, 1); PG8_SCHED; PG8_LDA(At, 1, 0); PG8_STAGE(PG8_SA(0, 1), a2 + hstep, voffA);
;             PG8_WAIT_V(8); PG8_WAIT_L(0); PG8_BAR; PG8_MMA(0, 0, At, B0); PG8_MMA(0, 1, At, B1); PG8_BAR; PG8_SCHED;
;             PG8_LDA(At, 1, 1); PG8_STAGEB(PG8_SB(1, 0), b3, voffB); PG8_STAGEB(PG8_SB(1, 1), b3 + hstep, voffB); PG8_STAGE(PG8_SA(1, 0), a3, voffA);
;             PG8_WAIT_V(8); PG8_WAIT_L(0); PG8_BAR; PG8_MMA(1, 0, At, B0); PG8_MMA(1, 1, At, B1); PG8_BAR; PG8_SCHED;
	v_mfma_f32_16x16x32_bf16 v[66:69], v[188:191], v[238:241], v[66:69]
	v_mfma_f32_16x16x32_bf16 v[66:69], v[192:195], v[242:245], v[66:69]
	s_setprio 0
	s_mov_b32 m0, s1
	v_lshl_add_u64 v[166:167], v[166:167], 0, s[76:77]
	ds_read_b128 v[196:199], v149 offset:49152
	ds_read_b128 v[200:203], v149 offset:50176
	ds_read_b128 v[222:225], v149 offset:51200
	ds_read_b128 v[226:229], v149 offset:52224
	ds_read_b128 v[230:233], v149 offset:53248
	ds_read_b128 v[234:237], v149 offset:54272
	ds_read_b128 v[238:241], v149 offset:55296
	ds_read_b128 v[242:245], v149 offset:56320
	global_load_lds_dwordx4 v[166:167], off
	v_lshl_add_u64 v[166:167], v[168:169], 0, s[76:77]
	s_mov_b32 m0, s0
	s_nop 0
	global_load_lds_dwordx4 v[166:167], off
	v_lshl_add_u64 v[166:167], s[36:37], 0, v[136:137]
	s_mov_b32 m0, s46
	s_nop 0
	global_load_lds_dwordx4 v[166:167], off
	v_lshl_add_u64 v[166:167], s[36:37], 0, v[132:133]
	s_mov_b32 m0, s31
	s_nop 0
	global_load_lds_dwordx4 v[166:167], off
	s_waitcnt vmcnt(6)
	s_waitcnt lgkmcnt(0)
	s_setprio 1
	s_barrier
	v_mfma_f32_16x16x32_bf16 v[62:65], v[150:153], v[196:199], v[62:65]
	v_mfma_f32_16x16x32_bf16 v[62:65], v[154:157], v[200:203], v[62:65]
	v_mfma_f32_16x16x32_bf16 v[54:57], v[158:161], v[196:199], v[54:57]
	v_mfma_f32_16x16x32_bf16 v[54:57], v[162:165], v[200:203], v[54:57]
	v_mfma_f32_16x16x32_bf16 v[46:49], v[150:153], v[222:225], v[46:49]
	v_mfma_f32_16x16x32_bf16 v[46:49], v[154:157], v[226:229], v[46:49]
	v_mfma_f32_16x16x32_bf16 v[38:41], v[158:161], v[222:225], v[38:41]
	v_mfma_f32_16x16x32_bf16 v[38:41], v[162:165], v[226:229], v[38:41]
	v_mfma_f32_16x16x32_bf16 v[30:33], v[150:153], v[230:233], v[30:33]
	v_mfma_f32_16x16x32_bf16 v[30:33], v[154:157], v[234:237], v[30:33]
	v_mfma_f32_16x16x32_bf16 v[22:25], v[158:161], v[230:233], v[22:25]
	v_mfma_f32_16x16x32_bf16 v[22:25], v[162:165], v[234:237], v[22:25]
	v_mfma_f32_16x16x32_bf16 v[14:17], v[150:153], v[238:241], v[14:17]
	v_mfma_f32_16x16x32_bf16 v[14:17], v[154:157], v[242:245], v[14:17]
	v_mfma_f32_16x16x32_bf16 v[6:9], v[158:161], v[238:241], v[6:9]
	v_mfma_f32_16x16x32_bf16 v[6:9], v[162:165], v[242:245], v[6:9]
	s_setprio 0
	s_setprio 1
	v_mfma_f32_16x16x32_bf16 v[58:61], v[180:183], v[196:199], v[58:61]
	v_mfma_f32_16x16x32_bf16 v[58:61], v[184:187], v[200:203], v[58:61]
	v_mfma_f32_16x16x32_bf16 v[50:53], v[188:191], v[196:199], v[50:53]
	v_mfma_f32_16x16x32_bf16 v[50:53], v[192:195], v[200:203], v[50:53]
	v_mfma_f32_16x16x32_bf16 v[42:45], v[180:183], v[222:225], v[42:45]
	v_mfma_f32_16x16x32_bf16 v[42:45], v[184:187], v[226:229], v[42:45]
	v_mfma_f32_16x16x32_bf16 v[34:37], v[188:191], v[222:225], v[34:37]
	v_mfma_f32_16x16x32_bf16 v[34:37], v[192:195], v[226:229], v[34:37]
	v_mfma_f32_16x16x32_bf16 v[26:29], v[180:183], v[230:233], v[26:29]
	v_mfma_f32_16x16x32_bf16 v[26:29], v[184:187], v[234:237], v[26:29]
	v_mfma_f32_16x16x32_bf16 v[18:21], v[188:191], v[230:233], v[18:21]
	v_mfma_f32_16x16x32_bf16 v[18:21], v[192:195], v[234:237], v[18:21]
	v_mfma_f32_16x16x32_bf16 v[10:13], v[180:183], v[238:241], v[10:13]
	v_mfma_f32_16x16x32_bf16 v[10:13], v[184:187], v[242:245], v[10:13]
	s_setprio 2
	s_barrier
	v_mfma_f32_16x16x32_bf16 v[2:5], v[188:191], v[238:241], v[2:5]
	v_mfma_f32_16x16x32_bf16 v[2:5], v[192:195], v[242:245], v[2:5]
	s_setprio 0
	v_lshl_add_u64 v[144:145], v[144:145], 0, s[86:87]
	v_lshl_add_u64 v[146:147], v[146:147], 0, s[86:87]
	s_cmp_gt_u32 s30, 31
	s_mov_b32 s29, s30
	s_cbranch_scc1 .Lpx_1458
.LBB0_1458:
	s_lshl_b32 s100, s29, 7
	s_add_u32 s100, s40, s100
	s_addc_u32 s101, s41, 0
	s_add_u32 s100, s100, 0x80
	s_addc_u32 s101, s101, 0
	s_add_i32 s30, s29, 2
	s_cmp_lt_u32 s29, 30
	s_cselect_b32 s0, 0, 0xffffffe0
	s_add_i32 s0, s30, s0
	s_ashr_i32 s1, s0, 31
	s_lshl_b64 s[0:1], s[0:1], 7
	s_add_u32 s2, s40, s0
	s_addc_u32 s31, s41, s1
	s_add_u32 s0, s34, s0
	s_addc_u32 s1, s35, s1
	s_cmp_eq_u32 s29, 30
	s_cselect_b32 s45, s13, s31
	s_cselect_b32 s44, s15, s2
	s_cselect_b32 s49, s71, s1
	s_cselect_b32 s48, s75, s0
	s_add_i32 s2, 0, 0x10000
	s_add_i32 s78, s2, s56
	s_add_i32 s31, 0, 0x14000
	s_add_i32 s47, s57, 0xe000
	s_add_i32 s81, s78, 0x2000
	s_add_u32 s50, s48, 0x80000
	s_addc_u32 s51, s49, 0
	s_add_i32 s82, s31, s56
	v_add_u32_e32 v162, s2, v99
	v_add_u32_e32 v166, s31, v99
	s_add_i32 s83, s82, 0x2000
	s_add_i32 s84, 0, 0x18000
	s_add_i32 s88, 0, 0x1c000
	ds_read_b128 v[150:153], v162
	ds_read_b128 v[154:157], v162 offset:1024
	ds_read_b128 v[158:161], v162 offset:2048
	ds_read_b128 v[162:165], v162 offset:3072
	ds_read_b128 v[180:183], v166
	ds_read_b128 v[184:187], v166 offset:1024
	ds_read_b128 v[188:191], v166 offset:2048
	ds_read_b128 v[192:195], v166 offset:3072
	s_add_u32 s42, s44, 0x80000
	s_addc_u32 s43, s45, 0
	s_add_i32 s1, s84, s56
	s_add_i32 s0, s1, 0x2000
	s_add_u32 s36, s48, 0x80080
	s_addc_u32 s37, s49, 0
	s_add_i32 s46, s88, s56
	s_add_i32 s31, s46, 0x2000
	ds_read_b128 v[196:199], v149
	ds_read_b128 v[200:203], v149 offset:1024
	ds_read_b128 v[222:225], v149 offset:2048
	ds_read_b128 v[226:229], v149 offset:3072
	ds_read_b128 v[230:233], v149 offset:4096
	ds_read_b128 v[234:237], v149 offset:5120
	ds_read_b128 v[238:241], v149 offset:6144
	ds_read_b128 v[242:245], v149 offset:7168
	v_lshl_add_u64 v[166:167], s[100:101], 0, v[138:139]
	s_mov_b32 m0, s61
	v_lshl_add_u64 v[168:169], s[100:101], 0, v[134:135]
	global_load_lds_dwordx4 v[166:167], off
	s_mov_b32 m0, s62
	s_nop 0
	global_load_lds_dwordx4 v[168:169], off
	s_add_i32 m0, s57, 0xc000
	s_nop 0
	global_load_lds_dwordx4 v[146:147], off
	s_mov_b32 m0, s47
	s_nop 0
	global_load_lds_dwordx4 v[144:145], off
	s_waitcnt vmcnt(8)
	s_waitcnt lgkmcnt(0)
	s_setprio 1
	s_barrier
; #define PG8_STAGE(bufoff, gbase, voff) do { _Pragma("unroll") for (int _i = 0; _i < 2; ++_i) \
;         __builtin_amdgcn_global_load_lds((const unsigned*)((const char*)(gbase) + (voff)[_i]), (PG8_LAS unsigned*)(lds + (bufoff) + ldsw + _i * 8192), 16, 0, AUX_A); } while (0)
; #define PG8_STAGEB(bufoff, gbase, voff) do { _Pragma("unroll") for (int _i = 0; _i < 2; ++_i) \
;         __builtin_amdgcn_global_load_lds((const unsigned*)((const char*)(gbase) + (voff)[_i]), (PG8_LAS unsigned*)(lds + (bufoff) + ldsw + _i * 8192), 16, 0, AUX_B); } while (0)
; #define PG8_LDA(dst, b, h) do { _Pragma("unroll") for (int m = 0; m < 4; ++m) _Pragma("unroll") for (int k = 0; k < 2; ++k) dst[m][k] = *(const PG8_LAS bf16x8*)(lds + PG8_SA(b, h) + aoff + m * 2048 + k * 1024); } while (0)
; #define PG8_LDB(dst, b, h) do { _Pragma("unroll") for (int n = 0; n < 2; ++n) _Pragma("unroll") for (int k = 0; k < 2; ++k) dst[n][k] = *(const PG8_LAS bf16x8*)(lds + PG8_SB(b, h) + boff + n * 2048 + k * 1024); } while (0)
; #define PG8_WAIT_V(n) asm volatile("s_waitcnt vmcnt(" #n ")" ::: "memory")
; #define PG8_WAIT_L(n) asm volatile("s_waitcnt lgkmcnt(" #n ")" ::: "memory")
; template <class Epi, class Sched, bool ALIGN_EPI = false, bool SP2 = false>
; __device__ __forceinline__ void gemm_phase(PG8_LAS unsigned char* lds, const Gemm g, const Sched& S, const Epi& E) {
;     ...
;             PG8_LDB(B0, 0, 0); PG8_LDB(B1, 0, 1); PG8_SCHED; PG8_LDA(At, 0, 0); PG8_STAGE(PG8_SA(1, 1), a1 + hstep, voffA);
;             PG8_WAIT_V(8); PG8_WAIT_L(0); PG8_BAR; PG8_MMA(0, 0, At, B0); PG8_MMA(0, 1, At, B1); PG8_BAR; PG8_SCHED;
;             PG8_LDA(At, 0, 1); PG8_STAGEB(PG8_SB(0, 0), b2, voffB); PG8_STAGEB(PG8_SB(0, 1), b2 + hstep, voffB); PG8_STAGE(PG8_SA(0, 0), a2, voffA);
;             PG8_WAIT_V(8); PG8_WAIT_L(0); PG8_BAR; PG8_MMA(1, 0, At, B0); PG8_MMA(1, 1, At, B1); PG8_BAR; PG8_SCHED;
;             PG8_LDB(B0, 1, 0); PG8_LDB(B1, 1, 1); PG8_SCHED; PG8_LDA(At, 1, 0); PG8_STAGE(PG8_SA(0, 1), a2 + hstep, voffA);
;             PG8_WAIT_V(8); PG8_WAIT_L(0); PG8_BAR; PG8_MMA(0, 0, At, B0); PG8_MMA(0, 1, At, B1); PG8_BAR; PG8_SCHED;
;             PG8_LDA(At, 1, 1); PG8_STAGEB(PG8_SB(1, 0), b3, voffB); PG8_STAGEB(PG8_SB(1, 1), b3 + hstep, voffB); PG8_STAGE(PG8_SA(1, 0), a3, voffA);
;             PG8_WAIT_V(8); PG8_WAIT_L(0); PG8_BAR; PG8_MMA(1, 0, At, B0); PG8_MMA(1, 1, At, B1); PG8_BAR; PG8_SCHED;
	v_mfma_f32_16x16x32_bf16 v[128:131], v[150:153], v[196:199], v[128:131]
	v_mfma_f32_16x16x32_bf16 v[128:131], v[154:157], v[200:203], v[128:131]
	v_mfma_f32_16x16x32_bf16 v[120:123], v[158:161], v[196:199], v[120:123]
	v_mfma_f32_16x16x32_bf16 v[120:123], v[162:165], v[200:203], v[120:123]
	v_mfma_f32_16x16x32_bf16 v[112:115], v[150:153], v[222:225], v[112:115]
	v_mfma_f32_16x16x32_bf16 v[112:115], v[154:157], v[226:229], v[112:115]
	v_mfma_f32_16x16x32_bf16 v[104:107], v[158:161], v[222:225], v[104:107]
	v_mfma_f32_16x16x32_bf16 v[104:107], v[162:165], v[226:229], v[104:107]
	v_mfma_f32_16x16x32_bf16 v[94:97], v[150:153], v[230:233], v[94:97]
	v_mfma_f32_16x16x32_bf16 v[94:97], v[154:157], v[234:237], v[94:97]
	v_mfma_f32_16x16x32_bf16 v[86:89], v[158:161], v[230:233], v[86:89]
	v_mfma_f32_16x16x32_bf16 v[86:89], v[162:165], v[234:237], v[86:89]
	v_mfma_f32_16x16x32_bf16 v[78:81], v[150:153], v[238:241], v[78:81]
	v_mfma_f32_16x16x32_bf16 v[78:81], v[154:157], v[242:245], v[78:81]
	v_mfma_f32_16x16x32_bf16 v[70:73], v[158:161], v[238:241], v[70:73]
	v_mfma_f32_16x16x32_bf16 v[70:73], v[162:165], v[242:245], v[70:73]
	s_setprio 0
	s_setprio 1
	v_mfma_f32_16x16x32_bf16 v[124:127], v[180:183], v[196:199], v[124:127]
	v_mfma_f32_16x16x32_bf16 v[124:127], v[184:187], v[200:203], v[124:127]
	v_mfma_f32_16x16x32_bf16 v[116:119], v[188:191], v[196:199], v[116:119]
	v_mfma_f32_16x16x32_bf16 v[116:119], v[192:195], v[200:203], v[116:119]
	v_mfma_f32_16x16x32_bf16 v[108:111], v[180:183], v[222:225], v[108:111]
	v_mfma_f32_16x16x32_bf16 v[108:111], v[184:187], v[226:229], v[108:111]
	v_mfma_f32_16x16x32_bf16 v[100:103], v[188:191], v[222:225], v[100:103]
	v_mfma_f32_16x16x32_bf16 v[100:103], v[192:195], v[226:229], v[100:103]
	v_mfma_f32_16x16x32_bf16 v[90:93], v[180:183], v[230:233], v[90:93]
	v_mfma_f32_16x16x32_bf16 v[90:93], v[184:187], v[234:237], v[90:93]
	v_mfma_f32_16x16x32_bf16 v[82:85], v[188:191], v[230:233], v[82:85]
	v_mfma_f32_16x16x32_bf16 v[82:85], v[192:195], v[234:237], v[82:85]
	v_mfma_f32_16x16x32_bf16 v[74:77], v[180:183], v[238:241], v[74:77]
	v_mfma_f32_16x16x32_bf16 v[74:77], v[184:187], v[242:245], v[74:77]
	s_setprio 2
	s_barrier
	v_mfma_f32_16x16x32_bf16 v[66:69], v[188:191], v[238:241], v[66:69]
	v_mfma_f32_16x16x32_bf16 v[66:69], v[192:195], v[242:245], v[66:69]
	s_setprio 0
	s_mov_b32 m0, s78
	v_lshl_add_u64 v[166:167], s[48:49], 0, v[136:137]
	ds_read_b128 v[196:199], v149 offset:16384
	ds_read_b128 v[200:203], v149 offset:17408
	ds_read_b128 v[222:225], v149 offset:18432
	ds_read_b128 v[226:229], v149 offset:19456
	ds_read_b128 v[230:233], v149 offset:20480
	ds_read_b128 v[234:237], v149 offset:21504
	ds_read_b128 v[238:241], v149 offset:22528
	ds_read_b128 v[242:245], v149 offset:23552
	global_load_lds_dwordx4 v[166:167], off
	v_lshl_add_u64 v[168:169], s[48:49], 0, v[132:133]
	s_mov_b32 m0, s81
	v_lshl_add_u64 v[172:173], s[50:51], 0, v[136:137]
	global_load_lds_dwordx4 v[168:169], off
	s_mov_b32 m0, s82
	global_load_lds_dwordx4 v[172:173], off
	v_lshl_add_u64 v[172:173], s[50:51], 0, v[132:133]
	s_mov_b32 m0, s83
	s_nop 0
	global_load_lds_dwordx4 v[172:173], off
	s_waitcnt vmcnt(6)
	s_waitcnt lgkmcnt(0)
	s_setprio 1
	s_barrier
	v_mfma_f32_16x16x32_bf16 v[62:65], v[150:153], v[196:199], v[62:65]
	v_mfma_f32_16x16x32_bf16 v[62:65], v[154:157], v[200:203], v[62:65]
	v_mfma_f32_16x16x32_bf16 v[54:57], v[158:161], v[196:199], v[54:57]
	v_mfma_f32_16x16x32_bf16 v[54:57], v[162:165], v[200:203], v[54:57]
	v_mfma_f32_16x16x32_bf16 v[46:49], v[150:153], v[222:225], v[46:49]
	v_mfma_f32_16x16x32_bf16 v[46:49], v[154:157], v[226:229], v[46:49]
	v_mfma_f32_16x16x32_bf16 v[38:41], v[158:161], v[222:225], v[38:41]
	v_mfma_f32_16x16x32_bf16 v[38:41], v[162:165], v[226:229], v[38:41]
	v_mfma_f32_16x16x32_bf16 v[30:33], v[150:153], v[230:233], v[30:33]
	v_mfma_f32_16x16x32_bf16 v[30:33], v[154:157], v[234:237], v[30:33]
	v_mfma_f32_16x16x32_bf16 v[22:25], v[158:161], v[230:233], v[22:25]
	v_mfma_f32_16x16x32_bf16 v[22:25], v[162:165], v[234:237], v[22:25]
	v_mfma_f32_16x16x32_bf16 v[14:17], v[150:153], v[238:241], v[14:17]
	v_mfma_f32_16x16x32_bf16 v[14:17], v[154:157], v[242:245], v[14:17]
	v_mfma_f32_16x16x32_bf16 v[6:9], v[158:161], v[238:241], v[6:9]
	v_mfma_f32_16x16x32_bf16 v[6:9], v[162:165], v[242:245], v[6:9]
	s_setprio 0
	s_setprio 1
	v_mfma_f32_16x16x32_bf16 v[58:61], v[180:183], v[196:199], v[58:61]
	v_mfma_f32_16x16x32_bf16 v[58:61], v[184:187], v[200:203], v[58:61]
	v_mfma_f32_16x16x32_bf16 v[50:53], v[188:191], v[196:199], v[50:53]
	v_mfma_f32_16x16x32_bf16 v[50:53], v[192:195], v[200:203], v[50:53]
	v_mfma_f32_16x16x32_bf16 v[42:45], v[180:183], v[222:225], v[42:45]
	v_mfma_f32_16x16x32_bf16 v[42:45], v[184:187], v[226:229], v[42:45]
	v_mfma_f32_16x16x32_bf16 v[34:37], v[188:191], v[222:225], v[34:37]
	v_mfma_f32_16x16x32_bf16 v[34:37], v[192:195], v[226:229], v[34:37]
	v_mfma_f32_16x16x32_bf16 v[26:29], v[180:183], v[230:233], v[26:29]
	v_mfma_f32_16x16x32_bf16 v[26:29], v[184:187], v[234:237], v[26:29]
	v_mfma_f32_16x16x32_bf16 v[18:21], v[188:191], v[230:233], v[18:21]
	v_mfma_f32_16x16x32_bf16 v[18:21], v[192:195], v[234:237], v[18:21]
	v_mfma_f32_16x16x32_bf16 v[10:13], v[180:183], v[238:241], v[10:13]
	v_mfma_f32_16x16x32_bf16 v[10:13], v[184:187], v[242:245], v[10:13]
	s_setprio 2
	s_barrier
; #define PG8_STAGE(bufoff, gbase, voff) do { _Pragma("unroll") for (int _i = 0; _i < 2; ++_i) \
;         __builtin_amdgcn_global_load_lds((const unsigned*)((const char*)(gbase) + (voff)[_i]), (PG8_LAS unsigned*)(lds + (bufoff) + ldsw + _i * 8192), 16, 0, AUX_A); } while (0)
; #define PG8_STAGEB(bufoff, gbase, voff) do { _Pragma("unroll") for (int _i = 0; _i < 2; ++_i) \
;         __builtin_amdgcn_global_load_lds((const unsigned*)((const char*)(gbase) + (voff)[_i]), (PG8_LAS unsigned*)(lds + (bufoff) + ldsw + _i * 8192), 16, 0, AUX_B); } while (0)
; #define PG8_LDA(dst, b, h) do { _Pragma("unroll") for (int m = 0; m < 4; ++m) _Pragma("unroll") for (int k = 0; k < 2; ++k) dst[m][k] = *(const PG8_LAS bf16x8*)(lds + PG8_SA(b, h) + aoff + m * 2048 + k * 1024); } while (0)
; #define PG8_LDB(dst, b, h) do { _Pragma("unroll") for (int n = 0; n < 2; ++n) _Pragma("unroll") for (int k = 0; k < 2; ++k) dst[n][k] = *(const PG8_LAS bf16x8*)(lds + PG8_SB(b, h) + boff + n * 2048 + k * 1024); } while (0)
; #define PG8_MMA(ai, bj, At, Bt) do { __builtin_amdgcn_s_setprio(1); _Pragma("unroll") for (int m = 0; m < 4; ++m) _Pragma("unroll") for (int n = 0; n < 2; ++n) _Pragma("unroll") for (int k = 0; k < 2; ++k) \
;         acc[ai][bj][m][n] = __builtin_amdgcn_mfma_f32_16x16x32_bf16(Bt[n][k], At[m][k], acc[ai][bj][m][n], 0, 0, 0); __builtin_amdgcn_s_setprio(0); } while (0)
; #define PG8_WAIT_V(n) asm volatile("s_waitcnt vmcnt(" #n ")" ::: "memory")
; #define PG8_WAIT_L(n) asm volatile("s_waitcnt lgkmcnt(" #n ")" ::: "memory")
; #define PG8_BAR __builtin_amdgcn_s_barrier()
; #define PG8_SCHED __builtin_amdgcn_sched_barrier(0)
; template <class Epi, class Sched, bool ALIGN_EPI = false, bool SP2 = false>
; __device__ __forceinline__ void gemm_phase(PG8_LAS unsigned char* lds, const Gemm g, const Sched& S, const Epi& E) {
;     ...
;             PG8_LDB(B0, 1, 0); PG8_LDB(B1, 1, 1); PG8_SCHED; PG8_LDA(At, 1, 0); PG8_STAGE(PG8_SA(0, 1), a2 + hstep, voffA);
;             PG8_WAIT_V(8); PG8_WAIT_L(0); PG8_BAR; PG8_MMA(0, 0, At, B0); PG8_MMA(0, 1, At, B1); PG8_BAR; PG8_SCHED;
;             PG8_LDA(At, 1, 1); PG8_STAGEB(PG8_SB(1, 0), b3, voffB); PG8_STAGEB(PG8_SB(1, 1), b3 + hstep, voffB); PG8_STAGE(PG8_SA(1, 0), a3, voffA);
;             PG8_WAIT_V(8); PG8_WAIT_L(0); PG8_BAR; PG8_MMA(1, 0, At, B0); PG8_MMA(1, 1, At, B1); PG8_BAR; PG8_SCHED;
	v_mfma_f32_16x16x32_bf16 v[2:5], v[188:191], v[238:241], v[2:5]
	v_mfma_f32_16x16x32_bf16 v[2:5], v[192:195], v[242:245], v[2:5]
	s_setprio 0
	v_add_u32_e32 v162, s84, v99
	v_add_u32_e32 v192, s88, v99
	ds_read_b128 v[150:153], v162
	ds_read_b128 v[154:157], v162 offset:1024
	ds_read_b128 v[158:161], v162 offset:2048
	ds_read_b128 v[162:165], v162 offset:3072
	ds_read_b128 v[180:183], v192
	ds_read_b128 v[184:187], v192 offset:1024
	ds_read_b128 v[188:191], v192 offset:2048
	ds_read_b128 v[192:195], v192 offset:3072
	s_mov_b32 m0, s59
	v_lshl_add_u64 v[246:247], s[42:43], 0, v[138:139]
	ds_read_b128 v[196:199], v149 offset:32768
	ds_read_b128 v[200:203], v149 offset:33792
	ds_read_b128 v[222:225], v149 offset:34816
	ds_read_b128 v[226:229], v149 offset:35840
	ds_read_b128 v[230:233], v149 offset:36864
	ds_read_b128 v[234:237], v149 offset:37888
	ds_read_b128 v[238:241], v149 offset:38912
	ds_read_b128 v[242:245], v149 offset:39936
	v_lshl_add_u64 v[172:173], s[44:45], 0, v[138:139]
	s_mov_b32 m0, s57
	v_lshl_add_u64 v[212:213], s[44:45], 0, v[134:135]
	global_load_lds_dwordx4 v[172:173], off
	s_mov_b32 m0, s58
	s_nop 0
	global_load_lds_dwordx4 v[212:213], off
	s_mov_b32 m0, s59
	s_nop 0
	global_load_lds_dwordx4 v[246:247], off
	v_lshl_add_u64 v[246:247], s[42:43], 0, v[134:135]
	s_mov_b32 m0, s60
	s_nop 0
	global_load_lds_dwordx4 v[246:247], off
	s_waitcnt vmcnt(8)
	s_waitcnt lgkmcnt(0)
	s_setprio 1
	s_barrier
	v_mfma_f32_16x16x32_bf16 v[128:131], v[150:153], v[196:199], v[128:131]
	v_mfma_f32_16x16x32_bf16 v[128:131], v[154:157], v[200:203], v[128:131]
	v_mfma_f32_16x16x32_bf16 v[120:123], v[158:161], v[196:199], v[120:123]
	v_mfma_f32_16x16x32_bf16 v[120:123], v[162:165], v[200:203], v[120:123]
	v_mfma_f32_16x16x32_bf16 v[112:115], v[150:153], v[222:225], v[112:115]
	v_mfma_f32_16x16x32_bf16 v[112:115], v[154:157], v[226:229], v[112:115]
	v_mfma_f32_16x16x32_bf16 v[104:107], v[158:161], v[222:225], v[104:107]
	v_mfma_f32_16x16x32_bf16 v[104:107], v[162:165], v[226:229], v[104:107]
	v_mfma_f32_16x16x32_bf16 v[94:97], v[150:153], v[230:233], v[94:97]
	v_mfma_f32_16x16x32_bf16 v[94:97], v[154:157], v[234:237], v[94:97]
	v_mfma_f32_16x16x32_bf16 v[86:89], v[158:161], v[230:233], v[86:89]
	v_mfma_f32_16x16x32_bf16 v[86:89], v[162:165], v[234:237], v[86:89]
	v_mfma_f32_16x16x32_bf16 v[78:81], v[150:153], v[238:241], v[78:81]
	v_mfma_f32_16x16x32_bf16 v[78:81], v[154:157], v[242:245], v[78:81]
	v_mfma_f32_16x16x32_bf16 v[70:73], v[158:161], v[238:241], v[70:73]
	v_mfma_f32_16x16x32_bf16 v[70:73], v[162:165], v[242:245], v[70:73]
	s_setprio 0
	s_setprio 1
	v_mfma_f32_16x16x32_bf16 v[124:127], v[180:183], v[196:199], v[124:127]
	v_mfma_f32_16x16x32_bf16 v[124:127], v[184:187], v[200:203], v[124:127]
	v_mfma_f32_16x16x32_bf16 v[116:119], v[188:191], v[196:199], v[116:119]
	v_mfma_f32_16x16x32_bf16 v[116:119], v[192:195], v[200:203], v[116:119]
	v_mfma_f32_16x16x32_bf16 v[108:111], v[180:183], v[222:225], v[108:111]
	v_mfma_f32_16x16x32_bf16 v[108:111], v[184:187], v[226:229], v[108:111]
	v_mfma_f32_16x16x32_bf16 v[100:103], v[188:191], v[222:225], v[100:103]
	v_mfma_f32_16x16x32_bf16 v[100:103], v[192:195], v[226:229], v[100:103]
	v_mfma_f32_16x16x32_bf16 v[90:93], v[180:183], v[230:233], v[90:93]
	v_mfma_f32_16x16x32_bf16 v[90:93], v[184:187], v[234:237], v[90:93]
	v_mfma_f32_16x16x32_bf16 v[82:85], v[188:191], v[230:233], v[82:85]
	v_mfma_f32_16x16x32_bf16 v[82:85], v[192:195], v[234:237], v[82:85]
	v_mfma_f32_16x16x32_bf16 v[74:77], v[180:183], v[238:241], v[74:77]
	v_mfma_f32_16x16x32_bf16 v[74:77], v[184:187], v[242:245], v[74:77]
	s_setprio 2
	s_barrier
; #define PG8_STAGE(bufoff, gbase, voff) do { _Pragma("unroll") for (int _i = 0; _i < 2; ++_i) \
;         __builtin_amdgcn_global_load_lds((const unsigned*)((const char*)(gbase) + (voff)[_i]), (PG8_LAS unsigned*)(lds + (bufoff) + ldsw + _i * 8192), 16, 0, AUX_A); } while (0)
; #define PG8_STAGEB(bufoff, gbase, voff) do { _Pragma("unroll") for (int _i = 0; _i < 2; ++_i) \
;         __builtin_amdgcn_global_load_lds((const unsigned*)((const char*)(gbase) + (voff)[_i]), (PG8_LAS unsigned*)(lds + (bufoff) + ldsw + _i * 8192), 16, 0, AUX_B); } while (0)
; #define PG8_WAIT_V(n) asm volatile("s_waitcnt vmcnt(" #n ")" ::: "memory")
; #define PG8_WAIT_L(n) asm volatile("s_waitcnt lgkmcnt(" #n ")" ::: "memory")
; template <class Epi, class Sched, bool ALIGN_EPI = false, bool SP2 = false>
; __device__ __forceinline__ void gemm_phase(PG8_LAS unsigned char* lds, const Gemm g, const Sched& S, const Epi& E) {
;     ...
;         for (int t = 0; t < nt; t += 2) {
;             const bool last = (t == nt - 2);
;             const char* a1 = PG8_KP(cA, t + 1, rot, nt);
;             const char* a2 = last ? nAr : PG8_KP(cA, t + 2, rot, nt); const char* b2 = last ? nBr : PG8_KP(cB, t + 2, rot, nt);
;             const char* a3 = a2 + kstep; const char* b3 = b2 + kstep;
;             if (last && has_next) S.a_ready(nxt);
;             if constexpr (SP2) {
;             PG8_LDB(B0, 0, 0); PG8_LDB(B1, 0, 1); PG8_SCHED; PG8_LDA(At, 0, 0); PG8_STAGE(PG8_SA(1, 1), a1 + hstep, voffA);
;             PG8_WAIT_V(8); PG8_WAIT_L(0); PG8_BAR; PG8_MMA(0, 0, At, B0); PG8_MMA(0, 1, At, B1); PG8_BAR; PG8_SCHED;
;             PG8_LDA(At, 0, 1); PG8_STAGEB(PG8_SB(0, 0), b2, voffB); PG8_STAGEB(PG8_SB(0, 1), b2 + hstep, voffB); PG8_STAGE(PG8_SA(0, 0), a2, voffA);
;             PG8_WAIT_V(8); PG8_WAIT_L(0); PG8_BAR; PG8_MMA(1, 0, At, B0); PG8_MMA(1, 1, At, B1); PG8_BAR; PG8_SCHED;
;             PG8_LDB(B0, 1, 0); PG8_LDB(B1, 1, 1); PG8_SCHED; PG8_LDA(At, 1, 0); PG8_STAGE(PG8_SA(0, 1), a2 + hstep, voffA);
;             PG8_WAIT_V(8); PG8_WAIT_L(0); PG8_BAR; PG8_MMA(0, 0, At, B0); PG8_MMA(0, 1, At, B1); PG8_BAR; PG8_SCHED;
;             PG8_LDA(At, 1, 1); PG8_STAGEB(PG8_SB(1, 0), b3, voffB); PG8_STAGEB(PG8_SB(1, 1), b3 + hstep, voffB); PG8_STAGE(PG8_SA(1, 0), a3, voffA);
;             PG8_WAIT_V(8); PG8_WAIT_L(0); PG8_BAR; PG8_MMA(1, 0, At, B0); PG8_MMA(1, 1, At, B1); PG8_BAR; PG8_SCHED;
	v_mfma_f32_16x16x32_bf16 v[66:69], v[188:191], v[238:241], v[66:69]
	v_mfma_f32_16x16x32_bf16 v[66:69], v[192:195], v[242:245], v[66:69]
	s_setprio 0
	s_mov_b32 m0, s1
	v_lshl_add_u64 v[166:167], v[166:167], 0, s[76:77]
	ds_read_b128 v[196:199], v149 offset:49152
	ds_read_b128 v[200:203], v149 offset:50176
	ds_read_b128 v[222:225], v149 offset:51200
	ds_read_b128 v[226:229], v149 offset:52224
	ds_read_b128 v[230:233], v149 offset:53248
	ds_read_b128 v[234:237], v149 offset:54272
	ds_read_b128 v[238:241], v149 offset:55296
	ds_read_b128 v[242:245], v149 offset:56320
	global_load_lds_dwordx4 v[166:167], off
	v_lshl_add_u64 v[166:167], v[168:169], 0, s[76:77]
	s_mov_b32 m0, s0
	s_nop 0
	global_load_lds_dwordx4 v[166:167], off
	v_lshl_add_u64 v[166:167], s[36:37], 0, v[136:137]
	s_mov_b32 m0, s46
	s_nop 0
	global_load_lds_dwordx4 v[166:167], off
	v_lshl_add_u64 v[166:167], s[36:37], 0, v[132:133]
	s_mov_b32 m0, s31
	s_nop 0
	global_load_lds_dwordx4 v[166:167], off
	s_waitcnt vmcnt(6)
	s_waitcnt lgkmcnt(0)
	s_setprio 1
	s_barrier
	v_mfma_f32_16x16x32_bf16 v[62:65], v[150:153], v[196:199], v[62:65]
	v_mfma_f32_16x16x32_bf16 v[62:65], v[154:157], v[200:203], v[62:65]
	v_mfma_f32_16x16x32_bf16 v[54:57], v[158:161], v[196:199], v[54:57]
	v_mfma_f32_16x16x32_bf16 v[54:57], v[162:165], v[200:203], v[54:57]
	v_mfma_f32_16x16x32_bf16 v[46:49], v[150:153], v[222:225], v[46:49]
	v_mfma_f32_16x16x32_bf16 v[46:49], v[154:157], v[226:229], v[46:49]
	v_mfma_f32_16x16x32_bf16 v[38:41], v[158:161], v[222:225], v[38:41]
	v_mfma_f32_16x16x32_bf16 v[38:41], v[162:165], v[226:229], v[38:41]
	v_mfma_f32_16x16x32_bf16 v[30:33], v[150:153], v[230:233], v[30:33]
	v_mfma_f32_16x16x32_bf16 v[30:33], v[154:157], v[234:237], v[30:33]
	v_mfma_f32_16x16x32_bf16 v[22:25], v[158:161], v[230:233], v[22:25]
	v_mfma_f32_16x16x32_bf16 v[22:25], v[162:165], v[234:237], v[22:25]
	v_mfma_f32_16x16x32_bf16 v[14:17], v[150:153], v[238:241], v[14:17]
	v_mfma_f32_16x16x32_bf16 v[14:17], v[154:157], v[242:245], v[14:17]
	v_mfma_f32_16x16x32_bf16 v[6:9], v[158:161], v[238:241], v[6:9]
	v_mfma_f32_16x16x32_bf16 v[6:9], v[162:165], v[242:245], v[6:9]
	s_setprio 0
	s_setprio 1
	v_mfma_f32_16x16x32_bf16 v[58:61], v[180:183], v[196:199], v[58:61]
	v_mfma_f32_16x16x32_bf16 v[58:61], v[184:187], v[200:203], v[58:61]
	v_mfma_f32_16x16x32_bf16 v[50:53], v[188:191], v[196:199], v[50:53]
	v_mfma_f32_16x16x32_bf16 v[50:53], v[192:195], v[200:203], v[50:53]
	v_mfma_f32_16x16x32_bf16 v[42:45], v[180:183], v[222:225], v[42:45]
	v_mfma_f32_16x16x32_bf16 v[42:45], v[184:187], v[226:229], v[42:45]
	v_mfma_f32_16x16x32_bf16 v[34:37], v[188:191], v[222:225], v[34:37]
	v_mfma_f32_16x16x32_bf16 v[34:37], v[192:195], v[226:229], v[34:37]
	v_mfma_f32_16x16x32_bf16 v[26:29], v[180:183], v[230:233], v[26:29]
	v_mfma_f32_16x16x32_bf16 v[26:29], v[184:187], v[234:237], v[26:29]
	v_mfma_f32_16x16x32_bf16 v[18:21], v[188:191], v[230:233], v[18:21]
	v_mfma_f32_16x16x32_bf16 v[18:21], v[192:195], v[234:237], v[18:21]
	v_mfma_f32_16x16x32_bf16 v[10:13], v[180:183], v[238:241], v[10:13]
	v_mfma_f32_16x16x32_bf16 v[10:13], v[184:187], v[242:245], v[10:13]
	s_setprio 2
	s_barrier
	v_mfma_f32_16x16x32_bf16 v[2:5], v[188:191], v[238:241], v[2:5]
	v_mfma_f32_16x16x32_bf16 v[2:5], v[192:195], v[242:245], v[2:5]
	s_setprio 0
	v_lshl_add_u64 v[144:145], v[144:145], 0, s[86:87]
	v_lshl_add_u64 v[146:147], v[146:147], 0, s[86:87]
	s_cmp_gt_u32 s30, 31
	s_mov_b32 s29, s30
	s_cbranch_scc0 .LBB0_1458

; template <class Epi, class Sched, bool ALIGN_EPI = false, bool SP2 = false>
; __device__ __forceinline__ void gemm_phase(PG8_LAS unsigned char* lds, const Gemm g, const Sched& S, const Epi& E) {
;     ...
;     for (;;) {
;         const bool has_next = S.next(ui + 1, nxt);
;         const char* nA = has_next ? (const char*)g.A + (size_t)nxt.pm * tstep + (size_t)nxt.kt0 * kstep : cA; const char* nB = has_next ? (const char*)g.Bt + (size_t)nxt.pn * tstep + (size_t)nxt.kt0 * kstep : cB;
;         const int nt = cur.nkt, rot = cur.krot;
;         const char* nAr = has_next ? nA + (size_t)nxt.krot * kstep : PG8_KP(cA, 0, rot, nt); const char* nBr = has_next ? nB + (size_t)nxt.krot * kstep : PG8_KP(cB, 0, rot, nt);
;         for (int t = 0; t < nt; t += 2) {
;             const bool last = (t == nt - 2);
;             const char* a1 = PG8_KP(cA, t + 1, rot, nt);
;             const char* a2 = last ? nAr : PG8_KP(cA, t + 2, rot, nt); const char* b2 = last ? nBr : PG8_KP(cB, t + 2, rot, nt);
;             const char* a3 = a2 + kstep; const char* b3 = b2 + kstep;
;             if (last && has_next) S.a_ready(nxt);
;             if constexpr (SP2) {
;             PG8_LDB(B0, 0, 0); PG8_LDB(B1, 0, 1); PG8_SCHED; PG8_LDA(At, 0, 0); PG8_STAGE(PG8_SA(1, 1), a1 + hstep, voffA);
;             PG8_WAIT_V(8); PG8_WAIT_L(0); PG8_BAR; PG8_MMA(0, 0, At, B0); PG8_MMA(0, 1, At, B1); PG8_BAR; PG8_SCHED;
;             PG8_LDA(At, 0, 1); PG8_STAGEB(PG8_SB(0, 0), b2, voffB); PG8_STAGEB(PG8_SB(0, 1), b2 + hstep, voffB); PG8_STAGE(PG8_SA(0, 0), a2, voffA);
;             PG8_WAIT_V(8); PG8_WAIT_L(0); PG8_BAR; PG8_MMA(1, 0, At, B0); PG8_MMA(1, 1, At, B1); PG8_BAR; PG8_SCHED;
;             PG8_LDB(B0, 1, 0); PG8_LDB(B1, 1, 1); PG8_SCHED; PG8_LDA(At, 1, 0); PG8_STAGE(PG8_SA(0, 1), a2 + hstep, voffA);
;             PG8_WAIT_V(8); PG8_WAIT_L(0); PG8_BAR; PG8_MMA(0, 0, At, B0); PG8_MMA(0, 1, At, B1); PG8_BAR; PG8_SCHED;
;             PG8_LDA(At, 1, 1); PG8_STAGEB(PG8_SB(1, 0), b3, voffB); PG8_STAGEB(PG8_SB(1, 1), b3 + hstep, voffB); PG8_STAGE(PG8_SA(1, 0), a3, voffA);
;             PG8_WAIT_V(8); PG8_WAIT_L(0); PG8_BAR; PG8_MMA(1, 0, At, B0); PG8_MMA(1, 1, At, B1); PG8_BAR; PG8_SCHED;
;     ...
;         for (int a = 0; a < 2; ++a)
; #pragma unroll
;             for (int b = 0; b < 2; ++b)
; #pragma unroll
;                 for (int m = 0; m < 4; ++m)
; #pragma unroll
.LBB0_1653:
	s_add_u32 s0, s38, 0x160080
	s_addc_u32 s1, s39, 0
	s_waitcnt vmcnt(0)
	v_lshl_add_u64 v[132:133], s[0:1], 0, v[164:165]
	v_lshl_add_u64 v[134:135], s[0:1], 0, v[166:167]
	s_mov_b32 s15, 0
	s_mov_b32 s83, 2
	s_waitcnt lgkmcnt(0)
.Lpk_1654:
	s_or_b32 s0, s15, 1
	s_cmp_ge_i32 s0, s82
	s_cselect_b32 s2, s82, 0
	s_add_i32 s15, s15, 2
	s_cmp_ge_i32 s15, s82
	s_cselect_b32 s0, s82, 0
	s_sub_i32 s0, s83, s0
	s_ashr_i32 s1, s0, 31
	s_lshl_b64 s[0:1], s[0:1], 7
	s_add_u32 s29, s38, s0
	s_addc_u32 s42, s39, s1
	s_add_u32 s0, s34, s0
	s_addc_u32 s1, s35, s1
	s_cmp_eq_u32 s82, s83
	s_cselect_b32 s45, s41, s42
	s_cselect_b32 s44, s40, s29
	s_cselect_b32 s43, s19, s1
	s_cselect_b32 s42, s18, s0
	s_add_i32 s29, 0, 0x10000
	s_add_i32 s46, 0, 0x14000
	v_add_u32_e32 v148, s29, v99
	v_add_u32_e32 v168, s46, v99
	ds_read_b128 v[136:139], v148
	ds_read_b128 v[140:143], v148 offset:1024
	ds_read_b128 v[144:147], v148 offset:2048
	ds_read_b128 v[148:151], v148 offset:3072
	ds_read_b128 v[152:155], v168
	ds_read_b128 v[180:183], v168 offset:1024
	ds_read_b128 v[184:187], v168 offset:2048
	ds_read_b128 v[190:193], v168 offset:3072
	v_mad_i64_i32 v[168:169], s[0:1], s2, v220, v[134:135]
	s_add_i32 m0, s50, 0xc000
	ds_read_b128 v[194:197], v189
	ds_read_b128 v[198:201], v189 offset:1024
	ds_read_b128 v[222:225], v189 offset:2048
	ds_read_b128 v[226:229], v189 offset:3072
	ds_read_b128 v[230:233], v189 offset:4096
	ds_read_b128 v[234:237], v189 offset:5120
	ds_read_b128 v[238:241], v189 offset:6144
	ds_read_b128 v[242:245], v189 offset:7168
	global_load_lds_dwordx4 v[168:169], off
	v_mad_i64_i32 v[168:169], s[0:1], s2, v220, v[132:133]
	s_add_i32 m0, s50, 0xe000
	s_nop 0
	global_load_lds_dwordx4 v[168:169], off
	s_waitcnt vmcnt(8)
	s_waitcnt lgkmcnt(0)
	s_setprio 1
	s_barrier
	v_mfma_f32_16x16x32_bf16 v[128:131], v[136:139], v[194:197], 0
	v_mfma_f32_16x16x32_bf16 v[128:131], v[140:143], v[198:201], v[128:131]
	v_mfma_f32_16x16x32_bf16 v[124:127], v[144:147], v[194:197], 0
	v_mfma_f32_16x16x32_bf16 v[124:127], v[148:151], v[198:201], v[124:127]
	v_mfma_f32_16x16x32_bf16 v[120:123], v[136:139], v[222:225], 0
	v_mfma_f32_16x16x32_bf16 v[120:123], v[140:143], v[226:229], v[120:123]
	v_mfma_f32_16x16x32_bf16 v[112:115], v[144:147], v[222:225], 0
	v_mfma_f32_16x16x32_bf16 v[112:115], v[148:151], v[226:229], v[112:115]
	v_mfma_f32_16x16x32_bf16 v[104:107], v[136:139], v[230:233], 0
	v_mfma_f32_16x16x32_bf16 v[104:107], v[140:143], v[234:237], v[104:107]
	v_mfma_f32_16x16x32_bf16 v[94:97], v[144:147], v[230:233], 0
	v_mfma_f32_16x16x32_bf16 v[94:97], v[148:151], v[234:237], v[94:97]
	v_mfma_f32_16x16x32_bf16 v[86:89], v[136:139], v[238:241], 0
	v_mfma_f32_16x16x32_bf16 v[86:89], v[140:143], v[242:245], v[86:89]
	v_mfma_f32_16x16x32_bf16 v[78:81], v[144:147], v[238:241], 0
	v_mfma_f32_16x16x32_bf16 v[78:81], v[148:151], v[242:245], v[78:81]
	s_setprio 0
	s_setprio 1
	v_mfma_f32_16x16x32_bf16 v[116:119], v[152:155], v[194:197], 0
	v_mfma_f32_16x16x32_bf16 v[116:119], v[180:183], v[198:201], v[116:119]
	v_mfma_f32_16x16x32_bf16 v[108:111], v[184:187], v[194:197], 0
	v_mfma_f32_16x16x32_bf16 v[108:111], v[190:193], v[198:201], v[108:111]
	v_mfma_f32_16x16x32_bf16 v[100:103], v[152:155], v[222:225], 0
	v_mfma_f32_16x16x32_bf16 v[100:103], v[180:183], v[226:229], v[100:103]
	v_mfma_f32_16x16x32_bf16 v[90:93], v[184:187], v[222:225], 0
	v_mfma_f32_16x16x32_bf16 v[90:93], v[190:193], v[226:229], v[90:93]
	v_mfma_f32_16x16x32_bf16 v[82:85], v[152:155], v[230:233], 0
	v_mfma_f32_16x16x32_bf16 v[82:85], v[180:183], v[234:237], v[82:85]
	v_mfma_f32_16x16x32_bf16 v[74:77], v[184:187], v[230:233], 0
	v_mfma_f32_16x16x32_bf16 v[74:77], v[190:193], v[234:237], v[74:77]
	v_mfma_f32_16x16x32_bf16 v[70:73], v[152:155], v[238:241], 0
	v_mfma_f32_16x16x32_bf16 v[70:73], v[180:183], v[242:245], v[70:73]
	s_setprio 2
	s_barrier
	v_mfma_f32_16x16x32_bf16 v[66:69], v[184:187], v[238:241], 0
	v_mfma_f32_16x16x32_bf16 v[66:69], v[190:193], v[242:245], v[66:69]
	s_setprio 0
	s_add_i32 s0, s29, s49
	v_lshl_add_u64 v[168:169], s[42:43], 0, v[160:161]
	s_mov_b32 m0, s0
	ds_read_b128 v[194:197], v189 offset:16384
	ds_read_b128 v[198:201], v189 offset:17408
	ds_read_b128 v[222:225], v189 offset:18432
	ds_read_b128 v[226:229], v189 offset:19456
	ds_read_b128 v[230:233], v189 offset:20480
	ds_read_b128 v[234:237], v189 offset:21504
	ds_read_b128 v[238:241], v189 offset:22528
	ds_read_b128 v[242:245], v189 offset:23552
	global_load_lds_dwordx4 v[168:169], off
	s_add_i32 m0, s0, 0x2000
	s_add_u32 s0, s42, 0x160000
	v_lshl_add_u64 v[172:173], s[42:43], 0, v[156:157]
	s_addc_u32 s1, s43, 0
	s_add_i32 s2, s46, s49
	global_load_lds_dwordx4 v[172:173], off
	v_lshl_add_u64 v[202:203], s[0:1], 0, v[160:161]
	s_mov_b32 m0, s2
	v_lshl_add_u64 v[212:213], s[44:45], 0, v[158:159]
	global_load_lds_dwordx4 v[202:203], off
	v_lshl_add_u64 v[202:203], s[0:1], 0, v[156:157]
	s_add_i32 m0, s2, 0x2000
	s_nop 0
	global_load_lds_dwordx4 v[202:203], off
	v_lshl_add_u64 v[202:203], s[44:45], 0, v[162:163]
	s_mov_b32 m0, s50
	s_nop 0
	global_load_lds_dwordx4 v[202:203], off
	s_mov_b32 m0, s51
	s_nop 0
	global_load_lds_dwordx4 v[212:213], off
	s_waitcnt vmcnt(8)
	s_waitcnt lgkmcnt(0)
	s_setprio 1
	s_barrier
; #define PG8_STAGE(bufoff, gbase, voff) do { _Pragma("unroll") for (int _i = 0; _i < 2; ++_i) \
;         __builtin_amdgcn_global_load_lds((const unsigned*)((const char*)(gbase) + (voff)[_i]), (PG8_LAS unsigned*)(lds + (bufoff) + ldsw + _i * 8192), 16, 0, AUX_A); } while (0)
; #define PG8_STAGEB(bufoff, gbase, voff) do { _Pragma("unroll") for (int _i = 0; _i < 2; ++_i) \
;         __builtin_amdgcn_global_load_lds((const unsigned*)((const char*)(gbase) + (voff)[_i]), (PG8_LAS unsigned*)(lds + (bufoff) + ldsw + _i * 8192), 16, 0, AUX_B); } while (0)
; #define PG8_LDA(dst, b, h) do { _Pragma("unroll") for (int m = 0; m < 4; ++m) _Pragma("unroll") for (int k = 0; k < 2; ++k) dst[m][k] = *(const PG8_LAS bf16x8*)(lds + PG8_SA(b, h) + aoff + m * 2048 + k * 1024); } while (0)
; #define PG8_LDB(dst, b, h) do { _Pragma("unroll") for (int n = 0; n < 2; ++n) _Pragma("unroll") for (int k = 0; k < 2; ++k) dst[n][k] = *(const PG8_LAS bf16x8*)(lds + PG8_SB(b, h) + boff + n * 2048 + k * 1024); } while (0)
; #define PG8_WAIT_V(n) asm volatile("s_waitcnt vmcnt(" #n ")" ::: "memory")
; #define PG8_WAIT_L(n) asm volatile("s_waitcnt lgkmcnt(" #n ")" ::: "memory")
; template <class Epi, class Sched, bool ALIGN_EPI = false, bool SP2 = false>
; __device__ __forceinline__ void gemm_phase(PG8_LAS unsigned char* lds, const Gemm g, const Sched& S, const Epi& E) {
;     ...
;             PG8_LDB(B0, 0, 0); PG8_LDB(B1, 0, 1); PG8_SCHED; PG8_LDA(At, 0, 0); PG8_STAGE(PG8_SA(1, 1), a1 + hstep, voffA);
;             PG8_WAIT_V(8); PG8_WAIT_L(0); PG8_BAR; PG8_MMA(0, 0, At, B0); PG8_MMA(0, 1, At, B1); PG8_BAR; PG8_SCHED;
;             PG8_LDA(At, 0, 1); PG8_STAGEB(PG8_SB(0, 0), b2, voffB); PG8_STAGEB(PG8_SB(0, 1), b2 + hstep, voffB); PG8_STAGE(PG8_SA(0, 0), a2, voffA);
;             PG8_WAIT_V(8); PG8_WAIT_L(0); PG8_BAR; PG8_MMA(1, 0, At, B0); PG8_MMA(1, 1, At, B1); PG8_BAR; PG8_SCHED;
;             PG8_LDB(B0, 1, 0); PG8_LDB(B1, 1, 1); PG8_SCHED; PG8_LDA(At, 1, 0); PG8_STAGE(PG8_SA(0, 1), a2 + hstep, voffA);
;             PG8_WAIT_V(8); PG8_WAIT_L(0); PG8_BAR; PG8_MMA(0, 0, At, B0); PG8_MMA(0, 1, At, B1); PG8_BAR; PG8_SCHED;
;             PG8_LDA(At, 1, 1); PG8_STAGEB(PG8_SB(1, 0), b3, voffB); PG8_STAGEB(PG8_SB(1, 1), b3 + hstep, voffB); PG8_STAGE(PG8_SA(1, 0), a3, voffA);
;             PG8_WAIT_V(8); PG8_WAIT_L(0); PG8_BAR; PG8_MMA(1, 0, At, B0); PG8_MMA(1, 1, At, B1); PG8_BAR; PG8_SCHED;
	v_mfma_f32_16x16x32_bf16 v[62:65], v[136:139], v[194:197], 0
	v_mfma_f32_16x16x32_bf16 v[62:65], v[140:143], v[198:201], v[62:65]
	v_mfma_f32_16x16x32_bf16 v[58:61], v[144:147], v[194:197], 0
	v_mfma_f32_16x16x32_bf16 v[58:61], v[148:151], v[198:201], v[58:61]
	v_mfma_f32_16x16x32_bf16 v[54:57], v[136:139], v[222:225], 0
	v_mfma_f32_16x16x32_bf16 v[54:57], v[140:143], v[226:229], v[54:57]
	v_mfma_f32_16x16x32_bf16 v[46:49], v[144:147], v[222:225], 0
	v_mfma_f32_16x16x32_bf16 v[46:49], v[148:151], v[226:229], v[46:49]
	v_mfma_f32_16x16x32_bf16 v[38:41], v[136:139], v[230:233], 0
	v_mfma_f32_16x16x32_bf16 v[38:41], v[140:143], v[234:237], v[38:41]
	v_mfma_f32_16x16x32_bf16 v[30:33], v[144:147], v[230:233], 0
	v_mfma_f32_16x16x32_bf16 v[30:33], v[148:151], v[234:237], v[30:33]
	v_mfma_f32_16x16x32_bf16 v[22:25], v[136:139], v[238:241], 0
	v_mfma_f32_16x16x32_bf16 v[22:25], v[140:143], v[242:245], v[22:25]
	v_mfma_f32_16x16x32_bf16 v[14:17], v[144:147], v[238:241], 0
	v_mfma_f32_16x16x32_bf16 v[14:17], v[148:151], v[242:245], v[14:17]
	s_setprio 0
	s_setprio 1
	v_mfma_f32_16x16x32_bf16 v[50:53], v[152:155], v[194:197], 0
	v_mfma_f32_16x16x32_bf16 v[50:53], v[180:183], v[198:201], v[50:53]
	v_mfma_f32_16x16x32_bf16 v[42:45], v[184:187], v[194:197], 0
	v_mfma_f32_16x16x32_bf16 v[42:45], v[190:193], v[198:201], v[42:45]
	v_mfma_f32_16x16x32_bf16 v[34:37], v[152:155], v[222:225], 0
	v_mfma_f32_16x16x32_bf16 v[34:37], v[180:183], v[226:229], v[34:37]
	v_mfma_f32_16x16x32_bf16 v[26:29], v[184:187], v[222:225], 0
	v_mfma_f32_16x16x32_bf16 v[26:29], v[190:193], v[226:229], v[26:29]
	v_mfma_f32_16x16x32_bf16 v[18:21], v[152:155], v[230:233], 0
	v_mfma_f32_16x16x32_bf16 v[18:21], v[180:183], v[234:237], v[18:21]
	v_mfma_f32_16x16x32_bf16 v[10:13], v[184:187], v[230:233], 0
	v_mfma_f32_16x16x32_bf16 v[10:13], v[190:193], v[234:237], v[10:13]
	v_mfma_f32_16x16x32_bf16 v[6:9], v[152:155], v[238:241], 0
	v_mfma_f32_16x16x32_bf16 v[6:9], v[180:183], v[242:245], v[6:9]
	s_setprio 2
	s_barrier
	v_mfma_f32_16x16x32_bf16 v[2:5], v[184:187], v[238:241], 0
	v_mfma_f32_16x16x32_bf16 v[2:5], v[190:193], v[242:245], v[2:5]
	s_setprio 0
	s_add_i32 s2, 0, 0x18000
	s_add_i32 s29, 0, 0x1c000
	v_add_u32_e32 v148, s2, v99
	v_add_u32_e32 v190, s29, v99
	ds_read_b128 v[136:139], v148
	ds_read_b128 v[140:143], v148 offset:1024
	ds_read_b128 v[144:147], v148 offset:2048
	ds_read_b128 v[148:151], v148 offset:3072
	ds_read_b128 v[152:155], v190
	ds_read_b128 v[180:183], v190 offset:1024
	ds_read_b128 v[184:187], v190 offset:2048
	ds_read_b128 v[190:193], v190 offset:3072
	s_add_u32 s0, s44, 0x160000
	s_addc_u32 s1, s45, 0
	s_mov_b32 m0, s52
	v_lshl_add_u64 v[246:247], s[0:1], 0, v[162:163]
	ds_read_b128 v[194:197], v189 offset:32768
	ds_read_b128 v[198:201], v189 offset:33792
	ds_read_b128 v[222:225], v189 offset:34816
	ds_read_b128 v[226:229], v189 offset:35840
	ds_read_b128 v[230:233], v189 offset:36864
	ds_read_b128 v[234:237], v189 offset:37888
	ds_read_b128 v[238:241], v189 offset:38912
	ds_read_b128 v[242:245], v189 offset:39936
	global_load_lds_dwordx4 v[246:247], off
	v_lshl_add_u64 v[246:247], s[0:1], 0, v[158:159]
	s_mov_b32 m0, s53
	s_nop 0
	global_load_lds_dwordx4 v[246:247], off
	s_waitcnt vmcnt(8)
	s_waitcnt lgkmcnt(0)
	s_setprio 1
	s_barrier
	v_mfma_f32_16x16x32_bf16 v[128:131], v[136:139], v[194:197], v[128:131]
	v_mfma_f32_16x16x32_bf16 v[128:131], v[140:143], v[198:201], v[128:131]
	v_mfma_f32_16x16x32_bf16 v[124:127], v[144:147], v[194:197], v[124:127]
	v_mfma_f32_16x16x32_bf16 v[124:127], v[148:151], v[198:201], v[124:127]
	v_mfma_f32_16x16x32_bf16 v[120:123], v[136:139], v[222:225], v[120:123]
	v_mfma_f32_16x16x32_bf16 v[120:123], v[140:143], v[226:229], v[120:123]
	v_mfma_f32_16x16x32_bf16 v[112:115], v[144:147], v[222:225], v[112:115]
	v_mfma_f32_16x16x32_bf16 v[112:115], v[148:151], v[226:229], v[112:115]
	v_mfma_f32_16x16x32_bf16 v[104:107], v[136:139], v[230:233], v[104:107]
	v_mfma_f32_16x16x32_bf16 v[104:107], v[140:143], v[234:237], v[104:107]
	v_mfma_f32_16x16x32_bf16 v[94:97], v[144:147], v[230:233], v[94:97]
	v_mfma_f32_16x16x32_bf16 v[94:97], v[148:151], v[234:237], v[94:97]
	v_mfma_f32_16x16x32_bf16 v[86:89], v[136:139], v[238:241], v[86:89]
	v_mfma_f32_16x16x32_bf16 v[86:89], v[140:143], v[242:245], v[86:89]
	v_mfma_f32_16x16x32_bf16 v[78:81], v[144:147], v[238:241], v[78:81]
	v_mfma_f32_16x16x32_bf16 v[78:81], v[148:151], v[242:245], v[78:81]
	s_setprio 0
	s_setprio 1
	v_mfma_f32_16x16x32_bf16 v[116:119], v[152:155], v[194:197], v[116:119]
	v_mfma_f32_16x16x32_bf16 v[116:119], v[180:183], v[198:201], v[116:119]
	v_mfma_f32_16x16x32_bf16 v[108:111], v[184:187], v[194:197], v[108:111]
	v_mfma_f32_16x16x32_bf16 v[108:111], v[190:193], v[198:201], v[108:111]
	v_mfma_f32_16x16x32_bf16 v[100:103], v[152:155], v[222:225], v[100:103]
	v_mfma_f32_16x16x32_bf16 v[100:103], v[180:183], v[226:229], v[100:103]
	v_mfma_f32_16x16x32_bf16 v[90:93], v[184:187], v[222:225], v[90:93]
	v_mfma_f32_16x16x32_bf16 v[90:93], v[190:193], v[226:229], v[90:93]
	v_mfma_f32_16x16x32_bf16 v[82:85], v[152:155], v[230:233], v[82:85]
	v_mfma_f32_16x16x32_bf16 v[82:85], v[180:183], v[234:237], v[82:85]
	v_mfma_f32_16x16x32_bf16 v[74:77], v[184:187], v[230:233], v[74:77]
	v_mfma_f32_16x16x32_bf16 v[74:77], v[190:193], v[234:237], v[74:77]
	v_mfma_f32_16x16x32_bf16 v[70:73], v[152:155], v[238:241], v[70:73]
	v_mfma_f32_16x16x32_bf16 v[70:73], v[180:183], v[242:245], v[70:73]
	s_setprio 2
	s_barrier
; #define PG8_STAGE(bufoff, gbase, voff) do { _Pragma("unroll") for (int _i = 0; _i < 2; ++_i) \
;         __builtin_amdgcn_global_load_lds((const unsigned*)((const char*)(gbase) + (voff)[_i]), (PG8_LAS unsigned*)(lds + (bufoff) + ldsw + _i * 8192), 16, 0, AUX_A); } while (0)
; #define PG8_STAGEB(bufoff, gbase, voff) do { _Pragma("unroll") for (int _i = 0; _i < 2; ++_i) \
;         __builtin_amdgcn_global_load_lds((const unsigned*)((const char*)(gbase) + (voff)[_i]), (PG8_LAS unsigned*)(lds + (bufoff) + ldsw + _i * 8192), 16, 0, AUX_B); } while (0)
; #define PG8_WAIT_V(n) asm volatile("s_waitcnt vmcnt(" #n ")" ::: "memory")
; #define PG8_WAIT_L(n) asm volatile("s_waitcnt lgkmcnt(" #n ")" ::: "memory")
; template <class Epi, class Sched, bool ALIGN_EPI = false, bool SP2 = false>
; __device__ __forceinline__ void gemm_phase(PG8_LAS unsigned char* lds, const Gemm g, const Sched& S, const Epi& E) {
;     ...
;         for (int t = 0; t < nt; t += 2) {
;             const bool last = (t == nt - 2);
;             const char* a1 = PG8_KP(cA, t + 1, rot, nt);
;             const char* a2 = last ? nAr : PG8_KP(cA, t + 2, rot, nt); const char* b2 = last ? nBr : PG8_KP(cB, t + 2, rot, nt);
;             const char* a3 = a2 + kstep; const char* b3 = b2 + kstep;
;             if (last && has_next) S.a_ready(nxt);
;             if constexpr (SP2) {
;             PG8_LDB(B0, 0, 0); PG8_LDB(B1, 0, 1); PG8_SCHED; PG8_LDA(At, 0, 0); PG8_STAGE(PG8_SA(1, 1), a1 + hstep, voffA);
;             PG8_WAIT_V(8); PG8_WAIT_L(0); PG8_BAR; PG8_MMA(0, 0, At, B0); PG8_MMA(0, 1, At, B1); PG8_BAR; PG8_SCHED;
;             PG8_LDA(At, 0, 1); PG8_STAGEB(PG8_SB(0, 0), b2, voffB); PG8_STAGEB(PG8_SB(0, 1), b2 + hstep, voffB); PG8_STAGE(PG8_SA(0, 0), a2, voffA);
;             PG8_WAIT_V(8); PG8_WAIT_L(0); PG8_BAR; PG8_MMA(1, 0, At, B0); PG8_MMA(1, 1, At, B1); PG8_BAR; PG8_SCHED;
;             PG8_LDB(B0, 1, 0); PG8_LDB(B1, 1, 1); PG8_SCHED; PG8_LDA(At, 1, 0); PG8_STAGE(PG8_SA(0, 1), a2 + hstep, voffA);
;             PG8_WAIT_V(8); PG8_WAIT_L(0); PG8_BAR; PG8_MMA(0, 0, At, B0); PG8_MMA(0, 1, At, B1); PG8_BAR; PG8_SCHED;
;             PG8_LDA(At, 1, 1); PG8_STAGEB(PG8_SB(1, 0), b3, voffB); PG8_STAGEB(PG8_SB(1, 1), b3 + hstep, voffB); PG8_STAGE(PG8_SA(1, 0), a3, voffA);
;             PG8_WAIT_V(8); PG8_WAIT_L(0); PG8_BAR; PG8_MMA(1, 0, At, B0); PG8_MMA(1, 1, At, B1); PG8_BAR; PG8_SCHED;
	v_mfma_f32_16x16x32_bf16 v[66:69], v[184:187], v[238:241], v[66:69]
	v_mfma_f32_16x16x32_bf16 v[66:69], v[190:193], v[242:245], v[66:69]
	s_setprio 0
	s_add_i32 s0, s2, s49
	v_lshl_add_u64 v[168:169], v[168:169], 0, s[76:77]
	s_mov_b32 m0, s0
	ds_read_b128 v[194:197], v189 offset:49152
	ds_read_b128 v[198:201], v189 offset:50176
	ds_read_b128 v[222:225], v189 offset:51200
	ds_read_b128 v[226:229], v189 offset:52224
	ds_read_b128 v[230:233], v189 offset:53248
	ds_read_b128 v[234:237], v189 offset:54272
	ds_read_b128 v[238:241], v189 offset:55296
	ds_read_b128 v[242:245], v189 offset:56320
	global_load_lds_dwordx4 v[168:169], off
	s_add_i32 m0, s0, 0x2000
	s_add_u32 s0, s42, 0x160080
	v_lshl_add_u64 v[168:169], v[172:173], 0, s[76:77]
	s_addc_u32 s1, s43, 0
	s_add_i32 s2, s29, s49
	global_load_lds_dwordx4 v[168:169], off
	v_lshl_add_u64 v[168:169], s[0:1], 0, v[160:161]
	s_mov_b32 m0, s2
	s_nop 0
	global_load_lds_dwordx4 v[168:169], off
	v_lshl_add_u64 v[168:169], s[0:1], 0, v[156:157]
	s_add_i32 m0, s2, 0x2000
	s_nop 0
	global_load_lds_dwordx4 v[168:169], off
	v_lshl_add_u64 v[168:169], v[202:203], 0, s[76:77]
	s_mov_b32 m0, s60
	s_nop 0
	global_load_lds_dwordx4 v[168:169], off
	v_lshl_add_u64 v[168:169], v[212:213], 0, s[76:77]
	s_mov_b32 m0, s61
	s_nop 0
	global_load_lds_dwordx4 v[168:169], off
	s_waitcnt vmcnt(8)
	s_waitcnt lgkmcnt(0)
	s_setprio 1
	s_barrier
	v_mfma_f32_16x16x32_bf16 v[62:65], v[136:139], v[194:197], v[62:65]
	v_mfma_f32_16x16x32_bf16 v[62:65], v[140:143], v[198:201], v[62:65]
	v_mfma_f32_16x16x32_bf16 v[58:61], v[144:147], v[194:197], v[58:61]
	v_mfma_f32_16x16x32_bf16 v[58:61], v[148:151], v[198:201], v[58:61]
	v_mfma_f32_16x16x32_bf16 v[54:57], v[136:139], v[222:225], v[54:57]
	v_mfma_f32_16x16x32_bf16 v[54:57], v[140:143], v[226:229], v[54:57]
	v_mfma_f32_16x16x32_bf16 v[46:49], v[144:147], v[222:225], v[46:49]
	v_mfma_f32_16x16x32_bf16 v[46:49], v[148:151], v[226:229], v[46:49]
	v_mfma_f32_16x16x32_bf16 v[38:41], v[136:139], v[230:233], v[38:41]
	v_mfma_f32_16x16x32_bf16 v[38:41], v[140:143], v[234:237], v[38:41]
	v_mfma_f32_16x16x32_bf16 v[30:33], v[144:147], v[230:233], v[30:33]
	v_mfma_f32_16x16x32_bf16 v[30:33], v[148:151], v[234:237], v[30:33]
	v_mfma_f32_16x16x32_bf16 v[22:25], v[136:139], v[238:241], v[22:25]
	v_mfma_f32_16x16x32_bf16 v[22:25], v[140:143], v[242:245], v[22:25]
	v_mfma_f32_16x16x32_bf16 v[14:17], v[144:147], v[238:241], v[14:17]
	v_mfma_f32_16x16x32_bf16 v[14:17], v[148:151], v[242:245], v[14:17]
	s_setprio 0
	s_setprio 1
	v_mfma_f32_16x16x32_bf16 v[50:53], v[152:155], v[194:197], v[50:53]
	v_mfma_f32_16x16x32_bf16 v[50:53], v[180:183], v[198:201], v[50:53]
	v_mfma_f32_16x16x32_bf16 v[42:45], v[184:187], v[194:197], v[42:45]
	v_mfma_f32_16x16x32_bf16 v[42:45], v[190:193], v[198:201], v[42:45]
	v_mfma_f32_16x16x32_bf16 v[34:37], v[152:155], v[222:225], v[34:37]
	v_mfma_f32_16x16x32_bf16 v[34:37], v[180:183], v[226:229], v[34:37]
	v_mfma_f32_16x16x32_bf16 v[26:29], v[184:187], v[222:225], v[26:29]
	v_mfma_f32_16x16x32_bf16 v[26:29], v[190:193], v[226:229], v[26:29]
	v_mfma_f32_16x16x32_bf16 v[18:21], v[152:155], v[230:233], v[18:21]
	v_mfma_f32_16x16x32_bf16 v[18:21], v[180:183], v[234:237], v[18:21]
	v_mfma_f32_16x16x32_bf16 v[10:13], v[184:187], v[230:233], v[10:13]
	v_mfma_f32_16x16x32_bf16 v[10:13], v[190:193], v[234:237], v[10:13]
	v_mfma_f32_16x16x32_bf16 v[6:9], v[152:155], v[238:241], v[6:9]
	v_mfma_f32_16x16x32_bf16 v[6:9], v[180:183], v[242:245], v[6:9]
	s_setprio 2
	s_barrier
	v_mfma_f32_16x16x32_bf16 v[2:5], v[184:187], v[238:241], v[2:5]
	v_mfma_f32_16x16x32_bf16 v[2:5], v[190:193], v[242:245], v[2:5]
	s_setprio 0
	s_add_i32 s0, s83, 2
	v_lshl_add_u64 v[132:133], v[132:133], 0, s[86:87]
	v_lshl_add_u64 v[134:135], v[134:135], 0, s[86:87]
	s_cmp_ge_i32 s83, s82
	s_mov_b32 s83, s0
	s_cbranch_scc1 .Lpx_1654
.LBB0_1654:
	s_or_b32 s0, s15, 1
	s_cmp_ge_i32 s0, s82
	s_cselect_b32 s2, s82, 0
	s_add_i32 s15, s15, 2
	s_cmp_ge_i32 s15, s82
	s_cselect_b32 s0, s82, 0
	s_sub_i32 s0, s83, s0
	s_ashr_i32 s1, s0, 31
	s_lshl_b64 s[0:1], s[0:1], 7
	s_add_u32 s29, s38, s0
	s_addc_u32 s42, s39, s1
	s_add_u32 s0, s34, s0
	s_addc_u32 s1, s35, s1
	s_cmp_eq_u32 s82, s83
	s_cselect_b32 s45, s41, s42
	s_cselect_b32 s44, s40, s29
	s_cselect_b32 s43, s19, s1
	s_cselect_b32 s42, s18, s0
	s_add_i32 s29, 0, 0x10000
	s_add_i32 s46, 0, 0x14000
	v_add_u32_e32 v148, s29, v99
	v_add_u32_e32 v168, s46, v99
	ds_read_b128 v[136:139], v148
	ds_read_b128 v[140:143], v148 offset:1024
	ds_read_b128 v[144:147], v148 offset:2048
	ds_read_b128 v[148:151], v148 offset:3072
	ds_read_b128 v[152:155], v168
	ds_read_b128 v[180:183], v168 offset:1024
	ds_read_b128 v[184:187], v168 offset:2048
	ds_read_b128 v[190:193], v168 offset:3072
	v_mad_i64_i32 v[168:169], s[0:1], s2, v220, v[134:135]
	s_add_i32 m0, s50, 0xc000
	ds_read_b128 v[194:197], v189
	ds_read_b128 v[198:201], v189 offset:1024
	ds_read_b128 v[222:225], v189 offset:2048
	ds_read_b128 v[226:229], v189 offset:3072
	ds_read_b128 v[230:233], v189 offset:4096
	ds_read_b128 v[234:237], v189 offset:5120
	ds_read_b128 v[238:241], v189 offset:6144
	ds_read_b128 v[242:245], v189 offset:7168
	global_load_lds_dwordx4 v[168:169], off
	v_mad_i64_i32 v[168:169], s[0:1], s2, v220, v[132:133]
	s_add_i32 m0, s50, 0xe000
	s_nop 0
	global_load_lds_dwordx4 v[168:169], off
	s_waitcnt vmcnt(8)
	s_waitcnt lgkmcnt(0)
	s_setprio 1
	s_barrier
; #define PG8_STAGE(bufoff, gbase, voff) do { _Pragma("unroll") for (int _i = 0; _i < 2; ++_i) \
;         __builtin_amdgcn_global_load_lds((const unsigned*)((const char*)(gbase) + (voff)[_i]), (PG8_LAS unsigned*)(lds + (bufoff) + ldsw + _i * 8192), 16, 0, AUX_A); } while (0)
; #define PG8_STAGEB(bufoff, gbase, voff) do { _Pragma("unroll") for (int _i = 0; _i < 2; ++_i) \
;         __builtin_amdgcn_global_load_lds((const unsigned*)((const char*)(gbase) + (voff)[_i]), (PG8_LAS unsigned*)(lds + (bufoff) + ldsw + _i * 8192), 16, 0, AUX_B); } while (0)
; #define PG8_LDA(dst, b, h) do { _Pragma("unroll") for (int m = 0; m < 4; ++m) _Pragma("unroll") for (int k = 0; k < 2; ++k) dst[m][k] = *(const PG8_LAS bf16x8*)(lds + PG8_SA(b, h) + aoff + m * 2048 + k * 1024); } while (0)
; #define PG8_LDB(dst, b, h) do { _Pragma("unroll") for (int n = 0; n < 2; ++n) _Pragma("unroll") for (int k = 0; k < 2; ++k) dst[n][k] = *(const PG8_LAS bf16x8*)(lds + PG8_SB(b, h) + boff + n * 2048 + k * 1024); } while (0)
; #define PG8_MMA(ai, bj, At, Bt) do { __builtin_amdgcn_s_setprio(1); _Pragma("unroll") for (int m = 0; m < 4; ++m) _Pragma("unroll") for (int n = 0; n < 2; ++n) _Pragma("unroll") for (int k = 0; k < 2; ++k) \
;         acc[ai][bj][m][n] = __builtin_amdgcn_mfma_f32_16x16x32_bf16(Bt[n][k], At[m][k], acc[ai][bj][m][n], 0, 0, 0); __builtin_amdgcn_s_setprio(0); } while (0)
; #define PG8_WAIT_V(n) asm volatile("s_waitcnt vmcnt(" #n ")" ::: "memory")
; #define PG8_WAIT_L(n) asm volatile("s_waitcnt lgkmcnt(" #n ")" ::: "memory")
; #define PG8_BAR __builtin_amdgcn_s_barrier()
; #define PG8_SCHED __builtin_amdgcn_sched_barrier(0)
; template <class Epi, class Sched, bool ALIGN_EPI = false, bool SP2 = false>
; __device__ __forceinline__ void gemm_phase(PG8_LAS unsigned char* lds, const Gemm g, const Sched& S, const Epi& E) {
;     ...
;             PG8_LDB(B0, 0, 0); PG8_LDB(B1, 0, 1); PG8_SCHED; PG8_LDA(At, 0, 0); PG8_STAGE(PG8_SA(1, 1), a1 + hstep, voffA);
;             PG8_WAIT_V(8); PG8_WAIT_L(0); PG8_BAR; PG8_MMA(0, 0, At, B0); PG8_MMA(0, 1, At, B1); PG8_BAR; PG8_SCHED;
;             PG8_LDA(At, 0, 1); PG8_STAGEB(PG8_SB(0, 0), b2, voffB); PG8_STAGEB(PG8_SB(0, 1), b2 + hstep, voffB); PG8_STAGE(PG8_SA(0, 0), a2, voffA);
;             PG8_WAIT_V(8); PG8_WAIT_L(0); PG8_BAR; PG8_MMA(1, 0, At, B0); PG8_MMA(1, 1, At, B1); PG8_BAR; PG8_SCHED;
	v_mfma_f32_16x16x32_bf16 v[128:131], v[136:139], v[194:197], v[128:131]
	v_mfma_f32_16x16x32_bf16 v[128:131], v[140:143], v[198:201], v[128:131]
	v_mfma_f32_16x16x32_bf16 v[124:127], v[144:147], v[194:197], v[124:127]
	v_mfma_f32_16x16x32_bf16 v[124:127], v[148:151], v[198:201], v[124:127]
	v_mfma_f32_16x16x32_bf16 v[120:123], v[136:139], v[222:225], v[120:123]
	v_mfma_f32_16x16x32_bf16 v[120:123], v[140:143], v[226:229], v[120:123]
	v_mfma_f32_16x16x32_bf16 v[112:115], v[144:147], v[222:225], v[112:115]
	v_mfma_f32_16x16x32_bf16 v[112:115], v[148:151], v[226:229], v[112:115]
	v_mfma_f32_16x16x32_bf16 v[104:107], v[136:139], v[230:233], v[104:107]
	v_mfma_f32_16x16x32_bf16 v[104:107], v[140:143], v[234:237], v[104:107]
	v_mfma_f32_16x16x32_bf16 v[94:97], v[144:147], v[230:233], v[94:97]
	v_mfma_f32_16x16x32_bf16 v[94:97], v[148:151], v[234:237], v[94:97]
	v_mfma_f32_16x16x32_bf16 v[86:89], v[136:139], v[238:241], v[86:89]
	v_mfma_f32_16x16x32_bf16 v[86:89], v[140:143], v[242:245], v[86:89]
	v_mfma_f32_16x16x32_bf16 v[78:81], v[144:147], v[238:241], v[78:81]
	v_mfma_f32_16x16x32_bf16 v[78:81], v[148:151], v[242:245], v[78:81]
	s_setprio 0
	s_setprio 1
	v_mfma_f32_16x16x32_bf16 v[116:119], v[152:155], v[194:197], v[116:119]
	v_mfma_f32_16x16x32_bf16 v[116:119], v[180:183], v[198:201], v[116:119]
	v_mfma_f32_16x16x32_bf16 v[108:111], v[184:187], v[194:197], v[108:111]
	v_mfma_f32_16x16x32_bf16 v[108:111], v[190:193], v[198:201], v[108:111]
	v_mfma_f32_16x16x32_bf16 v[100:103], v[152:155], v[222:225], v[100:103]
	v_mfma_f32_16x16x32_bf16 v[100:103], v[180:183], v[226:229], v[100:103]
	v_mfma_f32_16x16x32_bf16 v[90:93], v[184:187], v[222:225], v[90:93]
	v_mfma_f32_16x16x32_bf16 v[90:93], v[190:193], v[226:229], v[90:93]
	v_mfma_f32_16x16x32_bf16 v[82:85], v[152:155], v[230:233], v[82:85]
	v_mfma_f32_16x16x32_bf16 v[82:85], v[180:183], v[234:237], v[82:85]
	v_mfma_f32_16x16x32_bf16 v[74:77], v[184:187], v[230:233], v[74:77]
	v_mfma_f32_16x16x32_bf16 v[74:77], v[190:193], v[234:237], v[74:77]
	v_mfma_f32_16x16x32_bf16 v[70:73], v[152:155], v[238:241], v[70:73]
	v_mfma_f32_16x16x32_bf16 v[70:73], v[180:183], v[242:245], v[70:73]
	s_setprio 2
	s_barrier
	v_mfma_f32_16x16x32_bf16 v[66:69], v[184:187], v[238:241], v[66:69]
	v_mfma_f32_16x16x32_bf16 v[66:69], v[190:193], v[242:245], v[66:69]
	s_setprio 0
	s_add_i32 s0, s29, s49
	v_lshl_add_u64 v[168:169], s[42:43], 0, v[160:161]
	s_mov_b32 m0, s0
	ds_read_b128 v[194:197], v189 offset:16384
	ds_read_b128 v[198:201], v189 offset:17408
	ds_read_b128 v[222:225], v189 offset:18432
	ds_read_b128 v[226:229], v189 offset:19456
	ds_read_b128 v[230:233], v189 offset:20480
	ds_read_b128 v[234:237], v189 offset:21504
	ds_read_b128 v[238:241], v189 offset:22528
	ds_read_b128 v[242:245], v189 offset:23552
	global_load_lds_dwordx4 v[168:169], off
	s_add_i32 m0, s0, 0x2000
	s_add_u32 s0, s42, 0x160000
	v_lshl_add_u64 v[172:173], s[42:43], 0, v[156:157]
	s_addc_u32 s1, s43, 0
	s_add_i32 s2, s46, s49
	global_load_lds_dwordx4 v[172:173], off
	v_lshl_add_u64 v[202:203], s[0:1], 0, v[160:161]
	s_mov_b32 m0, s2
	v_lshl_add_u64 v[212:213], s[44:45], 0, v[158:159]
	global_load_lds_dwordx4 v[202:203], off
	v_lshl_add_u64 v[202:203], s[0:1], 0, v[156:157]
	s_add_i32 m0, s2, 0x2000
	s_nop 0
	global_load_lds_dwordx4 v[202:203], off
	v_lshl_add_u64 v[202:203], s[44:45], 0, v[162:163]
	s_mov_b32 m0, s50
	s_nop 0
	global_load_lds_dwordx4 v[202:203], off
	s_mov_b32 m0, s51
	s_nop 0
	global_load_lds_dwordx4 v[212:213], off
	s_waitcnt vmcnt(8)
	s_waitcnt lgkmcnt(0)
	s_setprio 1
	s_barrier
	v_mfma_f32_16x16x32_bf16 v[62:65], v[136:139], v[194:197], v[62:65]
	v_mfma_f32_16x16x32_bf16 v[62:65], v[140:143], v[198:201], v[62:65]
	v_mfma_f32_16x16x32_bf16 v[58:61], v[144:147], v[194:197], v[58:61]
	v_mfma_f32_16x16x32_bf16 v[58:61], v[148:151], v[198:201], v[58:61]
	v_mfma_f32_16x16x32_bf16 v[54:57], v[136:139], v[222:225], v[54:57]
	v_mfma_f32_16x16x32_bf16 v[54:57], v[140:143], v[226:229], v[54:57]
	v_mfma_f32_16x16x32_bf16 v[46:49], v[144:147], v[222:225], v[46:49]
	v_mfma_f32_16x16x32_bf16 v[46:49], v[148:151], v[226:229], v[46:49]
	v_mfma_f32_16x16x32_bf16 v[38:41], v[136:139], v[230:233], v[38:41]
	v_mfma_f32_16x16x32_bf16 v[38:41], v[140:143], v[234:237], v[38:41]
	v_mfma_f32_16x16x32_bf16 v[30:33], v[144:147], v[230:233], v[30:33]
	v_mfma_f32_16x16x32_bf16 v[30:33], v[148:151], v[234:237], v[30:33]
	v_mfma_f32_16x16x32_bf16 v[22:25], v[136:139], v[238:241], v[22:25]
	v_mfma_f32_16x16x32_bf16 v[22:25], v[140:143], v[242:245], v[22:25]
	v_mfma_f32_16x16x32_bf16 v[14:17], v[144:147], v[238:241], v[14:17]
	v_mfma_f32_16x16x32_bf16 v[14:17], v[148:151], v[242:245], v[14:17]
	s_setprio 0
	s_setprio 1
	v_mfma_f32_16x16x32_bf16 v[50:53], v[152:155], v[194:197], v[50:53]
	v_mfma_f32_16x16x32_bf16 v[50:53], v[180:183], v[198:201], v[50:53]
	v_mfma_f32_16x16x32_bf16 v[42:45], v[184:187], v[194:197], v[42:45]
	v_mfma_f32_16x16x32_bf16 v[42:45], v[190:193], v[198:201], v[42:45]
	v_mfma_f32_16x16x32_bf16 v[34:37], v[152:155], v[222:225], v[34:37]
	v_mfma_f32_16x16x32_bf16 v[34:37], v[180:183], v[226:229], v[34:37]
	v_mfma_f32_16x16x32_bf16 v[26:29], v[184:187], v[222:225], v[26:29]
	v_mfma_f32_16x16x32_bf16 v[26:29], v[190:193], v[226:229], v[26:29]
	v_mfma_f32_16x16x32_bf16 v[18:21], v[152:155], v[230:233], v[18:21]
	v_mfma_f32_16x16x32_bf16 v[18:21], v[180:183], v[234:237], v[18:21]
	v_mfma_f32_16x16x32_bf16 v[10:13], v[184:187], v[230:233], v[10:13]
	v_mfma_f32_16x16x32_bf16 v[10:13], v[190:193], v[234:237], v[10:13]
	v_mfma_f32_16x16x32_bf16 v[6:9], v[152:155], v[238:241], v[6:9]
	v_mfma_f32_16x16x32_bf16 v[6:9], v[180:183], v[242:245], v[6:9]
	s_setprio 2
	s_barrier
; #define PG8_STAGE(bufoff, gbase, voff) do { _Pragma("unroll") for (int _i = 0; _i < 2; ++_i) \
;         __builtin_amdgcn_global_load_lds((const unsigned*)((const char*)(gbase) + (voff)[_i]), (PG8_LAS unsigned*)(lds + (bufoff) + ldsw + _i * 8192), 16, 0, AUX_A); } while (0)
; #define PG8_LDA(dst, b, h) do { _Pragma("unroll") for (int m = 0; m < 4; ++m) _Pragma("unroll") for (int k = 0; k < 2; ++k) dst[m][k] = *(const PG8_LAS bf16x8*)(lds + PG8_SA(b, h) + aoff + m * 2048 + k * 1024); } while (0)
; #define PG8_LDB(dst, b, h) do { _Pragma("unroll") for (int n = 0; n < 2; ++n) _Pragma("unroll") for (int k = 0; k < 2; ++k) dst[n][k] = *(const PG8_LAS bf16x8*)(lds + PG8_SB(b, h) + boff + n * 2048 + k * 1024); } while (0)
; #define PG8_MMA(ai, bj, At, Bt) do { __builtin_amdgcn_s_setprio(1); _Pragma("unroll") for (int m = 0; m < 4; ++m) _Pragma("unroll") for (int n = 0; n < 2; ++n) _Pragma("unroll") for (int k = 0; k < 2; ++k) \
;         acc[ai][bj][m][n] = __builtin_amdgcn_mfma_f32_16x16x32_bf16(Bt[n][k], At[m][k], acc[ai][bj][m][n], 0, 0, 0); __builtin_amdgcn_s_setprio(0); } while (0)
; #define PG8_WAIT_V(n) asm volatile("s_waitcnt vmcnt(" #n ")" ::: "memory")
; #define PG8_WAIT_L(n) asm volatile("s_waitcnt lgkmcnt(" #n ")" ::: "memory")
; #define PG8_BAR __builtin_amdgcn_s_barrier()
; #define PG8_SCHED __builtin_amdgcn_sched_barrier(0)
; template <class Epi, class Sched, bool ALIGN_EPI = false, bool SP2 = false>
; __device__ __forceinline__ void gemm_phase(PG8_LAS unsigned char* lds, const Gemm g, const Sched& S, const Epi& E) {
;     ...
;             PG8_LDB(B0, 1, 0); PG8_LDB(B1, 1, 1); PG8_SCHED; PG8_LDA(At, 1, 0); PG8_STAGE(PG8_SA(0, 1), a2 + hstep, voffA);
;             PG8_WAIT_V(8); PG8_WAIT_L(0); PG8_BAR; PG8_MMA(0, 0, At, B0); PG8_MMA(0, 1, At, B1); PG8_BAR; PG8_SCHED;
	v_mfma_f32_16x16x32_bf16 v[2:5], v[184:187], v[238:241], v[2:5]
	v_mfma_f32_16x16x32_bf16 v[2:5], v[190:193], v[242:245], v[2:5]
	s_setprio 0
	s_add_i32 s2, 0, 0x18000
	s_add_i32 s29, 0, 0x1c000
	v_add_u32_e32 v148, s2, v99
	v_add_u32_e32 v190, s29, v99
	ds_read_b128 v[136:139], v148
	ds_read_b128 v[140:143], v148 offset:1024
	ds_read_b128 v[144:147], v148 offset:2048
	ds_read_b128 v[148:151], v148 offset:3072
	ds_read_b128 v[152:155], v190
	ds_read_b128 v[180:183], v190 offset:1024
	ds_read_b128 v[184:187], v190 offset:2048
	ds_read_b128 v[190:193], v190 offset:3072
	s_add_u32 s0, s44, 0x160000
	s_addc_u32 s1, s45, 0
	s_mov_b32 m0, s52
	v_lshl_add_u64 v[246:247], s[0:1], 0, v[162:163]
	ds_read_b128 v[194:197], v189 offset:32768
	ds_read_b128 v[198:201], v189 offset:33792
	ds_read_b128 v[222:225], v189 offset:34816
	ds_read_b128 v[226:229], v189 offset:35840
	ds_read_b128 v[230:233], v189 offset:36864
	ds_read_b128 v[234:237], v189 offset:37888
	ds_read_b128 v[238:241], v189 offset:38912
	ds_read_b128 v[242:245], v189 offset:39936
	global_load_lds_dwordx4 v[246:247], off
	v_lshl_add_u64 v[246:247], s[0:1], 0, v[158:159]
	s_mov_b32 m0, s53
	s_nop 0
	global_load_lds_dwordx4 v[246:247], off
	s_waitcnt vmcnt(8)
	s_waitcnt lgkmcnt(0)
	s_setprio 1
	s_barrier
	v_mfma_f32_16x16x32_bf16 v[128:131], v[136:139], v[194:197], v[128:131]
	v_mfma_f32_16x16x32_bf16 v[128:131], v[140:143], v[198:201], v[128:131]
	v_mfma_f32_16x16x32_bf16 v[124:127], v[144:147], v[194:197], v[124:127]
	v_mfma_f32_16x16x32_bf16 v[124:127], v[148:151], v[198:201], v[124:127]
	v_mfma_f32_16x16x32_bf16 v[120:123], v[136:139], v[222:225], v[120:123]
	v_mfma_f32_16x16x32_bf16 v[120:123], v[140:143], v[226:229], v[120:123]
	v_mfma_f32_16x16x32_bf16 v[112:115], v[144:147], v[222:225], v[112:115]
	v_mfma_f32_16x16x32_bf16 v[112:115], v[148:151], v[226:229], v[112:115]
	v_mfma_f32_16x16x32_bf16 v[104:107], v[136:139], v[230:233], v[104:107]
	v_mfma_f32_16x16x32_bf16 v[104:107], v[140:143], v[234:237], v[104:107]
	v_mfma_f32_16x16x32_bf16 v[94:97], v[144:147], v[230:233], v[94:97]
	v_mfma_f32_16x16x32_bf16 v[94:97], v[148:151], v[234:237], v[94:97]
	v_mfma_f32_16x16x32_bf16 v[86:89], v[136:139], v[238:241], v[86:89]
	v_mfma_f32_16x16x32_bf16 v[86:89], v[140:143], v[242:245], v[86:89]
	v_mfma_f32_16x16x32_bf16 v[78:81], v[144:147], v[238:241], v[78:81]
	v_mfma_f32_16x16x32_bf16 v[78:81], v[148:151], v[242:245], v[78:81]
	s_setprio 0
	s_setprio 1
	v_mfma_f32_16x16x32_bf16 v[116:119], v[152:155], v[194:197], v[116:119]
	v_mfma_f32_16x16x32_bf16 v[116:119], v[180:183], v[198:201], v[116:119]
	v_mfma_f32_16x16x32_bf16 v[108:111], v[184:187], v[194:197], v[108:111]
	v_mfma_f32_16x16x32_bf16 v[108:111], v[190:193], v[198:201], v[108:111]
	v_mfma_f32_16x16x32_bf16 v[100:103], v[152:155], v[222:225], v[100:103]
	v_mfma_f32_16x16x32_bf16 v[100:103], v[180:183], v[226:229], v[100:103]
	v_mfma_f32_16x16x32_bf16 v[90:93], v[184:187], v[222:225], v[90:93]
	v_mfma_f32_16x16x32_bf16 v[90:93], v[190:193], v[226:229], v[90:93]
	v_mfma_f32_16x16x32_bf16 v[82:85], v[152:155], v[230:233], v[82:85]
	v_mfma_f32_16x16x32_bf16 v[82:85], v[180:183], v[234:237], v[82:85]
	v_mfma_f32_16x16x32_bf16 v[74:77], v[184:187], v[230:233], v[74:77]
	v_mfma_f32_16x16x32_bf16 v[74:77], v[190:193], v[234:237], v[74:77]
	v_mfma_f32_16x16x32_bf16 v[70:73], v[152:155], v[238:241], v[70:73]
	v_mfma_f32_16x16x32_bf16 v[70:73], v[180:183], v[242:245], v[70:73]
	s_setprio 2
	s_barrier
; #define PG8_STAGE(bufoff, gbase, voff) do { _Pragma("unroll") for (int _i = 0; _i < 2; ++_i) \
;         __builtin_amdgcn_global_load_lds((const unsigned*)((const char*)(gbase) + (voff)[_i]), (PG8_LAS unsigned*)(lds + (bufoff) + ldsw + _i * 8192), 16, 0, AUX_A); } while (0)
; #define PG8_STAGEB(bufoff, gbase, voff) do { _Pragma("unroll") for (int _i = 0; _i < 2; ++_i) \
;         __builtin_amdgcn_global_load_lds((const unsigned*)((const char*)(gbase) + (voff)[_i]), (PG8_LAS unsigned*)(lds + (bufoff) + ldsw + _i * 8192), 16, 0, AUX_B); } while (0)
; #define PG8_WAIT_V(n) asm volatile("s_waitcnt vmcnt(" #n ")" ::: "memory")
; #define PG8_WAIT_L(n) asm volatile("s_waitcnt lgkmcnt(" #n ")" ::: "memory")
; template <class Epi, class Sched, bool ALIGN_EPI = false, bool SP2 = false>
; __device__ __forceinline__ void gemm_phase(PG8_LAS unsigned char* lds, const Gemm g, const Sched& S, const Epi& E) {
;     ...
;         for (int t = 0; t < nt; t += 2) {
;             const bool last = (t == nt - 2);
;             const char* a1 = PG8_KP(cA, t + 1, rot, nt);
;             const char* a2 = last ? nAr : PG8_KP(cA, t + 2, rot, nt); const char* b2 = last ? nBr : PG8_KP(cB, t + 2, rot, nt);
;             const char* a3 = a2 + kstep; const char* b3 = b2 + kstep;
;             if (last && has_next) S.a_ready(nxt);
;             if constexpr (SP2) {
;             PG8_LDB(B0, 0, 0); PG8_LDB(B1, 0, 1); PG8_SCHED; PG8_LDA(At, 0, 0); PG8_STAGE(PG8_SA(1, 1), a1 + hstep, voffA);
;             PG8_WAIT_V(8); PG8_WAIT_L(0); PG8_BAR; PG8_MMA(0, 0, At, B0); PG8_MMA(0, 1, At, B1); PG8_BAR; PG8_SCHED;
;             PG8_LDA(At, 0, 1); PG8_STAGEB(PG8_SB(0, 0), b2, voffB); PG8_STAGEB(PG8_SB(0, 1), b2 + hstep, voffB); PG8_STAGE(PG8_SA(0, 0), a2, voffA);
;             PG8_WAIT_V(8); PG8_WAIT_L(0); PG8_BAR; PG8_MMA(1, 0, At, B0); PG8_MMA(1, 1, At, B1); PG8_BAR; PG8_SCHED;
;             PG8_LDB(B0, 1, 0); PG8_LDB(B1, 1, 1); PG8_SCHED; PG8_LDA(At, 1, 0); PG8_STAGE(PG8_SA(0, 1), a2 + hstep, voffA);
;             PG8_WAIT_V(8); PG8_WAIT_L(0); PG8_BAR; PG8_MMA(0, 0, At, B0); PG8_MMA(0, 1, At, B1); PG8_BAR; PG8_SCHED;
;             PG8_LDA(At, 1, 1); PG8_STAGEB(PG8_SB(1, 0), b3, voffB); PG8_STAGEB(PG8_SB(1, 1), b3 + hstep, voffB); PG8_STAGE(PG8_SA(1, 0), a3, voffA);
;             PG8_WAIT_V(8); PG8_WAIT_L(0); PG8_BAR; PG8_MMA(1, 0, At, B0); PG8_MMA(1, 1, At, B1); PG8_BAR; PG8_SCHED;
	v_mfma_f32_16x16x32_bf16 v[66:69], v[184:187], v[238:241], v[66:69]
	v_mfma_f32_16x16x32_bf16 v[66:69], v[190:193], v[242:245], v[66:69]
	s_setprio 0
	s_add_i32 s0, s2, s49
	v_lshl_add_u64 v[168:169], v[168:169], 0, s[76:77]
	s_mov_b32 m0, s0
	ds_read_b128 v[194:197], v189 offset:49152
	ds_read_b128 v[198:201], v189 offset:50176
	ds_read_b128 v[222:225], v189 offset:51200
	ds_read_b128 v[226:229], v189 offset:52224
	ds_read_b128 v[230:233], v189 offset:53248
	ds_read_b128 v[234:237], v189 offset:54272
	ds_read_b128 v[238:241], v189 offset:55296
	ds_read_b128 v[242:245], v189 offset:56320
	global_load_lds_dwordx4 v[168:169], off
	s_add_i32 m0, s0, 0x2000
	s_add_u32 s0, s42, 0x160080
	v_lshl_add_u64 v[168:169], v[172:173], 0, s[76:77]
	s_addc_u32 s1, s43, 0
	s_add_i32 s2, s29, s49
	global_load_lds_dwordx4 v[168:169], off
	v_lshl_add_u64 v[168:169], s[0:1], 0, v[160:161]
	s_mov_b32 m0, s2
	s_nop 0
	global_load_lds_dwordx4 v[168:169], off
	v_lshl_add_u64 v[168:169], s[0:1], 0, v[156:157]
	s_add_i32 m0, s2, 0x2000
	s_nop 0
	global_load_lds_dwordx4 v[168:169], off
	v_lshl_add_u64 v[168:169], v[202:203], 0, s[76:77]
	s_mov_b32 m0, s60
	s_nop 0
	global_load_lds_dwordx4 v[168:169], off
	v_lshl_add_u64 v[168:169], v[212:213], 0, s[76:77]
	s_mov_b32 m0, s61
	s_nop 0
	global_load_lds_dwordx4 v[168:169], off
	s_waitcnt vmcnt(8)
	s_waitcnt lgkmcnt(0)
	s_setprio 1
	s_barrier
	v_mfma_f32_16x16x32_bf16 v[62:65], v[136:139], v[194:197], v[62:65]
	v_mfma_f32_16x16x32_bf16 v[62:65], v[140:143], v[198:201], v[62:65]
	v_mfma_f32_16x16x32_bf16 v[58:61], v[144:147], v[194:197], v[58:61]
	v_mfma_f32_16x16x32_bf16 v[58:61], v[148:151], v[198:201], v[58:61]
	v_mfma_f32_16x16x32_bf16 v[54:57], v[136:139], v[222:225], v[54:57]
	v_mfma_f32_16x16x32_bf16 v[54:57], v[140:143], v[226:229], v[54:57]
	v_mfma_f32_16x16x32_bf16 v[46:49], v[144:147], v[222:225], v[46:49]
	v_mfma_f32_16x16x32_bf16 v[46:49], v[148:151], v[226:229], v[46:49]
	v_mfma_f32_16x16x32_bf16 v[38:41], v[136:139], v[230:233], v[38:41]
	v_mfma_f32_16x16x32_bf16 v[38:41], v[140:143], v[234:237], v[38:41]
	v_mfma_f32_16x16x32_bf16 v[30:33], v[144:147], v[230:233], v[30:33]
	v_mfma_f32_16x16x32_bf16 v[30:33], v[148:151], v[234:237], v[30:33]
	v_mfma_f32_16x16x32_bf16 v[22:25], v[136:139], v[238:241], v[22:25]
	v_mfma_f32_16x16x32_bf16 v[22:25], v[140:143], v[242:245], v[22:25]
	v_mfma_f32_16x16x32_bf16 v[14:17], v[144:147], v[238:241], v[14:17]
	v_mfma_f32_16x16x32_bf16 v[14:17], v[148:151], v[242:245], v[14:17]
	s_setprio 0
	s_setprio 1
	v_mfma_f32_16x16x32_bf16 v[50:53], v[152:155], v[194:197], v[50:53]
	v_mfma_f32_16x16x32_bf16 v[50:53], v[180:183], v[198:201], v[50:53]
	v_mfma_f32_16x16x32_bf16 v[42:45], v[184:187], v[194:197], v[42:45]
	v_mfma_f32_16x16x32_bf16 v[42:45], v[190:193], v[198:201], v[42:45]
	v_mfma_f32_16x16x32_bf16 v[34:37], v[152:155], v[222:225], v[34:37]
	v_mfma_f32_16x16x32_bf16 v[34:37], v[180:183], v[226:229], v[34:37]
	v_mfma_f32_16x16x32_bf16 v[26:29], v[184:187], v[222:225], v[26:29]
	v_mfma_f32_16x16x32_bf16 v[26:29], v[190:193], v[226:229], v[26:29]
	v_mfma_f32_16x16x32_bf16 v[18:21], v[152:155], v[230:233], v[18:21]
	v_mfma_f32_16x16x32_bf16 v[18:21], v[180:183], v[234:237], v[18:21]
	v_mfma_f32_16x16x32_bf16 v[10:13], v[184:187], v[230:233], v[10:13]
	v_mfma_f32_16x16x32_bf16 v[10:13], v[190:193], v[234:237], v[10:13]
	v_mfma_f32_16x16x32_bf16 v[6:9], v[152:155], v[238:241], v[6:9]
	v_mfma_f32_16x16x32_bf16 v[6:9], v[180:183], v[242:245], v[6:9]
	s_setprio 2
	s_barrier
	v_mfma_f32_16x16x32_bf16 v[2:5], v[184:187], v[238:241], v[2:5]
	v_mfma_f32_16x16x32_bf16 v[2:5], v[190:193], v[242:245], v[2:5]
	s_setprio 0
	s_add_i32 s0, s83, 2
	v_lshl_add_u64 v[132:133], v[132:133], 0, s[86:87]
	v_lshl_add_u64 v[134:135], v[134:135], 0, s[86:87]
	s_cmp_ge_i32 s83, s82
	s_mov_b32 s83, s0
	s_cbranch_scc0 .LBB0_1654
